# baseline (speedup 1.0000x reference)
; #define STAGE_A(b, h, kt) { const u16* ap_ = A + (size_t)((h) * ahalf + (unsigned)(kt) * 64u); glds16(ap_ + ao0, l0 + SA_(b, h)); glds16(ap_ + ao1, l0 + SA_(b, h) + 8192); }
; #define STAGE_B(b, h, kt) { const u16* bp_ = ((h) ? B1 : B0) + (unsigned)(kt) * 64u; glds16(bp_ + bo0, l0 + SB_(b, h)); glds16(bp_ + bo1, l0 + SB_(b, h) + 8192); }
; #define LDA(dst, b, h) _Pragma("unroll") for (int m = 0; m < 4; ++m) _Pragma("unroll") for (int k = 0; k < 2; ++k) \
;     dst[m][k] = *(const bf16x8*)(lds + SA_(b, h) + lds_byte(wr * 64 + m * 16 + fr, k * 32 + fq * 8));
; #define LDB(dst, b, h) _Pragma("unroll") for (int n = 0; n < 2; ++n) _Pragma("unroll") for (int k = 0; k < 2; ++k) \
;     dst[n][k] = *(const bf16x8*)(lds + SB_(b, h) + lds_byte(wc * 32 + n * 16 + fr, k * 32 + fq * 8));
; #define MMA(ai, bj, At_, Bt_) { __builtin_amdgcn_s_setprio(1); \
;     _Pragma("unroll") for (int m = 0; m < 4; ++m) _Pragma("unroll") for (int n = 0; n < 2; ++n) _Pragma("unroll") for (int k = 0; k < 2; ++k) \
;       acc[ai][bj][m][n] = MFMA16(Bt_[n][k], At_[m][k], acc[ai][bj][m][n]); \
;     __builtin_amdgcn_s_setprio(0); }
; #define WAIT_L(n) asm volatile("s_waitcnt lgkmcnt(" #n ")" ::: "memory");
; #define BAR __builtin_amdgcn_s_barrier();
; #define SCHED __builtin_amdgcn_sched_barrier(0);
; DI void gemm256(const u16* __restrict__ A, int lda, const u16* __restrict__ B0, const u16* __restrict__ B1, int ldb, int nt, acc_t& acc, char* lds) {
;     ...
;     LDB(Bq0, 0, 0) SCHED LDA(At, 0, 0) STAGE_A(1, 1, t + 1)
;     WAIT_L(8) BAR WAIT_L(0) MMA(0, 0, At, Bq0) BAR SCHED
;     LDB(Bq1, 0, 1) STAGE_B(0, 0, t + 2)
;     BAR WAIT_L(0) MMA(0, 1, At, Bq1) BAR
;     LDA(At, 0, 1) STAGE_A(0, 0, t + 2)
;     BAR WAIT_L(0) MMA(1, 0, At, Bq0) BAR SCHED
.LBB0_168:
	ds_read_b128 v[142:145], v166
	ds_read_b128 v[170:173], v166 offset:1024
	ds_read_b128 v[174:177], v166 offset:2048
	ds_read_b128 v[178:181], v166 offset:3072
	v_add_u32_e32 v167, 0xc000, v149
	v_lshl_add_u64 v[222:223], s[22:23], 0, v[136:137]
	v_readfirstlane_b32 s7, v167
	v_lshl_add_u64 v[168:169], v[222:223], 0, s[0:1]
	s_mov_b32 m0, s7
	ds_read_b128 v[182:185], v148
	ds_read_b128 v[186:189], v148 offset:1024
	ds_read_b128 v[190:193], v147
	ds_read_b128 v[194:197], v147 offset:1024
	ds_read_b128 v[198:201], v146
	ds_read_b128 v[202:205], v146 offset:1024
	ds_read_b128 v[206:209], v141
	ds_read_b128 v[210:213], v141 offset:1024
	global_load_lds_dwordx4 v[168:169], off
	v_add_u32_e32 v168, 0xe000, v149
	v_lshl_add_u64 v[224:225], s[22:23], 0, v[138:139]
	v_readfirstlane_b32 s7, v168
	v_lshl_add_u64 v[216:217], v[224:225], 0, s[0:1]
	s_mov_b32 m0, s7
	s_nop 0
	global_load_lds_dwordx4 v[216:217], off
	s_waitcnt lgkmcnt(8)
	s_barrier
	s_waitcnt lgkmcnt(0)
	s_setprio 0
	s_waitcnt lgkmcnt(0)
	v_mfma_f32_16x16x32_bf16 v[126:129], v[142:145], v[182:185], v[126:129]
	v_mfma_f32_16x16x32_bf16 v[122:125], v[174:177], v[182:185], v[122:125]
	v_mfma_f32_16x16x32_bf16 v[118:121], v[142:145], v[190:193], v[118:121]
	v_mfma_f32_16x16x32_bf16 v[114:117], v[174:177], v[190:193], v[114:117]
	v_mfma_f32_16x16x32_bf16 v[110:113], v[142:145], v[198:201], v[110:113]
	v_mfma_f32_16x16x32_bf16 v[106:109], v[174:177], v[198:201], v[106:109]
	v_mfma_f32_16x16x32_bf16 v[102:105], v[142:145], v[206:209], v[102:105]
	v_mfma_f32_16x16x32_bf16 v[98:101], v[174:177], v[206:209], v[98:101]
	v_mfma_f32_16x16x32_bf16 v[126:129], v[170:173], v[186:189], v[126:129]
	v_mfma_f32_16x16x32_bf16 v[122:125], v[178:181], v[186:189], v[122:125]
	v_mfma_f32_16x16x32_bf16 v[118:121], v[170:173], v[194:197], v[118:121]
	v_mfma_f32_16x16x32_bf16 v[114:117], v[178:181], v[194:197], v[114:117]
	v_mfma_f32_16x16x32_bf16 v[110:113], v[170:173], v[202:205], v[110:113]
	v_mfma_f32_16x16x32_bf16 v[106:109], v[178:181], v[202:205], v[106:109]
	v_mfma_f32_16x16x32_bf16 v[102:105], v[170:173], v[210:213], v[102:105]
	v_mfma_f32_16x16x32_bf16 v[98:101], v[178:181], v[210:213], v[98:101]
	s_setprio 1
	s_barrier
	v_lshl_add_u64 v[238:239], s[22:23], 0, v[132:133]
	v_readfirstlane_b32 s7, v151
	v_lshl_add_u64 v[240:241], v[238:239], 0, s[28:29]
	s_mov_b32 m0, s7
	ds_read_b128 v[216:219], v165
	ds_read_b128 v[226:229], v165 offset:1024
	ds_read_b128 v[230:233], v165 offset:2048
	ds_read_b128 v[234:237], v165 offset:3072
	global_load_lds_dwordx4 v[240:241], off
	v_lshl_add_u64 v[240:241], s[22:23], 0, v[134:135]
	v_readfirstlane_b32 s7, v152
	v_lshl_add_u64 v[242:243], v[240:241], 0, s[28:29]
	s_mov_b32 m0, s7
	s_nop 0
	global_load_lds_dwordx4 v[242:243], off
	s_barrier
	s_waitcnt lgkmcnt(0)
	s_setprio 0
	s_waitcnt lgkmcnt(0)
	v_mfma_f32_16x16x32_bf16 v[94:97], v[216:219], v[182:185], v[94:97]
	v_mfma_f32_16x16x32_bf16 v[90:93], v[230:233], v[182:185], v[90:93]
	v_mfma_f32_16x16x32_bf16 v[86:89], v[216:219], v[190:193], v[86:89]
	v_mfma_f32_16x16x32_bf16 v[82:85], v[230:233], v[190:193], v[82:85]
	v_mfma_f32_16x16x32_bf16 v[78:81], v[216:219], v[198:201], v[78:81]
	v_mfma_f32_16x16x32_bf16 v[74:77], v[230:233], v[198:201], v[74:77]
	v_mfma_f32_16x16x32_bf16 v[70:73], v[216:219], v[206:209], v[70:73]
	v_mfma_f32_16x16x32_bf16 v[66:69], v[230:233], v[206:209], v[66:69]
	v_mfma_f32_16x16x32_bf16 v[94:97], v[226:229], v[186:189], v[94:97]
	v_mfma_f32_16x16x32_bf16 v[90:93], v[234:237], v[186:189], v[90:93]
	v_mfma_f32_16x16x32_bf16 v[86:89], v[226:229], v[194:197], v[86:89]
	v_mfma_f32_16x16x32_bf16 v[82:85], v[234:237], v[194:197], v[82:85]
	v_mfma_f32_16x16x32_bf16 v[78:81], v[226:229], v[202:205], v[78:81]
	v_mfma_f32_16x16x32_bf16 v[74:77], v[234:237], v[202:205], v[74:77]
	v_mfma_f32_16x16x32_bf16 v[70:73], v[226:229], v[210:213], v[70:73]
	v_mfma_f32_16x16x32_bf16 v[66:69], v[234:237], v[210:213], v[66:69]
	s_setprio 1
	v_readfirstlane_b32 s7, v149
	v_lshl_add_u64 v[242:243], v[222:223], 0, s[20:21]
	s_mov_b32 m0, s7
	v_readfirstlane_b32 s7, v153
	s_barrier
	ds_read_b128 v[182:185], v148 offset:16384
	ds_read_b128 v[186:189], v148 offset:17408
	ds_read_b128 v[190:193], v147 offset:16384
	ds_read_b128 v[194:197], v147 offset:17408
	ds_read_b128 v[198:201], v146 offset:16384
	ds_read_b128 v[202:205], v146 offset:17408
	ds_read_b128 v[206:209], v141 offset:16384
	ds_read_b128 v[210:213], v141 offset:17408
	global_load_lds_dwordx4 v[242:243], off
	v_lshl_add_u64 v[242:243], v[224:225], 0, s[20:21]
	s_mov_b32 m0, s7
	s_nop 0
	global_load_lds_dwordx4 v[242:243], off
	s_barrier
	s_waitcnt lgkmcnt(0)
	s_setprio 0
	s_waitcnt lgkmcnt(0)
	v_mfma_f32_16x16x32_bf16 v[60:63], v[142:145], v[182:185], v[60:63]
	v_mfma_f32_16x16x32_bf16 v[56:59], v[174:177], v[182:185], v[56:59]
	v_mfma_f32_16x16x32_bf16 v[52:55], v[142:145], v[190:193], v[52:55]
	v_mfma_f32_16x16x32_bf16 v[48:51], v[174:177], v[190:193], v[48:51]
	v_mfma_f32_16x16x32_bf16 v[44:47], v[142:145], v[198:201], v[44:47]
	v_mfma_f32_16x16x32_bf16 v[40:43], v[174:177], v[198:201], v[40:43]
	v_mfma_f32_16x16x32_bf16 v[36:39], v[142:145], v[206:209], v[36:39]
	v_mfma_f32_16x16x32_bf16 v[32:35], v[174:177], v[206:209], v[32:35]
	v_mfma_f32_16x16x32_bf16 v[60:63], v[170:173], v[186:189], v[60:63]
	v_mfma_f32_16x16x32_bf16 v[56:59], v[178:181], v[186:189], v[56:59]
	v_mfma_f32_16x16x32_bf16 v[52:55], v[170:173], v[194:197], v[52:55]
	v_mfma_f32_16x16x32_bf16 v[48:51], v[178:181], v[194:197], v[48:51]
	v_mfma_f32_16x16x32_bf16 v[44:47], v[170:173], v[202:205], v[44:47]
	v_mfma_f32_16x16x32_bf16 v[40:43], v[178:181], v[202:205], v[40:43]
	v_mfma_f32_16x16x32_bf16 v[36:39], v[170:173], v[210:213], v[36:39]
	v_mfma_f32_16x16x32_bf16 v[32:35], v[178:181], v[210:213], v[32:35]
	s_setprio 1
	s_barrier
; #define STAGE_A(b, h, kt) { const u16* ap_ = A + (size_t)((h) * ahalf + (unsigned)(kt) * 64u); glds16(ap_ + ao0, l0 + SA_(b, h)); glds16(ap_ + ao1, l0 + SA_(b, h) + 8192); }
; #define STAGE_B(b, h, kt) { const u16* bp_ = ((h) ? B1 : B0) + (unsigned)(kt) * 64u; glds16(bp_ + bo0, l0 + SB_(b, h)); glds16(bp_ + bo1, l0 + SB_(b, h) + 8192); }
; #define LDA(dst, b, h) _Pragma("unroll") for (int m = 0; m < 4; ++m) _Pragma("unroll") for (int k = 0; k < 2; ++k) \
;     dst[m][k] = *(const bf16x8*)(lds + SA_(b, h) + lds_byte(wr * 64 + m * 16 + fr, k * 32 + fq * 8));
; #define LDB(dst, b, h) _Pragma("unroll") for (int n = 0; n < 2; ++n) _Pragma("unroll") for (int k = 0; k < 2; ++k) \
;     dst[n][k] = *(const bf16x8*)(lds + SB_(b, h) + lds_byte(wc * 32 + n * 16 + fr, k * 32 + fq * 8));
; #define MMA(ai, bj, At_, Bt_) { __builtin_amdgcn_s_setprio(1); \
;     _Pragma("unroll") for (int m = 0; m < 4; ++m) _Pragma("unroll") for (int n = 0; n < 2; ++n) _Pragma("unroll") for (int k = 0; k < 2; ++k) \
;       acc[ai][bj][m][n] = MFMA16(Bt_[n][k], At_[m][k], acc[ai][bj][m][n]); \
;     __builtin_amdgcn_s_setprio(0); }
; #define WAIT_V(n) asm volatile("s_waitcnt vmcnt(" #n ")" ::: "memory");
; #define WAIT_L(n) asm volatile("s_waitcnt lgkmcnt(" #n ")" ::: "memory");
; #define BAR __builtin_amdgcn_s_barrier();
; #define SCHED __builtin_amdgcn_sched_barrier(0);
; DI void gemm256(const u16* __restrict__ A, int lda, const u16* __restrict__ B0, const u16* __restrict__ B1, int ldb, int nt, acc_t& acc, char* lds) {
;     ...
;     STAGE_B(0, 1, t + 2)
;     WAIT_V(6) BAR MMA(1, 1, At, Bq1) BAR
;     LDB(Bq0, 1, 0) SCHED LDA(At, 1, 0) STAGE_A(0, 1, t + 2)
;     WAIT_L(8) BAR WAIT_L(0) MMA(0, 0, At, Bq0) BAR SCHED
;     LDB(Bq1, 1, 1) STAGE_B(1, 0, t + 3)
;     BAR WAIT_L(0) MMA(0, 1, At, Bq1) BAR
;     LDA(At, 1, 1) STAGE_A(1, 0, t + 3)
	v_readfirstlane_b32 s7, v154
	v_lshl_add_u64 v[142:143], v[238:239], 0, s[36:37]
	s_mov_b32 m0, s7
	v_readfirstlane_b32 s7, v156
	global_load_lds_dwordx4 v[142:143], off
	v_lshl_add_u64 v[142:143], v[240:241], 0, s[36:37]
	s_mov_b32 m0, s7
	s_nop 0
	global_load_lds_dwordx4 v[142:143], off
	s_waitcnt vmcnt(6)
	s_barrier
	s_setprio 0
	v_mfma_f32_16x16x32_bf16 v[28:31], v[216:219], v[182:185], v[28:31]
	v_mfma_f32_16x16x32_bf16 v[24:27], v[230:233], v[182:185], v[24:27]
	v_mfma_f32_16x16x32_bf16 v[20:23], v[216:219], v[190:193], v[20:23]
	v_mfma_f32_16x16x32_bf16 v[16:19], v[230:233], v[190:193], v[16:19]
	v_mfma_f32_16x16x32_bf16 v[12:15], v[216:219], v[198:201], v[12:15]
	v_mfma_f32_16x16x32_bf16 v[8:11], v[230:233], v[198:201], v[8:11]
	v_mfma_f32_16x16x32_bf16 v[4:7], v[216:219], v[206:209], v[4:7]
	v_mfma_f32_16x16x32_bf16 v[0:3], v[230:233], v[206:209], v[0:3]
	v_mfma_f32_16x16x32_bf16 v[28:31], v[226:229], v[186:189], v[28:31]
	v_mfma_f32_16x16x32_bf16 v[24:27], v[234:237], v[186:189], v[24:27]
	v_mfma_f32_16x16x32_bf16 v[20:23], v[226:229], v[194:197], v[20:23]
	v_mfma_f32_16x16x32_bf16 v[16:19], v[234:237], v[194:197], v[16:19]
	v_mfma_f32_16x16x32_bf16 v[12:15], v[226:229], v[202:205], v[12:15]
	v_mfma_f32_16x16x32_bf16 v[8:11], v[234:237], v[202:205], v[8:11]
	v_mfma_f32_16x16x32_bf16 v[4:7], v[226:229], v[210:213], v[4:7]
	v_mfma_f32_16x16x32_bf16 v[0:3], v[234:237], v[210:213], v[0:3]
	s_setprio 1
	s_barrier
	ds_read_b128 v[142:145], v155
	ds_read_b128 v[170:173], v155 offset:1024
	ds_read_b128 v[174:177], v155 offset:2048
	ds_read_b128 v[178:181], v155 offset:3072
	v_readfirstlane_b32 s7, v157
	v_lshl_add_u64 v[216:217], v[222:223], 0, s[24:25]
	s_mov_b32 m0, s7
	v_readfirstlane_b32 s7, v158
	ds_read_b128 v[182:185], v148 offset:32768
	ds_read_b128 v[186:189], v148 offset:33792
	ds_read_b128 v[190:193], v147 offset:32768
	ds_read_b128 v[194:197], v147 offset:33792
	ds_read_b128 v[198:201], v146 offset:32768
	ds_read_b128 v[202:205], v146 offset:33792
	ds_read_b128 v[206:209], v141 offset:32768
	ds_read_b128 v[210:213], v141 offset:33792
	global_load_lds_dwordx4 v[216:217], off
	v_lshl_add_u64 v[216:217], v[224:225], 0, s[24:25]
	s_mov_b32 m0, s7
	s_nop 0
	global_load_lds_dwordx4 v[216:217], off
	s_waitcnt lgkmcnt(8)
	s_barrier
	s_waitcnt lgkmcnt(0)
	s_setprio 0
	s_waitcnt lgkmcnt(0)
	v_mfma_f32_16x16x32_bf16 v[126:129], v[142:145], v[182:185], v[126:129]
	v_mfma_f32_16x16x32_bf16 v[122:125], v[174:177], v[182:185], v[122:125]
	v_mfma_f32_16x16x32_bf16 v[118:121], v[142:145], v[190:193], v[118:121]
	v_mfma_f32_16x16x32_bf16 v[114:117], v[174:177], v[190:193], v[114:117]
	v_mfma_f32_16x16x32_bf16 v[110:113], v[142:145], v[198:201], v[110:113]
	v_mfma_f32_16x16x32_bf16 v[106:109], v[174:177], v[198:201], v[106:109]
	v_mfma_f32_16x16x32_bf16 v[102:105], v[142:145], v[206:209], v[102:105]
	v_mfma_f32_16x16x32_bf16 v[98:101], v[174:177], v[206:209], v[98:101]
	v_mfma_f32_16x16x32_bf16 v[126:129], v[170:173], v[186:189], v[126:129]
	v_mfma_f32_16x16x32_bf16 v[122:125], v[178:181], v[186:189], v[122:125]
	v_mfma_f32_16x16x32_bf16 v[118:121], v[170:173], v[194:197], v[118:121]
	v_mfma_f32_16x16x32_bf16 v[114:117], v[178:181], v[194:197], v[114:117]
	v_mfma_f32_16x16x32_bf16 v[110:113], v[170:173], v[202:205], v[110:113]
	v_mfma_f32_16x16x32_bf16 v[106:109], v[178:181], v[202:205], v[106:109]
	v_mfma_f32_16x16x32_bf16 v[102:105], v[170:173], v[210:213], v[102:105]
	v_mfma_f32_16x16x32_bf16 v[98:101], v[178:181], v[210:213], v[98:101]
	s_setprio 1
	s_barrier
	v_readfirstlane_b32 s7, v159
	v_lshl_add_u64 v[242:243], v[238:239], 0, s[26:27]
	s_mov_b32 m0, s7
	v_readfirstlane_b32 s7, v160
	ds_read_b128 v[216:219], v150
	ds_read_b128 v[226:229], v150 offset:1024
	ds_read_b128 v[230:233], v150 offset:2048
	ds_read_b128 v[234:237], v150 offset:3072
	global_load_lds_dwordx4 v[242:243], off
	v_lshl_add_u64 v[242:243], v[240:241], 0, s[26:27]
	s_mov_b32 m0, s7
	s_nop 0
	global_load_lds_dwordx4 v[242:243], off
	s_barrier
	s_waitcnt lgkmcnt(0)
	s_setprio 0
	s_waitcnt lgkmcnt(0)
	v_mfma_f32_16x16x32_bf16 v[94:97], v[216:219], v[182:185], v[94:97]
	v_mfma_f32_16x16x32_bf16 v[90:93], v[230:233], v[182:185], v[90:93]
	v_mfma_f32_16x16x32_bf16 v[86:89], v[216:219], v[190:193], v[86:89]
	v_mfma_f32_16x16x32_bf16 v[82:85], v[230:233], v[190:193], v[82:85]
	v_mfma_f32_16x16x32_bf16 v[78:81], v[216:219], v[198:201], v[78:81]
	v_mfma_f32_16x16x32_bf16 v[74:77], v[230:233], v[198:201], v[74:77]
	v_mfma_f32_16x16x32_bf16 v[70:73], v[216:219], v[206:209], v[70:73]
	v_mfma_f32_16x16x32_bf16 v[66:69], v[230:233], v[206:209], v[66:69]
	v_mfma_f32_16x16x32_bf16 v[94:97], v[226:229], v[186:189], v[94:97]
	v_mfma_f32_16x16x32_bf16 v[90:93], v[234:237], v[186:189], v[90:93]
	v_mfma_f32_16x16x32_bf16 v[86:89], v[226:229], v[194:197], v[86:89]
	v_mfma_f32_16x16x32_bf16 v[82:85], v[234:237], v[194:197], v[82:85]
	v_mfma_f32_16x16x32_bf16 v[78:81], v[226:229], v[202:205], v[78:81]
	v_mfma_f32_16x16x32_bf16 v[74:77], v[234:237], v[202:205], v[74:77]
	v_mfma_f32_16x16x32_bf16 v[70:73], v[226:229], v[210:213], v[70:73]
	v_mfma_f32_16x16x32_bf16 v[66:69], v[234:237], v[210:213], v[66:69]
	s_setprio 1
	v_readfirstlane_b32 s7, v161
	v_lshl_add_u64 v[222:223], v[222:223], 0, s[34:35]
	s_mov_b32 m0, s7
	v_readfirstlane_b32 s7, v162
	s_barrier
	ds_read_b128 v[182:185], v148 offset:49152
	ds_read_b128 v[186:189], v148 offset:50176
	ds_read_b128 v[190:193], v147 offset:49152
	ds_read_b128 v[194:197], v147 offset:50176
	ds_read_b128 v[198:201], v146 offset:49152
	ds_read_b128 v[202:205], v146 offset:50176
	ds_read_b128 v[206:209], v141 offset:49152
	ds_read_b128 v[210:213], v141 offset:50176
	global_load_lds_dwordx4 v[222:223], off
	v_lshl_add_u64 v[222:223], v[224:225], 0, s[34:35]
	s_mov_b32 m0, s7
	s_nop 0
	global_load_lds_dwordx4 v[222:223], off
	s_barrier
; #define STAGE_A(b, h, kt) { const u16* ap_ = A + (size_t)((h) * ahalf + (unsigned)(kt) * 64u); glds16(ap_ + ao0, l0 + SA_(b, h)); glds16(ap_ + ao1, l0 + SA_(b, h) + 8192); }
; #define STAGE_B(b, h, kt) { const u16* bp_ = ((h) ? B1 : B0) + (unsigned)(kt) * 64u; glds16(bp_ + bo0, l0 + SB_(b, h)); glds16(bp_ + bo1, l0 + SB_(b, h) + 8192); }
; #define LDA(dst, b, h) _Pragma("unroll") for (int m = 0; m < 4; ++m) _Pragma("unroll") for (int k = 0; k < 2; ++k) \
;     dst[m][k] = *(const bf16x8*)(lds + SA_(b, h) + lds_byte(wr * 64 + m * 16 + fr, k * 32 + fq * 8));
; #define LDB(dst, b, h) _Pragma("unroll") for (int n = 0; n < 2; ++n) _Pragma("unroll") for (int k = 0; k < 2; ++k) \
;     dst[n][k] = *(const bf16x8*)(lds + SB_(b, h) + lds_byte(wc * 32 + n * 16 + fr, k * 32 + fq * 8));
; #define MMA(ai, bj, At_, Bt_) { __builtin_amdgcn_s_setprio(1); \
;     _Pragma("unroll") for (int m = 0; m < 4; ++m) _Pragma("unroll") for (int n = 0; n < 2; ++n) _Pragma("unroll") for (int k = 0; k < 2; ++k) \
;       acc[ai][bj][m][n] = MFMA16(Bt_[n][k], At_[m][k], acc[ai][bj][m][n]); \
;     __builtin_amdgcn_s_setprio(0); }
; #define WAIT_V(n) asm volatile("s_waitcnt vmcnt(" #n ")" ::: "memory");
; #define WAIT_L(n) asm volatile("s_waitcnt lgkmcnt(" #n ")" ::: "memory");
; #define BAR __builtin_amdgcn_s_barrier();
; #define SCHED __builtin_amdgcn_sched_barrier(0);
; DI void gemm256(const u16* __restrict__ A, int lda, const u16* __restrict__ B0, const u16* __restrict__ B1, int ldb, int nt, acc_t& acc, char* lds) {
;     ...
;     BAR WAIT_L(0) MMA(1, 0, At, Bq0) BAR SCHED
;     STAGE_B(1, 1, t + 3)
;     WAIT_V(6) BAR MMA(1, 1, At, Bq1) BAR
;   }
;   { LDB(Bq0, 0, 0) LDA(At, 0, 0) STAGE_A(1, 1, nt - 1)
;     BAR WAIT_L(0) MMA(0, 0, At, Bq0) BAR
;     LDB(Bq1, 0, 1) BAR WAIT_L(0) MMA(0, 1, At, Bq1) BAR
	s_waitcnt lgkmcnt(0)
	s_setprio 0
	s_waitcnt lgkmcnt(0)
	v_mfma_f32_16x16x32_bf16 v[60:63], v[142:145], v[182:185], v[60:63]
	v_mfma_f32_16x16x32_bf16 v[56:59], v[174:177], v[182:185], v[56:59]
	v_mfma_f32_16x16x32_bf16 v[52:55], v[142:145], v[190:193], v[52:55]
	v_mfma_f32_16x16x32_bf16 v[48:51], v[174:177], v[190:193], v[48:51]
	v_mfma_f32_16x16x32_bf16 v[44:47], v[142:145], v[198:201], v[44:47]
	v_mfma_f32_16x16x32_bf16 v[40:43], v[174:177], v[198:201], v[40:43]
	v_mfma_f32_16x16x32_bf16 v[36:39], v[142:145], v[206:209], v[36:39]
	v_mfma_f32_16x16x32_bf16 v[32:35], v[174:177], v[206:209], v[32:35]
	v_mfma_f32_16x16x32_bf16 v[60:63], v[170:173], v[186:189], v[60:63]
	v_mfma_f32_16x16x32_bf16 v[56:59], v[178:181], v[186:189], v[56:59]
	v_mfma_f32_16x16x32_bf16 v[52:55], v[170:173], v[194:197], v[52:55]
	v_mfma_f32_16x16x32_bf16 v[48:51], v[178:181], v[194:197], v[48:51]
	v_mfma_f32_16x16x32_bf16 v[44:47], v[170:173], v[202:205], v[44:47]
	v_mfma_f32_16x16x32_bf16 v[40:43], v[178:181], v[202:205], v[40:43]
	v_mfma_f32_16x16x32_bf16 v[36:39], v[170:173], v[210:213], v[36:39]
	v_mfma_f32_16x16x32_bf16 v[32:35], v[178:181], v[210:213], v[32:35]
	s_setprio 1
	s_barrier
	v_readfirstlane_b32 s7, v163
	v_lshl_add_u64 v[142:143], v[238:239], 0, s[38:39]
	s_mov_b32 m0, s7
	v_readfirstlane_b32 s7, v164
	global_load_lds_dwordx4 v[142:143], off
	v_lshl_add_u64 v[142:143], v[240:241], 0, s[38:39]
	s_mov_b32 m0, s7
	s_nop 0
	global_load_lds_dwordx4 v[142:143], off
	s_waitcnt vmcnt(6)
	s_barrier
	s_setprio 0
	v_mfma_f32_16x16x32_bf16 v[28:31], v[216:219], v[182:185], v[28:31]
	v_mfma_f32_16x16x32_bf16 v[24:27], v[230:233], v[182:185], v[24:27]
	v_mfma_f32_16x16x32_bf16 v[20:23], v[216:219], v[190:193], v[20:23]
	v_mfma_f32_16x16x32_bf16 v[16:19], v[230:233], v[190:193], v[16:19]
	v_mfma_f32_16x16x32_bf16 v[12:15], v[216:219], v[198:201], v[12:15]
	v_mfma_f32_16x16x32_bf16 v[8:11], v[230:233], v[198:201], v[8:11]
	v_mfma_f32_16x16x32_bf16 v[4:7], v[216:219], v[206:209], v[4:7]
	v_mfma_f32_16x16x32_bf16 v[0:3], v[230:233], v[206:209], v[0:3]
	v_mfma_f32_16x16x32_bf16 v[28:31], v[226:229], v[186:189], v[28:31]
	v_mfma_f32_16x16x32_bf16 v[24:27], v[234:237], v[186:189], v[24:27]
	v_mfma_f32_16x16x32_bf16 v[20:23], v[226:229], v[194:197], v[20:23]
	v_mfma_f32_16x16x32_bf16 v[16:19], v[234:237], v[194:197], v[16:19]
	v_mfma_f32_16x16x32_bf16 v[12:15], v[226:229], v[202:205], v[12:15]
	v_mfma_f32_16x16x32_bf16 v[8:11], v[234:237], v[202:205], v[8:11]
	v_mfma_f32_16x16x32_bf16 v[4:7], v[226:229], v[210:213], v[4:7]
	v_mfma_f32_16x16x32_bf16 v[0:3], v[234:237], v[210:213], v[0:3]
	s_setprio 1
	s_add_i32 s3, s3, 2
	s_add_u32 s22, s22, 0x100
	s_addc_u32 s23, s23, 0
	s_cmp_lt_u32 s3, 12
	s_barrier
	s_cbranch_scc1 .LBB0_168
	s_add_u32 s8, s8, 0x40780
	s_addc_u32 s9, s9, 0
	v_readfirstlane_b32 s3, v167
	v_lshl_add_u64 v[152:153], v[64:65], 1, s[8:9]
	s_mov_b32 m0, s3
	v_readfirstlane_b32 s3, v168
	ds_read_b128 v[132:135], v166
	ds_read_b128 v[136:139], v166 offset:1024
	ds_read_b128 v[142:145], v166 offset:2048
	ds_read_b128 v[156:159], v166 offset:3072
	ds_read_b128 v[160:163], v148
	ds_read_b128 v[170:173], v148 offset:1024
	ds_read_b128 v[174:177], v147
	ds_read_b128 v[178:181], v147 offset:1024
	ds_read_b128 v[182:185], v146
	ds_read_b128 v[186:189], v146 offset:1024
	ds_read_b128 v[190:193], v141
	ds_read_b128 v[194:197], v141 offset:1024
	global_load_lds_dwordx4 v[152:153], off
	v_lshl_add_u64 v[130:131], v[130:131], 1, s[8:9]
	s_mov_b32 m0, s3
	s_nop 0
	global_load_lds_dwordx4 v[130:131], off
	s_barrier
	s_waitcnt lgkmcnt(0)
	s_setprio 0
	s_waitcnt lgkmcnt(0)
	v_mfma_f32_16x16x32_bf16 v[126:129], v[132:135], v[160:163], v[126:129]
	v_mfma_f32_16x16x32_bf16 v[122:125], v[142:145], v[160:163], v[122:125]
	v_mfma_f32_16x16x32_bf16 v[118:121], v[132:135], v[174:177], v[118:121]
	v_mfma_f32_16x16x32_bf16 v[114:117], v[142:145], v[174:177], v[114:117]
	v_mfma_f32_16x16x32_bf16 v[102:105], v[132:135], v[190:193], v[102:105]
	v_mfma_f32_16x16x32_bf16 v[98:101], v[142:145], v[190:193], v[98:101]
	v_mfma_f32_16x16x32_bf16 v[126:129], v[136:139], v[170:173], v[126:129]
	v_mfma_f32_16x16x32_bf16 v[122:125], v[156:159], v[170:173], v[122:125]
	v_mfma_f32_16x16x32_bf16 v[118:121], v[136:139], v[178:181], v[118:121]
	v_mfma_f32_16x16x32_bf16 v[114:117], v[156:159], v[178:181], v[114:117]
	v_mfma_f32_16x16x32_bf16 v[110:113], v[132:135], v[182:185], v[110:113]
	v_mfma_f32_16x16x32_bf16 v[106:109], v[142:145], v[182:185], v[106:109]
	v_mfma_f32_16x16x32_bf16 v[102:105], v[136:139], v[194:197], v[102:105]
	v_mfma_f32_16x16x32_bf16 v[98:101], v[156:159], v[194:197], v[98:101]
	v_mfma_f32_16x16x32_bf16 v[166:169], v[136:139], v[186:189], v[110:113]
	v_mfma_f32_16x16x32_bf16 v[198:201], v[156:159], v[186:189], v[106:109]
	s_setprio 1
	s_barrier
	s_nop 1
	ds_read_b128 v[106:109], v165
	ds_read_b128 v[110:113], v165 offset:1024
	ds_read_b128 v[202:205], v165 offset:2048
	ds_read_b128 v[206:209], v165 offset:3072
	s_barrier
	s_waitcnt lgkmcnt(0)
	s_setprio 0
	s_waitcnt lgkmcnt(0)
	v_mfma_f32_16x16x32_bf16 v[86:89], v[106:109], v[174:177], v[86:89]
	v_mfma_f32_16x16x32_bf16 v[82:85], v[202:205], v[174:177], v[82:85]
	v_mfma_f32_16x16x32_bf16 v[70:73], v[106:109], v[190:193], v[70:73]
	v_mfma_f32_16x16x32_bf16 v[66:69], v[202:205], v[190:193], v[66:69]
	v_mfma_f32_16x16x32_bf16 v[94:97], v[106:109], v[160:163], v[94:97]
	v_mfma_f32_16x16x32_bf16 v[90:93], v[202:205], v[160:163], v[90:93]
	v_mfma_f32_16x16x32_bf16 v[86:89], v[110:113], v[178:181], v[86:89]
	v_mfma_f32_16x16x32_bf16 v[82:85], v[206:209], v[178:181], v[82:85]
	v_mfma_f32_16x16x32_bf16 v[78:81], v[106:109], v[182:185], v[78:81]
	v_mfma_f32_16x16x32_bf16 v[74:77], v[202:205], v[182:185], v[74:77]
	v_mfma_f32_16x16x32_bf16 v[70:73], v[110:113], v[194:197], v[70:73]
	v_mfma_f32_16x16x32_bf16 v[66:69], v[206:209], v[194:197], v[66:69]
	v_mfma_f32_16x16x32_bf16 v[210:213], v[110:113], v[170:173], v[94:97]
	v_mfma_f32_16x16x32_bf16 v[160:163], v[206:209], v[170:173], v[90:93]
	v_mfma_f32_16x16x32_bf16 v[170:173], v[110:113], v[186:189], v[78:81]
	v_mfma_f32_16x16x32_bf16 v[174:177], v[206:209], v[186:189], v[74:77]
	s_setprio 1
	s_barrier
; #define LDA(dst, b, h) _Pragma("unroll") for (int m = 0; m < 4; ++m) _Pragma("unroll") for (int k = 0; k < 2; ++k) \
;     dst[m][k] = *(const bf16x8*)(lds + SA_(b, h) + lds_byte(wr * 64 + m * 16 + fr, k * 32 + fq * 8));
; #define LDB(dst, b, h) _Pragma("unroll") for (int n = 0; n < 2; ++n) _Pragma("unroll") for (int k = 0; k < 2; ++k) \
;     dst[n][k] = *(const bf16x8*)(lds + SB_(b, h) + lds_byte(wc * 32 + n * 16 + fr, k * 32 + fq * 8));
; #define MMA(ai, bj, At_, Bt_) { __builtin_amdgcn_s_setprio(1); \
;     _Pragma("unroll") for (int m = 0; m < 4; ++m) _Pragma("unroll") for (int n = 0; n < 2; ++n) _Pragma("unroll") for (int k = 0; k < 2; ++k) \
;       acc[ai][bj][m][n] = MFMA16(Bt_[n][k], At_[m][k], acc[ai][bj][m][n]); \
;     __builtin_amdgcn_s_setprio(0); }
; #define WAIT_V(n) asm volatile("s_waitcnt vmcnt(" #n ")" ::: "memory");
; #define WAIT_L(n) asm volatile("s_waitcnt lgkmcnt(" #n ")" ::: "memory");
; #define BAR __builtin_amdgcn_s_barrier();
; DI void gemm256(const u16* __restrict__ A, int lda, const u16* __restrict__ B0, const u16* __restrict__ B1, int ldb, int nt, acc_t& acc, char* lds) {
;     ...
;     LDA(At, 0, 1) WAIT_V(4) BAR WAIT_L(0) MMA(1, 0, At, Bq0) MMA(1, 1, At, Bq1) BAR }
;   { LDB(Bq0, 1, 0) LDA(At, 1, 0) WAIT_V(2) BAR WAIT_L(0) MMA(0, 0, At, Bq0) BAR
	s_nop 0
	ds_read_b128 v[74:77], v148 offset:16384
	ds_read_b128 v[78:81], v148 offset:17408
	ds_read_b128 v[90:93], v147 offset:16384
	ds_read_b128 v[94:97], v147 offset:17408
	ds_read_b128 v[178:181], v146 offset:16384
	ds_read_b128 v[182:185], v146 offset:17408
	ds_read_b128 v[186:189], v141 offset:16384
	ds_read_b128 v[190:193], v141 offset:17408
	s_waitcnt vmcnt(4)
	s_barrier
	s_waitcnt lgkmcnt(0)
	s_setprio 0
	s_waitcnt lgkmcnt(0)
	v_mfma_f32_16x16x32_bf16 v[60:63], v[132:135], v[74:77], v[60:63]
	v_mfma_f32_16x16x32_bf16 v[56:59], v[142:145], v[74:77], v[56:59]
	v_mfma_f32_16x16x32_bf16 v[52:55], v[132:135], v[90:93], v[52:55]
	v_mfma_f32_16x16x32_bf16 v[48:51], v[142:145], v[90:93], v[48:51]
	v_mfma_f32_16x16x32_bf16 v[36:39], v[132:135], v[186:189], v[36:39]
	v_mfma_f32_16x16x32_bf16 v[32:35], v[142:145], v[186:189], v[32:35]
	v_mfma_f32_16x16x32_bf16 v[60:63], v[136:139], v[78:81], v[60:63]
	v_mfma_f32_16x16x32_bf16 v[56:59], v[156:159], v[78:81], v[56:59]
	v_mfma_f32_16x16x32_bf16 v[52:55], v[136:139], v[94:97], v[52:55]
	v_mfma_f32_16x16x32_bf16 v[48:51], v[156:159], v[94:97], v[48:51]
	v_mfma_f32_16x16x32_bf16 v[44:47], v[132:135], v[178:181], v[44:47]
	v_mfma_f32_16x16x32_bf16 v[40:43], v[142:145], v[178:181], v[40:43]
	v_mfma_f32_16x16x32_bf16 v[36:39], v[136:139], v[190:193], v[36:39]
	v_mfma_f32_16x16x32_bf16 v[32:35], v[156:159], v[190:193], v[32:35]
	v_mfma_f32_16x16x32_bf16 v[194:197], v[136:139], v[182:185], v[44:47]
	v_mfma_f32_16x16x32_bf16 v[216:219], v[156:159], v[182:185], v[40:43]
	s_setprio 1
	s_setprio 0
	v_mfma_f32_16x16x32_bf16 v[20:23], v[106:109], v[90:93], v[20:23]
	v_mfma_f32_16x16x32_bf16 v[16:19], v[202:205], v[90:93], v[16:19]
	v_mfma_f32_16x16x32_bf16 v[4:7], v[106:109], v[186:189], v[4:7]
	v_mfma_f32_16x16x32_bf16 v[0:3], v[202:205], v[186:189], v[0:3]
	v_mfma_f32_16x16x32_bf16 v[28:31], v[106:109], v[74:77], v[28:31]
	v_mfma_f32_16x16x32_bf16 v[24:27], v[202:205], v[74:77], v[24:27]
	v_mfma_f32_16x16x32_bf16 v[20:23], v[110:113], v[94:97], v[20:23]
	v_mfma_f32_16x16x32_bf16 v[16:19], v[206:209], v[94:97], v[16:19]
	v_mfma_f32_16x16x32_bf16 v[12:15], v[106:109], v[178:181], v[12:15]
	v_mfma_f32_16x16x32_bf16 v[8:11], v[202:205], v[178:181], v[8:11]
	v_mfma_f32_16x16x32_bf16 v[4:7], v[110:113], v[190:193], v[4:7]
	v_mfma_f32_16x16x32_bf16 v[0:3], v[206:209], v[190:193], v[0:3]
	v_mfma_f32_16x16x32_bf16 v[130:133], v[110:113], v[78:81], v[28:31]
	v_mfma_f32_16x16x32_bf16 v[134:137], v[206:209], v[78:81], v[24:27]
	v_mfma_f32_16x16x32_bf16 v[142:145], v[110:113], v[182:185], v[12:15]
	v_mfma_f32_16x16x32_bf16 v[156:159], v[206:209], v[182:185], v[8:11]
	s_setprio 1
	s_barrier
	s_nop 0
	ds_read_b128 v[8:11], v155
	ds_read_b128 v[12:15], v155 offset:1024
	ds_read_b128 v[178:181], v155 offset:2048
	ds_read_b128 v[152:155], v155 offset:3072
	ds_read_b128 v[24:27], v148 offset:32768
	ds_read_b128 v[28:31], v148 offset:33792
	ds_read_b128 v[40:43], v147 offset:32768
	ds_read_b128 v[44:47], v147 offset:33792
	ds_read_b128 v[182:185], v146 offset:32768
	ds_read_b128 v[186:189], v146 offset:33792
	ds_read_b128 v[190:193], v141 offset:32768
	ds_read_b128 v[202:205], v141 offset:33792
	s_waitcnt vmcnt(2)
	s_barrier
	s_waitcnt lgkmcnt(0)
	s_setprio 0
	s_waitcnt lgkmcnt(0)
	v_mfma_f32_16x16x32_bf16 v[74:77], v[8:11], v[24:27], v[126:129]
	v_mfma_f32_16x16x32_bf16 v[126:129], v[12:15], v[28:31], v[74:77]
	v_mfma_f32_16x16x32_bf16 v[74:77], v[178:181], v[24:27], v[122:125]
	v_mfma_f32_16x16x32_bf16 v[122:125], v[152:155], v[28:31], v[74:77]
	v_mfma_f32_16x16x32_bf16 v[74:77], v[8:11], v[40:43], v[118:121]
	v_mfma_f32_16x16x32_bf16 v[110:113], v[12:15], v[44:47], v[74:77]
	v_mfma_f32_16x16x32_bf16 v[74:77], v[178:181], v[40:43], v[114:117]
	v_mfma_f32_16x16x32_bf16 v[106:109], v[152:155], v[44:47], v[74:77]
	v_mfma_f32_16x16x32_bf16 v[74:77], v[8:11], v[182:185], v[166:169]
	v_mfma_f32_16x16x32_bf16 v[94:97], v[12:15], v[186:189], v[74:77]
	v_mfma_f32_16x16x32_bf16 v[74:77], v[178:181], v[182:185], v[198:201]
	v_mfma_f32_16x16x32_bf16 v[90:93], v[152:155], v[186:189], v[74:77]
	v_mfma_f32_16x16x32_bf16 v[74:77], v[8:11], v[190:193], v[102:105]
	v_mfma_f32_16x16x32_bf16 v[78:81], v[12:15], v[202:205], v[74:77]
	v_mfma_f32_16x16x32_bf16 v[74:77], v[178:181], v[190:193], v[98:101]
	v_mfma_f32_16x16x32_bf16 v[74:77], v[152:155], v[202:205], v[74:77]
	s_setprio 1
	s_barrier
; #define LDA(dst, b, h) _Pragma("unroll") for (int m = 0; m < 4; ++m) _Pragma("unroll") for (int k = 0; k < 2; ++k) \
;     dst[m][k] = *(const bf16x8*)(lds + SA_(b, h) + lds_byte(wr * 64 + m * 16 + fr, k * 32 + fq * 8));
; #define LDB(dst, b, h) _Pragma("unroll") for (int n = 0; n < 2; ++n) _Pragma("unroll") for (int k = 0; k < 2; ++k) \
;     dst[n][k] = *(const bf16x8*)(lds + SB_(b, h) + lds_byte(wc * 32 + n * 16 + fr, k * 32 + fq * 8));
; #define MMA(ai, bj, At_, Bt_) { __builtin_amdgcn_s_setprio(1); \
;     _Pragma("unroll") for (int m = 0; m < 4; ++m) _Pragma("unroll") for (int n = 0; n < 2; ++n) _Pragma("unroll") for (int k = 0; k < 2; ++k) \
;       acc[ai][bj][m][n] = MFMA16(Bt_[n][k], At_[m][k], acc[ai][bj][m][n]); \
;     __builtin_amdgcn_s_setprio(0); }
; #define WAIT_V(n) asm volatile("s_waitcnt vmcnt(" #n ")" ::: "memory");
; #define WAIT_L(n) asm volatile("s_waitcnt lgkmcnt(" #n ")" ::: "memory");
; #define BAR __builtin_amdgcn_s_barrier();
; DI void gemm256(const u16* __restrict__ A, int lda, const u16* __restrict__ B0, const u16* __restrict__ B1, int ldb, int nt, acc_t& acc, char* lds) {
;     ...
;     LDB(Bq1, 1, 1) WAIT_V(0) BAR WAIT_L(0) MMA(0, 1, At, Bq1) BAR
;     LDA(At, 1, 1) BAR WAIT_L(0) MMA(1, 0, At, Bq0) MMA(1, 1, At, Bq1) BAR }
;   if (wr == 0) BAR
;   __syncthreads();
	ds_read_b128 v[164:167], v150
	ds_read_b128 v[198:201], v150 offset:1024
	ds_read_b128 v[206:209], v150 offset:2048
	ds_read_b128 v[226:229], v150 offset:3072
	s_waitcnt vmcnt(0)
	s_barrier
	s_waitcnt lgkmcnt(0)
	s_setprio 0
	s_waitcnt lgkmcnt(0)
	v_mfma_f32_16x16x32_bf16 v[98:101], v[164:167], v[24:27], v[210:213]
	v_mfma_f32_16x16x32_bf16 v[24:27], v[206:209], v[24:27], v[160:163]
	v_mfma_f32_16x16x32_bf16 v[114:117], v[226:229], v[28:31], v[24:27]
	v_mfma_f32_16x16x32_bf16 v[24:27], v[164:167], v[40:43], v[86:89]
	v_mfma_f32_16x16x32_bf16 v[102:105], v[198:201], v[44:47], v[24:27]
	v_mfma_f32_16x16x32_bf16 v[24:27], v[206:209], v[40:43], v[82:85]
	v_mfma_f32_16x16x32_bf16 v[118:121], v[198:201], v[28:31], v[98:101]
	v_mfma_f32_16x16x32_bf16 v[98:101], v[226:229], v[44:47], v[24:27]
	v_mfma_f32_16x16x32_bf16 v[24:27], v[164:167], v[182:185], v[170:173]
	v_mfma_f32_16x16x32_bf16 v[86:89], v[198:201], v[186:189], v[24:27]
	v_mfma_f32_16x16x32_bf16 v[24:27], v[206:209], v[182:185], v[174:177]
	v_mfma_f32_16x16x32_bf16 v[82:85], v[226:229], v[186:189], v[24:27]
	v_mfma_f32_16x16x32_bf16 v[24:27], v[164:167], v[190:193], v[70:73]
	v_mfma_f32_16x16x32_bf16 v[70:73], v[198:201], v[202:205], v[24:27]
	v_mfma_f32_16x16x32_bf16 v[24:27], v[206:209], v[190:193], v[66:69]
	v_mfma_f32_16x16x32_bf16 v[66:69], v[226:229], v[202:205], v[24:27]
	s_setprio 1
	s_barrier
	ds_read_b128 v[160:163], v148 offset:49152
	ds_read_b128 v[148:151], v148 offset:50176
	ds_read_b128 v[168:171], v147 offset:49152
	ds_read_b128 v[172:175], v147 offset:50176
	ds_read_b128 v[182:185], v146 offset:49152
	ds_read_b128 v[186:189], v146 offset:50176
	ds_read_b128 v[190:193], v141 offset:49152
	ds_read_b128 v[202:205], v141 offset:50176
	s_barrier
	s_waitcnt lgkmcnt(0)
	s_setprio 0
	s_waitcnt lgkmcnt(0)
	v_mfma_f32_16x16x32_bf16 v[24:27], v[8:11], v[160:163], v[60:63]
	v_mfma_f32_16x16x32_bf16 v[60:63], v[12:15], v[148:151], v[24:27]
	v_mfma_f32_16x16x32_bf16 v[24:27], v[178:181], v[160:163], v[56:59]
	v_mfma_f32_16x16x32_bf16 v[56:59], v[152:155], v[148:151], v[24:27]
	v_mfma_f32_16x16x32_bf16 v[24:27], v[8:11], v[168:171], v[52:55]
	v_mfma_f32_16x16x32_bf16 v[44:47], v[12:15], v[172:175], v[24:27]
	v_mfma_f32_16x16x32_bf16 v[24:27], v[178:181], v[168:171], v[48:51]
	v_mfma_f32_16x16x32_bf16 v[40:43], v[152:155], v[172:175], v[24:27]
	v_mfma_f32_16x16x32_bf16 v[24:27], v[8:11], v[182:185], v[194:197]
	v_mfma_f32_16x16x32_bf16 v[8:11], v[8:11], v[190:193], v[36:39]
	v_mfma_f32_16x16x32_bf16 v[28:31], v[12:15], v[186:189], v[24:27]
	v_mfma_f32_16x16x32_bf16 v[24:27], v[178:181], v[182:185], v[216:219]
	v_mfma_f32_16x16x32_bf16 v[12:15], v[12:15], v[202:205], v[8:11]
	v_mfma_f32_16x16x32_bf16 v[8:11], v[178:181], v[190:193], v[32:35]
	v_mfma_f32_16x16x32_bf16 v[24:27], v[152:155], v[186:189], v[24:27]
	v_mfma_f32_16x16x32_bf16 v[8:11], v[152:155], v[202:205], v[8:11]
	s_setprio 1
	s_setprio 0
	v_mfma_f32_16x16x32_bf16 v[32:35], v[164:167], v[160:163], v[130:133]
	v_mfma_f32_16x16x32_bf16 v[52:55], v[198:201], v[148:151], v[32:35]
	v_mfma_f32_16x16x32_bf16 v[32:35], v[206:209], v[160:163], v[134:137]
	v_mfma_f32_16x16x32_bf16 v[16:19], v[206:209], v[168:171], v[16:19]
	v_mfma_f32_16x16x32_bf16 v[48:51], v[226:229], v[148:151], v[32:35]
	v_mfma_f32_16x16x32_bf16 v[20:23], v[164:167], v[168:171], v[20:23]
	v_mfma_f32_16x16x32_bf16 v[32:35], v[226:229], v[172:175], v[16:19]
	v_mfma_f32_16x16x32_bf16 v[16:19], v[164:167], v[182:185], v[142:145]
	v_mfma_f32_16x16x32_bf16 v[36:39], v[198:201], v[172:175], v[20:23]
	v_mfma_f32_16x16x32_bf16 v[20:23], v[198:201], v[186:189], v[16:19]
	v_mfma_f32_16x16x32_bf16 v[16:19], v[206:209], v[182:185], v[156:159]
	v_mfma_f32_16x16x32_bf16 v[4:7], v[164:167], v[190:193], v[4:7]
	v_mfma_f32_16x16x32_bf16 v[0:3], v[206:209], v[190:193], v[0:3]
	v_mfma_f32_16x16x32_bf16 v[16:19], v[226:229], v[186:189], v[16:19]
	v_mfma_f32_16x16x32_bf16 v[4:7], v[198:201], v[202:205], v[4:7]
	v_mfma_f32_16x16x32_bf16 v[0:3], v[226:229], v[202:205], v[0:3]
	s_setprio 1
	s_movk_i32 s3, 0x100
	v_cmp_gt_u32_e32 vcc, s3, v140
	s_barrier
	s_and_saveexec_b64 s[8:9], vcc
	s_cbranch_execz .LBB0_171
	s_barrier

; #define STAGE_A(b, h, kt) { const u16* ap_ = A + (size_t)((h) * ahalf + (unsigned)(kt) * 64u); glds16(ap_ + ao0, l0 + SA_(b, h)); glds16(ap_ + ao1, l0 + SA_(b, h) + 8192); }
; #define STAGE_B(b, h, kt) { const u16* bp_ = ((h) ? B1 : B0) + (unsigned)(kt) * 64u; glds16(bp_ + bo0, l0 + SB_(b, h)); glds16(bp_ + bo1, l0 + SB_(b, h) + 8192); }
; #define LDA(dst, b, h) _Pragma("unroll") for (int m = 0; m < 4; ++m) _Pragma("unroll") for (int k = 0; k < 2; ++k) \
;     dst[m][k] = *(const bf16x8*)(lds + SA_(b, h) + lds_byte(wr * 64 + m * 16 + fr, k * 32 + fq * 8));
; #define LDB(dst, b, h) _Pragma("unroll") for (int n = 0; n < 2; ++n) _Pragma("unroll") for (int k = 0; k < 2; ++k) \
;     dst[n][k] = *(const bf16x8*)(lds + SB_(b, h) + lds_byte(wc * 32 + n * 16 + fr, k * 32 + fq * 8));
; #define MMA(ai, bj, At_, Bt_) { __builtin_amdgcn_s_setprio(1); \
;     _Pragma("unroll") for (int m = 0; m < 4; ++m) _Pragma("unroll") for (int n = 0; n < 2; ++n) _Pragma("unroll") for (int k = 0; k < 2; ++k) \
;       acc[ai][bj][m][n] = MFMA16(Bt_[n][k], At_[m][k], acc[ai][bj][m][n]); \
;     __builtin_amdgcn_s_setprio(0); }
; #define WAIT_V(n) asm volatile("s_waitcnt vmcnt(" #n ")" ::: "memory");
; #define WAIT_L(n) asm volatile("s_waitcnt lgkmcnt(" #n ")" ::: "memory");
; #define BAR __builtin_amdgcn_s_barrier();
; #define SCHED __builtin_amdgcn_sched_barrier(0);
; DI void gemm256(const u16* __restrict__ A, int lda, const u16* __restrict__ B0, const u16* __restrict__ B1, int ldb, int nt, acc_t& acc, char* lds) {
;     ...
;   for (int t = 0; t < nt - 2; t += 2) {
;     LDB(Bq0, 0, 0) SCHED LDA(At, 0, 0) STAGE_A(1, 1, t + 1)
;     WAIT_L(8) BAR WAIT_L(0) MMA(0, 0, At, Bq0) BAR SCHED
;     LDB(Bq1, 0, 1) STAGE_B(0, 0, t + 2)
;     BAR WAIT_L(0) MMA(0, 1, At, Bq1) BAR
;     LDA(At, 0, 1) STAGE_A(0, 0, t + 2)
;     BAR WAIT_L(0) MMA(1, 0, At, Bq0) BAR SCHED
;     STAGE_B(0, 1, t + 2)
;     WAIT_V(6) BAR MMA(1, 1, At, Bq1) BAR
.LBB0_564:
	ds_read_b128 v[170:173], v166
	ds_read_b128 v[174:177], v166 offset:1024
	ds_read_b128 v[178:181], v166 offset:2048
	ds_read_b128 v[182:185], v166 offset:3072
	v_add_u32_e32 v167, 0xc000, v149
	v_lshl_add_u64 v[142:143], s[22:23], 0, v[138:139]
	v_readfirstlane_b32 s3, v167
	v_lshl_add_u64 v[144:145], v[142:143], 0, s[38:39]
	s_mov_b32 m0, s3
	v_add_u32_e32 v168, 0xe000, v149
	ds_read_b128 v[186:189], v148
	ds_read_b128 v[190:193], v148 offset:1024
	ds_read_b128 v[194:197], v147
	ds_read_b128 v[198:201], v147 offset:1024
	ds_read_b128 v[202:205], v146
	ds_read_b128 v[206:209], v146 offset:1024
	ds_read_b128 v[210:213], v141
	ds_read_b128 v[226:229], v141 offset:1024
	global_load_lds_dwordx4 v[144:145], off
	v_lshl_add_u64 v[144:145], s[22:23], 0, v[136:137]
	v_readfirstlane_b32 s3, v168
	v_lshl_add_u64 v[216:217], v[144:145], 0, s[38:39]
	s_mov_b32 m0, s3
	s_nop 0
	global_load_lds_dwordx4 v[216:217], off
	s_waitcnt lgkmcnt(8)
	s_barrier
	s_waitcnt lgkmcnt(0)
	s_setprio 0
	s_waitcnt lgkmcnt(0)
	v_mfma_f32_16x16x32_bf16 v[126:129], v[170:173], v[186:189], v[126:129]
	v_mfma_f32_16x16x32_bf16 v[122:125], v[178:181], v[186:189], v[122:125]
	v_mfma_f32_16x16x32_bf16 v[118:121], v[170:173], v[194:197], v[118:121]
	v_mfma_f32_16x16x32_bf16 v[114:117], v[178:181], v[194:197], v[114:117]
	v_mfma_f32_16x16x32_bf16 v[110:113], v[170:173], v[202:205], v[110:113]
	v_mfma_f32_16x16x32_bf16 v[106:109], v[178:181], v[202:205], v[106:109]
	v_mfma_f32_16x16x32_bf16 v[102:105], v[170:173], v[210:213], v[102:105]
	v_mfma_f32_16x16x32_bf16 v[98:101], v[178:181], v[210:213], v[98:101]
	v_mfma_f32_16x16x32_bf16 v[126:129], v[174:177], v[190:193], v[126:129]
	v_mfma_f32_16x16x32_bf16 v[122:125], v[182:185], v[190:193], v[122:125]
	v_mfma_f32_16x16x32_bf16 v[118:121], v[174:177], v[198:201], v[118:121]
	v_mfma_f32_16x16x32_bf16 v[114:117], v[182:185], v[198:201], v[114:117]
	v_mfma_f32_16x16x32_bf16 v[110:113], v[174:177], v[206:209], v[110:113]
	v_mfma_f32_16x16x32_bf16 v[106:109], v[182:185], v[206:209], v[106:109]
	v_mfma_f32_16x16x32_bf16 v[102:105], v[174:177], v[226:229], v[102:105]
	v_mfma_f32_16x16x32_bf16 v[98:101], v[182:185], v[226:229], v[98:101]
	s_setprio 1
	s_barrier
	v_lshl_add_u64 v[216:217], s[22:23], 0, v[132:133]
	v_readfirstlane_b32 s3, v150
	v_lshl_add_u64 v[218:219], v[216:217], 0, s[20:21]
	s_mov_b32 m0, s3
	ds_read_b128 v[230:233], v165
	ds_read_b128 v[234:237], v165 offset:1024
	ds_read_b128 v[238:241], v165 offset:2048
	ds_read_b128 v[242:245], v165 offset:3072
	global_load_lds_dwordx4 v[218:219], off
	v_lshl_add_u64 v[218:219], s[22:23], 0, v[134:135]
	v_readfirstlane_b32 s3, v152
	v_lshl_add_u64 v[222:223], v[218:219], 0, s[20:21]
	s_mov_b32 m0, s3
	s_nop 0
	global_load_lds_dwordx4 v[222:223], off
	s_barrier
	s_waitcnt lgkmcnt(0)
	s_setprio 0
	s_waitcnt lgkmcnt(0)
	v_mfma_f32_16x16x32_bf16 v[94:97], v[230:233], v[186:189], v[94:97]
	v_mfma_f32_16x16x32_bf16 v[90:93], v[238:241], v[186:189], v[90:93]
	v_mfma_f32_16x16x32_bf16 v[86:89], v[230:233], v[194:197], v[86:89]
	v_mfma_f32_16x16x32_bf16 v[82:85], v[238:241], v[194:197], v[82:85]
	v_mfma_f32_16x16x32_bf16 v[78:81], v[230:233], v[202:205], v[78:81]
	v_mfma_f32_16x16x32_bf16 v[74:77], v[238:241], v[202:205], v[74:77]
	v_mfma_f32_16x16x32_bf16 v[70:73], v[230:233], v[210:213], v[70:73]
	v_mfma_f32_16x16x32_bf16 v[66:69], v[238:241], v[210:213], v[66:69]
	v_mfma_f32_16x16x32_bf16 v[94:97], v[234:237], v[190:193], v[94:97]
	v_mfma_f32_16x16x32_bf16 v[90:93], v[242:245], v[190:193], v[90:93]
	v_mfma_f32_16x16x32_bf16 v[86:89], v[234:237], v[198:201], v[86:89]
	v_mfma_f32_16x16x32_bf16 v[82:85], v[242:245], v[198:201], v[82:85]
	v_mfma_f32_16x16x32_bf16 v[78:81], v[234:237], v[206:209], v[78:81]
	v_mfma_f32_16x16x32_bf16 v[74:77], v[242:245], v[206:209], v[74:77]
	v_mfma_f32_16x16x32_bf16 v[70:73], v[234:237], v[226:229], v[70:73]
	v_mfma_f32_16x16x32_bf16 v[66:69], v[242:245], v[226:229], v[66:69]
	s_setprio 1
	v_readfirstlane_b32 s3, v149
	v_lshl_add_u64 v[222:223], v[142:143], 0, s[28:29]
	s_mov_b32 m0, s3
	v_readfirstlane_b32 s3, v153
	s_barrier
	ds_read_b128 v[186:189], v148 offset:16384
	ds_read_b128 v[190:193], v148 offset:17408
	ds_read_b128 v[194:197], v147 offset:16384
	ds_read_b128 v[198:201], v147 offset:17408
	ds_read_b128 v[202:205], v146 offset:16384
	ds_read_b128 v[206:209], v146 offset:17408
	ds_read_b128 v[210:213], v141 offset:16384
	ds_read_b128 v[226:229], v141 offset:17408
	global_load_lds_dwordx4 v[222:223], off
	v_lshl_add_u64 v[222:223], v[144:145], 0, s[28:29]
	s_mov_b32 m0, s3
	s_nop 0
	global_load_lds_dwordx4 v[222:223], off
	s_barrier
	s_waitcnt lgkmcnt(0)
	s_setprio 0
	s_waitcnt lgkmcnt(0)
	v_mfma_f32_16x16x32_bf16 v[60:63], v[170:173], v[186:189], v[60:63]
	v_mfma_f32_16x16x32_bf16 v[56:59], v[178:181], v[186:189], v[56:59]
	v_mfma_f32_16x16x32_bf16 v[52:55], v[170:173], v[194:197], v[52:55]
	v_mfma_f32_16x16x32_bf16 v[48:51], v[178:181], v[194:197], v[48:51]
	v_mfma_f32_16x16x32_bf16 v[44:47], v[170:173], v[202:205], v[44:47]
	v_mfma_f32_16x16x32_bf16 v[40:43], v[178:181], v[202:205], v[40:43]
	v_mfma_f32_16x16x32_bf16 v[36:39], v[170:173], v[210:213], v[36:39]
	v_mfma_f32_16x16x32_bf16 v[32:35], v[178:181], v[210:213], v[32:35]
	v_mfma_f32_16x16x32_bf16 v[60:63], v[174:177], v[190:193], v[60:63]
	v_mfma_f32_16x16x32_bf16 v[56:59], v[182:185], v[190:193], v[56:59]
	v_mfma_f32_16x16x32_bf16 v[52:55], v[174:177], v[198:201], v[52:55]
	v_mfma_f32_16x16x32_bf16 v[48:51], v[182:185], v[198:201], v[48:51]
	v_mfma_f32_16x16x32_bf16 v[44:47], v[174:177], v[206:209], v[44:47]
	v_mfma_f32_16x16x32_bf16 v[40:43], v[182:185], v[206:209], v[40:43]
	v_mfma_f32_16x16x32_bf16 v[36:39], v[174:177], v[226:229], v[36:39]
	v_mfma_f32_16x16x32_bf16 v[32:35], v[182:185], v[226:229], v[32:35]
	s_setprio 1
	s_barrier
; #define STAGE_A(b, h, kt) { const u16* ap_ = A + (size_t)((h) * ahalf + (unsigned)(kt) * 64u); glds16(ap_ + ao0, l0 + SA_(b, h)); glds16(ap_ + ao1, l0 + SA_(b, h) + 8192); }
; #define STAGE_B(b, h, kt) { const u16* bp_ = ((h) ? B1 : B0) + (unsigned)(kt) * 64u; glds16(bp_ + bo0, l0 + SB_(b, h)); glds16(bp_ + bo1, l0 + SB_(b, h) + 8192); }
; #define LDA(dst, b, h) _Pragma("unroll") for (int m = 0; m < 4; ++m) _Pragma("unroll") for (int k = 0; k < 2; ++k) \
;     dst[m][k] = *(const bf16x8*)(lds + SA_(b, h) + lds_byte(wr * 64 + m * 16 + fr, k * 32 + fq * 8));
; #define LDB(dst, b, h) _Pragma("unroll") for (int n = 0; n < 2; ++n) _Pragma("unroll") for (int k = 0; k < 2; ++k) \
;     dst[n][k] = *(const bf16x8*)(lds + SB_(b, h) + lds_byte(wc * 32 + n * 16 + fr, k * 32 + fq * 8));
; #define MMA(ai, bj, At_, Bt_) { __builtin_amdgcn_s_setprio(1); \
;     _Pragma("unroll") for (int m = 0; m < 4; ++m) _Pragma("unroll") for (int n = 0; n < 2; ++n) _Pragma("unroll") for (int k = 0; k < 2; ++k) \
;       acc[ai][bj][m][n] = MFMA16(Bt_[n][k], At_[m][k], acc[ai][bj][m][n]); \
;     __builtin_amdgcn_s_setprio(0); }
; #define WAIT_V(n) asm volatile("s_waitcnt vmcnt(" #n ")" ::: "memory");
; #define WAIT_L(n) asm volatile("s_waitcnt lgkmcnt(" #n ")" ::: "memory");
; #define BAR __builtin_amdgcn_s_barrier();
; #define SCHED __builtin_amdgcn_sched_barrier(0);
; DI void gemm256(const u16* __restrict__ A, int lda, const u16* __restrict__ B0, const u16* __restrict__ B1, int ldb, int nt, acc_t& acc, char* lds) {
;     ...
;     WAIT_V(6) BAR MMA(1, 1, At, Bq1) BAR
;     LDB(Bq0, 1, 0) SCHED LDA(At, 1, 0) STAGE_A(0, 1, t + 2)
;     WAIT_L(8) BAR WAIT_L(0) MMA(0, 0, At, Bq0) BAR SCHED
;     LDB(Bq1, 1, 1) STAGE_B(1, 0, t + 3)
;     BAR WAIT_L(0) MMA(0, 1, At, Bq1) BAR
;     LDA(At, 1, 1) STAGE_A(1, 0, t + 3)
;     BAR WAIT_L(0) MMA(1, 0, At, Bq0) BAR SCHED
;     STAGE_B(1, 1, t + 3)
	v_readfirstlane_b32 s3, v154
	v_lshl_add_u64 v[170:171], v[216:217], 0, s[24:25]
	s_mov_b32 m0, s3
	v_readfirstlane_b32 s3, v155
	global_load_lds_dwordx4 v[170:171], off
	v_lshl_add_u64 v[170:171], v[218:219], 0, s[24:25]
	s_mov_b32 m0, s3
	s_nop 0
	global_load_lds_dwordx4 v[170:171], off
	s_waitcnt vmcnt(6)
	s_barrier
	s_setprio 0
	v_mfma_f32_16x16x32_bf16 v[28:31], v[230:233], v[186:189], v[28:31]
	v_mfma_f32_16x16x32_bf16 v[24:27], v[238:241], v[186:189], v[24:27]
	v_mfma_f32_16x16x32_bf16 v[20:23], v[230:233], v[194:197], v[20:23]
	v_mfma_f32_16x16x32_bf16 v[16:19], v[238:241], v[194:197], v[16:19]
	v_mfma_f32_16x16x32_bf16 v[12:15], v[230:233], v[202:205], v[12:15]
	v_mfma_f32_16x16x32_bf16 v[8:11], v[238:241], v[202:205], v[8:11]
	v_mfma_f32_16x16x32_bf16 v[4:7], v[230:233], v[210:213], v[4:7]
	v_mfma_f32_16x16x32_bf16 v[0:3], v[238:241], v[210:213], v[0:3]
	v_mfma_f32_16x16x32_bf16 v[28:31], v[234:237], v[190:193], v[28:31]
	v_mfma_f32_16x16x32_bf16 v[24:27], v[242:245], v[190:193], v[24:27]
	v_mfma_f32_16x16x32_bf16 v[20:23], v[234:237], v[198:201], v[20:23]
	v_mfma_f32_16x16x32_bf16 v[16:19], v[242:245], v[198:201], v[16:19]
	v_mfma_f32_16x16x32_bf16 v[12:15], v[234:237], v[206:209], v[12:15]
	v_mfma_f32_16x16x32_bf16 v[8:11], v[242:245], v[206:209], v[8:11]
	v_mfma_f32_16x16x32_bf16 v[4:7], v[234:237], v[226:229], v[4:7]
	v_mfma_f32_16x16x32_bf16 v[0:3], v[242:245], v[226:229], v[0:3]
	s_setprio 1
	s_barrier
	ds_read_b128 v[170:173], v156
	ds_read_b128 v[174:177], v156 offset:1024
	ds_read_b128 v[178:181], v156 offset:2048
	ds_read_b128 v[182:185], v156 offset:3072
	v_readfirstlane_b32 s3, v157
	v_lshl_add_u64 v[222:223], v[142:143], 0, s[36:37]
	s_mov_b32 m0, s3
	v_readfirstlane_b32 s3, v158
	ds_read_b128 v[186:189], v148 offset:32768
	ds_read_b128 v[190:193], v148 offset:33792
	ds_read_b128 v[194:197], v147 offset:32768
	ds_read_b128 v[198:201], v147 offset:33792
	ds_read_b128 v[202:205], v146 offset:32768
	ds_read_b128 v[206:209], v146 offset:33792
	ds_read_b128 v[210:213], v141 offset:32768
	ds_read_b128 v[226:229], v141 offset:33792
	global_load_lds_dwordx4 v[222:223], off
	v_lshl_add_u64 v[222:223], v[144:145], 0, s[36:37]
	s_mov_b32 m0, s3
	s_nop 0
	global_load_lds_dwordx4 v[222:223], off
	s_waitcnt lgkmcnt(8)
	s_barrier
	s_waitcnt lgkmcnt(0)
	s_setprio 0
	s_waitcnt lgkmcnt(0)
	v_mfma_f32_16x16x32_bf16 v[126:129], v[170:173], v[186:189], v[126:129]
	v_mfma_f32_16x16x32_bf16 v[122:125], v[178:181], v[186:189], v[122:125]
	v_mfma_f32_16x16x32_bf16 v[118:121], v[170:173], v[194:197], v[118:121]
	v_mfma_f32_16x16x32_bf16 v[114:117], v[178:181], v[194:197], v[114:117]
	v_mfma_f32_16x16x32_bf16 v[110:113], v[170:173], v[202:205], v[110:113]
	v_mfma_f32_16x16x32_bf16 v[106:109], v[178:181], v[202:205], v[106:109]
	v_mfma_f32_16x16x32_bf16 v[102:105], v[170:173], v[210:213], v[102:105]
	v_mfma_f32_16x16x32_bf16 v[98:101], v[178:181], v[210:213], v[98:101]
	v_mfma_f32_16x16x32_bf16 v[126:129], v[174:177], v[190:193], v[126:129]
	v_mfma_f32_16x16x32_bf16 v[122:125], v[182:185], v[190:193], v[122:125]
	v_mfma_f32_16x16x32_bf16 v[118:121], v[174:177], v[198:201], v[118:121]
	v_mfma_f32_16x16x32_bf16 v[114:117], v[182:185], v[198:201], v[114:117]
	v_mfma_f32_16x16x32_bf16 v[110:113], v[174:177], v[206:209], v[110:113]
	v_mfma_f32_16x16x32_bf16 v[106:109], v[182:185], v[206:209], v[106:109]
	v_mfma_f32_16x16x32_bf16 v[102:105], v[174:177], v[226:229], v[102:105]
	v_mfma_f32_16x16x32_bf16 v[98:101], v[182:185], v[226:229], v[98:101]
	s_setprio 1
	s_barrier
	v_readfirstlane_b32 s3, v159
	v_lshl_add_u64 v[222:223], v[216:217], 0, s[34:35]
	s_mov_b32 m0, s3
	v_readfirstlane_b32 s3, v160
	ds_read_b128 v[230:233], v151
	ds_read_b128 v[234:237], v151 offset:1024
	ds_read_b128 v[238:241], v151 offset:2048
	ds_read_b128 v[242:245], v151 offset:3072
	global_load_lds_dwordx4 v[222:223], off
	v_lshl_add_u64 v[222:223], v[218:219], 0, s[34:35]
	s_mov_b32 m0, s3
	s_nop 0
	global_load_lds_dwordx4 v[222:223], off
	s_barrier
	s_waitcnt lgkmcnt(0)
	s_setprio 0
	s_waitcnt lgkmcnt(0)
	v_mfma_f32_16x16x32_bf16 v[94:97], v[230:233], v[186:189], v[94:97]
	v_mfma_f32_16x16x32_bf16 v[90:93], v[238:241], v[186:189], v[90:93]
	v_mfma_f32_16x16x32_bf16 v[86:89], v[230:233], v[194:197], v[86:89]
	v_mfma_f32_16x16x32_bf16 v[82:85], v[238:241], v[194:197], v[82:85]
	v_mfma_f32_16x16x32_bf16 v[78:81], v[230:233], v[202:205], v[78:81]
	v_mfma_f32_16x16x32_bf16 v[74:77], v[238:241], v[202:205], v[74:77]
	v_mfma_f32_16x16x32_bf16 v[70:73], v[230:233], v[210:213], v[70:73]
	v_mfma_f32_16x16x32_bf16 v[66:69], v[238:241], v[210:213], v[66:69]
	v_mfma_f32_16x16x32_bf16 v[94:97], v[234:237], v[190:193], v[94:97]
	v_mfma_f32_16x16x32_bf16 v[90:93], v[242:245], v[190:193], v[90:93]
	v_mfma_f32_16x16x32_bf16 v[86:89], v[234:237], v[198:201], v[86:89]
	v_mfma_f32_16x16x32_bf16 v[82:85], v[242:245], v[198:201], v[82:85]
	v_mfma_f32_16x16x32_bf16 v[78:81], v[234:237], v[206:209], v[78:81]
	v_mfma_f32_16x16x32_bf16 v[74:77], v[242:245], v[206:209], v[74:77]
	v_mfma_f32_16x16x32_bf16 v[70:73], v[234:237], v[226:229], v[70:73]
	v_mfma_f32_16x16x32_bf16 v[66:69], v[242:245], v[226:229], v[66:69]
	s_setprio 1
	v_readfirstlane_b32 s3, v161
	v_lshl_add_u64 v[142:143], v[142:143], 0, s[26:27]
	s_mov_b32 m0, s3
	v_readfirstlane_b32 s3, v162
	s_barrier
	ds_read_b128 v[186:189], v148 offset:49152
	ds_read_b128 v[190:193], v148 offset:50176
	ds_read_b128 v[194:197], v147 offset:49152
	ds_read_b128 v[198:201], v147 offset:50176
	ds_read_b128 v[202:205], v146 offset:49152
	ds_read_b128 v[206:209], v146 offset:50176
	ds_read_b128 v[210:213], v141 offset:49152
	ds_read_b128 v[226:229], v141 offset:50176
	global_load_lds_dwordx4 v[142:143], off
	v_lshl_add_u64 v[142:143], v[144:145], 0, s[26:27]
	s_mov_b32 m0, s3
	s_nop 0
	global_load_lds_dwordx4 v[142:143], off
	s_barrier
; #define STAGE_A(b, h, kt) { const u16* ap_ = A + (size_t)((h) * ahalf + (unsigned)(kt) * 64u); glds16(ap_ + ao0, l0 + SA_(b, h)); glds16(ap_ + ao1, l0 + SA_(b, h) + 8192); }
; #define STAGE_B(b, h, kt) { const u16* bp_ = ((h) ? B1 : B0) + (unsigned)(kt) * 64u; glds16(bp_ + bo0, l0 + SB_(b, h)); glds16(bp_ + bo1, l0 + SB_(b, h) + 8192); }
; #define LDA(dst, b, h) _Pragma("unroll") for (int m = 0; m < 4; ++m) _Pragma("unroll") for (int k = 0; k < 2; ++k) \
;     dst[m][k] = *(const bf16x8*)(lds + SA_(b, h) + lds_byte(wr * 64 + m * 16 + fr, k * 32 + fq * 8));
; #define LDB(dst, b, h) _Pragma("unroll") for (int n = 0; n < 2; ++n) _Pragma("unroll") for (int k = 0; k < 2; ++k) \
;     dst[n][k] = *(const bf16x8*)(lds + SB_(b, h) + lds_byte(wc * 32 + n * 16 + fr, k * 32 + fq * 8));
; #define MMA(ai, bj, At_, Bt_) { __builtin_amdgcn_s_setprio(1); \
;     _Pragma("unroll") for (int m = 0; m < 4; ++m) _Pragma("unroll") for (int n = 0; n < 2; ++n) _Pragma("unroll") for (int k = 0; k < 2; ++k) \
;       acc[ai][bj][m][n] = MFMA16(Bt_[n][k], At_[m][k], acc[ai][bj][m][n]); \
;     __builtin_amdgcn_s_setprio(0); }
; #define WAIT_V(n) asm volatile("s_waitcnt vmcnt(" #n ")" ::: "memory");
; #define WAIT_L(n) asm volatile("s_waitcnt lgkmcnt(" #n ")" ::: "memory");
; #define BAR __builtin_amdgcn_s_barrier();
; #define SCHED __builtin_amdgcn_sched_barrier(0);
; DI void gemm256(const u16* __restrict__ A, int lda, const u16* __restrict__ B0, const u16* __restrict__ B1, int ldb, int nt, acc_t& acc, char* lds) {
;     ...
;     BAR WAIT_L(0) MMA(1, 0, At, Bq0) BAR SCHED
;     STAGE_B(1, 1, t + 3)
;     WAIT_V(6) BAR MMA(1, 1, At, Bq1) BAR
;   }
;   { LDB(Bq0, 0, 0) LDA(At, 0, 0) STAGE_A(1, 1, nt - 1)
;     BAR WAIT_L(0) MMA(0, 0, At, Bq0) BAR
;     LDB(Bq1, 0, 1) BAR WAIT_L(0) MMA(0, 1, At, Bq1) BAR
;     LDA(At, 0, 1) WAIT_V(4) BAR WAIT_L(0) MMA(1, 0, At, Bq0) MMA(1, 1, At, Bq1) BAR }
;   { LDB(Bq0, 1, 0) LDA(At, 1, 0) WAIT_V(2) BAR WAIT_L(0) MMA(0, 0, At, Bq0) BAR
	s_waitcnt lgkmcnt(0)
	s_setprio 0
	s_waitcnt lgkmcnt(0)
	v_mfma_f32_16x16x32_bf16 v[60:63], v[170:173], v[186:189], v[60:63]
	v_mfma_f32_16x16x32_bf16 v[56:59], v[178:181], v[186:189], v[56:59]
	v_mfma_f32_16x16x32_bf16 v[52:55], v[170:173], v[194:197], v[52:55]
	v_mfma_f32_16x16x32_bf16 v[48:51], v[178:181], v[194:197], v[48:51]
	v_mfma_f32_16x16x32_bf16 v[44:47], v[170:173], v[202:205], v[44:47]
	v_mfma_f32_16x16x32_bf16 v[40:43], v[178:181], v[202:205], v[40:43]
	v_mfma_f32_16x16x32_bf16 v[36:39], v[170:173], v[210:213], v[36:39]
	v_mfma_f32_16x16x32_bf16 v[32:35], v[178:181], v[210:213], v[32:35]
	v_mfma_f32_16x16x32_bf16 v[60:63], v[174:177], v[190:193], v[60:63]
	v_mfma_f32_16x16x32_bf16 v[56:59], v[182:185], v[190:193], v[56:59]
	v_mfma_f32_16x16x32_bf16 v[52:55], v[174:177], v[198:201], v[52:55]
	v_mfma_f32_16x16x32_bf16 v[48:51], v[182:185], v[198:201], v[48:51]
	v_mfma_f32_16x16x32_bf16 v[44:47], v[174:177], v[206:209], v[44:47]
	v_mfma_f32_16x16x32_bf16 v[40:43], v[182:185], v[206:209], v[40:43]
	v_mfma_f32_16x16x32_bf16 v[36:39], v[174:177], v[226:229], v[36:39]
	v_mfma_f32_16x16x32_bf16 v[32:35], v[182:185], v[226:229], v[32:35]
	s_setprio 1
	s_barrier
	v_readfirstlane_b32 s3, v163
	v_lshl_add_u64 v[142:143], v[216:217], 0, s[50:51]
	s_mov_b32 m0, s3
	v_readfirstlane_b32 s3, v164
	global_load_lds_dwordx4 v[142:143], off
	v_lshl_add_u64 v[142:143], v[218:219], 0, s[50:51]
	s_mov_b32 m0, s3
	s_nop 0
	global_load_lds_dwordx4 v[142:143], off
	s_waitcnt vmcnt(6)
	s_barrier
	s_setprio 0
	v_mfma_f32_16x16x32_bf16 v[28:31], v[230:233], v[186:189], v[28:31]
	v_mfma_f32_16x16x32_bf16 v[24:27], v[238:241], v[186:189], v[24:27]
	v_mfma_f32_16x16x32_bf16 v[20:23], v[230:233], v[194:197], v[20:23]
	v_mfma_f32_16x16x32_bf16 v[16:19], v[238:241], v[194:197], v[16:19]
	v_mfma_f32_16x16x32_bf16 v[12:15], v[230:233], v[202:205], v[12:15]
	v_mfma_f32_16x16x32_bf16 v[8:11], v[238:241], v[202:205], v[8:11]
	v_mfma_f32_16x16x32_bf16 v[4:7], v[230:233], v[210:213], v[4:7]
	v_mfma_f32_16x16x32_bf16 v[0:3], v[238:241], v[210:213], v[0:3]
	v_mfma_f32_16x16x32_bf16 v[28:31], v[234:237], v[190:193], v[28:31]
	v_mfma_f32_16x16x32_bf16 v[24:27], v[242:245], v[190:193], v[24:27]
	v_mfma_f32_16x16x32_bf16 v[20:23], v[234:237], v[198:201], v[20:23]
	v_mfma_f32_16x16x32_bf16 v[16:19], v[242:245], v[198:201], v[16:19]
	v_mfma_f32_16x16x32_bf16 v[12:15], v[234:237], v[206:209], v[12:15]
	v_mfma_f32_16x16x32_bf16 v[8:11], v[242:245], v[206:209], v[8:11]
	v_mfma_f32_16x16x32_bf16 v[4:7], v[234:237], v[226:229], v[4:7]
	v_mfma_f32_16x16x32_bf16 v[0:3], v[242:245], v[226:229], v[0:3]
	s_setprio 1
	s_add_i32 s2, s2, 2
	s_add_u32 s22, s22, 0x100
	s_addc_u32 s23, s23, 0
	s_cmp_lt_u32 s2, 12
	s_barrier
	s_cbranch_scc1 .LBB0_564
	s_add_u32 s2, s8, 0x40780
	s_addc_u32 s3, s9, 0
	v_readfirstlane_b32 s7, v167
	v_lshl_add_u64 v[142:143], v[64:65], 1, s[2:3]
	s_mov_b32 m0, s7
	v_lshl_add_u64 v[130:131], v[130:131], 1, s[2:3]
	v_readfirstlane_b32 s2, v168
	ds_read_b128 v[132:135], v166
	ds_read_b128 v[136:139], v166 offset:1024
	ds_read_b128 v[152:155], v166 offset:2048
	ds_read_b128 v[158:161], v166 offset:3072
	ds_read_b128 v[170:173], v148
	ds_read_b128 v[174:177], v148 offset:1024
	ds_read_b128 v[178:181], v147
	ds_read_b128 v[182:185], v147 offset:1024
	ds_read_b128 v[186:189], v146
	ds_read_b128 v[190:193], v146 offset:1024
	ds_read_b128 v[194:197], v141
	ds_read_b128 v[198:201], v141 offset:1024
	global_load_lds_dwordx4 v[142:143], off
	s_mov_b32 m0, s2
	s_nop 0
	global_load_lds_dwordx4 v[130:131], off
	s_barrier
	s_waitcnt lgkmcnt(0)
	s_setprio 0
	s_waitcnt lgkmcnt(0)
	v_mfma_f32_16x16x32_bf16 v[126:129], v[132:135], v[170:173], v[126:129]
	v_mfma_f32_16x16x32_bf16 v[122:125], v[152:155], v[170:173], v[122:125]
	v_mfma_f32_16x16x32_bf16 v[118:121], v[132:135], v[178:181], v[118:121]
	v_mfma_f32_16x16x32_bf16 v[114:117], v[152:155], v[178:181], v[114:117]
	v_mfma_f32_16x16x32_bf16 v[110:113], v[132:135], v[186:189], v[110:113]
	v_mfma_f32_16x16x32_bf16 v[106:109], v[152:155], v[186:189], v[106:109]
	v_mfma_f32_16x16x32_bf16 v[102:105], v[132:135], v[194:197], v[102:105]
	v_mfma_f32_16x16x32_bf16 v[98:101], v[152:155], v[194:197], v[98:101]
	v_mfma_f32_16x16x32_bf16 v[126:129], v[136:139], v[174:177], v[126:129]
	v_mfma_f32_16x16x32_bf16 v[122:125], v[158:161], v[174:177], v[122:125]
	v_mfma_f32_16x16x32_bf16 v[118:121], v[136:139], v[182:185], v[118:121]
	v_mfma_f32_16x16x32_bf16 v[114:117], v[158:161], v[182:185], v[114:117]
	v_mfma_f32_16x16x32_bf16 v[110:113], v[136:139], v[190:193], v[110:113]
	v_mfma_f32_16x16x32_bf16 v[106:109], v[158:161], v[190:193], v[106:109]
	v_mfma_f32_16x16x32_bf16 v[102:105], v[136:139], v[198:201], v[102:105]
	v_mfma_f32_16x16x32_bf16 v[98:101], v[158:161], v[198:201], v[98:101]
	s_setprio 1
	s_barrier
	ds_read_b128 v[166:169], v165
	ds_read_b128 v[202:205], v165 offset:1024
	ds_read_b128 v[206:209], v165 offset:2048
	ds_read_b128 v[162:165], v165 offset:3072
	s_barrier
	s_waitcnt lgkmcnt(0)
	s_setprio 0
	s_waitcnt lgkmcnt(0)
	v_mfma_f32_16x16x32_bf16 v[94:97], v[166:169], v[170:173], v[94:97]
	v_mfma_f32_16x16x32_bf16 v[90:93], v[206:209], v[170:173], v[90:93]
	v_mfma_f32_16x16x32_bf16 v[86:89], v[166:169], v[178:181], v[86:89]
	v_mfma_f32_16x16x32_bf16 v[82:85], v[206:209], v[178:181], v[82:85]
	v_mfma_f32_16x16x32_bf16 v[78:81], v[166:169], v[186:189], v[78:81]
	v_mfma_f32_16x16x32_bf16 v[74:77], v[206:209], v[186:189], v[74:77]
	v_mfma_f32_16x16x32_bf16 v[70:73], v[166:169], v[194:197], v[70:73]
	v_mfma_f32_16x16x32_bf16 v[66:69], v[206:209], v[194:197], v[66:69]
	v_mfma_f32_16x16x32_bf16 v[94:97], v[202:205], v[174:177], v[94:97]
	v_mfma_f32_16x16x32_bf16 v[90:93], v[162:165], v[174:177], v[90:93]
	v_mfma_f32_16x16x32_bf16 v[86:89], v[202:205], v[182:185], v[86:89]
	v_mfma_f32_16x16x32_bf16 v[82:85], v[162:165], v[182:185], v[82:85]
	v_mfma_f32_16x16x32_bf16 v[78:81], v[202:205], v[190:193], v[78:81]
	v_mfma_f32_16x16x32_bf16 v[74:77], v[162:165], v[190:193], v[74:77]
	v_mfma_f32_16x16x32_bf16 v[70:73], v[202:205], v[198:201], v[70:73]
	v_mfma_f32_16x16x32_bf16 v[66:69], v[162:165], v[198:201], v[66:69]
	s_setprio 1
	s_barrier
; #define LDA(dst, b, h) _Pragma("unroll") for (int m = 0; m < 4; ++m) _Pragma("unroll") for (int k = 0; k < 2; ++k) \
;     dst[m][k] = *(const bf16x8*)(lds + SA_(b, h) + lds_byte(wr * 64 + m * 16 + fr, k * 32 + fq * 8));
; #define LDB(dst, b, h) _Pragma("unroll") for (int n = 0; n < 2; ++n) _Pragma("unroll") for (int k = 0; k < 2; ++k) \
;     dst[n][k] = *(const bf16x8*)(lds + SB_(b, h) + lds_byte(wc * 32 + n * 16 + fr, k * 32 + fq * 8));
; #define MMA(ai, bj, At_, Bt_) { __builtin_amdgcn_s_setprio(1); \
;     _Pragma("unroll") for (int m = 0; m < 4; ++m) _Pragma("unroll") for (int n = 0; n < 2; ++n) _Pragma("unroll") for (int k = 0; k < 2; ++k) \
;       acc[ai][bj][m][n] = MFMA16(Bt_[n][k], At_[m][k], acc[ai][bj][m][n]); \
;     __builtin_amdgcn_s_setprio(0); }
; #define WAIT_V(n) asm volatile("s_waitcnt vmcnt(" #n ")" ::: "memory");
; #define WAIT_L(n) asm volatile("s_waitcnt lgkmcnt(" #n ")" ::: "memory");
; #define BAR __builtin_amdgcn_s_barrier();
; DI void gemm256(const u16* __restrict__ A, int lda, const u16* __restrict__ B0, const u16* __restrict__ B1, int ldb, int nt, acc_t& acc, char* lds) {
;     ...
;     LDA(At, 0, 1) WAIT_V(4) BAR WAIT_L(0) MMA(1, 0, At, Bq0) MMA(1, 1, At, Bq1) BAR }
;   { LDB(Bq0, 1, 0) LDA(At, 1, 0) WAIT_V(2) BAR WAIT_L(0) MMA(0, 0, At, Bq0) BAR
	ds_read_b128 v[170:173], v148 offset:16384
	ds_read_b128 v[174:177], v148 offset:17408
	ds_read_b128 v[178:181], v147 offset:16384
	ds_read_b128 v[182:185], v147 offset:17408
	ds_read_b128 v[186:189], v146 offset:16384
	ds_read_b128 v[190:193], v146 offset:17408
	ds_read_b128 v[194:197], v141 offset:16384
	ds_read_b128 v[198:201], v141 offset:17408
	s_waitcnt vmcnt(4)
	s_barrier
	s_waitcnt lgkmcnt(0)
	s_setprio 0
	s_waitcnt lgkmcnt(0)
	v_mfma_f32_16x16x32_bf16 v[60:63], v[132:135], v[170:173], v[60:63]
	v_mfma_f32_16x16x32_bf16 v[52:55], v[132:135], v[178:181], v[52:55]
	v_mfma_f32_16x16x32_bf16 v[44:47], v[132:135], v[186:189], v[44:47]
	v_mfma_f32_16x16x32_bf16 v[36:39], v[132:135], v[194:197], v[36:39]
	v_mfma_f32_16x16x32_bf16 v[32:35], v[152:155], v[194:197], v[32:35]
	v_mfma_f32_16x16x32_bf16 v[60:63], v[136:139], v[174:177], v[60:63]
	v_mfma_f32_16x16x32_bf16 v[56:59], v[152:155], v[170:173], v[56:59]
	v_mfma_f32_16x16x32_bf16 v[210:213], v[136:139], v[182:185], v[52:55]
	v_mfma_f32_16x16x32_bf16 v[48:51], v[152:155], v[178:181], v[48:51]
	v_mfma_f32_16x16x32_bf16 v[230:233], v[136:139], v[190:193], v[44:47]
	v_mfma_f32_16x16x32_bf16 v[40:43], v[152:155], v[186:189], v[40:43]
	v_mfma_f32_16x16x32_bf16 v[130:133], v[136:139], v[198:201], v[36:39]
	v_mfma_f32_16x16x32_bf16 v[134:137], v[158:161], v[198:201], v[32:35]
	v_mfma_f32_16x16x32_bf16 v[56:59], v[158:161], v[174:177], v[56:59]
	v_mfma_f32_16x16x32_bf16 v[226:229], v[158:161], v[182:185], v[48:51]
	v_mfma_f32_16x16x32_bf16 v[234:237], v[158:161], v[190:193], v[40:43]
	s_setprio 1
	s_setprio 0
	v_mfma_f32_16x16x32_bf16 v[28:31], v[166:169], v[170:173], v[28:31]
	v_mfma_f32_16x16x32_bf16 v[24:27], v[206:209], v[170:173], v[24:27]
	v_mfma_f32_16x16x32_bf16 v[20:23], v[166:169], v[178:181], v[20:23]
	v_mfma_f32_16x16x32_bf16 v[16:19], v[206:209], v[178:181], v[16:19]
	v_mfma_f32_16x16x32_bf16 v[12:15], v[166:169], v[186:189], v[12:15]
	v_mfma_f32_16x16x32_bf16 v[8:11], v[206:209], v[186:189], v[8:11]
	v_mfma_f32_16x16x32_bf16 v[4:7], v[166:169], v[194:197], v[4:7]
	v_mfma_f32_16x16x32_bf16 v[0:3], v[206:209], v[194:197], v[0:3]
	v_mfma_f32_16x16x32_bf16 v[152:155], v[202:205], v[174:177], v[28:31]
	v_mfma_f32_16x16x32_bf16 v[158:161], v[162:165], v[174:177], v[24:27]
	v_mfma_f32_16x16x32_bf16 v[170:173], v[202:205], v[182:185], v[20:23]
	v_mfma_f32_16x16x32_bf16 v[174:177], v[162:165], v[182:185], v[16:19]
	v_mfma_f32_16x16x32_bf16 v[178:181], v[202:205], v[190:193], v[12:15]
	v_mfma_f32_16x16x32_bf16 v[182:185], v[162:165], v[190:193], v[8:11]
	v_mfma_f32_16x16x32_bf16 v[166:169], v[202:205], v[198:201], v[4:7]
	v_mfma_f32_16x16x32_bf16 v[162:165], v[162:165], v[198:201], v[0:3]
	s_setprio 1
	s_barrier
	ds_read_b128 v[186:189], v156
	ds_read_b128 v[190:193], v156 offset:1024
	ds_read_b128 v[194:197], v156 offset:2048
	ds_read_b128 v[198:201], v156 offset:3072
	ds_read_b128 v[32:35], v148 offset:32768
	ds_read_b128 v[36:39], v148 offset:33792
	ds_read_b128 v[44:47], v147 offset:32768
	ds_read_b128 v[202:205], v147 offset:33792
	ds_read_b128 v[206:209], v146 offset:32768
	ds_read_b128 v[238:241], v146 offset:33792
	ds_read_b128 v[242:245], v141 offset:32768
	ds_read_b128 v[246:249], v141 offset:33792
	s_waitcnt vmcnt(2)
	s_barrier
	s_waitcnt lgkmcnt(0)
	s_setprio 0
	s_waitcnt lgkmcnt(0)
	v_mfma_f32_16x16x32_bf16 v[0:3], v[186:189], v[32:35], v[126:129]
	v_mfma_f32_16x16x32_bf16 v[28:31], v[190:193], v[36:39], v[0:3]
	v_mfma_f32_16x16x32_bf16 v[0:3], v[194:197], v[32:35], v[122:125]
	v_mfma_f32_16x16x32_bf16 v[24:27], v[198:201], v[36:39], v[0:3]
	v_mfma_f32_16x16x32_bf16 v[0:3], v[186:189], v[44:47], v[118:121]
	v_mfma_f32_16x16x32_bf16 v[16:19], v[190:193], v[202:205], v[0:3]
	v_mfma_f32_16x16x32_bf16 v[0:3], v[194:197], v[44:47], v[114:117]
	v_mfma_f32_16x16x32_bf16 v[20:23], v[198:201], v[202:205], v[0:3]
	v_mfma_f32_16x16x32_bf16 v[0:3], v[186:189], v[206:209], v[110:113]
	v_mfma_f32_16x16x32_bf16 v[8:11], v[190:193], v[238:241], v[0:3]
	v_mfma_f32_16x16x32_bf16 v[0:3], v[194:197], v[206:209], v[106:109]
	v_mfma_f32_16x16x32_bf16 v[12:15], v[198:201], v[238:241], v[0:3]
	v_mfma_f32_16x16x32_bf16 v[0:3], v[186:189], v[242:245], v[102:105]
	v_mfma_f32_16x16x32_bf16 v[4:7], v[194:197], v[242:245], v[98:101]
	v_mfma_f32_16x16x32_bf16 v[0:3], v[190:193], v[246:249], v[0:3]
	v_mfma_f32_16x16x32_bf16 v[4:7], v[198:201], v[246:249], v[4:7]
	s_setprio 1
	s_barrier
; DI unsigned pk_bf16(float lo, float hi) { f32x2_t v = {lo, hi}; return __builtin_bit_cast(unsigned, __builtin_convertvector(v, bf16x2_t)); }
; DI float fsigmoid(float x) { return __builtin_amdgcn_rcpf(1.0f + __expf(-x)); }
; DI float fsilu(float x) { return x * fsigmoid(x); }
; #define LDA(dst, b, h) _Pragma("unroll") for (int m = 0; m < 4; ++m) _Pragma("unroll") for (int k = 0; k < 2; ++k) \
;     dst[m][k] = *(const bf16x8*)(lds + SA_(b, h) + lds_byte(wr * 64 + m * 16 + fr, k * 32 + fq * 8));
; #define LDB(dst, b, h) _Pragma("unroll") for (int n = 0; n < 2; ++n) _Pragma("unroll") for (int k = 0; k < 2; ++k) \
;     dst[n][k] = *(const bf16x8*)(lds + SB_(b, h) + lds_byte(wc * 32 + n * 16 + fr, k * 32 + fq * 8));
; #define MMA(ai, bj, At_, Bt_) { __builtin_amdgcn_s_setprio(1); \
;     _Pragma("unroll") for (int m = 0; m < 4; ++m) _Pragma("unroll") for (int n = 0; n < 2; ++n) _Pragma("unroll") for (int k = 0; k < 2; ++k) \
;       acc[ai][bj][m][n] = MFMA16(Bt_[n][k], At_[m][k], acc[ai][bj][m][n]); \
;     __builtin_amdgcn_s_setprio(0); }
; #define WAIT_V(n) asm volatile("s_waitcnt vmcnt(" #n ")" ::: "memory");
; #define WAIT_L(n) asm volatile("s_waitcnt lgkmcnt(" #n ")" ::: "memory");
; #define BAR __builtin_amdgcn_s_barrier();
; DI void gemm256(const u16* __restrict__ A, int lda, const u16* __restrict__ B0, const u16* __restrict__ B1, int ldb, int nt, acc_t& acc, char* lds) {
;     ...
;     LDB(Bq1, 1, 1) WAIT_V(0) BAR WAIT_L(0) MMA(0, 1, At, Bq1) BAR
;     LDA(At, 1, 1) BAR WAIT_L(0) MMA(1, 0, At, Bq0) MMA(1, 1, At, Bq1) BAR }
;   if (wr == 0) BAR
;   __syncthreads();
; DI void p1_phase(const Params& p, int layer, char* lds) {
;     ...
;         if (seg == 0) {
; #pragma unroll
;           for (int j = 0; j < 4; ++j) o[j] = pk_bf16(fsilu(v[2 * j]), fsilu(v[2 * j + 1]));
;           *(u32x4*)((u16*)(ws + OFF_QH) + (size_t)row * 512 + col) = o;
;         } else if (seg == 1) {
;           const int k = col - 512;
;           float g[8];
; #pragma unroll
;           for (int j = 0; j < 8; ++j) {
;             float lbv = 0.f;
;             if (layer == 1) lbv = __builtin_amdgcn_rcpf(1.0f + __expf(p.lb[k + j] - p.lb[512 + k + j]));
;             const float f = lbv + (1.0f - lbv) * fsigmoid(v[j]);
;             g[j] = __logf(fmaxf(f, 1e-30f));
	ds_read_b128 v[106:109], v151
	ds_read_b128 v[110:113], v151 offset:1024
	ds_read_b128 v[142:145], v151 offset:2048
	ds_read_b128 v[216:219], v151 offset:3072
	s_waitcnt vmcnt(0)
	s_barrier
	s_waitcnt lgkmcnt(0)
	s_setprio 0
	s_waitcnt lgkmcnt(0)
	v_mfma_f32_16x16x32_bf16 v[40:43], v[106:109], v[32:35], v[94:97]
	v_mfma_f32_16x16x32_bf16 v[32:35], v[142:145], v[32:35], v[90:93]
	v_mfma_f32_16x16x32_bf16 v[52:55], v[216:219], v[36:39], v[32:35]
	v_mfma_f32_16x16x32_bf16 v[32:35], v[106:109], v[44:47], v[86:89]
	v_mfma_f32_16x16x32_bf16 v[48:51], v[110:113], v[36:39], v[40:43]
	v_mfma_f32_16x16x32_bf16 v[40:43], v[110:113], v[202:205], v[32:35]
	v_mfma_f32_16x16x32_bf16 v[32:35], v[142:145], v[44:47], v[82:85]
	v_mfma_f32_16x16x32_bf16 v[44:47], v[216:219], v[202:205], v[32:35]
	v_mfma_f32_16x16x32_bf16 v[32:35], v[106:109], v[206:209], v[78:81]
	v_mfma_f32_16x16x32_bf16 v[36:39], v[110:113], v[238:241], v[32:35]
	v_mfma_f32_16x16x32_bf16 v[32:35], v[142:145], v[206:209], v[74:77]
	v_mfma_f32_16x16x32_bf16 v[78:81], v[216:219], v[238:241], v[32:35]
	v_mfma_f32_16x16x32_bf16 v[32:35], v[106:109], v[242:245], v[70:73]
	v_mfma_f32_16x16x32_bf16 v[66:69], v[142:145], v[242:245], v[66:69]
	v_mfma_f32_16x16x32_bf16 v[32:35], v[110:113], v[246:249], v[32:35]
	v_mfma_f32_16x16x32_bf16 v[66:69], v[216:219], v[246:249], v[66:69]
	s_setprio 1
	s_barrier
	ds_read_b128 v[114:117], v148 offset:49152
	ds_read_b128 v[118:121], v148 offset:50176
	ds_read_b128 v[126:129], v147 offset:49152
	ds_read_b128 v[148:151], v147 offset:50176
	ds_read_b128 v[202:205], v146 offset:49152
	ds_read_b128 v[206:209], v146 offset:50176
	ds_read_b128 v[238:241], v141 offset:49152
	ds_read_b128 v[242:245], v141 offset:50176
	s_barrier
	s_waitcnt lgkmcnt(0)
	s_setprio 0
	s_waitcnt lgkmcnt(0)
	v_mfma_f32_16x16x32_bf16 v[56:59], v[194:197], v[114:117], v[56:59]
	v_mfma_f32_16x16x32_bf16 v[102:105], v[198:201], v[118:121], v[56:59]
	v_mfma_f32_16x16x32_bf16 v[56:59], v[186:189], v[126:129], v[210:213]
	v_mfma_f32_16x16x32_bf16 v[90:93], v[190:193], v[148:151], v[56:59]
	v_mfma_f32_16x16x32_bf16 v[56:59], v[194:197], v[126:129], v[226:229]
	v_mfma_f32_16x16x32_bf16 v[94:97], v[198:201], v[148:151], v[56:59]
	v_mfma_f32_16x16x32_bf16 v[56:59], v[186:189], v[202:205], v[230:233]
	v_mfma_f32_16x16x32_bf16 v[82:85], v[190:193], v[206:209], v[56:59]
	v_mfma_f32_16x16x32_bf16 v[56:59], v[194:197], v[202:205], v[234:237]
	v_mfma_f32_16x16x32_bf16 v[86:89], v[198:201], v[206:209], v[56:59]
	v_mfma_f32_16x16x32_bf16 v[56:59], v[186:189], v[238:241], v[130:133]
	v_mfma_f32_16x16x32_bf16 v[60:63], v[186:189], v[114:117], v[60:63]
	v_mfma_f32_16x16x32_bf16 v[70:73], v[190:193], v[242:245], v[56:59]
	v_mfma_f32_16x16x32_bf16 v[56:59], v[194:197], v[238:241], v[134:137]
	v_mfma_f32_16x16x32_bf16 v[98:101], v[190:193], v[118:121], v[60:63]
	v_mfma_f32_16x16x32_bf16 v[74:77], v[198:201], v[242:245], v[56:59]
	s_setprio 1
	s_setprio 0
	v_mfma_f32_16x16x32_bf16 v[56:59], v[106:109], v[114:117], v[152:155]
	v_mfma_f32_16x16x32_bf16 v[130:133], v[110:113], v[118:121], v[56:59]
	v_mfma_f32_16x16x32_bf16 v[56:59], v[142:145], v[114:117], v[158:161]
	v_mfma_f32_16x16x32_bf16 v[134:137], v[216:219], v[118:121], v[56:59]
	v_mfma_f32_16x16x32_bf16 v[56:59], v[106:109], v[126:129], v[170:173]
	v_mfma_f32_16x16x32_bf16 v[122:125], v[110:113], v[148:151], v[56:59]
	v_mfma_f32_16x16x32_bf16 v[56:59], v[142:145], v[126:129], v[174:177]
	v_mfma_f32_16x16x32_bf16 v[126:129], v[216:219], v[148:151], v[56:59]
	v_mfma_f32_16x16x32_bf16 v[56:59], v[106:109], v[202:205], v[178:181]
	v_mfma_f32_16x16x32_bf16 v[114:117], v[110:113], v[206:209], v[56:59]
	v_mfma_f32_16x16x32_bf16 v[56:59], v[142:145], v[202:205], v[182:185]
	v_mfma_f32_16x16x32_bf16 v[118:121], v[216:219], v[206:209], v[56:59]
	v_mfma_f32_16x16x32_bf16 v[56:59], v[106:109], v[238:241], v[166:169]
	v_mfma_f32_16x16x32_bf16 v[106:109], v[110:113], v[242:245], v[56:59]
	v_mfma_f32_16x16x32_bf16 v[56:59], v[142:145], v[238:241], v[162:165]
	v_mfma_f32_16x16x32_bf16 v[110:113], v[216:219], v[242:245], v[56:59]
	s_setprio 1
	s_movk_i32 s2, 0x100
	v_cmp_gt_u32_e32 vcc, s2, v140
	s_barrier
	s_and_saveexec_b64 s[8:9], vcc
	s_mov_b32 s69, 0x800000
	s_mov_b32 s75, 0x3f317217
	s_mov_b32 s92, 0x7f800000
	s_cbranch_execz .LBB0_567
	s_barrier

; #define STAGE_A(b, h, kt) { const u16* ap_ = A + (size_t)((h) * ahalf + (unsigned)(kt) * 64u); glds16(ap_ + ao0, l0 + SA_(b, h)); glds16(ap_ + ao1, l0 + SA_(b, h) + 8192); }
; #define STAGE_B(b, h, kt) { const u16* bp_ = ((h) ? B1 : B0) + (unsigned)(kt) * 64u; glds16(bp_ + bo0, l0 + SB_(b, h)); glds16(bp_ + bo1, l0 + SB_(b, h) + 8192); }
; #define LDA(dst, b, h) _Pragma("unroll") for (int m = 0; m < 4; ++m) _Pragma("unroll") for (int k = 0; k < 2; ++k) \
;     dst[m][k] = *(const bf16x8*)(lds + SA_(b, h) + lds_byte(wr * 64 + m * 16 + fr, k * 32 + fq * 8));
; #define LDB(dst, b, h) _Pragma("unroll") for (int n = 0; n < 2; ++n) _Pragma("unroll") for (int k = 0; k < 2; ++k) \
;     dst[n][k] = *(const bf16x8*)(lds + SB_(b, h) + lds_byte(wc * 32 + n * 16 + fr, k * 32 + fq * 8));
; #define MMA(ai, bj, At_, Bt_) { __builtin_amdgcn_s_setprio(1); \
;     _Pragma("unroll") for (int m = 0; m < 4; ++m) _Pragma("unroll") for (int n = 0; n < 2; ++n) _Pragma("unroll") for (int k = 0; k < 2; ++k) \
;       acc[ai][bj][m][n] = MFMA16(Bt_[n][k], At_[m][k], acc[ai][bj][m][n]); \
;     __builtin_amdgcn_s_setprio(0); }
; #define WAIT_V(n) asm volatile("s_waitcnt vmcnt(" #n ")" ::: "memory");
; #define WAIT_L(n) asm volatile("s_waitcnt lgkmcnt(" #n ")" ::: "memory");
; #define BAR __builtin_amdgcn_s_barrier();
; #define SCHED __builtin_amdgcn_sched_barrier(0);
; DI void gemm256(const u16* __restrict__ A, int lda, const u16* __restrict__ B0, const u16* __restrict__ B1, int ldb, int nt, acc_t& acc, char* lds) {
;     ...
;   for (int t = 0; t < nt - 2; t += 2) {
;     LDB(Bq0, 0, 0) SCHED LDA(At, 0, 0) STAGE_A(1, 1, t + 1)
;     WAIT_L(8) BAR WAIT_L(0) MMA(0, 0, At, Bq0) BAR SCHED
;     LDB(Bq1, 0, 1) STAGE_B(0, 0, t + 2)
;     BAR WAIT_L(0) MMA(0, 1, At, Bq1) BAR
;     LDA(At, 0, 1) STAGE_A(0, 0, t + 2)
;     BAR WAIT_L(0) MMA(1, 0, At, Bq0) BAR SCHED
;     STAGE_B(0, 1, t + 2)
;     WAIT_V(6) BAR MMA(1, 1, At, Bq1) BAR
; DI void p5_phase(const Params& p, char* lds) {
;     ...
;   for (int tile = blockIdx.x; tile < 64 * 4; tile += gridDim.x) {
;     int rt, ct; tile_map(tile, 64, 4, rt, ct);
;     const int row0 = rt * 256, col0 = ct * 256;
;     acc_t acc;
;     zero_acc(acc);
;     gemm256(xb + (size_t)row0 * D, D, win + (size_t)(3584 + col0) * D, win + (size_t)(3584 + col0 + 128) * D, D, 16, acc, lds);
.LBB0_973:
	ds_read_b128 v[142:145], v166
	ds_read_b128 v[170:173], v166 offset:1024
	ds_read_b128 v[174:177], v166 offset:2048
	ds_read_b128 v[178:181], v166 offset:3072
	v_add_u32_e32 v167, 0xc000, v149
	v_lshl_add_u64 v[222:223], s[22:23], 0, v[136:137]
	v_readfirstlane_b32 s19, v167
	v_lshl_add_u64 v[168:169], v[222:223], 0, s[0:1]
	s_mov_b32 m0, s19
	ds_read_b128 v[182:185], v148
	ds_read_b128 v[186:189], v148 offset:1024
	ds_read_b128 v[190:193], v147
	ds_read_b128 v[194:197], v147 offset:1024
	ds_read_b128 v[198:201], v146
	ds_read_b128 v[202:205], v146 offset:1024
	ds_read_b128 v[206:209], v141
	ds_read_b128 v[210:213], v141 offset:1024
	global_load_lds_dwordx4 v[168:169], off
	v_add_u32_e32 v168, 0xe000, v149
	v_lshl_add_u64 v[224:225], s[22:23], 0, v[138:139]
	v_readfirstlane_b32 s19, v168
	v_lshl_add_u64 v[216:217], v[224:225], 0, s[0:1]
	s_mov_b32 m0, s19
	s_nop 0
	global_load_lds_dwordx4 v[216:217], off
	s_waitcnt lgkmcnt(8)
	s_barrier
	s_waitcnt lgkmcnt(0)
	s_setprio 0
	s_waitcnt lgkmcnt(0)
	v_mfma_f32_16x16x32_bf16 v[126:129], v[142:145], v[182:185], v[126:129]
	v_mfma_f32_16x16x32_bf16 v[122:125], v[174:177], v[182:185], v[122:125]
	v_mfma_f32_16x16x32_bf16 v[118:121], v[142:145], v[190:193], v[118:121]
	v_mfma_f32_16x16x32_bf16 v[114:117], v[174:177], v[190:193], v[114:117]
	v_mfma_f32_16x16x32_bf16 v[110:113], v[142:145], v[198:201], v[110:113]
	v_mfma_f32_16x16x32_bf16 v[106:109], v[174:177], v[198:201], v[106:109]
	v_mfma_f32_16x16x32_bf16 v[102:105], v[142:145], v[206:209], v[102:105]
	v_mfma_f32_16x16x32_bf16 v[98:101], v[174:177], v[206:209], v[98:101]
	v_mfma_f32_16x16x32_bf16 v[126:129], v[170:173], v[186:189], v[126:129]
	v_mfma_f32_16x16x32_bf16 v[122:125], v[178:181], v[186:189], v[122:125]
	v_mfma_f32_16x16x32_bf16 v[118:121], v[170:173], v[194:197], v[118:121]
	v_mfma_f32_16x16x32_bf16 v[114:117], v[178:181], v[194:197], v[114:117]
	v_mfma_f32_16x16x32_bf16 v[110:113], v[170:173], v[202:205], v[110:113]
	v_mfma_f32_16x16x32_bf16 v[106:109], v[178:181], v[202:205], v[106:109]
	v_mfma_f32_16x16x32_bf16 v[102:105], v[170:173], v[210:213], v[102:105]
	v_mfma_f32_16x16x32_bf16 v[98:101], v[178:181], v[210:213], v[98:101]
	s_setprio 1
	s_barrier
	v_lshl_add_u64 v[238:239], s[22:23], 0, v[132:133]
	v_readfirstlane_b32 s19, v150
	v_lshl_add_u64 v[240:241], v[238:239], 0, s[28:29]
	s_mov_b32 m0, s19
	ds_read_b128 v[216:219], v165
	ds_read_b128 v[226:229], v165 offset:1024
	ds_read_b128 v[230:233], v165 offset:2048
	ds_read_b128 v[234:237], v165 offset:3072
	global_load_lds_dwordx4 v[240:241], off
	v_lshl_add_u64 v[240:241], s[22:23], 0, v[134:135]
	v_readfirstlane_b32 s19, v151
	v_lshl_add_u64 v[242:243], v[240:241], 0, s[28:29]
	s_mov_b32 m0, s19
	s_nop 0
	global_load_lds_dwordx4 v[242:243], off
	s_barrier
	s_waitcnt lgkmcnt(0)
	s_setprio 0
	s_waitcnt lgkmcnt(0)
	v_mfma_f32_16x16x32_bf16 v[94:97], v[216:219], v[182:185], v[94:97]
	v_mfma_f32_16x16x32_bf16 v[90:93], v[230:233], v[182:185], v[90:93]
	v_mfma_f32_16x16x32_bf16 v[86:89], v[216:219], v[190:193], v[86:89]
	v_mfma_f32_16x16x32_bf16 v[82:85], v[230:233], v[190:193], v[82:85]
	v_mfma_f32_16x16x32_bf16 v[78:81], v[216:219], v[198:201], v[78:81]
	v_mfma_f32_16x16x32_bf16 v[74:77], v[230:233], v[198:201], v[74:77]
	v_mfma_f32_16x16x32_bf16 v[70:73], v[216:219], v[206:209], v[70:73]
	v_mfma_f32_16x16x32_bf16 v[66:69], v[230:233], v[206:209], v[66:69]
	v_mfma_f32_16x16x32_bf16 v[94:97], v[226:229], v[186:189], v[94:97]
	v_mfma_f32_16x16x32_bf16 v[90:93], v[234:237], v[186:189], v[90:93]
	v_mfma_f32_16x16x32_bf16 v[86:89], v[226:229], v[194:197], v[86:89]
	v_mfma_f32_16x16x32_bf16 v[82:85], v[234:237], v[194:197], v[82:85]
	v_mfma_f32_16x16x32_bf16 v[78:81], v[226:229], v[202:205], v[78:81]
	v_mfma_f32_16x16x32_bf16 v[74:77], v[234:237], v[202:205], v[74:77]
	v_mfma_f32_16x16x32_bf16 v[70:73], v[226:229], v[210:213], v[70:73]
	v_mfma_f32_16x16x32_bf16 v[66:69], v[234:237], v[210:213], v[66:69]
	s_setprio 1
	v_readfirstlane_b32 s19, v149
	v_lshl_add_u64 v[242:243], v[222:223], 0, s[20:21]
	s_mov_b32 m0, s19
	v_readfirstlane_b32 s19, v153
	s_barrier
	ds_read_b128 v[182:185], v148 offset:16384
	ds_read_b128 v[186:189], v148 offset:17408
	ds_read_b128 v[190:193], v147 offset:16384
	ds_read_b128 v[194:197], v147 offset:17408
	ds_read_b128 v[198:201], v146 offset:16384
	ds_read_b128 v[202:205], v146 offset:17408
	ds_read_b128 v[206:209], v141 offset:16384
	ds_read_b128 v[210:213], v141 offset:17408
	global_load_lds_dwordx4 v[242:243], off
	v_lshl_add_u64 v[242:243], v[224:225], 0, s[20:21]
	s_mov_b32 m0, s19
	s_nop 0
	global_load_lds_dwordx4 v[242:243], off
	s_barrier
	s_waitcnt lgkmcnt(0)
	s_setprio 0
	s_waitcnt lgkmcnt(0)
	v_mfma_f32_16x16x32_bf16 v[60:63], v[142:145], v[182:185], v[60:63]
	v_mfma_f32_16x16x32_bf16 v[56:59], v[174:177], v[182:185], v[56:59]
	v_mfma_f32_16x16x32_bf16 v[52:55], v[142:145], v[190:193], v[52:55]
	v_mfma_f32_16x16x32_bf16 v[48:51], v[174:177], v[190:193], v[48:51]
	v_mfma_f32_16x16x32_bf16 v[44:47], v[142:145], v[198:201], v[44:47]
	v_mfma_f32_16x16x32_bf16 v[40:43], v[174:177], v[198:201], v[40:43]
	v_mfma_f32_16x16x32_bf16 v[36:39], v[142:145], v[206:209], v[36:39]
	v_mfma_f32_16x16x32_bf16 v[32:35], v[174:177], v[206:209], v[32:35]
	v_mfma_f32_16x16x32_bf16 v[60:63], v[170:173], v[186:189], v[60:63]
	v_mfma_f32_16x16x32_bf16 v[56:59], v[178:181], v[186:189], v[56:59]
	v_mfma_f32_16x16x32_bf16 v[52:55], v[170:173], v[194:197], v[52:55]
	v_mfma_f32_16x16x32_bf16 v[48:51], v[178:181], v[194:197], v[48:51]
	v_mfma_f32_16x16x32_bf16 v[44:47], v[170:173], v[202:205], v[44:47]
	v_mfma_f32_16x16x32_bf16 v[40:43], v[178:181], v[202:205], v[40:43]
	v_mfma_f32_16x16x32_bf16 v[36:39], v[170:173], v[210:213], v[36:39]
	v_mfma_f32_16x16x32_bf16 v[32:35], v[178:181], v[210:213], v[32:35]
	s_setprio 1
	s_barrier
; #define STAGE_A(b, h, kt) { const u16* ap_ = A + (size_t)((h) * ahalf + (unsigned)(kt) * 64u); glds16(ap_ + ao0, l0 + SA_(b, h)); glds16(ap_ + ao1, l0 + SA_(b, h) + 8192); }
; #define STAGE_B(b, h, kt) { const u16* bp_ = ((h) ? B1 : B0) + (unsigned)(kt) * 64u; glds16(bp_ + bo0, l0 + SB_(b, h)); glds16(bp_ + bo1, l0 + SB_(b, h) + 8192); }
; #define LDA(dst, b, h) _Pragma("unroll") for (int m = 0; m < 4; ++m) _Pragma("unroll") for (int k = 0; k < 2; ++k) \
;     dst[m][k] = *(const bf16x8*)(lds + SA_(b, h) + lds_byte(wr * 64 + m * 16 + fr, k * 32 + fq * 8));
; #define LDB(dst, b, h) _Pragma("unroll") for (int n = 0; n < 2; ++n) _Pragma("unroll") for (int k = 0; k < 2; ++k) \
;     dst[n][k] = *(const bf16x8*)(lds + SB_(b, h) + lds_byte(wc * 32 + n * 16 + fr, k * 32 + fq * 8));
; #define MMA(ai, bj, At_, Bt_) { __builtin_amdgcn_s_setprio(1); \
;     _Pragma("unroll") for (int m = 0; m < 4; ++m) _Pragma("unroll") for (int n = 0; n < 2; ++n) _Pragma("unroll") for (int k = 0; k < 2; ++k) \
;       acc[ai][bj][m][n] = MFMA16(Bt_[n][k], At_[m][k], acc[ai][bj][m][n]); \
;     __builtin_amdgcn_s_setprio(0); }
; #define WAIT_V(n) asm volatile("s_waitcnt vmcnt(" #n ")" ::: "memory");
; #define WAIT_L(n) asm volatile("s_waitcnt lgkmcnt(" #n ")" ::: "memory");
; #define BAR __builtin_amdgcn_s_barrier();
; #define SCHED __builtin_amdgcn_sched_barrier(0);
; DI void gemm256(const u16* __restrict__ A, int lda, const u16* __restrict__ B0, const u16* __restrict__ B1, int ldb, int nt, acc_t& acc, char* lds) {
;     ...
;     WAIT_V(6) BAR MMA(1, 1, At, Bq1) BAR
;     LDB(Bq0, 1, 0) SCHED LDA(At, 1, 0) STAGE_A(0, 1, t + 2)
;     WAIT_L(8) BAR WAIT_L(0) MMA(0, 0, At, Bq0) BAR SCHED
;     LDB(Bq1, 1, 1) STAGE_B(1, 0, t + 3)
;     BAR WAIT_L(0) MMA(0, 1, At, Bq1) BAR
;     LDA(At, 1, 1) STAGE_A(1, 0, t + 3)
;     BAR WAIT_L(0) MMA(1, 0, At, Bq0) BAR SCHED
;     STAGE_B(1, 1, t + 3)
	v_readfirstlane_b32 s19, v154
	v_lshl_add_u64 v[142:143], v[238:239], 0, s[44:45]
	s_mov_b32 m0, s19
	v_readfirstlane_b32 s19, v155
	global_load_lds_dwordx4 v[142:143], off
	v_lshl_add_u64 v[142:143], v[240:241], 0, s[44:45]
	s_mov_b32 m0, s19
	s_nop 0
	global_load_lds_dwordx4 v[142:143], off
	s_waitcnt vmcnt(6)
	s_barrier
	s_setprio 0
	v_mfma_f32_16x16x32_bf16 v[28:31], v[216:219], v[182:185], v[28:31]
	v_mfma_f32_16x16x32_bf16 v[24:27], v[230:233], v[182:185], v[24:27]
	v_mfma_f32_16x16x32_bf16 v[20:23], v[216:219], v[190:193], v[20:23]
	v_mfma_f32_16x16x32_bf16 v[16:19], v[230:233], v[190:193], v[16:19]
	v_mfma_f32_16x16x32_bf16 v[12:15], v[216:219], v[198:201], v[12:15]
	v_mfma_f32_16x16x32_bf16 v[8:11], v[230:233], v[198:201], v[8:11]
	v_mfma_f32_16x16x32_bf16 v[4:7], v[216:219], v[206:209], v[4:7]
	v_mfma_f32_16x16x32_bf16 v[0:3], v[230:233], v[206:209], v[0:3]
	v_mfma_f32_16x16x32_bf16 v[28:31], v[226:229], v[186:189], v[28:31]
	v_mfma_f32_16x16x32_bf16 v[24:27], v[234:237], v[186:189], v[24:27]
	v_mfma_f32_16x16x32_bf16 v[20:23], v[226:229], v[194:197], v[20:23]
	v_mfma_f32_16x16x32_bf16 v[16:19], v[234:237], v[194:197], v[16:19]
	v_mfma_f32_16x16x32_bf16 v[12:15], v[226:229], v[202:205], v[12:15]
	v_mfma_f32_16x16x32_bf16 v[8:11], v[234:237], v[202:205], v[8:11]
	v_mfma_f32_16x16x32_bf16 v[4:7], v[226:229], v[210:213], v[4:7]
	v_mfma_f32_16x16x32_bf16 v[0:3], v[234:237], v[210:213], v[0:3]
	s_setprio 1
	s_barrier
	ds_read_b128 v[142:145], v156
	ds_read_b128 v[170:173], v156 offset:1024
	ds_read_b128 v[174:177], v156 offset:2048
	ds_read_b128 v[178:181], v156 offset:3072
	v_readfirstlane_b32 s19, v157
	v_lshl_add_u64 v[216:217], v[222:223], 0, s[24:25]
	s_mov_b32 m0, s19
	v_readfirstlane_b32 s19, v158
	ds_read_b128 v[182:185], v148 offset:32768
	ds_read_b128 v[186:189], v148 offset:33792
	ds_read_b128 v[190:193], v147 offset:32768
	ds_read_b128 v[194:197], v147 offset:33792
	ds_read_b128 v[198:201], v146 offset:32768
	ds_read_b128 v[202:205], v146 offset:33792
	ds_read_b128 v[206:209], v141 offset:32768
	ds_read_b128 v[210:213], v141 offset:33792
	global_load_lds_dwordx4 v[216:217], off
	v_lshl_add_u64 v[216:217], v[224:225], 0, s[24:25]
	s_mov_b32 m0, s19
	s_nop 0
	global_load_lds_dwordx4 v[216:217], off
	s_waitcnt lgkmcnt(8)
	s_barrier
	s_waitcnt lgkmcnt(0)
	s_setprio 0
	s_waitcnt lgkmcnt(0)
	v_mfma_f32_16x16x32_bf16 v[126:129], v[142:145], v[182:185], v[126:129]
	v_mfma_f32_16x16x32_bf16 v[122:125], v[174:177], v[182:185], v[122:125]
	v_mfma_f32_16x16x32_bf16 v[118:121], v[142:145], v[190:193], v[118:121]
	v_mfma_f32_16x16x32_bf16 v[114:117], v[174:177], v[190:193], v[114:117]
	v_mfma_f32_16x16x32_bf16 v[110:113], v[142:145], v[198:201], v[110:113]
	v_mfma_f32_16x16x32_bf16 v[106:109], v[174:177], v[198:201], v[106:109]
	v_mfma_f32_16x16x32_bf16 v[102:105], v[142:145], v[206:209], v[102:105]
	v_mfma_f32_16x16x32_bf16 v[98:101], v[174:177], v[206:209], v[98:101]
	v_mfma_f32_16x16x32_bf16 v[126:129], v[170:173], v[186:189], v[126:129]
	v_mfma_f32_16x16x32_bf16 v[122:125], v[178:181], v[186:189], v[122:125]
	v_mfma_f32_16x16x32_bf16 v[118:121], v[170:173], v[194:197], v[118:121]
	v_mfma_f32_16x16x32_bf16 v[114:117], v[178:181], v[194:197], v[114:117]
	v_mfma_f32_16x16x32_bf16 v[110:113], v[170:173], v[202:205], v[110:113]
	v_mfma_f32_16x16x32_bf16 v[106:109], v[178:181], v[202:205], v[106:109]
	v_mfma_f32_16x16x32_bf16 v[102:105], v[170:173], v[210:213], v[102:105]
	v_mfma_f32_16x16x32_bf16 v[98:101], v[178:181], v[210:213], v[98:101]
	s_setprio 1
	s_barrier
	v_readfirstlane_b32 s19, v159
	v_lshl_add_u64 v[242:243], v[238:239], 0, s[48:49]
	s_mov_b32 m0, s19
	v_readfirstlane_b32 s19, v160
	ds_read_b128 v[216:219], v152
	ds_read_b128 v[226:229], v152 offset:1024
	ds_read_b128 v[230:233], v152 offset:2048
	ds_read_b128 v[234:237], v152 offset:3072
	global_load_lds_dwordx4 v[242:243], off
	v_lshl_add_u64 v[242:243], v[240:241], 0, s[48:49]
	s_mov_b32 m0, s19
	s_nop 0
	global_load_lds_dwordx4 v[242:243], off
	s_barrier
	s_waitcnt lgkmcnt(0)
	s_setprio 0
	s_waitcnt lgkmcnt(0)
	v_mfma_f32_16x16x32_bf16 v[94:97], v[216:219], v[182:185], v[94:97]
	v_mfma_f32_16x16x32_bf16 v[90:93], v[230:233], v[182:185], v[90:93]
	v_mfma_f32_16x16x32_bf16 v[86:89], v[216:219], v[190:193], v[86:89]
	v_mfma_f32_16x16x32_bf16 v[82:85], v[230:233], v[190:193], v[82:85]
	v_mfma_f32_16x16x32_bf16 v[78:81], v[216:219], v[198:201], v[78:81]
	v_mfma_f32_16x16x32_bf16 v[74:77], v[230:233], v[198:201], v[74:77]
	v_mfma_f32_16x16x32_bf16 v[70:73], v[216:219], v[206:209], v[70:73]
	v_mfma_f32_16x16x32_bf16 v[66:69], v[230:233], v[206:209], v[66:69]
	v_mfma_f32_16x16x32_bf16 v[94:97], v[226:229], v[186:189], v[94:97]
	v_mfma_f32_16x16x32_bf16 v[90:93], v[234:237], v[186:189], v[90:93]
	v_mfma_f32_16x16x32_bf16 v[86:89], v[226:229], v[194:197], v[86:89]
	v_mfma_f32_16x16x32_bf16 v[82:85], v[234:237], v[194:197], v[82:85]
	v_mfma_f32_16x16x32_bf16 v[78:81], v[226:229], v[202:205], v[78:81]
	v_mfma_f32_16x16x32_bf16 v[74:77], v[234:237], v[202:205], v[74:77]
	v_mfma_f32_16x16x32_bf16 v[70:73], v[226:229], v[210:213], v[70:73]
	v_mfma_f32_16x16x32_bf16 v[66:69], v[234:237], v[210:213], v[66:69]
	s_setprio 1
	v_readfirstlane_b32 s19, v161
	v_lshl_add_u64 v[222:223], v[222:223], 0, s[34:35]
	s_mov_b32 m0, s19
	v_readfirstlane_b32 s19, v162
	s_barrier
	ds_read_b128 v[182:185], v148 offset:49152
	ds_read_b128 v[186:189], v148 offset:50176
	ds_read_b128 v[190:193], v147 offset:49152
	ds_read_b128 v[194:197], v147 offset:50176
	ds_read_b128 v[198:201], v146 offset:49152
	ds_read_b128 v[202:205], v146 offset:50176
	ds_read_b128 v[206:209], v141 offset:49152
	ds_read_b128 v[210:213], v141 offset:50176
	global_load_lds_dwordx4 v[222:223], off
	v_lshl_add_u64 v[222:223], v[224:225], 0, s[34:35]
	s_mov_b32 m0, s19
	s_nop 0
	global_load_lds_dwordx4 v[222:223], off
	s_barrier
; #define STAGE_A(b, h, kt) { const u16* ap_ = A + (size_t)((h) * ahalf + (unsigned)(kt) * 64u); glds16(ap_ + ao0, l0 + SA_(b, h)); glds16(ap_ + ao1, l0 + SA_(b, h) + 8192); }
; #define STAGE_B(b, h, kt) { const u16* bp_ = ((h) ? B1 : B0) + (unsigned)(kt) * 64u; glds16(bp_ + bo0, l0 + SB_(b, h)); glds16(bp_ + bo1, l0 + SB_(b, h) + 8192); }
; #define LDA(dst, b, h) _Pragma("unroll") for (int m = 0; m < 4; ++m) _Pragma("unroll") for (int k = 0; k < 2; ++k) \
;     dst[m][k] = *(const bf16x8*)(lds + SA_(b, h) + lds_byte(wr * 64 + m * 16 + fr, k * 32 + fq * 8));
; #define LDB(dst, b, h) _Pragma("unroll") for (int n = 0; n < 2; ++n) _Pragma("unroll") for (int k = 0; k < 2; ++k) \
;     dst[n][k] = *(const bf16x8*)(lds + SB_(b, h) + lds_byte(wc * 32 + n * 16 + fr, k * 32 + fq * 8));
; #define MMA(ai, bj, At_, Bt_) { __builtin_amdgcn_s_setprio(1); \
;     _Pragma("unroll") for (int m = 0; m < 4; ++m) _Pragma("unroll") for (int n = 0; n < 2; ++n) _Pragma("unroll") for (int k = 0; k < 2; ++k) \
;       acc[ai][bj][m][n] = MFMA16(Bt_[n][k], At_[m][k], acc[ai][bj][m][n]); \
;     __builtin_amdgcn_s_setprio(0); }
; #define WAIT_V(n) asm volatile("s_waitcnt vmcnt(" #n ")" ::: "memory");
; #define WAIT_L(n) asm volatile("s_waitcnt lgkmcnt(" #n ")" ::: "memory");
; #define BAR __builtin_amdgcn_s_barrier();
; #define SCHED __builtin_amdgcn_sched_barrier(0);
; DI void gemm256(const u16* __restrict__ A, int lda, const u16* __restrict__ B0, const u16* __restrict__ B1, int ldb, int nt, acc_t& acc, char* lds) {
;     ...
;     BAR WAIT_L(0) MMA(1, 0, At, Bq0) BAR SCHED
;     STAGE_B(1, 1, t + 3)
;     WAIT_V(6) BAR MMA(1, 1, At, Bq1) BAR
;   }
;   { LDB(Bq0, 0, 0) LDA(At, 0, 0) STAGE_A(1, 1, nt - 1)
;     BAR WAIT_L(0) MMA(0, 0, At, Bq0) BAR
;     LDB(Bq1, 0, 1) BAR WAIT_L(0) MMA(0, 1, At, Bq1) BAR
;     LDA(At, 0, 1) WAIT_V(4) BAR WAIT_L(0) MMA(1, 0, At, Bq0) MMA(1, 1, At, Bq1) BAR }
;   { LDB(Bq0, 1, 0) LDA(At, 1, 0) WAIT_V(2) BAR WAIT_L(0) MMA(0, 0, At, Bq0) BAR
	s_waitcnt lgkmcnt(0)
	s_setprio 0
	s_waitcnt lgkmcnt(0)
	v_mfma_f32_16x16x32_bf16 v[60:63], v[142:145], v[182:185], v[60:63]
	v_mfma_f32_16x16x32_bf16 v[56:59], v[174:177], v[182:185], v[56:59]
	v_mfma_f32_16x16x32_bf16 v[52:55], v[142:145], v[190:193], v[52:55]
	v_mfma_f32_16x16x32_bf16 v[48:51], v[174:177], v[190:193], v[48:51]
	v_mfma_f32_16x16x32_bf16 v[44:47], v[142:145], v[198:201], v[44:47]
	v_mfma_f32_16x16x32_bf16 v[40:43], v[174:177], v[198:201], v[40:43]
	v_mfma_f32_16x16x32_bf16 v[36:39], v[142:145], v[206:209], v[36:39]
	v_mfma_f32_16x16x32_bf16 v[32:35], v[174:177], v[206:209], v[32:35]
	v_mfma_f32_16x16x32_bf16 v[60:63], v[170:173], v[186:189], v[60:63]
	v_mfma_f32_16x16x32_bf16 v[56:59], v[178:181], v[186:189], v[56:59]
	v_mfma_f32_16x16x32_bf16 v[52:55], v[170:173], v[194:197], v[52:55]
	v_mfma_f32_16x16x32_bf16 v[48:51], v[178:181], v[194:197], v[48:51]
	v_mfma_f32_16x16x32_bf16 v[44:47], v[170:173], v[202:205], v[44:47]
	v_mfma_f32_16x16x32_bf16 v[40:43], v[178:181], v[202:205], v[40:43]
	v_mfma_f32_16x16x32_bf16 v[36:39], v[170:173], v[210:213], v[36:39]
	v_mfma_f32_16x16x32_bf16 v[32:35], v[178:181], v[210:213], v[32:35]
	s_setprio 1
	s_barrier
	v_readfirstlane_b32 s19, v163
	v_lshl_add_u64 v[142:143], v[238:239], 0, s[54:55]
	s_mov_b32 m0, s19
	v_readfirstlane_b32 s19, v164
	global_load_lds_dwordx4 v[142:143], off
	v_lshl_add_u64 v[142:143], v[240:241], 0, s[54:55]
	s_mov_b32 m0, s19
	s_nop 0
	global_load_lds_dwordx4 v[142:143], off
	s_waitcnt vmcnt(6)
	s_barrier
	s_setprio 0
	v_mfma_f32_16x16x32_bf16 v[28:31], v[216:219], v[182:185], v[28:31]
	v_mfma_f32_16x16x32_bf16 v[24:27], v[230:233], v[182:185], v[24:27]
	v_mfma_f32_16x16x32_bf16 v[20:23], v[216:219], v[190:193], v[20:23]
	v_mfma_f32_16x16x32_bf16 v[16:19], v[230:233], v[190:193], v[16:19]
	v_mfma_f32_16x16x32_bf16 v[12:15], v[216:219], v[198:201], v[12:15]
	v_mfma_f32_16x16x32_bf16 v[8:11], v[230:233], v[198:201], v[8:11]
	v_mfma_f32_16x16x32_bf16 v[4:7], v[216:219], v[206:209], v[4:7]
	v_mfma_f32_16x16x32_bf16 v[0:3], v[230:233], v[206:209], v[0:3]
	v_mfma_f32_16x16x32_bf16 v[28:31], v[226:229], v[186:189], v[28:31]
	v_mfma_f32_16x16x32_bf16 v[24:27], v[234:237], v[186:189], v[24:27]
	v_mfma_f32_16x16x32_bf16 v[20:23], v[226:229], v[194:197], v[20:23]
	v_mfma_f32_16x16x32_bf16 v[16:19], v[234:237], v[194:197], v[16:19]
	v_mfma_f32_16x16x32_bf16 v[12:15], v[226:229], v[202:205], v[12:15]
	v_mfma_f32_16x16x32_bf16 v[8:11], v[234:237], v[202:205], v[8:11]
	v_mfma_f32_16x16x32_bf16 v[4:7], v[226:229], v[210:213], v[4:7]
	v_mfma_f32_16x16x32_bf16 v[0:3], v[234:237], v[210:213], v[0:3]
	s_setprio 1
	s_add_i32 s7, s7, 2
	s_add_u32 s22, s22, 0x100
	s_addc_u32 s23, s23, 0
	s_cmp_lt_u32 s7, 12
	s_barrier
	s_cbranch_scc1 .LBB0_973
	s_add_u32 s54, s50, 0x40780
	s_addc_u32 s55, s51, 0
	v_readfirstlane_b32 s7, v167
	v_lshl_add_u64 v[150:151], v[64:65], 1, s[54:55]
	s_mov_b32 m0, s7
	v_readfirstlane_b32 s7, v168
	ds_read_b128 v[132:135], v166
	ds_read_b128 v[136:139], v166 offset:1024
	ds_read_b128 v[142:145], v166 offset:2048
	ds_read_b128 v[158:161], v166 offset:3072
	ds_read_b128 v[170:173], v148
	ds_read_b128 v[174:177], v148 offset:1024
	ds_read_b128 v[178:181], v147
	ds_read_b128 v[182:185], v147 offset:1024
	ds_read_b128 v[186:189], v146
	ds_read_b128 v[190:193], v146 offset:1024
	ds_read_b128 v[194:197], v141
	ds_read_b128 v[198:201], v141 offset:1024
	global_load_lds_dwordx4 v[150:151], off
	v_lshl_add_u64 v[130:131], v[130:131], 1, s[54:55]
	s_mov_b32 m0, s7
	s_nop 0
	global_load_lds_dwordx4 v[130:131], off
	s_barrier
	s_waitcnt lgkmcnt(0)
	s_setprio 0
	s_waitcnt lgkmcnt(0)
	v_mfma_f32_16x16x32_bf16 v[126:129], v[132:135], v[170:173], v[126:129]
	v_mfma_f32_16x16x32_bf16 v[122:125], v[142:145], v[170:173], v[122:125]
	v_mfma_f32_16x16x32_bf16 v[118:121], v[132:135], v[178:181], v[118:121]
	v_mfma_f32_16x16x32_bf16 v[114:117], v[142:145], v[178:181], v[114:117]
	v_mfma_f32_16x16x32_bf16 v[102:105], v[132:135], v[194:197], v[102:105]
	v_mfma_f32_16x16x32_bf16 v[98:101], v[142:145], v[194:197], v[98:101]
	v_mfma_f32_16x16x32_bf16 v[126:129], v[136:139], v[174:177], v[126:129]
	v_mfma_f32_16x16x32_bf16 v[122:125], v[158:161], v[174:177], v[122:125]
	v_mfma_f32_16x16x32_bf16 v[118:121], v[136:139], v[182:185], v[118:121]
	v_mfma_f32_16x16x32_bf16 v[114:117], v[158:161], v[182:185], v[114:117]
	v_mfma_f32_16x16x32_bf16 v[110:113], v[132:135], v[186:189], v[110:113]
	v_mfma_f32_16x16x32_bf16 v[106:109], v[142:145], v[186:189], v[106:109]
	v_mfma_f32_16x16x32_bf16 v[102:105], v[136:139], v[198:201], v[102:105]
	v_mfma_f32_16x16x32_bf16 v[98:101], v[158:161], v[198:201], v[98:101]
	v_mfma_f32_16x16x32_bf16 v[166:169], v[136:139], v[190:193], v[110:113]
	v_mfma_f32_16x16x32_bf16 v[202:205], v[158:161], v[190:193], v[106:109]
	s_setprio 1
	s_barrier
	s_nop 1
	ds_read_b128 v[106:109], v165
	ds_read_b128 v[110:113], v165 offset:1024
	ds_read_b128 v[206:209], v165 offset:2048
	ds_read_b128 v[162:165], v165 offset:3072
	s_barrier
	s_waitcnt lgkmcnt(0)
	s_setprio 0
	s_waitcnt lgkmcnt(0)
	v_mfma_f32_16x16x32_bf16 v[86:89], v[106:109], v[178:181], v[86:89]
	v_mfma_f32_16x16x32_bf16 v[82:85], v[206:209], v[178:181], v[82:85]
	v_mfma_f32_16x16x32_bf16 v[70:73], v[106:109], v[194:197], v[70:73]
	v_mfma_f32_16x16x32_bf16 v[66:69], v[206:209], v[194:197], v[66:69]
	v_mfma_f32_16x16x32_bf16 v[94:97], v[106:109], v[170:173], v[94:97]
	v_mfma_f32_16x16x32_bf16 v[90:93], v[206:209], v[170:173], v[90:93]
	v_mfma_f32_16x16x32_bf16 v[86:89], v[110:113], v[182:185], v[86:89]
	v_mfma_f32_16x16x32_bf16 v[82:85], v[162:165], v[182:185], v[82:85]
	v_mfma_f32_16x16x32_bf16 v[78:81], v[106:109], v[186:189], v[78:81]
	v_mfma_f32_16x16x32_bf16 v[74:77], v[206:209], v[186:189], v[74:77]
	v_mfma_f32_16x16x32_bf16 v[70:73], v[110:113], v[198:201], v[70:73]
	v_mfma_f32_16x16x32_bf16 v[66:69], v[162:165], v[198:201], v[66:69]
	v_mfma_f32_16x16x32_bf16 v[210:213], v[110:113], v[174:177], v[94:97]
	v_mfma_f32_16x16x32_bf16 v[170:173], v[162:165], v[174:177], v[90:93]
	v_mfma_f32_16x16x32_bf16 v[174:177], v[110:113], v[190:193], v[78:81]
	v_mfma_f32_16x16x32_bf16 v[178:181], v[162:165], v[190:193], v[74:77]
	s_setprio 1
	s_barrier
; #define LDA(dst, b, h) _Pragma("unroll") for (int m = 0; m < 4; ++m) _Pragma("unroll") for (int k = 0; k < 2; ++k) \
;     dst[m][k] = *(const bf16x8*)(lds + SA_(b, h) + lds_byte(wr * 64 + m * 16 + fr, k * 32 + fq * 8));
; #define LDB(dst, b, h) _Pragma("unroll") for (int n = 0; n < 2; ++n) _Pragma("unroll") for (int k = 0; k < 2; ++k) \
;     dst[n][k] = *(const bf16x8*)(lds + SB_(b, h) + lds_byte(wc * 32 + n * 16 + fr, k * 32 + fq * 8));
; #define MMA(ai, bj, At_, Bt_) { __builtin_amdgcn_s_setprio(1); \
;     _Pragma("unroll") for (int m = 0; m < 4; ++m) _Pragma("unroll") for (int n = 0; n < 2; ++n) _Pragma("unroll") for (int k = 0; k < 2; ++k) \
;       acc[ai][bj][m][n] = MFMA16(Bt_[n][k], At_[m][k], acc[ai][bj][m][n]); \
;     __builtin_amdgcn_s_setprio(0); }
; #define WAIT_V(n) asm volatile("s_waitcnt vmcnt(" #n ")" ::: "memory");
; #define WAIT_L(n) asm volatile("s_waitcnt lgkmcnt(" #n ")" ::: "memory");
; #define BAR __builtin_amdgcn_s_barrier();
; DI void gemm256(const u16* __restrict__ A, int lda, const u16* __restrict__ B0, const u16* __restrict__ B1, int ldb, int nt, acc_t& acc, char* lds) {
;     ...
;     LDA(At, 0, 1) WAIT_V(4) BAR WAIT_L(0) MMA(1, 0, At, Bq0) MMA(1, 1, At, Bq1) BAR }
;   { LDB(Bq0, 1, 0) LDA(At, 1, 0) WAIT_V(2) BAR WAIT_L(0) MMA(0, 0, At, Bq0) BAR
	s_nop 0
	ds_read_b128 v[74:77], v148 offset:16384
	ds_read_b128 v[78:81], v148 offset:17408
	ds_read_b128 v[90:93], v147 offset:16384
	ds_read_b128 v[94:97], v147 offset:17408
	ds_read_b128 v[182:185], v146 offset:16384
	ds_read_b128 v[186:189], v146 offset:17408
	ds_read_b128 v[190:193], v141 offset:16384
	ds_read_b128 v[194:197], v141 offset:17408
	s_waitcnt vmcnt(4)
	s_barrier
	s_waitcnt lgkmcnt(0)
	s_setprio 0
	s_waitcnt lgkmcnt(0)
	v_mfma_f32_16x16x32_bf16 v[60:63], v[132:135], v[74:77], v[60:63]
	v_mfma_f32_16x16x32_bf16 v[56:59], v[142:145], v[74:77], v[56:59]
	v_mfma_f32_16x16x32_bf16 v[52:55], v[132:135], v[90:93], v[52:55]
	v_mfma_f32_16x16x32_bf16 v[48:51], v[142:145], v[90:93], v[48:51]
	v_mfma_f32_16x16x32_bf16 v[36:39], v[132:135], v[190:193], v[36:39]
	v_mfma_f32_16x16x32_bf16 v[32:35], v[142:145], v[190:193], v[32:35]
	v_mfma_f32_16x16x32_bf16 v[60:63], v[136:139], v[78:81], v[60:63]
	v_mfma_f32_16x16x32_bf16 v[56:59], v[158:161], v[78:81], v[56:59]
	v_mfma_f32_16x16x32_bf16 v[52:55], v[136:139], v[94:97], v[52:55]
	v_mfma_f32_16x16x32_bf16 v[48:51], v[158:161], v[94:97], v[48:51]
	v_mfma_f32_16x16x32_bf16 v[44:47], v[132:135], v[182:185], v[44:47]
	v_mfma_f32_16x16x32_bf16 v[40:43], v[142:145], v[182:185], v[40:43]
	v_mfma_f32_16x16x32_bf16 v[36:39], v[136:139], v[194:197], v[36:39]
	v_mfma_f32_16x16x32_bf16 v[32:35], v[158:161], v[194:197], v[32:35]
	v_mfma_f32_16x16x32_bf16 v[198:201], v[136:139], v[186:189], v[44:47]
	v_mfma_f32_16x16x32_bf16 v[216:219], v[158:161], v[186:189], v[40:43]
	s_setprio 1
	s_setprio 0
	v_mfma_f32_16x16x32_bf16 v[20:23], v[106:109], v[90:93], v[20:23]
	v_mfma_f32_16x16x32_bf16 v[16:19], v[206:209], v[90:93], v[16:19]
	v_mfma_f32_16x16x32_bf16 v[4:7], v[106:109], v[190:193], v[4:7]
	v_mfma_f32_16x16x32_bf16 v[0:3], v[206:209], v[190:193], v[0:3]
	v_mfma_f32_16x16x32_bf16 v[28:31], v[106:109], v[74:77], v[28:31]
	v_mfma_f32_16x16x32_bf16 v[24:27], v[206:209], v[74:77], v[24:27]
	v_mfma_f32_16x16x32_bf16 v[20:23], v[110:113], v[94:97], v[20:23]
	v_mfma_f32_16x16x32_bf16 v[16:19], v[162:165], v[94:97], v[16:19]
	v_mfma_f32_16x16x32_bf16 v[12:15], v[106:109], v[182:185], v[12:15]
	v_mfma_f32_16x16x32_bf16 v[8:11], v[206:209], v[182:185], v[8:11]
	v_mfma_f32_16x16x32_bf16 v[4:7], v[110:113], v[194:197], v[4:7]
	v_mfma_f32_16x16x32_bf16 v[0:3], v[162:165], v[194:197], v[0:3]
	v_mfma_f32_16x16x32_bf16 v[130:133], v[110:113], v[78:81], v[28:31]
	v_mfma_f32_16x16x32_bf16 v[134:137], v[162:165], v[78:81], v[24:27]
	v_mfma_f32_16x16x32_bf16 v[142:145], v[110:113], v[186:189], v[12:15]
	v_mfma_f32_16x16x32_bf16 v[158:161], v[162:165], v[186:189], v[8:11]
	s_setprio 1
	s_barrier
	s_nop 0
	ds_read_b128 v[8:11], v156
	ds_read_b128 v[12:15], v156 offset:1024
	ds_read_b128 v[162:165], v156 offset:2048
	ds_read_b128 v[154:157], v156 offset:3072
	ds_read_b128 v[24:27], v148 offset:32768
	ds_read_b128 v[28:31], v148 offset:33792
	ds_read_b128 v[40:43], v147 offset:32768
	ds_read_b128 v[44:47], v147 offset:33792
	ds_read_b128 v[182:185], v146 offset:32768
	ds_read_b128 v[186:189], v146 offset:33792
	ds_read_b128 v[190:193], v141 offset:32768
	ds_read_b128 v[194:197], v141 offset:33792
	s_waitcnt vmcnt(2)
	s_barrier
	s_waitcnt lgkmcnt(0)
	s_setprio 0
	s_waitcnt lgkmcnt(0)
	v_mfma_f32_16x16x32_bf16 v[74:77], v[8:11], v[24:27], v[126:129]
	v_mfma_f32_16x16x32_bf16 v[126:129], v[12:15], v[28:31], v[74:77]
	v_mfma_f32_16x16x32_bf16 v[74:77], v[162:165], v[24:27], v[122:125]
	v_mfma_f32_16x16x32_bf16 v[122:125], v[154:157], v[28:31], v[74:77]
	v_mfma_f32_16x16x32_bf16 v[74:77], v[8:11], v[40:43], v[118:121]
	v_mfma_f32_16x16x32_bf16 v[110:113], v[12:15], v[44:47], v[74:77]
	v_mfma_f32_16x16x32_bf16 v[74:77], v[162:165], v[40:43], v[114:117]
	v_mfma_f32_16x16x32_bf16 v[106:109], v[154:157], v[44:47], v[74:77]
	v_mfma_f32_16x16x32_bf16 v[74:77], v[8:11], v[182:185], v[166:169]
	v_mfma_f32_16x16x32_bf16 v[94:97], v[12:15], v[186:189], v[74:77]
	v_mfma_f32_16x16x32_bf16 v[74:77], v[162:165], v[182:185], v[202:205]
	v_mfma_f32_16x16x32_bf16 v[90:93], v[154:157], v[186:189], v[74:77]
	v_mfma_f32_16x16x32_bf16 v[74:77], v[8:11], v[190:193], v[102:105]
	v_mfma_f32_16x16x32_bf16 v[78:81], v[12:15], v[194:197], v[74:77]
	v_mfma_f32_16x16x32_bf16 v[74:77], v[162:165], v[190:193], v[98:101]
	v_mfma_f32_16x16x32_bf16 v[74:77], v[154:157], v[194:197], v[74:77]
	s_setprio 1
	s_barrier
; #define LDA(dst, b, h) _Pragma("unroll") for (int m = 0; m < 4; ++m) _Pragma("unroll") for (int k = 0; k < 2; ++k) \
;     dst[m][k] = *(const bf16x8*)(lds + SA_(b, h) + lds_byte(wr * 64 + m * 16 + fr, k * 32 + fq * 8));
; #define LDB(dst, b, h) _Pragma("unroll") for (int n = 0; n < 2; ++n) _Pragma("unroll") for (int k = 0; k < 2; ++k) \
;     dst[n][k] = *(const bf16x8*)(lds + SB_(b, h) + lds_byte(wc * 32 + n * 16 + fr, k * 32 + fq * 8));
; #define MMA(ai, bj, At_, Bt_) { __builtin_amdgcn_s_setprio(1); \
;     _Pragma("unroll") for (int m = 0; m < 4; ++m) _Pragma("unroll") for (int n = 0; n < 2; ++n) _Pragma("unroll") for (int k = 0; k < 2; ++k) \
;       acc[ai][bj][m][n] = MFMA16(Bt_[n][k], At_[m][k], acc[ai][bj][m][n]); \
;     __builtin_amdgcn_s_setprio(0); }
; #define WAIT_V(n) asm volatile("s_waitcnt vmcnt(" #n ")" ::: "memory");
; #define WAIT_L(n) asm volatile("s_waitcnt lgkmcnt(" #n ")" ::: "memory");
; #define BAR __builtin_amdgcn_s_barrier();
; DI void gemm256(const u16* __restrict__ A, int lda, const u16* __restrict__ B0, const u16* __restrict__ B1, int ldb, int nt, acc_t& acc, char* lds) {
;     ...
;     LDB(Bq1, 1, 1) WAIT_V(0) BAR WAIT_L(0) MMA(0, 1, At, Bq1) BAR
;     LDA(At, 1, 1) BAR WAIT_L(0) MMA(1, 0, At, Bq0) MMA(1, 1, At, Bq1) BAR }
;   if (wr == 0) BAR
;   __syncthreads();
	ds_read_b128 v[166:169], v152
	ds_read_b128 v[202:205], v152 offset:1024
	ds_read_b128 v[206:209], v152 offset:2048
	ds_read_b128 v[150:153], v152 offset:3072
	s_waitcnt vmcnt(0)
	s_barrier
	s_waitcnt lgkmcnt(0)
	s_setprio 0
	s_waitcnt lgkmcnt(0)
	v_mfma_f32_16x16x32_bf16 v[98:101], v[166:169], v[24:27], v[210:213]
	v_mfma_f32_16x16x32_bf16 v[24:27], v[206:209], v[24:27], v[170:173]
	v_mfma_f32_16x16x32_bf16 v[114:117], v[150:153], v[28:31], v[24:27]
	v_mfma_f32_16x16x32_bf16 v[24:27], v[166:169], v[40:43], v[86:89]
	v_mfma_f32_16x16x32_bf16 v[102:105], v[202:205], v[44:47], v[24:27]
	v_mfma_f32_16x16x32_bf16 v[24:27], v[206:209], v[40:43], v[82:85]
	v_mfma_f32_16x16x32_bf16 v[118:121], v[202:205], v[28:31], v[98:101]
	v_mfma_f32_16x16x32_bf16 v[98:101], v[150:153], v[44:47], v[24:27]
	v_mfma_f32_16x16x32_bf16 v[24:27], v[166:169], v[182:185], v[174:177]
	v_mfma_f32_16x16x32_bf16 v[86:89], v[202:205], v[186:189], v[24:27]
	v_mfma_f32_16x16x32_bf16 v[24:27], v[206:209], v[182:185], v[178:181]
	v_mfma_f32_16x16x32_bf16 v[82:85], v[150:153], v[186:189], v[24:27]
	v_mfma_f32_16x16x32_bf16 v[24:27], v[166:169], v[190:193], v[70:73]
	v_mfma_f32_16x16x32_bf16 v[70:73], v[202:205], v[194:197], v[24:27]
	v_mfma_f32_16x16x32_bf16 v[24:27], v[206:209], v[190:193], v[66:69]
	v_mfma_f32_16x16x32_bf16 v[66:69], v[150:153], v[194:197], v[24:27]
	s_setprio 1
	s_barrier
	ds_read_b128 v[170:173], v148 offset:49152
	ds_read_b128 v[174:177], v148 offset:50176
	ds_read_b128 v[178:181], v147 offset:49152
	ds_read_b128 v[182:185], v147 offset:50176
	ds_read_b128 v[186:189], v146 offset:49152
	ds_read_b128 v[146:149], v146 offset:50176
	ds_read_b128 v[190:193], v141 offset:49152
	ds_read_b128 v[194:197], v141 offset:50176
	s_barrier
	s_waitcnt lgkmcnt(0)
	s_setprio 0
	s_waitcnt lgkmcnt(0)
	v_mfma_f32_16x16x32_bf16 v[24:27], v[8:11], v[170:173], v[60:63]
	v_mfma_f32_16x16x32_bf16 v[60:63], v[12:15], v[174:177], v[24:27]
	v_mfma_f32_16x16x32_bf16 v[24:27], v[162:165], v[170:173], v[56:59]
	v_mfma_f32_16x16x32_bf16 v[56:59], v[154:157], v[174:177], v[24:27]
	v_mfma_f32_16x16x32_bf16 v[24:27], v[8:11], v[178:181], v[52:55]
	v_mfma_f32_16x16x32_bf16 v[44:47], v[12:15], v[182:185], v[24:27]
	v_mfma_f32_16x16x32_bf16 v[24:27], v[162:165], v[178:181], v[48:51]
	v_mfma_f32_16x16x32_bf16 v[40:43], v[154:157], v[182:185], v[24:27]
	v_mfma_f32_16x16x32_bf16 v[24:27], v[8:11], v[186:189], v[198:201]
	v_mfma_f32_16x16x32_bf16 v[8:11], v[8:11], v[190:193], v[36:39]
	v_mfma_f32_16x16x32_bf16 v[28:31], v[12:15], v[146:149], v[24:27]
	v_mfma_f32_16x16x32_bf16 v[24:27], v[162:165], v[186:189], v[216:219]
	v_mfma_f32_16x16x32_bf16 v[12:15], v[12:15], v[194:197], v[8:11]
	v_mfma_f32_16x16x32_bf16 v[8:11], v[162:165], v[190:193], v[32:35]
	v_mfma_f32_16x16x32_bf16 v[24:27], v[154:157], v[146:149], v[24:27]
	v_mfma_f32_16x16x32_bf16 v[8:11], v[154:157], v[194:197], v[8:11]
	s_setprio 1
	s_setprio 0
	v_mfma_f32_16x16x32_bf16 v[32:35], v[166:169], v[170:173], v[130:133]
	v_mfma_f32_16x16x32_bf16 v[52:55], v[202:205], v[174:177], v[32:35]
	v_mfma_f32_16x16x32_bf16 v[32:35], v[206:209], v[170:173], v[134:137]
	v_mfma_f32_16x16x32_bf16 v[16:19], v[206:209], v[178:181], v[16:19]
	v_mfma_f32_16x16x32_bf16 v[48:51], v[150:153], v[174:177], v[32:35]
	v_mfma_f32_16x16x32_bf16 v[20:23], v[166:169], v[178:181], v[20:23]
	v_mfma_f32_16x16x32_bf16 v[32:35], v[150:153], v[182:185], v[16:19]
	v_mfma_f32_16x16x32_bf16 v[16:19], v[166:169], v[186:189], v[142:145]
	v_mfma_f32_16x16x32_bf16 v[36:39], v[202:205], v[182:185], v[20:23]
	v_mfma_f32_16x16x32_bf16 v[20:23], v[202:205], v[146:149], v[16:19]
	v_mfma_f32_16x16x32_bf16 v[16:19], v[206:209], v[186:189], v[158:161]
	v_mfma_f32_16x16x32_bf16 v[4:7], v[166:169], v[190:193], v[4:7]
	v_mfma_f32_16x16x32_bf16 v[0:3], v[206:209], v[190:193], v[0:3]
	v_mfma_f32_16x16x32_bf16 v[16:19], v[150:153], v[146:149], v[16:19]
	v_mfma_f32_16x16x32_bf16 v[4:7], v[202:205], v[194:197], v[4:7]
	v_mfma_f32_16x16x32_bf16 v[0:3], v[150:153], v[194:197], v[0:3]
	s_setprio 1
	s_movk_i32 s7, 0x100
	v_cmp_gt_u32_e32 vcc, s7, v140
	s_barrier
	s_and_saveexec_b64 s[22:23], vcc
	s_cbranch_execz .LBB0_976
	s_barrier

; #define STAGE_A(b, h, kt) { const u16* ap_ = A + (size_t)((h) * ahalf + (unsigned)(kt) * 64u); glds16(ap_ + ao0, l0 + SA_(b, h)); glds16(ap_ + ao1, l0 + SA_(b, h) + 8192); }
; #define STAGE_B(b, h, kt) { const u16* bp_ = ((h) ? B1 : B0) + (unsigned)(kt) * 64u; glds16(bp_ + bo0, l0 + SB_(b, h)); glds16(bp_ + bo1, l0 + SB_(b, h) + 8192); }
; #define LDA(dst, b, h) _Pragma("unroll") for (int m = 0; m < 4; ++m) _Pragma("unroll") for (int k = 0; k < 2; ++k) \
;     dst[m][k] = *(const bf16x8*)(lds + SA_(b, h) + lds_byte(wr * 64 + m * 16 + fr, k * 32 + fq * 8));
; #define LDB(dst, b, h) _Pragma("unroll") for (int n = 0; n < 2; ++n) _Pragma("unroll") for (int k = 0; k < 2; ++k) \
;     dst[n][k] = *(const bf16x8*)(lds + SB_(b, h) + lds_byte(wc * 32 + n * 16 + fr, k * 32 + fq * 8));
; #define MMA(ai, bj, At_, Bt_) { __builtin_amdgcn_s_setprio(1); \
;     _Pragma("unroll") for (int m = 0; m < 4; ++m) _Pragma("unroll") for (int n = 0; n < 2; ++n) _Pragma("unroll") for (int k = 0; k < 2; ++k) \
;       acc[ai][bj][m][n] = MFMA16(Bt_[n][k], At_[m][k], acc[ai][bj][m][n]); \
;     __builtin_amdgcn_s_setprio(0); }
; #define WAIT_V(n) asm volatile("s_waitcnt vmcnt(" #n ")" ::: "memory");
; #define WAIT_L(n) asm volatile("s_waitcnt lgkmcnt(" #n ")" ::: "memory");
; #define BAR __builtin_amdgcn_s_barrier();
; #define SCHED __builtin_amdgcn_sched_barrier(0);
; DI void gemm256(const u16* __restrict__ A, int lda, const u16* __restrict__ B0, const u16* __restrict__ B1, int ldb, int nt, acc_t& acc, char* lds) {
;     ...
;   for (int t = 0; t < nt - 2; t += 2) {
;     LDB(Bq0, 0, 0) SCHED LDA(At, 0, 0) STAGE_A(1, 1, t + 1)
;     WAIT_L(8) BAR WAIT_L(0) MMA(0, 0, At, Bq0) BAR SCHED
;     LDB(Bq1, 0, 1) STAGE_B(0, 0, t + 2)
;     BAR WAIT_L(0) MMA(0, 1, At, Bq1) BAR
;     LDA(At, 0, 1) STAGE_A(0, 0, t + 2)
;     BAR WAIT_L(0) MMA(1, 0, At, Bq0) BAR SCHED
;     STAGE_B(0, 1, t + 2)
;     WAIT_V(6) BAR MMA(1, 1, At, Bq1) BAR
; DI void p5_phase(const Params& p, char* lds) {
;     ...
;     zero_acc(acc);
;     gemm256(oab + (size_t)row0 * 1024, 1024, (const u16*)(ws + OFF_WA) + (size_t)col0 * 512, (const u16*)(ws + OFF_WA) + (size_t)(col0 + 128) * 512, 512, 8, acc, lds);
.LBB0_979:
	ds_read_b128 v[142:145], v166
	ds_read_b128 v[170:173], v166 offset:1024
	ds_read_b128 v[174:177], v166 offset:2048
	ds_read_b128 v[178:181], v166 offset:3072
	v_add_u32_e32 v167, 0xc000, v149
	v_lshl_add_u64 v[222:223], s[8:9], 0, v[136:137]
	v_readfirstlane_b32 s3, v167
	v_lshl_add_u64 v[168:169], v[222:223], 0, s[76:77]
	s_mov_b32 m0, s3
	ds_read_b128 v[182:185], v148
	ds_read_b128 v[186:189], v148 offset:1024
	ds_read_b128 v[190:193], v147
	ds_read_b128 v[194:197], v147 offset:1024
	ds_read_b128 v[198:201], v146
	ds_read_b128 v[202:205], v146 offset:1024
	ds_read_b128 v[206:209], v141
	ds_read_b128 v[210:213], v141 offset:1024
	global_load_lds_dwordx4 v[168:169], off
	v_add_u32_e32 v168, 0xe000, v149
	v_lshl_add_u64 v[224:225], s[8:9], 0, v[138:139]
	v_readfirstlane_b32 s3, v168
	v_lshl_add_u64 v[216:217], v[224:225], 0, s[76:77]
	s_mov_b32 m0, s3
	s_nop 0
	global_load_lds_dwordx4 v[216:217], off
	s_waitcnt lgkmcnt(8)
	s_barrier
	s_waitcnt lgkmcnt(0)
	s_setprio 0
	s_waitcnt lgkmcnt(0)
	v_mfma_f32_16x16x32_bf16 v[126:129], v[142:145], v[182:185], v[126:129]
	v_mfma_f32_16x16x32_bf16 v[122:125], v[174:177], v[182:185], v[122:125]
	v_mfma_f32_16x16x32_bf16 v[118:121], v[142:145], v[190:193], v[118:121]
	v_mfma_f32_16x16x32_bf16 v[114:117], v[174:177], v[190:193], v[114:117]
	v_mfma_f32_16x16x32_bf16 v[110:113], v[142:145], v[198:201], v[110:113]
	v_mfma_f32_16x16x32_bf16 v[106:109], v[174:177], v[198:201], v[106:109]
	v_mfma_f32_16x16x32_bf16 v[102:105], v[142:145], v[206:209], v[102:105]
	v_mfma_f32_16x16x32_bf16 v[98:101], v[174:177], v[206:209], v[98:101]
	v_mfma_f32_16x16x32_bf16 v[126:129], v[170:173], v[186:189], v[126:129]
	v_mfma_f32_16x16x32_bf16 v[122:125], v[178:181], v[186:189], v[122:125]
	v_mfma_f32_16x16x32_bf16 v[118:121], v[170:173], v[194:197], v[118:121]
	v_mfma_f32_16x16x32_bf16 v[114:117], v[178:181], v[194:197], v[114:117]
	v_mfma_f32_16x16x32_bf16 v[110:113], v[170:173], v[202:205], v[110:113]
	v_mfma_f32_16x16x32_bf16 v[106:109], v[178:181], v[202:205], v[106:109]
	v_mfma_f32_16x16x32_bf16 v[102:105], v[170:173], v[210:213], v[102:105]
	v_mfma_f32_16x16x32_bf16 v[98:101], v[178:181], v[210:213], v[98:101]
	s_setprio 1
	s_barrier
	v_lshl_add_u64 v[238:239], s[8:9], 0, v[132:133]
	v_readfirstlane_b32 s3, v150
	v_lshl_add_u64 v[240:241], v[238:239], 0, s[22:23]
	s_mov_b32 m0, s3
	ds_read_b128 v[216:219], v165
	ds_read_b128 v[226:229], v165 offset:1024
	ds_read_b128 v[230:233], v165 offset:2048
	ds_read_b128 v[234:237], v165 offset:3072
	global_load_lds_dwordx4 v[240:241], off
	v_lshl_add_u64 v[240:241], s[8:9], 0, v[134:135]
	v_readfirstlane_b32 s3, v152
	v_lshl_add_u64 v[242:243], v[240:241], 0, s[22:23]
	s_mov_b32 m0, s3
	s_nop 0
	global_load_lds_dwordx4 v[242:243], off
	s_barrier
	s_waitcnt lgkmcnt(0)
	s_setprio 0
	s_waitcnt lgkmcnt(0)
	v_mfma_f32_16x16x32_bf16 v[94:97], v[216:219], v[182:185], v[94:97]
	v_mfma_f32_16x16x32_bf16 v[90:93], v[230:233], v[182:185], v[90:93]
	v_mfma_f32_16x16x32_bf16 v[86:89], v[216:219], v[190:193], v[86:89]
	v_mfma_f32_16x16x32_bf16 v[82:85], v[230:233], v[190:193], v[82:85]
	v_mfma_f32_16x16x32_bf16 v[78:81], v[216:219], v[198:201], v[78:81]
	v_mfma_f32_16x16x32_bf16 v[74:77], v[230:233], v[198:201], v[74:77]
	v_mfma_f32_16x16x32_bf16 v[70:73], v[216:219], v[206:209], v[70:73]
	v_mfma_f32_16x16x32_bf16 v[66:69], v[230:233], v[206:209], v[66:69]
	v_mfma_f32_16x16x32_bf16 v[94:97], v[226:229], v[186:189], v[94:97]
	v_mfma_f32_16x16x32_bf16 v[90:93], v[234:237], v[186:189], v[90:93]
	v_mfma_f32_16x16x32_bf16 v[86:89], v[226:229], v[194:197], v[86:89]
	v_mfma_f32_16x16x32_bf16 v[82:85], v[234:237], v[194:197], v[82:85]
	v_mfma_f32_16x16x32_bf16 v[78:81], v[226:229], v[202:205], v[78:81]
	v_mfma_f32_16x16x32_bf16 v[74:77], v[234:237], v[202:205], v[74:77]
	v_mfma_f32_16x16x32_bf16 v[70:73], v[226:229], v[210:213], v[70:73]
	v_mfma_f32_16x16x32_bf16 v[66:69], v[234:237], v[210:213], v[66:69]
	s_setprio 1
	v_readfirstlane_b32 s3, v149
	v_lshl_add_u64 v[242:243], v[222:223], 0, s[80:81]
	s_mov_b32 m0, s3
	v_readfirstlane_b32 s3, v153
	s_barrier
	ds_read_b128 v[182:185], v148 offset:16384
	ds_read_b128 v[186:189], v148 offset:17408
	ds_read_b128 v[190:193], v147 offset:16384
	ds_read_b128 v[194:197], v147 offset:17408
	ds_read_b128 v[198:201], v146 offset:16384
	ds_read_b128 v[202:205], v146 offset:17408
	ds_read_b128 v[206:209], v141 offset:16384
	ds_read_b128 v[210:213], v141 offset:17408
	global_load_lds_dwordx4 v[242:243], off
	v_lshl_add_u64 v[242:243], v[224:225], 0, s[80:81]
	s_mov_b32 m0, s3
	s_nop 0
	global_load_lds_dwordx4 v[242:243], off
	s_barrier
	s_waitcnt lgkmcnt(0)
	s_setprio 0
	s_waitcnt lgkmcnt(0)
	v_mfma_f32_16x16x32_bf16 v[60:63], v[142:145], v[182:185], v[60:63]
	v_mfma_f32_16x16x32_bf16 v[56:59], v[174:177], v[182:185], v[56:59]
	v_mfma_f32_16x16x32_bf16 v[52:55], v[142:145], v[190:193], v[52:55]
	v_mfma_f32_16x16x32_bf16 v[48:51], v[174:177], v[190:193], v[48:51]
	v_mfma_f32_16x16x32_bf16 v[44:47], v[142:145], v[198:201], v[44:47]
	v_mfma_f32_16x16x32_bf16 v[40:43], v[174:177], v[198:201], v[40:43]
	v_mfma_f32_16x16x32_bf16 v[36:39], v[142:145], v[206:209], v[36:39]
	v_mfma_f32_16x16x32_bf16 v[32:35], v[174:177], v[206:209], v[32:35]
	v_mfma_f32_16x16x32_bf16 v[60:63], v[170:173], v[186:189], v[60:63]
	v_mfma_f32_16x16x32_bf16 v[56:59], v[178:181], v[186:189], v[56:59]
	v_mfma_f32_16x16x32_bf16 v[52:55], v[170:173], v[194:197], v[52:55]
	v_mfma_f32_16x16x32_bf16 v[48:51], v[178:181], v[194:197], v[48:51]
	v_mfma_f32_16x16x32_bf16 v[44:47], v[170:173], v[202:205], v[44:47]
	v_mfma_f32_16x16x32_bf16 v[40:43], v[178:181], v[202:205], v[40:43]
	v_mfma_f32_16x16x32_bf16 v[36:39], v[170:173], v[210:213], v[36:39]
	v_mfma_f32_16x16x32_bf16 v[32:35], v[178:181], v[210:213], v[32:35]
	s_setprio 1
	s_barrier
; #define STAGE_A(b, h, kt) { const u16* ap_ = A + (size_t)((h) * ahalf + (unsigned)(kt) * 64u); glds16(ap_ + ao0, l0 + SA_(b, h)); glds16(ap_ + ao1, l0 + SA_(b, h) + 8192); }
; #define STAGE_B(b, h, kt) { const u16* bp_ = ((h) ? B1 : B0) + (unsigned)(kt) * 64u; glds16(bp_ + bo0, l0 + SB_(b, h)); glds16(bp_ + bo1, l0 + SB_(b, h) + 8192); }
; #define LDA(dst, b, h) _Pragma("unroll") for (int m = 0; m < 4; ++m) _Pragma("unroll") for (int k = 0; k < 2; ++k) \
;     dst[m][k] = *(const bf16x8*)(lds + SA_(b, h) + lds_byte(wr * 64 + m * 16 + fr, k * 32 + fq * 8));
; #define LDB(dst, b, h) _Pragma("unroll") for (int n = 0; n < 2; ++n) _Pragma("unroll") for (int k = 0; k < 2; ++k) \
;     dst[n][k] = *(const bf16x8*)(lds + SB_(b, h) + lds_byte(wc * 32 + n * 16 + fr, k * 32 + fq * 8));
; #define MMA(ai, bj, At_, Bt_) { __builtin_amdgcn_s_setprio(1); \
;     _Pragma("unroll") for (int m = 0; m < 4; ++m) _Pragma("unroll") for (int n = 0; n < 2; ++n) _Pragma("unroll") for (int k = 0; k < 2; ++k) \
;       acc[ai][bj][m][n] = MFMA16(Bt_[n][k], At_[m][k], acc[ai][bj][m][n]); \
;     __builtin_amdgcn_s_setprio(0); }
; #define WAIT_V(n) asm volatile("s_waitcnt vmcnt(" #n ")" ::: "memory");
; #define WAIT_L(n) asm volatile("s_waitcnt lgkmcnt(" #n ")" ::: "memory");
; #define BAR __builtin_amdgcn_s_barrier();
; #define SCHED __builtin_amdgcn_sched_barrier(0);
; DI void gemm256(const u16* __restrict__ A, int lda, const u16* __restrict__ B0, const u16* __restrict__ B1, int ldb, int nt, acc_t& acc, char* lds) {
;     ...
;     WAIT_V(6) BAR MMA(1, 1, At, Bq1) BAR
;     LDB(Bq0, 1, 0) SCHED LDA(At, 1, 0) STAGE_A(0, 1, t + 2)
;     WAIT_L(8) BAR WAIT_L(0) MMA(0, 0, At, Bq0) BAR SCHED
;     LDB(Bq1, 1, 1) STAGE_B(1, 0, t + 3)
;     BAR WAIT_L(0) MMA(0, 1, At, Bq1) BAR
;     LDA(At, 1, 1) STAGE_A(1, 0, t + 3)
;     BAR WAIT_L(0) MMA(1, 0, At, Bq0) BAR SCHED
;     STAGE_B(1, 1, t + 3)
	v_readfirstlane_b32 s3, v154
	v_lshl_add_u64 v[142:143], v[238:239], 0, s[28:29]
	s_mov_b32 m0, s3
	v_readfirstlane_b32 s3, v155
	global_load_lds_dwordx4 v[142:143], off
	v_lshl_add_u64 v[142:143], v[240:241], 0, s[28:29]
	s_mov_b32 m0, s3
	s_nop 0
	global_load_lds_dwordx4 v[142:143], off
	s_waitcnt vmcnt(6)
	s_barrier
	s_setprio 0
	v_mfma_f32_16x16x32_bf16 v[28:31], v[216:219], v[182:185], v[28:31]
	v_mfma_f32_16x16x32_bf16 v[24:27], v[230:233], v[182:185], v[24:27]
	v_mfma_f32_16x16x32_bf16 v[20:23], v[216:219], v[190:193], v[20:23]
	v_mfma_f32_16x16x32_bf16 v[16:19], v[230:233], v[190:193], v[16:19]
	v_mfma_f32_16x16x32_bf16 v[12:15], v[216:219], v[198:201], v[12:15]
	v_mfma_f32_16x16x32_bf16 v[8:11], v[230:233], v[198:201], v[8:11]
	v_mfma_f32_16x16x32_bf16 v[4:7], v[216:219], v[206:209], v[4:7]
	v_mfma_f32_16x16x32_bf16 v[0:3], v[230:233], v[206:209], v[0:3]
	v_mfma_f32_16x16x32_bf16 v[28:31], v[226:229], v[186:189], v[28:31]
	v_mfma_f32_16x16x32_bf16 v[24:27], v[234:237], v[186:189], v[24:27]
	v_mfma_f32_16x16x32_bf16 v[20:23], v[226:229], v[194:197], v[20:23]
	v_mfma_f32_16x16x32_bf16 v[16:19], v[234:237], v[194:197], v[16:19]
	v_mfma_f32_16x16x32_bf16 v[12:15], v[226:229], v[202:205], v[12:15]
	v_mfma_f32_16x16x32_bf16 v[8:11], v[234:237], v[202:205], v[8:11]
	v_mfma_f32_16x16x32_bf16 v[4:7], v[226:229], v[210:213], v[4:7]
	v_mfma_f32_16x16x32_bf16 v[0:3], v[234:237], v[210:213], v[0:3]
	s_setprio 1
	s_barrier
	ds_read_b128 v[142:145], v156
	ds_read_b128 v[170:173], v156 offset:1024
	ds_read_b128 v[174:177], v156 offset:2048
	ds_read_b128 v[178:181], v156 offset:3072
	v_readfirstlane_b32 s3, v157
	v_lshl_add_u64 v[216:217], v[222:223], 0, s[4:5]
	s_mov_b32 m0, s3
	v_readfirstlane_b32 s3, v158
	ds_read_b128 v[182:185], v148 offset:32768
	ds_read_b128 v[186:189], v148 offset:33792
	ds_read_b128 v[190:193], v147 offset:32768
	ds_read_b128 v[194:197], v147 offset:33792
	ds_read_b128 v[198:201], v146 offset:32768
	ds_read_b128 v[202:205], v146 offset:33792
	ds_read_b128 v[206:209], v141 offset:32768
	ds_read_b128 v[210:213], v141 offset:33792
	global_load_lds_dwordx4 v[216:217], off
	v_lshl_add_u64 v[216:217], v[224:225], 0, s[4:5]
	s_mov_b32 m0, s3
	s_nop 0
	global_load_lds_dwordx4 v[216:217], off
	s_waitcnt lgkmcnt(8)
	s_barrier
	s_waitcnt lgkmcnt(0)
	s_setprio 0
	s_waitcnt lgkmcnt(0)
	v_mfma_f32_16x16x32_bf16 v[126:129], v[142:145], v[182:185], v[126:129]
	v_mfma_f32_16x16x32_bf16 v[122:125], v[174:177], v[182:185], v[122:125]
	v_mfma_f32_16x16x32_bf16 v[118:121], v[142:145], v[190:193], v[118:121]
	v_mfma_f32_16x16x32_bf16 v[114:117], v[174:177], v[190:193], v[114:117]
	v_mfma_f32_16x16x32_bf16 v[110:113], v[142:145], v[198:201], v[110:113]
	v_mfma_f32_16x16x32_bf16 v[106:109], v[174:177], v[198:201], v[106:109]
	v_mfma_f32_16x16x32_bf16 v[102:105], v[142:145], v[206:209], v[102:105]
	v_mfma_f32_16x16x32_bf16 v[98:101], v[174:177], v[206:209], v[98:101]
	v_mfma_f32_16x16x32_bf16 v[126:129], v[170:173], v[186:189], v[126:129]
	v_mfma_f32_16x16x32_bf16 v[122:125], v[178:181], v[186:189], v[122:125]
	v_mfma_f32_16x16x32_bf16 v[118:121], v[170:173], v[194:197], v[118:121]
	v_mfma_f32_16x16x32_bf16 v[114:117], v[178:181], v[194:197], v[114:117]
	v_mfma_f32_16x16x32_bf16 v[110:113], v[170:173], v[202:205], v[110:113]
	v_mfma_f32_16x16x32_bf16 v[106:109], v[178:181], v[202:205], v[106:109]
	v_mfma_f32_16x16x32_bf16 v[102:105], v[170:173], v[210:213], v[102:105]
	v_mfma_f32_16x16x32_bf16 v[98:101], v[178:181], v[210:213], v[98:101]
	s_setprio 1
	s_barrier
	v_readfirstlane_b32 s3, v159
	v_lshl_add_u64 v[242:243], v[238:239], 0, s[64:65]
	s_mov_b32 m0, s3
	v_readfirstlane_b32 s3, v160
	ds_read_b128 v[216:219], v151
	ds_read_b128 v[226:229], v151 offset:1024
	ds_read_b128 v[230:233], v151 offset:2048
	ds_read_b128 v[234:237], v151 offset:3072
	global_load_lds_dwordx4 v[242:243], off
	v_lshl_add_u64 v[242:243], v[240:241], 0, s[64:65]
	s_mov_b32 m0, s3
	s_nop 0
	global_load_lds_dwordx4 v[242:243], off
	s_barrier
	s_waitcnt lgkmcnt(0)
	s_setprio 0
	s_waitcnt lgkmcnt(0)
	v_mfma_f32_16x16x32_bf16 v[94:97], v[216:219], v[182:185], v[94:97]
	v_mfma_f32_16x16x32_bf16 v[90:93], v[230:233], v[182:185], v[90:93]
	v_mfma_f32_16x16x32_bf16 v[86:89], v[216:219], v[190:193], v[86:89]
	v_mfma_f32_16x16x32_bf16 v[82:85], v[230:233], v[190:193], v[82:85]
	v_mfma_f32_16x16x32_bf16 v[78:81], v[216:219], v[198:201], v[78:81]
	v_mfma_f32_16x16x32_bf16 v[74:77], v[230:233], v[198:201], v[74:77]
	v_mfma_f32_16x16x32_bf16 v[70:73], v[216:219], v[206:209], v[70:73]
	v_mfma_f32_16x16x32_bf16 v[66:69], v[230:233], v[206:209], v[66:69]
	v_mfma_f32_16x16x32_bf16 v[94:97], v[226:229], v[186:189], v[94:97]
	v_mfma_f32_16x16x32_bf16 v[90:93], v[234:237], v[186:189], v[90:93]
	v_mfma_f32_16x16x32_bf16 v[86:89], v[226:229], v[194:197], v[86:89]
	v_mfma_f32_16x16x32_bf16 v[82:85], v[234:237], v[194:197], v[82:85]
	v_mfma_f32_16x16x32_bf16 v[78:81], v[226:229], v[202:205], v[78:81]
	v_mfma_f32_16x16x32_bf16 v[74:77], v[234:237], v[202:205], v[74:77]
	v_mfma_f32_16x16x32_bf16 v[70:73], v[226:229], v[210:213], v[70:73]
	v_mfma_f32_16x16x32_bf16 v[66:69], v[234:237], v[210:213], v[66:69]
	s_setprio 1
	v_readfirstlane_b32 s3, v161
	v_lshl_add_u64 v[222:223], v[222:223], 0, s[30:31]
	s_mov_b32 m0, s3
	v_readfirstlane_b32 s3, v162
	s_barrier
	ds_read_b128 v[182:185], v148 offset:49152
	ds_read_b128 v[186:189], v148 offset:50176
	ds_read_b128 v[190:193], v147 offset:49152
	ds_read_b128 v[194:197], v147 offset:50176
	ds_read_b128 v[198:201], v146 offset:49152
	ds_read_b128 v[202:205], v146 offset:50176
	ds_read_b128 v[206:209], v141 offset:49152
	ds_read_b128 v[210:213], v141 offset:50176
	global_load_lds_dwordx4 v[222:223], off
	v_lshl_add_u64 v[222:223], v[224:225], 0, s[30:31]
	s_mov_b32 m0, s3
	s_nop 0
	global_load_lds_dwordx4 v[222:223], off
	s_barrier
; #define STAGE_A(b, h, kt) { const u16* ap_ = A + (size_t)((h) * ahalf + (unsigned)(kt) * 64u); glds16(ap_ + ao0, l0 + SA_(b, h)); glds16(ap_ + ao1, l0 + SA_(b, h) + 8192); }
; #define STAGE_B(b, h, kt) { const u16* bp_ = ((h) ? B1 : B0) + (unsigned)(kt) * 64u; glds16(bp_ + bo0, l0 + SB_(b, h)); glds16(bp_ + bo1, l0 + SB_(b, h) + 8192); }
; #define LDA(dst, b, h) _Pragma("unroll") for (int m = 0; m < 4; ++m) _Pragma("unroll") for (int k = 0; k < 2; ++k) \
;     dst[m][k] = *(const bf16x8*)(lds + SA_(b, h) + lds_byte(wr * 64 + m * 16 + fr, k * 32 + fq * 8));
; #define LDB(dst, b, h) _Pragma("unroll") for (int n = 0; n < 2; ++n) _Pragma("unroll") for (int k = 0; k < 2; ++k) \
;     dst[n][k] = *(const bf16x8*)(lds + SB_(b, h) + lds_byte(wc * 32 + n * 16 + fr, k * 32 + fq * 8));
; #define MMA(ai, bj, At_, Bt_) { __builtin_amdgcn_s_setprio(1); \
;     _Pragma("unroll") for (int m = 0; m < 4; ++m) _Pragma("unroll") for (int n = 0; n < 2; ++n) _Pragma("unroll") for (int k = 0; k < 2; ++k) \
;       acc[ai][bj][m][n] = MFMA16(Bt_[n][k], At_[m][k], acc[ai][bj][m][n]); \
;     __builtin_amdgcn_s_setprio(0); }
; #define WAIT_V(n) asm volatile("s_waitcnt vmcnt(" #n ")" ::: "memory");
; #define WAIT_L(n) asm volatile("s_waitcnt lgkmcnt(" #n ")" ::: "memory");
; #define BAR __builtin_amdgcn_s_barrier();
; #define SCHED __builtin_amdgcn_sched_barrier(0);
; DI void gemm256(const u16* __restrict__ A, int lda, const u16* __restrict__ B0, const u16* __restrict__ B1, int ldb, int nt, acc_t& acc, char* lds) {
;     ...
;     BAR WAIT_L(0) MMA(1, 0, At, Bq0) BAR SCHED
;     STAGE_B(1, 1, t + 3)
;     WAIT_V(6) BAR MMA(1, 1, At, Bq1) BAR
;   }
;   { LDB(Bq0, 0, 0) LDA(At, 0, 0) STAGE_A(1, 1, nt - 1)
;     BAR WAIT_L(0) MMA(0, 0, At, Bq0) BAR
;     LDB(Bq1, 0, 1) BAR WAIT_L(0) MMA(0, 1, At, Bq1) BAR
;     LDA(At, 0, 1) WAIT_V(4) BAR WAIT_L(0) MMA(1, 0, At, Bq0) MMA(1, 1, At, Bq1) BAR }
;   { LDB(Bq0, 1, 0) LDA(At, 1, 0) WAIT_V(2) BAR WAIT_L(0) MMA(0, 0, At, Bq0) BAR
	s_waitcnt lgkmcnt(0)
	s_setprio 0
	s_waitcnt lgkmcnt(0)
	v_mfma_f32_16x16x32_bf16 v[60:63], v[142:145], v[182:185], v[60:63]
	v_mfma_f32_16x16x32_bf16 v[56:59], v[174:177], v[182:185], v[56:59]
	v_mfma_f32_16x16x32_bf16 v[52:55], v[142:145], v[190:193], v[52:55]
	v_mfma_f32_16x16x32_bf16 v[48:51], v[174:177], v[190:193], v[48:51]
	v_mfma_f32_16x16x32_bf16 v[44:47], v[142:145], v[198:201], v[44:47]
	v_mfma_f32_16x16x32_bf16 v[40:43], v[174:177], v[198:201], v[40:43]
	v_mfma_f32_16x16x32_bf16 v[36:39], v[142:145], v[206:209], v[36:39]
	v_mfma_f32_16x16x32_bf16 v[32:35], v[174:177], v[206:209], v[32:35]
	v_mfma_f32_16x16x32_bf16 v[60:63], v[170:173], v[186:189], v[60:63]
	v_mfma_f32_16x16x32_bf16 v[56:59], v[178:181], v[186:189], v[56:59]
	v_mfma_f32_16x16x32_bf16 v[52:55], v[170:173], v[194:197], v[52:55]
	v_mfma_f32_16x16x32_bf16 v[48:51], v[178:181], v[194:197], v[48:51]
	v_mfma_f32_16x16x32_bf16 v[44:47], v[170:173], v[202:205], v[44:47]
	v_mfma_f32_16x16x32_bf16 v[40:43], v[178:181], v[202:205], v[40:43]
	v_mfma_f32_16x16x32_bf16 v[36:39], v[170:173], v[210:213], v[36:39]
	v_mfma_f32_16x16x32_bf16 v[32:35], v[178:181], v[210:213], v[32:35]
	s_setprio 1
	s_barrier
	v_readfirstlane_b32 s3, v163
	v_lshl_add_u64 v[142:143], v[238:239], 0, s[66:67]
	s_mov_b32 m0, s3
	v_readfirstlane_b32 s3, v164
	global_load_lds_dwordx4 v[142:143], off
	v_lshl_add_u64 v[142:143], v[240:241], 0, s[66:67]
	s_mov_b32 m0, s3
	s_nop 0
	global_load_lds_dwordx4 v[142:143], off
	s_waitcnt vmcnt(6)
	s_barrier
	s_setprio 0
	v_mfma_f32_16x16x32_bf16 v[28:31], v[216:219], v[182:185], v[28:31]
	v_mfma_f32_16x16x32_bf16 v[24:27], v[230:233], v[182:185], v[24:27]
	v_mfma_f32_16x16x32_bf16 v[20:23], v[216:219], v[190:193], v[20:23]
	v_mfma_f32_16x16x32_bf16 v[16:19], v[230:233], v[190:193], v[16:19]
	v_mfma_f32_16x16x32_bf16 v[12:15], v[216:219], v[198:201], v[12:15]
	v_mfma_f32_16x16x32_bf16 v[8:11], v[230:233], v[198:201], v[8:11]
	v_mfma_f32_16x16x32_bf16 v[4:7], v[216:219], v[206:209], v[4:7]
	v_mfma_f32_16x16x32_bf16 v[0:3], v[230:233], v[206:209], v[0:3]
	v_mfma_f32_16x16x32_bf16 v[28:31], v[226:229], v[186:189], v[28:31]
	v_mfma_f32_16x16x32_bf16 v[24:27], v[234:237], v[186:189], v[24:27]
	v_mfma_f32_16x16x32_bf16 v[20:23], v[226:229], v[194:197], v[20:23]
	v_mfma_f32_16x16x32_bf16 v[16:19], v[234:237], v[194:197], v[16:19]
	v_mfma_f32_16x16x32_bf16 v[12:15], v[226:229], v[202:205], v[12:15]
	v_mfma_f32_16x16x32_bf16 v[8:11], v[234:237], v[202:205], v[8:11]
	v_mfma_f32_16x16x32_bf16 v[4:7], v[226:229], v[210:213], v[4:7]
	v_mfma_f32_16x16x32_bf16 v[0:3], v[234:237], v[210:213], v[0:3]
	s_setprio 1
	s_add_i32 s2, s2, 2
	s_add_u32 s8, s8, 0x100
	s_addc_u32 s9, s9, 0
	s_cmp_lt_u32 s2, 4
	s_barrier
	s_cbranch_scc1 .LBB0_979
	s_add_u32 s2, s44, 0x40380
	s_addc_u32 s3, s45, 0
	v_readfirstlane_b32 s7, v167
	v_lshl_add_u64 v[162:163], v[64:65], 1, s[2:3]
	s_mov_b32 m0, s7
	v_lshl_add_u64 v[130:131], v[130:131], 1, s[2:3]
	v_readfirstlane_b32 s2, v168
	ds_read_b128 v[132:135], v166
	ds_read_b128 v[136:139], v166 offset:1024
	ds_read_b128 v[142:145], v166 offset:2048
	ds_read_b128 v[152:155], v166 offset:3072
	ds_read_b128 v[158:161], v148
	ds_read_b128 v[170:173], v148 offset:1024
	ds_read_b128 v[174:177], v147
	ds_read_b128 v[178:181], v147 offset:1024
	ds_read_b128 v[182:185], v146
	ds_read_b128 v[186:189], v146 offset:1024
	ds_read_b128 v[190:193], v141
	ds_read_b128 v[194:197], v141 offset:1024
	global_load_lds_dwordx4 v[162:163], off
	s_mov_b32 m0, s2
	s_nop 0
	global_load_lds_dwordx4 v[130:131], off
	s_barrier
	s_waitcnt lgkmcnt(0)
	s_setprio 0
	s_waitcnt lgkmcnt(0)
	v_mfma_f32_16x16x32_bf16 v[126:129], v[132:135], v[158:161], v[126:129]
	v_mfma_f32_16x16x32_bf16 v[122:125], v[142:145], v[158:161], v[122:125]
	v_mfma_f32_16x16x32_bf16 v[118:121], v[132:135], v[174:177], v[118:121]
	v_mfma_f32_16x16x32_bf16 v[114:117], v[142:145], v[174:177], v[114:117]
	v_mfma_f32_16x16x32_bf16 v[106:109], v[142:145], v[182:185], v[106:109]
	v_mfma_f32_16x16x32_bf16 v[98:101], v[142:145], v[190:193], v[98:101]
	v_mfma_f32_16x16x32_bf16 v[126:129], v[136:139], v[170:173], v[126:129]
	v_mfma_f32_16x16x32_bf16 v[122:125], v[152:155], v[170:173], v[122:125]
	v_mfma_f32_16x16x32_bf16 v[118:121], v[136:139], v[178:181], v[118:121]
	v_mfma_f32_16x16x32_bf16 v[114:117], v[152:155], v[178:181], v[114:117]
	v_mfma_f32_16x16x32_bf16 v[110:113], v[132:135], v[182:185], v[110:113]
	v_mfma_f32_16x16x32_bf16 v[106:109], v[152:155], v[186:189], v[106:109]
	v_mfma_f32_16x16x32_bf16 v[102:105], v[132:135], v[190:193], v[102:105]
	v_mfma_f32_16x16x32_bf16 v[98:101], v[152:155], v[194:197], v[98:101]
	v_mfma_f32_16x16x32_bf16 v[166:169], v[136:139], v[186:189], v[110:113]
	v_mfma_f32_16x16x32_bf16 v[198:201], v[136:139], v[194:197], v[102:105]
	s_setprio 1
	s_barrier
	s_nop 2
	ds_read_b128 v[102:105], v165
	ds_read_b128 v[110:113], v165 offset:1024
	ds_read_b128 v[202:205], v165 offset:2048
	ds_read_b128 v[162:165], v165 offset:3072
	s_barrier
	s_waitcnt lgkmcnt(0)
	s_setprio 0
	s_waitcnt lgkmcnt(0)
	v_mfma_f32_16x16x32_bf16 v[90:93], v[202:205], v[158:161], v[90:93]
	v_mfma_f32_16x16x32_bf16 v[82:85], v[202:205], v[174:177], v[82:85]
	v_mfma_f32_16x16x32_bf16 v[74:77], v[202:205], v[182:185], v[74:77]
	v_mfma_f32_16x16x32_bf16 v[66:69], v[202:205], v[190:193], v[66:69]
	v_mfma_f32_16x16x32_bf16 v[94:97], v[102:105], v[158:161], v[94:97]
	v_mfma_f32_16x16x32_bf16 v[90:93], v[162:165], v[170:173], v[90:93]
	v_mfma_f32_16x16x32_bf16 v[86:89], v[102:105], v[174:177], v[86:89]
	v_mfma_f32_16x16x32_bf16 v[82:85], v[162:165], v[178:181], v[82:85]
	v_mfma_f32_16x16x32_bf16 v[78:81], v[102:105], v[182:185], v[78:81]
	v_mfma_f32_16x16x32_bf16 v[74:77], v[162:165], v[186:189], v[74:77]
	v_mfma_f32_16x16x32_bf16 v[70:73], v[102:105], v[190:193], v[70:73]
	v_mfma_f32_16x16x32_bf16 v[66:69], v[162:165], v[194:197], v[66:69]
	v_mfma_f32_16x16x32_bf16 v[206:209], v[110:113], v[170:173], v[94:97]
	v_mfma_f32_16x16x32_bf16 v[158:161], v[110:113], v[178:181], v[86:89]
	v_mfma_f32_16x16x32_bf16 v[170:173], v[110:113], v[186:189], v[78:81]
	v_mfma_f32_16x16x32_bf16 v[174:177], v[110:113], v[194:197], v[70:73]
	s_setprio 1
	s_barrier
; #define LDA(dst, b, h) _Pragma("unroll") for (int m = 0; m < 4; ++m) _Pragma("unroll") for (int k = 0; k < 2; ++k) \
;     dst[m][k] = *(const bf16x8*)(lds + SA_(b, h) + lds_byte(wr * 64 + m * 16 + fr, k * 32 + fq * 8));
; #define LDB(dst, b, h) _Pragma("unroll") for (int n = 0; n < 2; ++n) _Pragma("unroll") for (int k = 0; k < 2; ++k) \
;     dst[n][k] = *(const bf16x8*)(lds + SB_(b, h) + lds_byte(wc * 32 + n * 16 + fr, k * 32 + fq * 8));
; #define MMA(ai, bj, At_, Bt_) { __builtin_amdgcn_s_setprio(1); \
;     _Pragma("unroll") for (int m = 0; m < 4; ++m) _Pragma("unroll") for (int n = 0; n < 2; ++n) _Pragma("unroll") for (int k = 0; k < 2; ++k) \
;       acc[ai][bj][m][n] = MFMA16(Bt_[n][k], At_[m][k], acc[ai][bj][m][n]); \
;     __builtin_amdgcn_s_setprio(0); }
; #define WAIT_V(n) asm volatile("s_waitcnt vmcnt(" #n ")" ::: "memory");
; #define WAIT_L(n) asm volatile("s_waitcnt lgkmcnt(" #n ")" ::: "memory");
; #define BAR __builtin_amdgcn_s_barrier();
; DI void gemm256(const u16* __restrict__ A, int lda, const u16* __restrict__ B0, const u16* __restrict__ B1, int ldb, int nt, acc_t& acc, char* lds) {
;     ...
;     LDA(At, 0, 1) WAIT_V(4) BAR WAIT_L(0) MMA(1, 0, At, Bq0) MMA(1, 1, At, Bq1) BAR }
;   { LDB(Bq0, 1, 0) LDA(At, 1, 0) WAIT_V(2) BAR WAIT_L(0) MMA(0, 0, At, Bq0) BAR
	s_nop 0
	ds_read_b128 v[70:73], v148 offset:16384
	ds_read_b128 v[78:81], v148 offset:17408
	ds_read_b128 v[86:89], v147 offset:16384
	ds_read_b128 v[94:97], v147 offset:17408
	ds_read_b128 v[178:181], v146 offset:16384
	ds_read_b128 v[182:185], v146 offset:17408
	ds_read_b128 v[186:189], v141 offset:16384
	ds_read_b128 v[190:193], v141 offset:17408
	s_waitcnt vmcnt(4)
	s_barrier
	s_waitcnt lgkmcnt(0)
	s_setprio 0
	s_waitcnt lgkmcnt(0)
	v_mfma_f32_16x16x32_bf16 v[60:63], v[132:135], v[70:73], v[60:63]
	v_mfma_f32_16x16x32_bf16 v[56:59], v[142:145], v[70:73], v[56:59]
	v_mfma_f32_16x16x32_bf16 v[52:55], v[132:135], v[86:89], v[52:55]
	v_mfma_f32_16x16x32_bf16 v[48:51], v[142:145], v[86:89], v[48:51]
	v_mfma_f32_16x16x32_bf16 v[36:39], v[132:135], v[186:189], v[36:39]
	v_mfma_f32_16x16x32_bf16 v[32:35], v[142:145], v[186:189], v[32:35]
	v_mfma_f32_16x16x32_bf16 v[60:63], v[136:139], v[78:81], v[60:63]
	v_mfma_f32_16x16x32_bf16 v[56:59], v[152:155], v[78:81], v[56:59]
	v_mfma_f32_16x16x32_bf16 v[52:55], v[136:139], v[94:97], v[52:55]
	v_mfma_f32_16x16x32_bf16 v[48:51], v[152:155], v[94:97], v[48:51]
	v_mfma_f32_16x16x32_bf16 v[44:47], v[132:135], v[178:181], v[44:47]
	v_mfma_f32_16x16x32_bf16 v[40:43], v[142:145], v[178:181], v[40:43]
	v_mfma_f32_16x16x32_bf16 v[36:39], v[136:139], v[190:193], v[36:39]
	v_mfma_f32_16x16x32_bf16 v[32:35], v[152:155], v[190:193], v[32:35]
	v_mfma_f32_16x16x32_bf16 v[194:197], v[136:139], v[182:185], v[44:47]
	v_mfma_f32_16x16x32_bf16 v[210:213], v[152:155], v[182:185], v[40:43]
	s_setprio 1
	s_setprio 0
	v_mfma_f32_16x16x32_bf16 v[20:23], v[102:105], v[86:89], v[20:23]
	v_mfma_f32_16x16x32_bf16 v[16:19], v[202:205], v[86:89], v[16:19]
	v_mfma_f32_16x16x32_bf16 v[4:7], v[102:105], v[186:189], v[4:7]
	v_mfma_f32_16x16x32_bf16 v[0:3], v[202:205], v[186:189], v[0:3]
	v_mfma_f32_16x16x32_bf16 v[28:31], v[102:105], v[70:73], v[28:31]
	v_mfma_f32_16x16x32_bf16 v[24:27], v[202:205], v[70:73], v[24:27]
	v_mfma_f32_16x16x32_bf16 v[20:23], v[110:113], v[94:97], v[20:23]
	v_mfma_f32_16x16x32_bf16 v[16:19], v[162:165], v[94:97], v[16:19]
	v_mfma_f32_16x16x32_bf16 v[12:15], v[102:105], v[178:181], v[12:15]
	v_mfma_f32_16x16x32_bf16 v[8:11], v[202:205], v[178:181], v[8:11]
	v_mfma_f32_16x16x32_bf16 v[4:7], v[110:113], v[190:193], v[4:7]
	v_mfma_f32_16x16x32_bf16 v[0:3], v[162:165], v[190:193], v[0:3]
	v_mfma_f32_16x16x32_bf16 v[130:133], v[110:113], v[78:81], v[28:31]
	v_mfma_f32_16x16x32_bf16 v[134:137], v[162:165], v[78:81], v[24:27]
	v_mfma_f32_16x16x32_bf16 v[142:145], v[110:113], v[182:185], v[12:15]
	v_mfma_f32_16x16x32_bf16 v[152:155], v[162:165], v[182:185], v[8:11]
	s_setprio 1
	s_barrier
	s_nop 0
	ds_read_b128 v[8:11], v156
	ds_read_b128 v[12:15], v156 offset:1024
	ds_read_b128 v[162:165], v156 offset:2048
	ds_read_b128 v[178:181], v156 offset:3072
	ds_read_b128 v[24:27], v148 offset:32768
	ds_read_b128 v[28:31], v148 offset:33792
	ds_read_b128 v[40:43], v147 offset:32768
	ds_read_b128 v[44:47], v147 offset:33792
	ds_read_b128 v[182:185], v146 offset:32768
	ds_read_b128 v[186:189], v146 offset:33792
	ds_read_b128 v[190:193], v141 offset:32768
	ds_read_b128 v[202:205], v141 offset:33792
	s_waitcnt vmcnt(2)
	s_barrier
	s_waitcnt lgkmcnt(0)
	s_setprio 0
	s_waitcnt lgkmcnt(0)
	v_mfma_f32_16x16x32_bf16 v[70:73], v[8:11], v[24:27], v[126:129]
	v_mfma_f32_16x16x32_bf16 v[126:129], v[12:15], v[28:31], v[70:73]
	v_mfma_f32_16x16x32_bf16 v[70:73], v[162:165], v[24:27], v[122:125]
	v_mfma_f32_16x16x32_bf16 v[122:125], v[178:181], v[28:31], v[70:73]
	v_mfma_f32_16x16x32_bf16 v[70:73], v[8:11], v[40:43], v[118:121]
	v_mfma_f32_16x16x32_bf16 v[110:113], v[12:15], v[44:47], v[70:73]
	v_mfma_f32_16x16x32_bf16 v[70:73], v[162:165], v[40:43], v[114:117]
	v_mfma_f32_16x16x32_bf16 v[102:105], v[178:181], v[44:47], v[70:73]
	v_mfma_f32_16x16x32_bf16 v[70:73], v[8:11], v[182:185], v[166:169]
	v_mfma_f32_16x16x32_bf16 v[94:97], v[12:15], v[186:189], v[70:73]
	v_mfma_f32_16x16x32_bf16 v[70:73], v[162:165], v[182:185], v[106:109]
	v_mfma_f32_16x16x32_bf16 v[86:89], v[178:181], v[186:189], v[70:73]
	v_mfma_f32_16x16x32_bf16 v[70:73], v[8:11], v[190:193], v[198:201]
	v_mfma_f32_16x16x32_bf16 v[78:81], v[12:15], v[202:205], v[70:73]
	v_mfma_f32_16x16x32_bf16 v[70:73], v[162:165], v[190:193], v[98:101]
	v_mfma_f32_16x16x32_bf16 v[70:73], v[178:181], v[202:205], v[70:73]
	s_setprio 1
	s_barrier
; #define LDA(dst, b, h) _Pragma("unroll") for (int m = 0; m < 4; ++m) _Pragma("unroll") for (int k = 0; k < 2; ++k) \
;     dst[m][k] = *(const bf16x8*)(lds + SA_(b, h) + lds_byte(wr * 64 + m * 16 + fr, k * 32 + fq * 8));
; #define LDB(dst, b, h) _Pragma("unroll") for (int n = 0; n < 2; ++n) _Pragma("unroll") for (int k = 0; k < 2; ++k) \
;     dst[n][k] = *(const bf16x8*)(lds + SB_(b, h) + lds_byte(wc * 32 + n * 16 + fr, k * 32 + fq * 8));
; #define MMA(ai, bj, At_, Bt_) { __builtin_amdgcn_s_setprio(1); \
;     _Pragma("unroll") for (int m = 0; m < 4; ++m) _Pragma("unroll") for (int n = 0; n < 2; ++n) _Pragma("unroll") for (int k = 0; k < 2; ++k) \
;       acc[ai][bj][m][n] = MFMA16(Bt_[n][k], At_[m][k], acc[ai][bj][m][n]); \
;     __builtin_amdgcn_s_setprio(0); }
; #define WAIT_V(n) asm volatile("s_waitcnt vmcnt(" #n ")" ::: "memory");
; #define WAIT_L(n) asm volatile("s_waitcnt lgkmcnt(" #n ")" ::: "memory");
; #define BAR __builtin_amdgcn_s_barrier();
; DI void gemm256(const u16* __restrict__ A, int lda, const u16* __restrict__ B0, const u16* __restrict__ B1, int ldb, int nt, acc_t& acc, char* lds) {
;     ...
;     LDB(Bq1, 1, 1) WAIT_V(0) BAR WAIT_L(0) MMA(0, 1, At, Bq1) BAR
;     LDA(At, 1, 1) BAR WAIT_L(0) MMA(1, 0, At, Bq0) MMA(1, 1, At, Bq1) BAR }
;   if (wr == 0) BAR
;   __syncthreads();
	ds_read_b128 v[166:169], v151
	ds_read_b128 v[198:201], v151 offset:1024
	ds_read_b128 v[216:219], v151 offset:2048
	ds_read_b128 v[226:229], v151 offset:3072
	s_waitcnt vmcnt(0)
	s_barrier
	s_waitcnt lgkmcnt(0)
	s_setprio 0
	s_waitcnt lgkmcnt(0)
	v_mfma_f32_16x16x32_bf16 v[98:101], v[166:169], v[24:27], v[206:209]
	v_mfma_f32_16x16x32_bf16 v[24:27], v[216:219], v[24:27], v[90:93]
	v_mfma_f32_16x16x32_bf16 v[114:117], v[226:229], v[28:31], v[24:27]
	v_mfma_f32_16x16x32_bf16 v[24:27], v[166:169], v[40:43], v[158:161]
	v_mfma_f32_16x16x32_bf16 v[106:109], v[198:201], v[44:47], v[24:27]
	v_mfma_f32_16x16x32_bf16 v[24:27], v[216:219], v[40:43], v[82:85]
	v_mfma_f32_16x16x32_bf16 v[118:121], v[198:201], v[28:31], v[98:101]
	v_mfma_f32_16x16x32_bf16 v[98:101], v[226:229], v[44:47], v[24:27]
	v_mfma_f32_16x16x32_bf16 v[24:27], v[166:169], v[182:185], v[170:173]
	v_mfma_f32_16x16x32_bf16 v[90:93], v[198:201], v[186:189], v[24:27]
	v_mfma_f32_16x16x32_bf16 v[24:27], v[216:219], v[182:185], v[74:77]
	v_mfma_f32_16x16x32_bf16 v[82:85], v[226:229], v[186:189], v[24:27]
	v_mfma_f32_16x16x32_bf16 v[24:27], v[166:169], v[190:193], v[174:177]
	v_mfma_f32_16x16x32_bf16 v[74:77], v[198:201], v[202:205], v[24:27]
	v_mfma_f32_16x16x32_bf16 v[24:27], v[216:219], v[190:193], v[66:69]
	v_mfma_f32_16x16x32_bf16 v[66:69], v[226:229], v[202:205], v[24:27]
	s_setprio 1
	s_barrier
	ds_read_b128 v[156:159], v148 offset:49152
	ds_read_b128 v[148:151], v148 offset:50176
	ds_read_b128 v[170:173], v147 offset:49152
	ds_read_b128 v[174:177], v147 offset:50176
	ds_read_b128 v[182:185], v146 offset:49152
	ds_read_b128 v[186:189], v146 offset:50176
	ds_read_b128 v[190:193], v141 offset:49152
	ds_read_b128 v[202:205], v141 offset:50176
	s_barrier
	s_waitcnt lgkmcnt(0)
	s_setprio 0
	s_waitcnt lgkmcnt(0)
	v_mfma_f32_16x16x32_bf16 v[24:27], v[8:11], v[156:159], v[60:63]
	v_mfma_f32_16x16x32_bf16 v[60:63], v[12:15], v[148:151], v[24:27]
	v_mfma_f32_16x16x32_bf16 v[24:27], v[162:165], v[156:159], v[56:59]
	v_mfma_f32_16x16x32_bf16 v[56:59], v[178:181], v[148:151], v[24:27]
	v_mfma_f32_16x16x32_bf16 v[24:27], v[8:11], v[170:173], v[52:55]
	v_mfma_f32_16x16x32_bf16 v[44:47], v[12:15], v[174:177], v[24:27]
	v_mfma_f32_16x16x32_bf16 v[24:27], v[162:165], v[170:173], v[48:51]
	v_mfma_f32_16x16x32_bf16 v[40:43], v[178:181], v[174:177], v[24:27]
	v_mfma_f32_16x16x32_bf16 v[24:27], v[8:11], v[182:185], v[194:197]
	v_mfma_f32_16x16x32_bf16 v[8:11], v[8:11], v[190:193], v[36:39]
	v_mfma_f32_16x16x32_bf16 v[28:31], v[12:15], v[186:189], v[24:27]
	v_mfma_f32_16x16x32_bf16 v[24:27], v[162:165], v[182:185], v[210:213]
	v_mfma_f32_16x16x32_bf16 v[12:15], v[12:15], v[202:205], v[8:11]
	v_mfma_f32_16x16x32_bf16 v[8:11], v[162:165], v[190:193], v[32:35]
	v_mfma_f32_16x16x32_bf16 v[24:27], v[178:181], v[186:189], v[24:27]
	v_mfma_f32_16x16x32_bf16 v[8:11], v[178:181], v[202:205], v[8:11]
	s_setprio 1
	s_setprio 0
	v_mfma_f32_16x16x32_bf16 v[32:35], v[166:169], v[156:159], v[130:133]
	v_mfma_f32_16x16x32_bf16 v[52:55], v[198:201], v[148:151], v[32:35]
	v_mfma_f32_16x16x32_bf16 v[32:35], v[216:219], v[156:159], v[134:137]
	v_mfma_f32_16x16x32_bf16 v[16:19], v[216:219], v[170:173], v[16:19]
	v_mfma_f32_16x16x32_bf16 v[48:51], v[226:229], v[148:151], v[32:35]
	v_mfma_f32_16x16x32_bf16 v[20:23], v[166:169], v[170:173], v[20:23]
	v_mfma_f32_16x16x32_bf16 v[32:35], v[226:229], v[174:177], v[16:19]
	v_mfma_f32_16x16x32_bf16 v[16:19], v[166:169], v[182:185], v[142:145]
	v_mfma_f32_16x16x32_bf16 v[36:39], v[198:201], v[174:177], v[20:23]
	v_mfma_f32_16x16x32_bf16 v[20:23], v[198:201], v[186:189], v[16:19]
	v_mfma_f32_16x16x32_bf16 v[16:19], v[216:219], v[182:185], v[152:155]
	v_mfma_f32_16x16x32_bf16 v[4:7], v[166:169], v[190:193], v[4:7]
	v_mfma_f32_16x16x32_bf16 v[0:3], v[216:219], v[190:193], v[0:3]
	v_mfma_f32_16x16x32_bf16 v[16:19], v[226:229], v[186:189], v[16:19]
	v_mfma_f32_16x16x32_bf16 v[4:7], v[198:201], v[202:205], v[4:7]
	v_mfma_f32_16x16x32_bf16 v[0:3], v[226:229], v[202:205], v[0:3]
	s_setprio 1
	s_movk_i32 s2, 0x100
	v_cmp_gt_u32_e32 vcc, s2, v140
	s_barrier
	s_and_saveexec_b64 s[8:9], vcc
	s_cbranch_execz .LBB0_982
	s_barrier

; #define STAGE_A(b, h, kt) { const u16* ap_ = A + (size_t)((h) * ahalf + (unsigned)(kt) * 64u); glds16(ap_ + ao0, l0 + SA_(b, h)); glds16(ap_ + ao1, l0 + SA_(b, h) + 8192); }
; #define STAGE_B(b, h, kt) { const u16* bp_ = ((h) ? B1 : B0) + (unsigned)(kt) * 64u; glds16(bp_ + bo0, l0 + SB_(b, h)); glds16(bp_ + bo1, l0 + SB_(b, h) + 8192); }
; #define LDA(dst, b, h) _Pragma("unroll") for (int m = 0; m < 4; ++m) _Pragma("unroll") for (int k = 0; k < 2; ++k) \
;     dst[m][k] = *(const bf16x8*)(lds + SA_(b, h) + lds_byte(wr * 64 + m * 16 + fr, k * 32 + fq * 8));
; #define LDB(dst, b, h) _Pragma("unroll") for (int n = 0; n < 2; ++n) _Pragma("unroll") for (int k = 0; k < 2; ++k) \
;     dst[n][k] = *(const bf16x8*)(lds + SB_(b, h) + lds_byte(wc * 32 + n * 16 + fr, k * 32 + fq * 8));
; #define MMA(ai, bj, At_, Bt_) { __builtin_amdgcn_s_setprio(1); \
;     _Pragma("unroll") for (int m = 0; m < 4; ++m) _Pragma("unroll") for (int n = 0; n < 2; ++n) _Pragma("unroll") for (int k = 0; k < 2; ++k) \
;       acc[ai][bj][m][n] = MFMA16(Bt_[n][k], At_[m][k], acc[ai][bj][m][n]); \
;     __builtin_amdgcn_s_setprio(0); }
; #define WAIT_V(n) asm volatile("s_waitcnt vmcnt(" #n ")" ::: "memory");
; #define WAIT_L(n) asm volatile("s_waitcnt lgkmcnt(" #n ")" ::: "memory");
; #define BAR __builtin_amdgcn_s_barrier();
; #define SCHED __builtin_amdgcn_sched_barrier(0);
; DI void gemm256(const u16* __restrict__ A, int lda, const u16* __restrict__ B0, const u16* __restrict__ B1, int ldb, int nt, acc_t& acc, char* lds) {
;     ...
;   for (int t = 0; t < nt - 2; t += 2) {
;     LDB(Bq0, 0, 0) SCHED LDA(At, 0, 0) STAGE_A(1, 1, t + 1)
;     WAIT_L(8) BAR WAIT_L(0) MMA(0, 0, At, Bq0) BAR SCHED
;     LDB(Bq1, 0, 1) STAGE_B(0, 0, t + 2)
;     BAR WAIT_L(0) MMA(0, 1, At, Bq1) BAR
;     LDA(At, 0, 1) STAGE_A(0, 0, t + 2)
;     BAR WAIT_L(0) MMA(1, 0, At, Bq0) BAR SCHED
;     STAGE_B(0, 1, t + 2)
;     WAIT_V(6) BAR MMA(1, 1, At, Bq1) BAR
; DI void p5_phase(const Params& p, char* lds) {
;     ...
;     zero_acc(acc);
;     gemm256(xb + (size_t)row0 * D, D, win + (size_t)(4608 + col0) * D, win + (size_t)(4608 + col0 + 128) * D, D, 16, acc, lds);
.LBB0_985:
	ds_read_b128 v[142:145], v166
	ds_read_b128 v[170:173], v166 offset:1024
	ds_read_b128 v[174:177], v166 offset:2048
	ds_read_b128 v[178:181], v166 offset:3072
	v_add_u32_e32 v167, 0xc000, v150
	v_lshl_add_u64 v[222:223], s[8:9], 0, v[136:137]
	v_readfirstlane_b32 s3, v167
	v_lshl_add_u64 v[168:169], v[222:223], 0, s[0:1]
	s_mov_b32 m0, s3
	ds_read_b128 v[182:185], v148
	ds_read_b128 v[186:189], v148 offset:1024
	ds_read_b128 v[190:193], v147
	ds_read_b128 v[194:197], v147 offset:1024
	ds_read_b128 v[198:201], v146
	ds_read_b128 v[202:205], v146 offset:1024
	ds_read_b128 v[206:209], v141
	ds_read_b128 v[210:213], v141 offset:1024
	global_load_lds_dwordx4 v[168:169], off
	v_add_u32_e32 v168, 0xe000, v150
	v_lshl_add_u64 v[224:225], s[8:9], 0, v[138:139]
	v_readfirstlane_b32 s3, v168
	v_lshl_add_u64 v[216:217], v[224:225], 0, s[0:1]
	s_mov_b32 m0, s3
	s_nop 0
	global_load_lds_dwordx4 v[216:217], off
	s_waitcnt lgkmcnt(8)
	s_barrier
	s_waitcnt lgkmcnt(0)
	s_setprio 0
	s_waitcnt lgkmcnt(0)
	v_mfma_f32_16x16x32_bf16 v[126:129], v[142:145], v[182:185], v[126:129]
	v_mfma_f32_16x16x32_bf16 v[122:125], v[174:177], v[182:185], v[122:125]
	v_mfma_f32_16x16x32_bf16 v[118:121], v[142:145], v[190:193], v[118:121]
	v_mfma_f32_16x16x32_bf16 v[114:117], v[174:177], v[190:193], v[114:117]
	v_mfma_f32_16x16x32_bf16 v[110:113], v[142:145], v[198:201], v[110:113]
	v_mfma_f32_16x16x32_bf16 v[106:109], v[174:177], v[198:201], v[106:109]
	v_mfma_f32_16x16x32_bf16 v[102:105], v[142:145], v[206:209], v[102:105]
	v_mfma_f32_16x16x32_bf16 v[98:101], v[174:177], v[206:209], v[98:101]
	v_mfma_f32_16x16x32_bf16 v[126:129], v[170:173], v[186:189], v[126:129]
	v_mfma_f32_16x16x32_bf16 v[122:125], v[178:181], v[186:189], v[122:125]
	v_mfma_f32_16x16x32_bf16 v[118:121], v[170:173], v[194:197], v[118:121]
	v_mfma_f32_16x16x32_bf16 v[114:117], v[178:181], v[194:197], v[114:117]
	v_mfma_f32_16x16x32_bf16 v[110:113], v[170:173], v[202:205], v[110:113]
	v_mfma_f32_16x16x32_bf16 v[106:109], v[178:181], v[202:205], v[106:109]
	v_mfma_f32_16x16x32_bf16 v[102:105], v[170:173], v[210:213], v[102:105]
	v_mfma_f32_16x16x32_bf16 v[98:101], v[178:181], v[210:213], v[98:101]
	s_setprio 1
	s_barrier
	v_lshl_add_u64 v[238:239], s[8:9], 0, v[132:133]
	v_readfirstlane_b32 s3, v151
	v_lshl_add_u64 v[240:241], v[238:239], 0, s[22:23]
	s_mov_b32 m0, s3
	ds_read_b128 v[216:219], v165
	ds_read_b128 v[226:229], v165 offset:1024
	ds_read_b128 v[230:233], v165 offset:2048
	ds_read_b128 v[234:237], v165 offset:3072
	global_load_lds_dwordx4 v[240:241], off
	v_lshl_add_u64 v[240:241], s[8:9], 0, v[134:135]
	v_readfirstlane_b32 s3, v152
	v_lshl_add_u64 v[242:243], v[240:241], 0, s[22:23]
	s_mov_b32 m0, s3
	s_nop 0
	global_load_lds_dwordx4 v[242:243], off
	s_barrier
	s_waitcnt lgkmcnt(0)
	s_setprio 0
	s_waitcnt lgkmcnt(0)
	v_mfma_f32_16x16x32_bf16 v[94:97], v[216:219], v[182:185], v[94:97]
	v_mfma_f32_16x16x32_bf16 v[90:93], v[230:233], v[182:185], v[90:93]
	v_mfma_f32_16x16x32_bf16 v[86:89], v[216:219], v[190:193], v[86:89]
	v_mfma_f32_16x16x32_bf16 v[82:85], v[230:233], v[190:193], v[82:85]
	v_mfma_f32_16x16x32_bf16 v[78:81], v[216:219], v[198:201], v[78:81]
	v_mfma_f32_16x16x32_bf16 v[74:77], v[230:233], v[198:201], v[74:77]
	v_mfma_f32_16x16x32_bf16 v[70:73], v[216:219], v[206:209], v[70:73]
	v_mfma_f32_16x16x32_bf16 v[66:69], v[230:233], v[206:209], v[66:69]
	v_mfma_f32_16x16x32_bf16 v[94:97], v[226:229], v[186:189], v[94:97]
	v_mfma_f32_16x16x32_bf16 v[90:93], v[234:237], v[186:189], v[90:93]
	v_mfma_f32_16x16x32_bf16 v[86:89], v[226:229], v[194:197], v[86:89]
	v_mfma_f32_16x16x32_bf16 v[82:85], v[234:237], v[194:197], v[82:85]
	v_mfma_f32_16x16x32_bf16 v[78:81], v[226:229], v[202:205], v[78:81]
	v_mfma_f32_16x16x32_bf16 v[74:77], v[234:237], v[202:205], v[74:77]
	v_mfma_f32_16x16x32_bf16 v[70:73], v[226:229], v[210:213], v[70:73]
	v_mfma_f32_16x16x32_bf16 v[66:69], v[234:237], v[210:213], v[66:69]
	s_setprio 1
	v_readfirstlane_b32 s3, v150
	v_lshl_add_u64 v[242:243], v[222:223], 0, s[20:21]
	s_mov_b32 m0, s3
	v_readfirstlane_b32 s3, v153
	s_barrier
	ds_read_b128 v[182:185], v148 offset:16384
	ds_read_b128 v[186:189], v148 offset:17408
	ds_read_b128 v[190:193], v147 offset:16384
	ds_read_b128 v[194:197], v147 offset:17408
	ds_read_b128 v[198:201], v146 offset:16384
	ds_read_b128 v[202:205], v146 offset:17408
	ds_read_b128 v[206:209], v141 offset:16384
	ds_read_b128 v[210:213], v141 offset:17408
	global_load_lds_dwordx4 v[242:243], off
	v_lshl_add_u64 v[242:243], v[224:225], 0, s[20:21]
	s_mov_b32 m0, s3
	s_nop 0
	global_load_lds_dwordx4 v[242:243], off
	s_barrier
	s_waitcnt lgkmcnt(0)
	s_setprio 0
	s_waitcnt lgkmcnt(0)
	v_mfma_f32_16x16x32_bf16 v[60:63], v[142:145], v[182:185], v[60:63]
	v_mfma_f32_16x16x32_bf16 v[56:59], v[174:177], v[182:185], v[56:59]
	v_mfma_f32_16x16x32_bf16 v[52:55], v[142:145], v[190:193], v[52:55]
	v_mfma_f32_16x16x32_bf16 v[48:51], v[174:177], v[190:193], v[48:51]
	v_mfma_f32_16x16x32_bf16 v[44:47], v[142:145], v[198:201], v[44:47]
	v_mfma_f32_16x16x32_bf16 v[40:43], v[174:177], v[198:201], v[40:43]
	v_mfma_f32_16x16x32_bf16 v[36:39], v[142:145], v[206:209], v[36:39]
	v_mfma_f32_16x16x32_bf16 v[32:35], v[174:177], v[206:209], v[32:35]
	v_mfma_f32_16x16x32_bf16 v[60:63], v[170:173], v[186:189], v[60:63]
	v_mfma_f32_16x16x32_bf16 v[56:59], v[178:181], v[186:189], v[56:59]
	v_mfma_f32_16x16x32_bf16 v[52:55], v[170:173], v[194:197], v[52:55]
	v_mfma_f32_16x16x32_bf16 v[48:51], v[178:181], v[194:197], v[48:51]
	v_mfma_f32_16x16x32_bf16 v[44:47], v[170:173], v[202:205], v[44:47]
	v_mfma_f32_16x16x32_bf16 v[40:43], v[178:181], v[202:205], v[40:43]
	v_mfma_f32_16x16x32_bf16 v[36:39], v[170:173], v[210:213], v[36:39]
	v_mfma_f32_16x16x32_bf16 v[32:35], v[178:181], v[210:213], v[32:35]
	s_setprio 1
	s_barrier
; #define STAGE_A(b, h, kt) { const u16* ap_ = A + (size_t)((h) * ahalf + (unsigned)(kt) * 64u); glds16(ap_ + ao0, l0 + SA_(b, h)); glds16(ap_ + ao1, l0 + SA_(b, h) + 8192); }
; #define STAGE_B(b, h, kt) { const u16* bp_ = ((h) ? B1 : B0) + (unsigned)(kt) * 64u; glds16(bp_ + bo0, l0 + SB_(b, h)); glds16(bp_ + bo1, l0 + SB_(b, h) + 8192); }
; #define LDA(dst, b, h) _Pragma("unroll") for (int m = 0; m < 4; ++m) _Pragma("unroll") for (int k = 0; k < 2; ++k) \
;     dst[m][k] = *(const bf16x8*)(lds + SA_(b, h) + lds_byte(wr * 64 + m * 16 + fr, k * 32 + fq * 8));
; #define LDB(dst, b, h) _Pragma("unroll") for (int n = 0; n < 2; ++n) _Pragma("unroll") for (int k = 0; k < 2; ++k) \
;     dst[n][k] = *(const bf16x8*)(lds + SB_(b, h) + lds_byte(wc * 32 + n * 16 + fr, k * 32 + fq * 8));
; #define MMA(ai, bj, At_, Bt_) { __builtin_amdgcn_s_setprio(1); \
;     _Pragma("unroll") for (int m = 0; m < 4; ++m) _Pragma("unroll") for (int n = 0; n < 2; ++n) _Pragma("unroll") for (int k = 0; k < 2; ++k) \
;       acc[ai][bj][m][n] = MFMA16(Bt_[n][k], At_[m][k], acc[ai][bj][m][n]); \
;     __builtin_amdgcn_s_setprio(0); }
; #define WAIT_V(n) asm volatile("s_waitcnt vmcnt(" #n ")" ::: "memory");
; #define WAIT_L(n) asm volatile("s_waitcnt lgkmcnt(" #n ")" ::: "memory");
; #define BAR __builtin_amdgcn_s_barrier();
; #define SCHED __builtin_amdgcn_sched_barrier(0);
; DI void gemm256(const u16* __restrict__ A, int lda, const u16* __restrict__ B0, const u16* __restrict__ B1, int ldb, int nt, acc_t& acc, char* lds) {
;     ...
;     WAIT_V(6) BAR MMA(1, 1, At, Bq1) BAR
;     LDB(Bq0, 1, 0) SCHED LDA(At, 1, 0) STAGE_A(0, 1, t + 2)
;     WAIT_L(8) BAR WAIT_L(0) MMA(0, 0, At, Bq0) BAR SCHED
;     LDB(Bq1, 1, 1) STAGE_B(1, 0, t + 3)
;     BAR WAIT_L(0) MMA(0, 1, At, Bq1) BAR
;     LDA(At, 1, 1) STAGE_A(1, 0, t + 3)
;     BAR WAIT_L(0) MMA(1, 0, At, Bq0) BAR SCHED
;     STAGE_B(1, 1, t + 3)
	v_readfirstlane_b32 s3, v155
	v_lshl_add_u64 v[142:143], v[238:239], 0, s[28:29]
	s_mov_b32 m0, s3
	v_readfirstlane_b32 s3, v156
	global_load_lds_dwordx4 v[142:143], off
	v_lshl_add_u64 v[142:143], v[240:241], 0, s[28:29]
	s_mov_b32 m0, s3
	s_nop 0
	global_load_lds_dwordx4 v[142:143], off
	s_waitcnt vmcnt(6)
	s_barrier
	s_setprio 0
	v_mfma_f32_16x16x32_bf16 v[28:31], v[216:219], v[182:185], v[28:31]
	v_mfma_f32_16x16x32_bf16 v[24:27], v[230:233], v[182:185], v[24:27]
	v_mfma_f32_16x16x32_bf16 v[20:23], v[216:219], v[190:193], v[20:23]
	v_mfma_f32_16x16x32_bf16 v[16:19], v[230:233], v[190:193], v[16:19]
	v_mfma_f32_16x16x32_bf16 v[12:15], v[216:219], v[198:201], v[12:15]
	v_mfma_f32_16x16x32_bf16 v[8:11], v[230:233], v[198:201], v[8:11]
	v_mfma_f32_16x16x32_bf16 v[4:7], v[216:219], v[206:209], v[4:7]
	v_mfma_f32_16x16x32_bf16 v[0:3], v[230:233], v[206:209], v[0:3]
	v_mfma_f32_16x16x32_bf16 v[28:31], v[226:229], v[186:189], v[28:31]
	v_mfma_f32_16x16x32_bf16 v[24:27], v[234:237], v[186:189], v[24:27]
	v_mfma_f32_16x16x32_bf16 v[20:23], v[226:229], v[194:197], v[20:23]
	v_mfma_f32_16x16x32_bf16 v[16:19], v[234:237], v[194:197], v[16:19]
	v_mfma_f32_16x16x32_bf16 v[12:15], v[226:229], v[202:205], v[12:15]
	v_mfma_f32_16x16x32_bf16 v[8:11], v[234:237], v[202:205], v[8:11]
	v_mfma_f32_16x16x32_bf16 v[4:7], v[226:229], v[210:213], v[4:7]
	v_mfma_f32_16x16x32_bf16 v[0:3], v[234:237], v[210:213], v[0:3]
	s_setprio 1
	s_barrier
	ds_read_b128 v[142:145], v154
	ds_read_b128 v[170:173], v154 offset:1024
	ds_read_b128 v[174:177], v154 offset:2048
	ds_read_b128 v[178:181], v154 offset:3072
	v_readfirstlane_b32 s3, v157
	v_lshl_add_u64 v[216:217], v[222:223], 0, s[24:25]
	s_mov_b32 m0, s3
	v_readfirstlane_b32 s3, v158
	ds_read_b128 v[182:185], v148 offset:32768
	ds_read_b128 v[186:189], v148 offset:33792
	ds_read_b128 v[190:193], v147 offset:32768
	ds_read_b128 v[194:197], v147 offset:33792
	ds_read_b128 v[198:201], v146 offset:32768
	ds_read_b128 v[202:205], v146 offset:33792
	ds_read_b128 v[206:209], v141 offset:32768
	ds_read_b128 v[210:213], v141 offset:33792
	global_load_lds_dwordx4 v[216:217], off
	v_lshl_add_u64 v[216:217], v[224:225], 0, s[24:25]
	s_mov_b32 m0, s3
	s_nop 0
	global_load_lds_dwordx4 v[216:217], off
	s_waitcnt lgkmcnt(8)
	s_barrier
	s_waitcnt lgkmcnt(0)
	s_setprio 0
	s_waitcnt lgkmcnt(0)
	v_mfma_f32_16x16x32_bf16 v[126:129], v[142:145], v[182:185], v[126:129]
	v_mfma_f32_16x16x32_bf16 v[122:125], v[174:177], v[182:185], v[122:125]
	v_mfma_f32_16x16x32_bf16 v[118:121], v[142:145], v[190:193], v[118:121]
	v_mfma_f32_16x16x32_bf16 v[114:117], v[174:177], v[190:193], v[114:117]
	v_mfma_f32_16x16x32_bf16 v[110:113], v[142:145], v[198:201], v[110:113]
	v_mfma_f32_16x16x32_bf16 v[106:109], v[174:177], v[198:201], v[106:109]
	v_mfma_f32_16x16x32_bf16 v[102:105], v[142:145], v[206:209], v[102:105]
	v_mfma_f32_16x16x32_bf16 v[98:101], v[174:177], v[206:209], v[98:101]
	v_mfma_f32_16x16x32_bf16 v[126:129], v[170:173], v[186:189], v[126:129]
	v_mfma_f32_16x16x32_bf16 v[122:125], v[178:181], v[186:189], v[122:125]
	v_mfma_f32_16x16x32_bf16 v[118:121], v[170:173], v[194:197], v[118:121]
	v_mfma_f32_16x16x32_bf16 v[114:117], v[178:181], v[194:197], v[114:117]
	v_mfma_f32_16x16x32_bf16 v[110:113], v[170:173], v[202:205], v[110:113]
	v_mfma_f32_16x16x32_bf16 v[106:109], v[178:181], v[202:205], v[106:109]
	v_mfma_f32_16x16x32_bf16 v[102:105], v[170:173], v[210:213], v[102:105]
	v_mfma_f32_16x16x32_bf16 v[98:101], v[178:181], v[210:213], v[98:101]
	s_setprio 1
	s_barrier
	v_readfirstlane_b32 s3, v159
	v_lshl_add_u64 v[242:243], v[238:239], 0, s[46:47]
	s_mov_b32 m0, s3
	v_readfirstlane_b32 s3, v160
	ds_read_b128 v[216:219], v149
	ds_read_b128 v[226:229], v149 offset:1024
	ds_read_b128 v[230:233], v149 offset:2048
	ds_read_b128 v[234:237], v149 offset:3072
	global_load_lds_dwordx4 v[242:243], off
	v_lshl_add_u64 v[242:243], v[240:241], 0, s[46:47]
	s_mov_b32 m0, s3
	s_nop 0
	global_load_lds_dwordx4 v[242:243], off
	s_barrier
	s_waitcnt lgkmcnt(0)
	s_setprio 0
	s_waitcnt lgkmcnt(0)
	v_mfma_f32_16x16x32_bf16 v[94:97], v[216:219], v[182:185], v[94:97]
	v_mfma_f32_16x16x32_bf16 v[90:93], v[230:233], v[182:185], v[90:93]
	v_mfma_f32_16x16x32_bf16 v[86:89], v[216:219], v[190:193], v[86:89]
	v_mfma_f32_16x16x32_bf16 v[82:85], v[230:233], v[190:193], v[82:85]
	v_mfma_f32_16x16x32_bf16 v[78:81], v[216:219], v[198:201], v[78:81]
	v_mfma_f32_16x16x32_bf16 v[74:77], v[230:233], v[198:201], v[74:77]
	v_mfma_f32_16x16x32_bf16 v[70:73], v[216:219], v[206:209], v[70:73]
	v_mfma_f32_16x16x32_bf16 v[66:69], v[230:233], v[206:209], v[66:69]
	v_mfma_f32_16x16x32_bf16 v[94:97], v[226:229], v[186:189], v[94:97]
	v_mfma_f32_16x16x32_bf16 v[90:93], v[234:237], v[186:189], v[90:93]
	v_mfma_f32_16x16x32_bf16 v[86:89], v[226:229], v[194:197], v[86:89]
	v_mfma_f32_16x16x32_bf16 v[82:85], v[234:237], v[194:197], v[82:85]
	v_mfma_f32_16x16x32_bf16 v[78:81], v[226:229], v[202:205], v[78:81]
	v_mfma_f32_16x16x32_bf16 v[74:77], v[234:237], v[202:205], v[74:77]
	v_mfma_f32_16x16x32_bf16 v[70:73], v[226:229], v[210:213], v[70:73]
	v_mfma_f32_16x16x32_bf16 v[66:69], v[234:237], v[210:213], v[66:69]
	s_setprio 1
	v_readfirstlane_b32 s3, v161
	v_lshl_add_u64 v[222:223], v[222:223], 0, s[34:35]
	s_mov_b32 m0, s3
	v_readfirstlane_b32 s3, v162
	s_barrier
	ds_read_b128 v[182:185], v148 offset:49152
	ds_read_b128 v[186:189], v148 offset:50176
	ds_read_b128 v[190:193], v147 offset:49152
	ds_read_b128 v[194:197], v147 offset:50176
	ds_read_b128 v[198:201], v146 offset:49152
	ds_read_b128 v[202:205], v146 offset:50176
	ds_read_b128 v[206:209], v141 offset:49152
	ds_read_b128 v[210:213], v141 offset:50176
	global_load_lds_dwordx4 v[222:223], off
	v_lshl_add_u64 v[222:223], v[224:225], 0, s[34:35]
	s_mov_b32 m0, s3
	s_nop 0
	global_load_lds_dwordx4 v[222:223], off
	s_barrier
; #define STAGE_A(b, h, kt) { const u16* ap_ = A + (size_t)((h) * ahalf + (unsigned)(kt) * 64u); glds16(ap_ + ao0, l0 + SA_(b, h)); glds16(ap_ + ao1, l0 + SA_(b, h) + 8192); }
; #define STAGE_B(b, h, kt) { const u16* bp_ = ((h) ? B1 : B0) + (unsigned)(kt) * 64u; glds16(bp_ + bo0, l0 + SB_(b, h)); glds16(bp_ + bo1, l0 + SB_(b, h) + 8192); }
; #define LDA(dst, b, h) _Pragma("unroll") for (int m = 0; m < 4; ++m) _Pragma("unroll") for (int k = 0; k < 2; ++k) \
;     dst[m][k] = *(const bf16x8*)(lds + SA_(b, h) + lds_byte(wr * 64 + m * 16 + fr, k * 32 + fq * 8));
; #define LDB(dst, b, h) _Pragma("unroll") for (int n = 0; n < 2; ++n) _Pragma("unroll") for (int k = 0; k < 2; ++k) \
;     dst[n][k] = *(const bf16x8*)(lds + SB_(b, h) + lds_byte(wc * 32 + n * 16 + fr, k * 32 + fq * 8));
; #define MMA(ai, bj, At_, Bt_) { __builtin_amdgcn_s_setprio(1); \
;     _Pragma("unroll") for (int m = 0; m < 4; ++m) _Pragma("unroll") for (int n = 0; n < 2; ++n) _Pragma("unroll") for (int k = 0; k < 2; ++k) \
;       acc[ai][bj][m][n] = MFMA16(Bt_[n][k], At_[m][k], acc[ai][bj][m][n]); \
;     __builtin_amdgcn_s_setprio(0); }
; #define WAIT_V(n) asm volatile("s_waitcnt vmcnt(" #n ")" ::: "memory");
; #define WAIT_L(n) asm volatile("s_waitcnt lgkmcnt(" #n ")" ::: "memory");
; #define BAR __builtin_amdgcn_s_barrier();
; #define SCHED __builtin_amdgcn_sched_barrier(0);
; DI void gemm256(const u16* __restrict__ A, int lda, const u16* __restrict__ B0, const u16* __restrict__ B1, int ldb, int nt, acc_t& acc, char* lds) {
;     ...
;     BAR WAIT_L(0) MMA(1, 0, At, Bq0) BAR SCHED
;     STAGE_B(1, 1, t + 3)
;     WAIT_V(6) BAR MMA(1, 1, At, Bq1) BAR
;   }
;   { LDB(Bq0, 0, 0) LDA(At, 0, 0) STAGE_A(1, 1, nt - 1)
;     BAR WAIT_L(0) MMA(0, 0, At, Bq0) BAR
;     LDB(Bq1, 0, 1) BAR WAIT_L(0) MMA(0, 1, At, Bq1) BAR
;     LDA(At, 0, 1) WAIT_V(4) BAR WAIT_L(0) MMA(1, 0, At, Bq0) MMA(1, 1, At, Bq1) BAR }
;   { LDB(Bq0, 1, 0) LDA(At, 1, 0) WAIT_V(2) BAR WAIT_L(0) MMA(0, 0, At, Bq0) BAR
	s_waitcnt lgkmcnt(0)
	s_setprio 0
	s_waitcnt lgkmcnt(0)
	v_mfma_f32_16x16x32_bf16 v[60:63], v[142:145], v[182:185], v[60:63]
	v_mfma_f32_16x16x32_bf16 v[56:59], v[174:177], v[182:185], v[56:59]
	v_mfma_f32_16x16x32_bf16 v[52:55], v[142:145], v[190:193], v[52:55]
	v_mfma_f32_16x16x32_bf16 v[48:51], v[174:177], v[190:193], v[48:51]
	v_mfma_f32_16x16x32_bf16 v[44:47], v[142:145], v[198:201], v[44:47]
	v_mfma_f32_16x16x32_bf16 v[40:43], v[174:177], v[198:201], v[40:43]
	v_mfma_f32_16x16x32_bf16 v[36:39], v[142:145], v[206:209], v[36:39]
	v_mfma_f32_16x16x32_bf16 v[32:35], v[174:177], v[206:209], v[32:35]
	v_mfma_f32_16x16x32_bf16 v[60:63], v[170:173], v[186:189], v[60:63]
	v_mfma_f32_16x16x32_bf16 v[56:59], v[178:181], v[186:189], v[56:59]
	v_mfma_f32_16x16x32_bf16 v[52:55], v[170:173], v[194:197], v[52:55]
	v_mfma_f32_16x16x32_bf16 v[48:51], v[178:181], v[194:197], v[48:51]
	v_mfma_f32_16x16x32_bf16 v[44:47], v[170:173], v[202:205], v[44:47]
	v_mfma_f32_16x16x32_bf16 v[40:43], v[178:181], v[202:205], v[40:43]
	v_mfma_f32_16x16x32_bf16 v[36:39], v[170:173], v[210:213], v[36:39]
	v_mfma_f32_16x16x32_bf16 v[32:35], v[178:181], v[210:213], v[32:35]
	s_setprio 1
	s_barrier
	v_readfirstlane_b32 s3, v163
	v_lshl_add_u64 v[142:143], v[238:239], 0, s[50:51]
	s_mov_b32 m0, s3
	v_readfirstlane_b32 s3, v164
	global_load_lds_dwordx4 v[142:143], off
	v_lshl_add_u64 v[142:143], v[240:241], 0, s[50:51]
	s_mov_b32 m0, s3
	s_nop 0
	global_load_lds_dwordx4 v[142:143], off
	s_waitcnt vmcnt(6)
	s_barrier
	s_setprio 0
	v_mfma_f32_16x16x32_bf16 v[28:31], v[216:219], v[182:185], v[28:31]
	v_mfma_f32_16x16x32_bf16 v[24:27], v[230:233], v[182:185], v[24:27]
	v_mfma_f32_16x16x32_bf16 v[20:23], v[216:219], v[190:193], v[20:23]
	v_mfma_f32_16x16x32_bf16 v[16:19], v[230:233], v[190:193], v[16:19]
	v_mfma_f32_16x16x32_bf16 v[12:15], v[216:219], v[198:201], v[12:15]
	v_mfma_f32_16x16x32_bf16 v[8:11], v[230:233], v[198:201], v[8:11]
	v_mfma_f32_16x16x32_bf16 v[4:7], v[216:219], v[206:209], v[4:7]
	v_mfma_f32_16x16x32_bf16 v[0:3], v[230:233], v[206:209], v[0:3]
	v_mfma_f32_16x16x32_bf16 v[28:31], v[226:229], v[186:189], v[28:31]
	v_mfma_f32_16x16x32_bf16 v[24:27], v[234:237], v[186:189], v[24:27]
	v_mfma_f32_16x16x32_bf16 v[20:23], v[226:229], v[194:197], v[20:23]
	v_mfma_f32_16x16x32_bf16 v[16:19], v[234:237], v[194:197], v[16:19]
	v_mfma_f32_16x16x32_bf16 v[12:15], v[226:229], v[202:205], v[12:15]
	v_mfma_f32_16x16x32_bf16 v[8:11], v[234:237], v[202:205], v[8:11]
	v_mfma_f32_16x16x32_bf16 v[4:7], v[226:229], v[210:213], v[4:7]
	v_mfma_f32_16x16x32_bf16 v[0:3], v[234:237], v[210:213], v[0:3]
	s_setprio 1
	s_add_i32 s2, s2, 2
	s_add_u32 s8, s8, 0x100
	s_addc_u32 s9, s9, 0
	s_cmp_lt_u32 s2, 12
	s_barrier
	s_cbranch_scc1 .LBB0_985
	v_readfirstlane_b32 s2, v167
	v_lshl_add_u64 v[194:195], v[64:65], 1, s[54:55]
	s_mov_b32 m0, s2
	v_readfirstlane_b32 s2, v168
	ds_read_b128 v[132:135], v166
	ds_read_b128 v[136:139], v166 offset:1024
	ds_read_b128 v[142:145], v166 offset:2048
	ds_read_b128 v[150:153], v166 offset:3072
	ds_read_b128 v[156:159], v148
	ds_read_b128 v[160:163], v148 offset:1024
	ds_read_b128 v[170:173], v147
	ds_read_b128 v[174:177], v147 offset:1024
	ds_read_b128 v[178:181], v146
	ds_read_b128 v[182:185], v146 offset:1024
	ds_read_b128 v[186:189], v141
	ds_read_b128 v[190:193], v141 offset:1024
	global_load_lds_dwordx4 v[194:195], off
	v_lshl_add_u64 v[130:131], v[130:131], 1, s[54:55]
	s_mov_b32 m0, s2
	s_nop 0
	global_load_lds_dwordx4 v[130:131], off
	s_barrier
	s_waitcnt lgkmcnt(0)
	s_setprio 0
	s_waitcnt lgkmcnt(0)
	v_mfma_f32_16x16x32_bf16 v[126:129], v[132:135], v[156:159], v[126:129]
	v_mfma_f32_16x16x32_bf16 v[122:125], v[142:145], v[156:159], v[122:125]
	v_mfma_f32_16x16x32_bf16 v[118:121], v[132:135], v[170:173], v[118:121]
	v_mfma_f32_16x16x32_bf16 v[114:117], v[142:145], v[170:173], v[114:117]
	v_mfma_f32_16x16x32_bf16 v[102:105], v[132:135], v[186:189], v[102:105]
	v_mfma_f32_16x16x32_bf16 v[98:101], v[142:145], v[186:189], v[98:101]
	v_mfma_f32_16x16x32_bf16 v[126:129], v[136:139], v[160:163], v[126:129]
	v_mfma_f32_16x16x32_bf16 v[122:125], v[150:153], v[160:163], v[122:125]
	v_mfma_f32_16x16x32_bf16 v[118:121], v[136:139], v[174:177], v[118:121]
	v_mfma_f32_16x16x32_bf16 v[114:117], v[150:153], v[174:177], v[114:117]
	v_mfma_f32_16x16x32_bf16 v[110:113], v[132:135], v[178:181], v[110:113]
	v_mfma_f32_16x16x32_bf16 v[106:109], v[142:145], v[178:181], v[106:109]
	v_mfma_f32_16x16x32_bf16 v[102:105], v[136:139], v[190:193], v[102:105]
	v_mfma_f32_16x16x32_bf16 v[98:101], v[150:153], v[190:193], v[98:101]
	v_mfma_f32_16x16x32_bf16 v[166:169], v[136:139], v[182:185], v[110:113]
	v_mfma_f32_16x16x32_bf16 v[194:197], v[150:153], v[182:185], v[106:109]
	s_setprio 1
	s_barrier
	s_nop 1
	ds_read_b128 v[106:109], v165
	ds_read_b128 v[110:113], v165 offset:1024
	ds_read_b128 v[198:201], v165 offset:2048
	ds_read_b128 v[202:205], v165 offset:3072
	s_barrier
	s_waitcnt lgkmcnt(0)
	s_setprio 0
	s_waitcnt lgkmcnt(0)
	v_mfma_f32_16x16x32_bf16 v[86:89], v[106:109], v[170:173], v[86:89]
	v_mfma_f32_16x16x32_bf16 v[82:85], v[198:201], v[170:173], v[82:85]
	v_mfma_f32_16x16x32_bf16 v[70:73], v[106:109], v[186:189], v[70:73]
	v_mfma_f32_16x16x32_bf16 v[66:69], v[198:201], v[186:189], v[66:69]
	v_mfma_f32_16x16x32_bf16 v[94:97], v[106:109], v[156:159], v[94:97]
	v_mfma_f32_16x16x32_bf16 v[90:93], v[198:201], v[156:159], v[90:93]
	v_mfma_f32_16x16x32_bf16 v[86:89], v[110:113], v[174:177], v[86:89]
	v_mfma_f32_16x16x32_bf16 v[82:85], v[202:205], v[174:177], v[82:85]
	v_mfma_f32_16x16x32_bf16 v[78:81], v[106:109], v[178:181], v[78:81]
	v_mfma_f32_16x16x32_bf16 v[74:77], v[198:201], v[178:181], v[74:77]
	v_mfma_f32_16x16x32_bf16 v[70:73], v[110:113], v[190:193], v[70:73]
	v_mfma_f32_16x16x32_bf16 v[66:69], v[202:205], v[190:193], v[66:69]
	v_mfma_f32_16x16x32_bf16 v[206:209], v[110:113], v[160:163], v[94:97]
	v_mfma_f32_16x16x32_bf16 v[156:159], v[202:205], v[160:163], v[90:93]
	v_mfma_f32_16x16x32_bf16 v[160:163], v[110:113], v[182:185], v[78:81]
	v_mfma_f32_16x16x32_bf16 v[170:173], v[202:205], v[182:185], v[74:77]
	s_setprio 1
	s_barrier
; #define LDA(dst, b, h) _Pragma("unroll") for (int m = 0; m < 4; ++m) _Pragma("unroll") for (int k = 0; k < 2; ++k) \
;     dst[m][k] = *(const bf16x8*)(lds + SA_(b, h) + lds_byte(wr * 64 + m * 16 + fr, k * 32 + fq * 8));
; #define LDB(dst, b, h) _Pragma("unroll") for (int n = 0; n < 2; ++n) _Pragma("unroll") for (int k = 0; k < 2; ++k) \
;     dst[n][k] = *(const bf16x8*)(lds + SB_(b, h) + lds_byte(wc * 32 + n * 16 + fr, k * 32 + fq * 8));
; #define MMA(ai, bj, At_, Bt_) { __builtin_amdgcn_s_setprio(1); \
;     _Pragma("unroll") for (int m = 0; m < 4; ++m) _Pragma("unroll") for (int n = 0; n < 2; ++n) _Pragma("unroll") for (int k = 0; k < 2; ++k) \
;       acc[ai][bj][m][n] = MFMA16(Bt_[n][k], At_[m][k], acc[ai][bj][m][n]); \
;     __builtin_amdgcn_s_setprio(0); }
; #define WAIT_V(n) asm volatile("s_waitcnt vmcnt(" #n ")" ::: "memory");
; #define WAIT_L(n) asm volatile("s_waitcnt lgkmcnt(" #n ")" ::: "memory");
; #define BAR __builtin_amdgcn_s_barrier();
; DI void gemm256(const u16* __restrict__ A, int lda, const u16* __restrict__ B0, const u16* __restrict__ B1, int ldb, int nt, acc_t& acc, char* lds) {
;     ...
;     LDA(At, 0, 1) WAIT_V(4) BAR WAIT_L(0) MMA(1, 0, At, Bq0) MMA(1, 1, At, Bq1) BAR }
;   { LDB(Bq0, 1, 0) LDA(At, 1, 0) WAIT_V(2) BAR WAIT_L(0) MMA(0, 0, At, Bq0) BAR
	s_nop 0
	ds_read_b128 v[74:77], v148 offset:16384
	ds_read_b128 v[78:81], v148 offset:17408
	ds_read_b128 v[90:93], v147 offset:16384
	ds_read_b128 v[94:97], v147 offset:17408
	ds_read_b128 v[174:177], v146 offset:16384
	ds_read_b128 v[178:181], v146 offset:17408
	ds_read_b128 v[182:185], v141 offset:16384
	ds_read_b128 v[186:189], v141 offset:17408
	s_waitcnt vmcnt(4)
	s_barrier
	s_waitcnt lgkmcnt(0)
	s_setprio 0
	s_waitcnt lgkmcnt(0)
	v_mfma_f32_16x16x32_bf16 v[60:63], v[132:135], v[74:77], v[60:63]
	v_mfma_f32_16x16x32_bf16 v[56:59], v[142:145], v[74:77], v[56:59]
	v_mfma_f32_16x16x32_bf16 v[52:55], v[132:135], v[90:93], v[52:55]
	v_mfma_f32_16x16x32_bf16 v[48:51], v[142:145], v[90:93], v[48:51]
	v_mfma_f32_16x16x32_bf16 v[36:39], v[132:135], v[182:185], v[36:39]
	v_mfma_f32_16x16x32_bf16 v[32:35], v[142:145], v[182:185], v[32:35]
	v_mfma_f32_16x16x32_bf16 v[60:63], v[136:139], v[78:81], v[60:63]
	v_mfma_f32_16x16x32_bf16 v[56:59], v[150:153], v[78:81], v[56:59]
	v_mfma_f32_16x16x32_bf16 v[52:55], v[136:139], v[94:97], v[52:55]
	v_mfma_f32_16x16x32_bf16 v[48:51], v[150:153], v[94:97], v[48:51]
	v_mfma_f32_16x16x32_bf16 v[44:47], v[132:135], v[174:177], v[44:47]
	v_mfma_f32_16x16x32_bf16 v[40:43], v[142:145], v[174:177], v[40:43]
	v_mfma_f32_16x16x32_bf16 v[36:39], v[136:139], v[186:189], v[36:39]
	v_mfma_f32_16x16x32_bf16 v[32:35], v[150:153], v[186:189], v[32:35]
	v_mfma_f32_16x16x32_bf16 v[190:193], v[136:139], v[178:181], v[44:47]
	v_mfma_f32_16x16x32_bf16 v[210:213], v[150:153], v[178:181], v[40:43]
	s_setprio 1
	s_setprio 0
	v_mfma_f32_16x16x32_bf16 v[20:23], v[106:109], v[90:93], v[20:23]
	v_mfma_f32_16x16x32_bf16 v[16:19], v[198:201], v[90:93], v[16:19]
	v_mfma_f32_16x16x32_bf16 v[4:7], v[106:109], v[182:185], v[4:7]
	v_mfma_f32_16x16x32_bf16 v[0:3], v[198:201], v[182:185], v[0:3]
	v_mfma_f32_16x16x32_bf16 v[28:31], v[106:109], v[74:77], v[28:31]
	v_mfma_f32_16x16x32_bf16 v[24:27], v[198:201], v[74:77], v[24:27]
	v_mfma_f32_16x16x32_bf16 v[20:23], v[110:113], v[94:97], v[20:23]
	v_mfma_f32_16x16x32_bf16 v[16:19], v[202:205], v[94:97], v[16:19]
	v_mfma_f32_16x16x32_bf16 v[12:15], v[106:109], v[174:177], v[12:15]
	v_mfma_f32_16x16x32_bf16 v[8:11], v[198:201], v[174:177], v[8:11]
	v_mfma_f32_16x16x32_bf16 v[4:7], v[110:113], v[186:189], v[4:7]
	v_mfma_f32_16x16x32_bf16 v[0:3], v[202:205], v[186:189], v[0:3]
	v_mfma_f32_16x16x32_bf16 v[130:133], v[110:113], v[78:81], v[28:31]
	v_mfma_f32_16x16x32_bf16 v[134:137], v[202:205], v[78:81], v[24:27]
	v_mfma_f32_16x16x32_bf16 v[142:145], v[110:113], v[178:181], v[12:15]
	v_mfma_f32_16x16x32_bf16 v[150:153], v[202:205], v[178:181], v[8:11]
	s_setprio 1
	s_barrier
	s_nop 0
	ds_read_b128 v[8:11], v154
	ds_read_b128 v[12:15], v154 offset:1024
	ds_read_b128 v[174:177], v154 offset:2048
	ds_read_b128 v[178:181], v154 offset:3072
	ds_read_b128 v[24:27], v148 offset:32768
	ds_read_b128 v[28:31], v148 offset:33792
	ds_read_b128 v[40:43], v147 offset:32768
	ds_read_b128 v[44:47], v147 offset:33792
	ds_read_b128 v[182:185], v146 offset:32768
	ds_read_b128 v[186:189], v146 offset:33792
	ds_read_b128 v[198:201], v141 offset:32768
	ds_read_b128 v[202:205], v141 offset:33792
	s_waitcnt vmcnt(2)
	s_barrier
	s_waitcnt lgkmcnt(0)
	s_setprio 0
	s_waitcnt lgkmcnt(0)
	v_mfma_f32_16x16x32_bf16 v[74:77], v[8:11], v[24:27], v[126:129]
	v_mfma_f32_16x16x32_bf16 v[126:129], v[12:15], v[28:31], v[74:77]
	v_mfma_f32_16x16x32_bf16 v[74:77], v[174:177], v[24:27], v[122:125]
	v_mfma_f32_16x16x32_bf16 v[122:125], v[178:181], v[28:31], v[74:77]
	v_mfma_f32_16x16x32_bf16 v[74:77], v[8:11], v[40:43], v[118:121]
	v_mfma_f32_16x16x32_bf16 v[110:113], v[12:15], v[44:47], v[74:77]
	v_mfma_f32_16x16x32_bf16 v[74:77], v[174:177], v[40:43], v[114:117]
	v_mfma_f32_16x16x32_bf16 v[106:109], v[178:181], v[44:47], v[74:77]
	v_mfma_f32_16x16x32_bf16 v[74:77], v[8:11], v[182:185], v[166:169]
	v_mfma_f32_16x16x32_bf16 v[94:97], v[12:15], v[186:189], v[74:77]
	v_mfma_f32_16x16x32_bf16 v[74:77], v[174:177], v[182:185], v[194:197]
	v_mfma_f32_16x16x32_bf16 v[90:93], v[178:181], v[186:189], v[74:77]
	v_mfma_f32_16x16x32_bf16 v[74:77], v[8:11], v[198:201], v[102:105]
	v_mfma_f32_16x16x32_bf16 v[78:81], v[12:15], v[202:205], v[74:77]
	v_mfma_f32_16x16x32_bf16 v[74:77], v[174:177], v[198:201], v[98:101]
	v_mfma_f32_16x16x32_bf16 v[74:77], v[178:181], v[202:205], v[74:77]
	s_setprio 1
	s_barrier
; #define LDA(dst, b, h) _Pragma("unroll") for (int m = 0; m < 4; ++m) _Pragma("unroll") for (int k = 0; k < 2; ++k) \
;     dst[m][k] = *(const bf16x8*)(lds + SA_(b, h) + lds_byte(wr * 64 + m * 16 + fr, k * 32 + fq * 8));
; #define LDB(dst, b, h) _Pragma("unroll") for (int n = 0; n < 2; ++n) _Pragma("unroll") for (int k = 0; k < 2; ++k) \
;     dst[n][k] = *(const bf16x8*)(lds + SB_(b, h) + lds_byte(wc * 32 + n * 16 + fr, k * 32 + fq * 8));
; #define MMA(ai, bj, At_, Bt_) { __builtin_amdgcn_s_setprio(1); \
;     _Pragma("unroll") for (int m = 0; m < 4; ++m) _Pragma("unroll") for (int n = 0; n < 2; ++n) _Pragma("unroll") for (int k = 0; k < 2; ++k) \
;       acc[ai][bj][m][n] = MFMA16(Bt_[n][k], At_[m][k], acc[ai][bj][m][n]); \
;     __builtin_amdgcn_s_setprio(0); }
; #define WAIT_V(n) asm volatile("s_waitcnt vmcnt(" #n ")" ::: "memory");
; #define WAIT_L(n) asm volatile("s_waitcnt lgkmcnt(" #n ")" ::: "memory");
; #define BAR __builtin_amdgcn_s_barrier();
; DI void gemm256(const u16* __restrict__ A, int lda, const u16* __restrict__ B0, const u16* __restrict__ B1, int ldb, int nt, acc_t& acc, char* lds) {
;     ...
;     LDB(Bq1, 1, 1) WAIT_V(0) BAR WAIT_L(0) MMA(0, 1, At, Bq1) BAR
;     LDA(At, 1, 1) BAR WAIT_L(0) MMA(1, 0, At, Bq0) MMA(1, 1, At, Bq1) BAR }
;   if (wr == 0) BAR
;   __syncthreads();
	ds_read_b128 v[164:167], v149
	ds_read_b128 v[194:197], v149 offset:1024
	ds_read_b128 v[216:219], v149 offset:2048
	ds_read_b128 v[226:229], v149 offset:3072
	s_waitcnt vmcnt(0)
	s_barrier
	s_waitcnt lgkmcnt(0)
	s_setprio 0
	s_waitcnt lgkmcnt(0)
	v_mfma_f32_16x16x32_bf16 v[98:101], v[164:167], v[24:27], v[206:209]
	v_mfma_f32_16x16x32_bf16 v[24:27], v[216:219], v[24:27], v[156:159]
	v_mfma_f32_16x16x32_bf16 v[114:117], v[226:229], v[28:31], v[24:27]
	v_mfma_f32_16x16x32_bf16 v[24:27], v[164:167], v[40:43], v[86:89]
	v_mfma_f32_16x16x32_bf16 v[102:105], v[194:197], v[44:47], v[24:27]
	v_mfma_f32_16x16x32_bf16 v[24:27], v[216:219], v[40:43], v[82:85]
	v_mfma_f32_16x16x32_bf16 v[118:121], v[194:197], v[28:31], v[98:101]
	v_mfma_f32_16x16x32_bf16 v[98:101], v[226:229], v[44:47], v[24:27]
	v_mfma_f32_16x16x32_bf16 v[24:27], v[164:167], v[182:185], v[160:163]
	v_mfma_f32_16x16x32_bf16 v[86:89], v[194:197], v[186:189], v[24:27]
	v_mfma_f32_16x16x32_bf16 v[24:27], v[216:219], v[182:185], v[170:173]
	v_mfma_f32_16x16x32_bf16 v[82:85], v[226:229], v[186:189], v[24:27]
	v_mfma_f32_16x16x32_bf16 v[24:27], v[164:167], v[198:201], v[70:73]
	v_mfma_f32_16x16x32_bf16 v[70:73], v[194:197], v[202:205], v[24:27]
	v_mfma_f32_16x16x32_bf16 v[24:27], v[216:219], v[198:201], v[66:69]
	v_mfma_f32_16x16x32_bf16 v[66:69], v[226:229], v[202:205], v[24:27]
	s_setprio 1
	s_barrier
	ds_read_b128 v[154:157], v148 offset:49152
	ds_read_b128 v[158:161], v148 offset:50176
	ds_read_b128 v[168:171], v147 offset:49152
	ds_read_b128 v[182:185], v147 offset:50176
	ds_read_b128 v[186:189], v146 offset:49152
	ds_read_b128 v[146:149], v146 offset:50176
	ds_read_b128 v[198:201], v141 offset:49152
	ds_read_b128 v[202:205], v141 offset:50176
	s_barrier
	s_waitcnt lgkmcnt(0)
	s_setprio 0
	s_waitcnt lgkmcnt(0)
	v_mfma_f32_16x16x32_bf16 v[24:27], v[8:11], v[154:157], v[60:63]
	v_mfma_f32_16x16x32_bf16 v[60:63], v[12:15], v[158:161], v[24:27]
	v_mfma_f32_16x16x32_bf16 v[24:27], v[174:177], v[154:157], v[56:59]
	v_mfma_f32_16x16x32_bf16 v[56:59], v[178:181], v[158:161], v[24:27]
	v_mfma_f32_16x16x32_bf16 v[24:27], v[8:11], v[168:171], v[52:55]
	v_mfma_f32_16x16x32_bf16 v[44:47], v[12:15], v[182:185], v[24:27]
	v_mfma_f32_16x16x32_bf16 v[24:27], v[174:177], v[168:171], v[48:51]
	v_mfma_f32_16x16x32_bf16 v[40:43], v[178:181], v[182:185], v[24:27]
	v_mfma_f32_16x16x32_bf16 v[24:27], v[8:11], v[186:189], v[190:193]
	v_mfma_f32_16x16x32_bf16 v[8:11], v[8:11], v[198:201], v[36:39]
	v_mfma_f32_16x16x32_bf16 v[28:31], v[12:15], v[146:149], v[24:27]
	v_mfma_f32_16x16x32_bf16 v[24:27], v[174:177], v[186:189], v[210:213]
	v_mfma_f32_16x16x32_bf16 v[12:15], v[12:15], v[202:205], v[8:11]
	v_mfma_f32_16x16x32_bf16 v[8:11], v[174:177], v[198:201], v[32:35]
	v_mfma_f32_16x16x32_bf16 v[24:27], v[178:181], v[146:149], v[24:27]
	v_mfma_f32_16x16x32_bf16 v[8:11], v[178:181], v[202:205], v[8:11]
	s_setprio 1
	s_setprio 0
	v_mfma_f32_16x16x32_bf16 v[32:35], v[164:167], v[154:157], v[130:133]
	v_mfma_f32_16x16x32_bf16 v[52:55], v[194:197], v[158:161], v[32:35]
	v_mfma_f32_16x16x32_bf16 v[32:35], v[216:219], v[154:157], v[134:137]
	v_mfma_f32_16x16x32_bf16 v[16:19], v[216:219], v[168:171], v[16:19]
	v_mfma_f32_16x16x32_bf16 v[48:51], v[226:229], v[158:161], v[32:35]
	v_mfma_f32_16x16x32_bf16 v[20:23], v[164:167], v[168:171], v[20:23]
	v_mfma_f32_16x16x32_bf16 v[32:35], v[226:229], v[182:185], v[16:19]
	v_mfma_f32_16x16x32_bf16 v[16:19], v[164:167], v[186:189], v[142:145]
	v_mfma_f32_16x16x32_bf16 v[36:39], v[194:197], v[182:185], v[20:23]
	v_mfma_f32_16x16x32_bf16 v[20:23], v[194:197], v[146:149], v[16:19]
	v_mfma_f32_16x16x32_bf16 v[16:19], v[216:219], v[186:189], v[150:153]
	v_mfma_f32_16x16x32_bf16 v[4:7], v[164:167], v[198:201], v[4:7]
	v_mfma_f32_16x16x32_bf16 v[0:3], v[216:219], v[198:201], v[0:3]
	v_mfma_f32_16x16x32_bf16 v[16:19], v[226:229], v[146:149], v[16:19]
	v_mfma_f32_16x16x32_bf16 v[4:7], v[194:197], v[202:205], v[4:7]
	v_mfma_f32_16x16x32_bf16 v[0:3], v[226:229], v[202:205], v[0:3]
	s_setprio 1
	s_movk_i32 s2, 0x100
	v_cmp_gt_u32_e32 vcc, s2, v140
	s_barrier
	s_and_saveexec_b64 s[8:9], vcc
	s_cbranch_execz .LBB0_988
	s_barrier

; #define STAGE_A(b, h, kt) { const u16* ap_ = A + (size_t)((h) * ahalf + (unsigned)(kt) * 64u); glds16(ap_ + ao0, l0 + SA_(b, h)); glds16(ap_ + ao1, l0 + SA_(b, h) + 8192); }
; #define STAGE_B(b, h, kt) { const u16* bp_ = ((h) ? B1 : B0) + (unsigned)(kt) * 64u; glds16(bp_ + bo0, l0 + SB_(b, h)); glds16(bp_ + bo1, l0 + SB_(b, h) + 8192); }
; #define LDA(dst, b, h) _Pragma("unroll") for (int m = 0; m < 4; ++m) _Pragma("unroll") for (int k = 0; k < 2; ++k) \
;     dst[m][k] = *(const bf16x8*)(lds + SA_(b, h) + lds_byte(wr * 64 + m * 16 + fr, k * 32 + fq * 8));
; #define LDB(dst, b, h) _Pragma("unroll") for (int n = 0; n < 2; ++n) _Pragma("unroll") for (int k = 0; k < 2; ++k) \
;     dst[n][k] = *(const bf16x8*)(lds + SB_(b, h) + lds_byte(wc * 32 + n * 16 + fr, k * 32 + fq * 8));
; #define MMA(ai, bj, At_, Bt_) { __builtin_amdgcn_s_setprio(1); \
;     _Pragma("unroll") for (int m = 0; m < 4; ++m) _Pragma("unroll") for (int n = 0; n < 2; ++n) _Pragma("unroll") for (int k = 0; k < 2; ++k) \
;       acc[ai][bj][m][n] = MFMA16(Bt_[n][k], At_[m][k], acc[ai][bj][m][n]); \
;     __builtin_amdgcn_s_setprio(0); }
; #define WAIT_V(n) asm volatile("s_waitcnt vmcnt(" #n ")" ::: "memory");
; #define WAIT_L(n) asm volatile("s_waitcnt lgkmcnt(" #n ")" ::: "memory");
; #define BAR __builtin_amdgcn_s_barrier();
; #define SCHED __builtin_amdgcn_sched_barrier(0);
; DI void gemm256(const u16* __restrict__ A, int lda, const u16* __restrict__ B0, const u16* __restrict__ B1, int ldb, int nt, acc_t& acc, char* lds) {
;     ...
;   for (int t = 0; t < nt - 2; t += 2) {
;     LDB(Bq0, 0, 0) SCHED LDA(At, 0, 0) STAGE_A(1, 1, t + 1)
;     WAIT_L(8) BAR WAIT_L(0) MMA(0, 0, At, Bq0) BAR SCHED
;     LDB(Bq1, 0, 1) STAGE_B(0, 0, t + 2)
;     BAR WAIT_L(0) MMA(0, 1, At, Bq1) BAR
;     LDA(At, 0, 1) STAGE_A(0, 0, t + 2)
;     BAR WAIT_L(0) MMA(1, 0, At, Bq0) BAR SCHED
;     STAGE_B(0, 1, t + 2)
;     WAIT_V(6) BAR MMA(1, 1, At, Bq1) BAR
; DI void p5_phase(const Params& p, char* lds) {
;     ...
;     zero_acc(acc);
;     gemm256(oab + (size_t)row0 * 1024 + 512, 1024, (const u16*)(ws + OFF_WB) + (size_t)col0 * 512, (const u16*)(ws + OFF_WB) + (size_t)(col0 + 128) * 512, 512, 8, acc, lds);
.LBB0_991:
	ds_read_b128 v[142:145], v166
	ds_read_b128 v[170:173], v166 offset:1024
	ds_read_b128 v[174:177], v166 offset:2048
	ds_read_b128 v[178:181], v166 offset:3072
	v_add_u32_e32 v167, 0xc000, v149
	v_lshl_add_u64 v[222:223], s[8:9], 0, v[134:135]
	v_readfirstlane_b32 s3, v167
	v_lshl_add_u64 v[168:169], v[222:223], 0, s[22:23]
	s_mov_b32 m0, s3
	ds_read_b128 v[182:185], v148
	ds_read_b128 v[186:189], v148 offset:1024
	ds_read_b128 v[190:193], v147
	ds_read_b128 v[194:197], v147 offset:1024
	ds_read_b128 v[198:201], v146
	ds_read_b128 v[202:205], v146 offset:1024
	ds_read_b128 v[206:209], v141
	ds_read_b128 v[210:213], v141 offset:1024
	global_load_lds_dwordx4 v[168:169], off
	v_add_u32_e32 v168, 0xe000, v149
	v_lshl_add_u64 v[224:225], s[8:9], 0, v[132:133]
	v_readfirstlane_b32 s3, v168
	v_lshl_add_u64 v[216:217], v[224:225], 0, s[22:23]
	s_mov_b32 m0, s3
	s_nop 0
	global_load_lds_dwordx4 v[216:217], off
	s_waitcnt lgkmcnt(8)
	s_barrier
	s_waitcnt lgkmcnt(0)
	s_setprio 0
	s_waitcnt lgkmcnt(0)
	v_mfma_f32_16x16x32_bf16 v[126:129], v[142:145], v[182:185], v[126:129]
	v_mfma_f32_16x16x32_bf16 v[122:125], v[174:177], v[182:185], v[122:125]
	v_mfma_f32_16x16x32_bf16 v[118:121], v[142:145], v[190:193], v[118:121]
	v_mfma_f32_16x16x32_bf16 v[114:117], v[174:177], v[190:193], v[114:117]
	v_mfma_f32_16x16x32_bf16 v[110:113], v[142:145], v[198:201], v[110:113]
	v_mfma_f32_16x16x32_bf16 v[106:109], v[174:177], v[198:201], v[106:109]
	v_mfma_f32_16x16x32_bf16 v[102:105], v[142:145], v[206:209], v[102:105]
	v_mfma_f32_16x16x32_bf16 v[98:101], v[174:177], v[206:209], v[98:101]
	v_mfma_f32_16x16x32_bf16 v[126:129], v[170:173], v[186:189], v[126:129]
	v_mfma_f32_16x16x32_bf16 v[122:125], v[178:181], v[186:189], v[122:125]
	v_mfma_f32_16x16x32_bf16 v[118:121], v[170:173], v[194:197], v[118:121]
	v_mfma_f32_16x16x32_bf16 v[114:117], v[178:181], v[194:197], v[114:117]
	v_mfma_f32_16x16x32_bf16 v[110:113], v[170:173], v[202:205], v[110:113]
	v_mfma_f32_16x16x32_bf16 v[106:109], v[178:181], v[202:205], v[106:109]
	v_mfma_f32_16x16x32_bf16 v[102:105], v[170:173], v[210:213], v[102:105]
	v_mfma_f32_16x16x32_bf16 v[98:101], v[178:181], v[210:213], v[98:101]
	s_setprio 1
	s_barrier
	v_lshl_add_u64 v[238:239], s[8:9], 0, v[136:137]
	v_readfirstlane_b32 s3, v150
	v_lshl_add_u64 v[240:241], v[238:239], 0, s[28:29]
	s_mov_b32 m0, s3
	ds_read_b128 v[216:219], v165
	ds_read_b128 v[226:229], v165 offset:1024
	ds_read_b128 v[230:233], v165 offset:2048
	ds_read_b128 v[234:237], v165 offset:3072
	global_load_lds_dwordx4 v[240:241], off
	v_lshl_add_u64 v[240:241], s[8:9], 0, v[138:139]
	v_readfirstlane_b32 s3, v152
	v_lshl_add_u64 v[242:243], v[240:241], 0, s[28:29]
	s_mov_b32 m0, s3
	s_nop 0
	global_load_lds_dwordx4 v[242:243], off
	s_barrier
	s_waitcnt lgkmcnt(0)
	s_setprio 0
	s_waitcnt lgkmcnt(0)
	v_mfma_f32_16x16x32_bf16 v[94:97], v[216:219], v[182:185], v[94:97]
	v_mfma_f32_16x16x32_bf16 v[90:93], v[230:233], v[182:185], v[90:93]
	v_mfma_f32_16x16x32_bf16 v[86:89], v[216:219], v[190:193], v[86:89]
	v_mfma_f32_16x16x32_bf16 v[82:85], v[230:233], v[190:193], v[82:85]
	v_mfma_f32_16x16x32_bf16 v[78:81], v[216:219], v[198:201], v[78:81]
	v_mfma_f32_16x16x32_bf16 v[74:77], v[230:233], v[198:201], v[74:77]
	v_mfma_f32_16x16x32_bf16 v[70:73], v[216:219], v[206:209], v[70:73]
	v_mfma_f32_16x16x32_bf16 v[66:69], v[230:233], v[206:209], v[66:69]
	v_mfma_f32_16x16x32_bf16 v[94:97], v[226:229], v[186:189], v[94:97]
	v_mfma_f32_16x16x32_bf16 v[90:93], v[234:237], v[186:189], v[90:93]
	v_mfma_f32_16x16x32_bf16 v[86:89], v[226:229], v[194:197], v[86:89]
	v_mfma_f32_16x16x32_bf16 v[82:85], v[234:237], v[194:197], v[82:85]
	v_mfma_f32_16x16x32_bf16 v[78:81], v[226:229], v[202:205], v[78:81]
	v_mfma_f32_16x16x32_bf16 v[74:77], v[234:237], v[202:205], v[74:77]
	v_mfma_f32_16x16x32_bf16 v[70:73], v[226:229], v[210:213], v[70:73]
	v_mfma_f32_16x16x32_bf16 v[66:69], v[234:237], v[210:213], v[66:69]
	s_setprio 1
	v_readfirstlane_b32 s3, v149
	v_lshl_add_u64 v[242:243], v[222:223], 0, s[42:43]
	s_mov_b32 m0, s3
	v_readfirstlane_b32 s3, v153
	s_barrier
	ds_read_b128 v[182:185], v148 offset:16384
	ds_read_b128 v[186:189], v148 offset:17408
	ds_read_b128 v[190:193], v147 offset:16384
	ds_read_b128 v[194:197], v147 offset:17408
	ds_read_b128 v[198:201], v146 offset:16384
	ds_read_b128 v[202:205], v146 offset:17408
	ds_read_b128 v[206:209], v141 offset:16384
	ds_read_b128 v[210:213], v141 offset:17408
	global_load_lds_dwordx4 v[242:243], off
	v_lshl_add_u64 v[242:243], v[224:225], 0, s[42:43]
	s_mov_b32 m0, s3
	s_nop 0
	global_load_lds_dwordx4 v[242:243], off
	s_barrier
	s_waitcnt lgkmcnt(0)
	s_setprio 0
	s_waitcnt lgkmcnt(0)
	v_mfma_f32_16x16x32_bf16 v[60:63], v[142:145], v[182:185], v[60:63]
	v_mfma_f32_16x16x32_bf16 v[56:59], v[174:177], v[182:185], v[56:59]
	v_mfma_f32_16x16x32_bf16 v[52:55], v[142:145], v[190:193], v[52:55]
	v_mfma_f32_16x16x32_bf16 v[48:51], v[174:177], v[190:193], v[48:51]
	v_mfma_f32_16x16x32_bf16 v[44:47], v[142:145], v[198:201], v[44:47]
	v_mfma_f32_16x16x32_bf16 v[40:43], v[174:177], v[198:201], v[40:43]
	v_mfma_f32_16x16x32_bf16 v[36:39], v[142:145], v[206:209], v[36:39]
	v_mfma_f32_16x16x32_bf16 v[32:35], v[174:177], v[206:209], v[32:35]
	v_mfma_f32_16x16x32_bf16 v[60:63], v[170:173], v[186:189], v[60:63]
	v_mfma_f32_16x16x32_bf16 v[56:59], v[178:181], v[186:189], v[56:59]
	v_mfma_f32_16x16x32_bf16 v[52:55], v[170:173], v[194:197], v[52:55]
	v_mfma_f32_16x16x32_bf16 v[48:51], v[178:181], v[194:197], v[48:51]
	v_mfma_f32_16x16x32_bf16 v[44:47], v[170:173], v[202:205], v[44:47]
	v_mfma_f32_16x16x32_bf16 v[40:43], v[178:181], v[202:205], v[40:43]
	v_mfma_f32_16x16x32_bf16 v[36:39], v[170:173], v[210:213], v[36:39]
	v_mfma_f32_16x16x32_bf16 v[32:35], v[178:181], v[210:213], v[32:35]
	s_setprio 1
	s_barrier
; #define STAGE_A(b, h, kt) { const u16* ap_ = A + (size_t)((h) * ahalf + (unsigned)(kt) * 64u); glds16(ap_ + ao0, l0 + SA_(b, h)); glds16(ap_ + ao1, l0 + SA_(b, h) + 8192); }
; #define STAGE_B(b, h, kt) { const u16* bp_ = ((h) ? B1 : B0) + (unsigned)(kt) * 64u; glds16(bp_ + bo0, l0 + SB_(b, h)); glds16(bp_ + bo1, l0 + SB_(b, h) + 8192); }
; #define LDA(dst, b, h) _Pragma("unroll") for (int m = 0; m < 4; ++m) _Pragma("unroll") for (int k = 0; k < 2; ++k) \
;     dst[m][k] = *(const bf16x8*)(lds + SA_(b, h) + lds_byte(wr * 64 + m * 16 + fr, k * 32 + fq * 8));
; #define LDB(dst, b, h) _Pragma("unroll") for (int n = 0; n < 2; ++n) _Pragma("unroll") for (int k = 0; k < 2; ++k) \
;     dst[n][k] = *(const bf16x8*)(lds + SB_(b, h) + lds_byte(wc * 32 + n * 16 + fr, k * 32 + fq * 8));
; #define MMA(ai, bj, At_, Bt_) { __builtin_amdgcn_s_setprio(1); \
;     _Pragma("unroll") for (int m = 0; m < 4; ++m) _Pragma("unroll") for (int n = 0; n < 2; ++n) _Pragma("unroll") for (int k = 0; k < 2; ++k) \
;       acc[ai][bj][m][n] = MFMA16(Bt_[n][k], At_[m][k], acc[ai][bj][m][n]); \
;     __builtin_amdgcn_s_setprio(0); }
; #define WAIT_V(n) asm volatile("s_waitcnt vmcnt(" #n ")" ::: "memory");
; #define WAIT_L(n) asm volatile("s_waitcnt lgkmcnt(" #n ")" ::: "memory");
; #define BAR __builtin_amdgcn_s_barrier();
; #define SCHED __builtin_amdgcn_sched_barrier(0);
; DI void gemm256(const u16* __restrict__ A, int lda, const u16* __restrict__ B0, const u16* __restrict__ B1, int ldb, int nt, acc_t& acc, char* lds) {
;     ...
;     WAIT_V(6) BAR MMA(1, 1, At, Bq1) BAR
;     LDB(Bq0, 1, 0) SCHED LDA(At, 1, 0) STAGE_A(0, 1, t + 2)
;     WAIT_L(8) BAR WAIT_L(0) MMA(0, 0, At, Bq0) BAR SCHED
;     LDB(Bq1, 1, 1) STAGE_B(1, 0, t + 3)
;     BAR WAIT_L(0) MMA(0, 1, At, Bq1) BAR
;     LDA(At, 1, 1) STAGE_A(1, 0, t + 3)
;     BAR WAIT_L(0) MMA(1, 0, At, Bq0) BAR SCHED
;     STAGE_B(1, 1, t + 3)
	v_readfirstlane_b32 s3, v154
	v_lshl_add_u64 v[142:143], v[238:239], 0, s[46:47]
	s_mov_b32 m0, s3
	v_readfirstlane_b32 s3, v156
	global_load_lds_dwordx4 v[142:143], off
	v_lshl_add_u64 v[142:143], v[240:241], 0, s[46:47]
	s_mov_b32 m0, s3
	s_nop 0
	global_load_lds_dwordx4 v[142:143], off
	s_waitcnt vmcnt(6)
	s_barrier
	s_setprio 0
	v_mfma_f32_16x16x32_bf16 v[28:31], v[216:219], v[182:185], v[28:31]
	v_mfma_f32_16x16x32_bf16 v[24:27], v[230:233], v[182:185], v[24:27]
	v_mfma_f32_16x16x32_bf16 v[20:23], v[216:219], v[190:193], v[20:23]
	v_mfma_f32_16x16x32_bf16 v[16:19], v[230:233], v[190:193], v[16:19]
	v_mfma_f32_16x16x32_bf16 v[12:15], v[216:219], v[198:201], v[12:15]
	v_mfma_f32_16x16x32_bf16 v[8:11], v[230:233], v[198:201], v[8:11]
	v_mfma_f32_16x16x32_bf16 v[4:7], v[216:219], v[206:209], v[4:7]
	v_mfma_f32_16x16x32_bf16 v[0:3], v[230:233], v[206:209], v[0:3]
	v_mfma_f32_16x16x32_bf16 v[28:31], v[226:229], v[186:189], v[28:31]
	v_mfma_f32_16x16x32_bf16 v[24:27], v[234:237], v[186:189], v[24:27]
	v_mfma_f32_16x16x32_bf16 v[20:23], v[226:229], v[194:197], v[20:23]
	v_mfma_f32_16x16x32_bf16 v[16:19], v[234:237], v[194:197], v[16:19]
	v_mfma_f32_16x16x32_bf16 v[12:15], v[226:229], v[202:205], v[12:15]
	v_mfma_f32_16x16x32_bf16 v[8:11], v[234:237], v[202:205], v[8:11]
	v_mfma_f32_16x16x32_bf16 v[4:7], v[226:229], v[210:213], v[4:7]
	v_mfma_f32_16x16x32_bf16 v[0:3], v[234:237], v[210:213], v[0:3]
	s_setprio 1
	s_barrier
	ds_read_b128 v[142:145], v155
	ds_read_b128 v[170:173], v155 offset:1024
	ds_read_b128 v[174:177], v155 offset:2048
	ds_read_b128 v[178:181], v155 offset:3072
	v_readfirstlane_b32 s3, v157
	v_lshl_add_u64 v[216:217], v[222:223], 0, s[48:49]
	s_mov_b32 m0, s3
	v_readfirstlane_b32 s3, v158
	ds_read_b128 v[182:185], v148 offset:32768
	ds_read_b128 v[186:189], v148 offset:33792
	ds_read_b128 v[190:193], v147 offset:32768
	ds_read_b128 v[194:197], v147 offset:33792
	ds_read_b128 v[198:201], v146 offset:32768
	ds_read_b128 v[202:205], v146 offset:33792
	ds_read_b128 v[206:209], v141 offset:32768
	ds_read_b128 v[210:213], v141 offset:33792
	global_load_lds_dwordx4 v[216:217], off
	v_lshl_add_u64 v[216:217], v[224:225], 0, s[48:49]
	s_mov_b32 m0, s3
	s_nop 0
	global_load_lds_dwordx4 v[216:217], off
	s_waitcnt lgkmcnt(8)
	s_barrier
	s_waitcnt lgkmcnt(0)
	s_setprio 0
	s_waitcnt lgkmcnt(0)
	v_mfma_f32_16x16x32_bf16 v[126:129], v[142:145], v[182:185], v[126:129]
	v_mfma_f32_16x16x32_bf16 v[122:125], v[174:177], v[182:185], v[122:125]
	v_mfma_f32_16x16x32_bf16 v[118:121], v[142:145], v[190:193], v[118:121]
	v_mfma_f32_16x16x32_bf16 v[114:117], v[174:177], v[190:193], v[114:117]
	v_mfma_f32_16x16x32_bf16 v[110:113], v[142:145], v[198:201], v[110:113]
	v_mfma_f32_16x16x32_bf16 v[106:109], v[174:177], v[198:201], v[106:109]
	v_mfma_f32_16x16x32_bf16 v[102:105], v[142:145], v[206:209], v[102:105]
	v_mfma_f32_16x16x32_bf16 v[98:101], v[174:177], v[206:209], v[98:101]
	v_mfma_f32_16x16x32_bf16 v[126:129], v[170:173], v[186:189], v[126:129]
	v_mfma_f32_16x16x32_bf16 v[122:125], v[178:181], v[186:189], v[122:125]
	v_mfma_f32_16x16x32_bf16 v[118:121], v[170:173], v[194:197], v[118:121]
	v_mfma_f32_16x16x32_bf16 v[114:117], v[178:181], v[194:197], v[114:117]
	v_mfma_f32_16x16x32_bf16 v[110:113], v[170:173], v[202:205], v[110:113]
	v_mfma_f32_16x16x32_bf16 v[106:109], v[178:181], v[202:205], v[106:109]
	v_mfma_f32_16x16x32_bf16 v[102:105], v[170:173], v[210:213], v[102:105]
	v_mfma_f32_16x16x32_bf16 v[98:101], v[178:181], v[210:213], v[98:101]
	s_setprio 1
	s_barrier
	v_readfirstlane_b32 s3, v159
	v_lshl_add_u64 v[242:243], v[238:239], 0, s[50:51]
	s_mov_b32 m0, s3
	v_readfirstlane_b32 s3, v160
	ds_read_b128 v[216:219], v151
	ds_read_b128 v[226:229], v151 offset:1024
	ds_read_b128 v[230:233], v151 offset:2048
	ds_read_b128 v[234:237], v151 offset:3072
	global_load_lds_dwordx4 v[242:243], off
	v_lshl_add_u64 v[242:243], v[240:241], 0, s[50:51]
	s_mov_b32 m0, s3
	s_nop 0
	global_load_lds_dwordx4 v[242:243], off
	s_barrier
	s_waitcnt lgkmcnt(0)
	s_setprio 0
	s_waitcnt lgkmcnt(0)
	v_mfma_f32_16x16x32_bf16 v[94:97], v[216:219], v[182:185], v[94:97]
	v_mfma_f32_16x16x32_bf16 v[90:93], v[230:233], v[182:185], v[90:93]
	v_mfma_f32_16x16x32_bf16 v[86:89], v[216:219], v[190:193], v[86:89]
	v_mfma_f32_16x16x32_bf16 v[82:85], v[230:233], v[190:193], v[82:85]
	v_mfma_f32_16x16x32_bf16 v[78:81], v[216:219], v[198:201], v[78:81]
	v_mfma_f32_16x16x32_bf16 v[74:77], v[230:233], v[198:201], v[74:77]
	v_mfma_f32_16x16x32_bf16 v[70:73], v[216:219], v[206:209], v[70:73]
	v_mfma_f32_16x16x32_bf16 v[66:69], v[230:233], v[206:209], v[66:69]
	v_mfma_f32_16x16x32_bf16 v[94:97], v[226:229], v[186:189], v[94:97]
	v_mfma_f32_16x16x32_bf16 v[90:93], v[234:237], v[186:189], v[90:93]
	v_mfma_f32_16x16x32_bf16 v[86:89], v[226:229], v[194:197], v[86:89]
	v_mfma_f32_16x16x32_bf16 v[82:85], v[234:237], v[194:197], v[82:85]
	v_mfma_f32_16x16x32_bf16 v[78:81], v[226:229], v[202:205], v[78:81]
	v_mfma_f32_16x16x32_bf16 v[74:77], v[234:237], v[202:205], v[74:77]
	v_mfma_f32_16x16x32_bf16 v[70:73], v[226:229], v[210:213], v[70:73]
	v_mfma_f32_16x16x32_bf16 v[66:69], v[234:237], v[210:213], v[66:69]
	s_setprio 1
	v_readfirstlane_b32 s3, v161
	v_lshl_add_u64 v[222:223], v[222:223], 0, s[52:53]
	s_mov_b32 m0, s3
	v_readfirstlane_b32 s3, v162
	s_barrier
	ds_read_b128 v[182:185], v148 offset:49152
	ds_read_b128 v[186:189], v148 offset:50176
	ds_read_b128 v[190:193], v147 offset:49152
	ds_read_b128 v[194:197], v147 offset:50176
	ds_read_b128 v[198:201], v146 offset:49152
	ds_read_b128 v[202:205], v146 offset:50176
	ds_read_b128 v[206:209], v141 offset:49152
	ds_read_b128 v[210:213], v141 offset:50176
	global_load_lds_dwordx4 v[222:223], off
	v_lshl_add_u64 v[222:223], v[224:225], 0, s[52:53]
	s_mov_b32 m0, s3
	s_nop 0
	global_load_lds_dwordx4 v[222:223], off
	s_barrier
; #define STAGE_A(b, h, kt) { const u16* ap_ = A + (size_t)((h) * ahalf + (unsigned)(kt) * 64u); glds16(ap_ + ao0, l0 + SA_(b, h)); glds16(ap_ + ao1, l0 + SA_(b, h) + 8192); }
; #define STAGE_B(b, h, kt) { const u16* bp_ = ((h) ? B1 : B0) + (unsigned)(kt) * 64u; glds16(bp_ + bo0, l0 + SB_(b, h)); glds16(bp_ + bo1, l0 + SB_(b, h) + 8192); }
; #define LDA(dst, b, h) _Pragma("unroll") for (int m = 0; m < 4; ++m) _Pragma("unroll") for (int k = 0; k < 2; ++k) \
;     dst[m][k] = *(const bf16x8*)(lds + SA_(b, h) + lds_byte(wr * 64 + m * 16 + fr, k * 32 + fq * 8));
; #define LDB(dst, b, h) _Pragma("unroll") for (int n = 0; n < 2; ++n) _Pragma("unroll") for (int k = 0; k < 2; ++k) \
;     dst[n][k] = *(const bf16x8*)(lds + SB_(b, h) + lds_byte(wc * 32 + n * 16 + fr, k * 32 + fq * 8));
; #define MMA(ai, bj, At_, Bt_) { __builtin_amdgcn_s_setprio(1); \
;     _Pragma("unroll") for (int m = 0; m < 4; ++m) _Pragma("unroll") for (int n = 0; n < 2; ++n) _Pragma("unroll") for (int k = 0; k < 2; ++k) \
;       acc[ai][bj][m][n] = MFMA16(Bt_[n][k], At_[m][k], acc[ai][bj][m][n]); \
;     __builtin_amdgcn_s_setprio(0); }
; #define WAIT_V(n) asm volatile("s_waitcnt vmcnt(" #n ")" ::: "memory");
; #define WAIT_L(n) asm volatile("s_waitcnt lgkmcnt(" #n ")" ::: "memory");
; #define BAR __builtin_amdgcn_s_barrier();
; #define SCHED __builtin_amdgcn_sched_barrier(0);
; DI void gemm256(const u16* __restrict__ A, int lda, const u16* __restrict__ B0, const u16* __restrict__ B1, int ldb, int nt, acc_t& acc, char* lds) {
;     ...
;     BAR WAIT_L(0) MMA(1, 0, At, Bq0) BAR SCHED
;     STAGE_B(1, 1, t + 3)
;     WAIT_V(6) BAR MMA(1, 1, At, Bq1) BAR
;   }
;   { LDB(Bq0, 0, 0) LDA(At, 0, 0) STAGE_A(1, 1, nt - 1)
;     BAR WAIT_L(0) MMA(0, 0, At, Bq0) BAR
;     LDB(Bq1, 0, 1) BAR WAIT_L(0) MMA(0, 1, At, Bq1) BAR
	s_waitcnt lgkmcnt(0)
	s_setprio 0
	s_waitcnt lgkmcnt(0)
	v_mfma_f32_16x16x32_bf16 v[60:63], v[142:145], v[182:185], v[60:63]
	v_mfma_f32_16x16x32_bf16 v[56:59], v[174:177], v[182:185], v[56:59]
	v_mfma_f32_16x16x32_bf16 v[52:55], v[142:145], v[190:193], v[52:55]
	v_mfma_f32_16x16x32_bf16 v[48:51], v[174:177], v[190:193], v[48:51]
	v_mfma_f32_16x16x32_bf16 v[44:47], v[142:145], v[198:201], v[44:47]
	v_mfma_f32_16x16x32_bf16 v[40:43], v[174:177], v[198:201], v[40:43]
	v_mfma_f32_16x16x32_bf16 v[36:39], v[142:145], v[206:209], v[36:39]
	v_mfma_f32_16x16x32_bf16 v[32:35], v[174:177], v[206:209], v[32:35]
	v_mfma_f32_16x16x32_bf16 v[60:63], v[170:173], v[186:189], v[60:63]
	v_mfma_f32_16x16x32_bf16 v[56:59], v[178:181], v[186:189], v[56:59]
	v_mfma_f32_16x16x32_bf16 v[52:55], v[170:173], v[194:197], v[52:55]
	v_mfma_f32_16x16x32_bf16 v[48:51], v[178:181], v[194:197], v[48:51]
	v_mfma_f32_16x16x32_bf16 v[44:47], v[170:173], v[202:205], v[44:47]
	v_mfma_f32_16x16x32_bf16 v[40:43], v[178:181], v[202:205], v[40:43]
	v_mfma_f32_16x16x32_bf16 v[36:39], v[170:173], v[210:213], v[36:39]
	v_mfma_f32_16x16x32_bf16 v[32:35], v[178:181], v[210:213], v[32:35]
	s_setprio 1
	s_barrier
	v_readfirstlane_b32 s3, v163
	v_lshl_add_u64 v[142:143], v[238:239], 0, s[54:55]
	s_mov_b32 m0, s3
	v_readfirstlane_b32 s3, v164
	global_load_lds_dwordx4 v[142:143], off
	v_lshl_add_u64 v[142:143], v[240:241], 0, s[54:55]
	s_mov_b32 m0, s3
	s_nop 0
	global_load_lds_dwordx4 v[142:143], off
	s_waitcnt vmcnt(6)
	s_barrier
	s_setprio 0
	v_mfma_f32_16x16x32_bf16 v[28:31], v[216:219], v[182:185], v[28:31]
	v_mfma_f32_16x16x32_bf16 v[24:27], v[230:233], v[182:185], v[24:27]
	v_mfma_f32_16x16x32_bf16 v[20:23], v[216:219], v[190:193], v[20:23]
	v_mfma_f32_16x16x32_bf16 v[16:19], v[230:233], v[190:193], v[16:19]
	v_mfma_f32_16x16x32_bf16 v[12:15], v[216:219], v[198:201], v[12:15]
	v_mfma_f32_16x16x32_bf16 v[8:11], v[230:233], v[198:201], v[8:11]
	v_mfma_f32_16x16x32_bf16 v[4:7], v[216:219], v[206:209], v[4:7]
	v_mfma_f32_16x16x32_bf16 v[0:3], v[230:233], v[206:209], v[0:3]
	v_mfma_f32_16x16x32_bf16 v[28:31], v[226:229], v[186:189], v[28:31]
	v_mfma_f32_16x16x32_bf16 v[24:27], v[234:237], v[186:189], v[24:27]
	v_mfma_f32_16x16x32_bf16 v[20:23], v[226:229], v[194:197], v[20:23]
	v_mfma_f32_16x16x32_bf16 v[16:19], v[234:237], v[194:197], v[16:19]
	v_mfma_f32_16x16x32_bf16 v[12:15], v[226:229], v[202:205], v[12:15]
	v_mfma_f32_16x16x32_bf16 v[8:11], v[234:237], v[202:205], v[8:11]
	v_mfma_f32_16x16x32_bf16 v[4:7], v[226:229], v[210:213], v[4:7]
	v_mfma_f32_16x16x32_bf16 v[0:3], v[234:237], v[210:213], v[0:3]
	s_setprio 1
	s_add_i32 s2, s2, 2
	s_add_u32 s8, s8, 0x100
	s_addc_u32 s9, s9, 0
	s_cmp_lt_u32 s2, 4
	s_barrier
	s_cbranch_scc1 .LBB0_991
	s_add_u32 s2, s44, 0x40780
	s_addc_u32 s3, s45, 0
	v_readfirstlane_b32 s7, v167
	v_lshl_add_u64 v[152:153], v[64:65], 1, s[2:3]
	s_mov_b32 m0, s7
	v_lshl_add_u64 v[130:131], v[130:131], 1, s[2:3]
	v_readfirstlane_b32 s2, v168
	ds_read_b128 v[132:135], v166
	ds_read_b128 v[136:139], v166 offset:1024
	ds_read_b128 v[142:145], v166 offset:2048
	ds_read_b128 v[156:159], v166 offset:3072
	ds_read_b128 v[160:163], v148
	ds_read_b128 v[170:173], v148 offset:1024
	ds_read_b128 v[174:177], v147
	ds_read_b128 v[178:181], v147 offset:1024
	ds_read_b128 v[182:185], v146
	ds_read_b128 v[186:189], v146 offset:1024
	ds_read_b128 v[190:193], v141
	ds_read_b128 v[194:197], v141 offset:1024
	global_load_lds_dwordx4 v[152:153], off
	s_mov_b32 m0, s2
	s_nop 0
	global_load_lds_dwordx4 v[130:131], off
	s_barrier
	s_waitcnt lgkmcnt(0)
	s_setprio 0
	s_waitcnt lgkmcnt(0)
	v_mfma_f32_16x16x32_bf16 v[126:129], v[132:135], v[160:163], v[126:129]
	v_mfma_f32_16x16x32_bf16 v[122:125], v[142:145], v[160:163], v[122:125]
	v_mfma_f32_16x16x32_bf16 v[118:121], v[132:135], v[174:177], v[118:121]
	v_mfma_f32_16x16x32_bf16 v[114:117], v[142:145], v[174:177], v[114:117]
	v_mfma_f32_16x16x32_bf16 v[102:105], v[132:135], v[190:193], v[102:105]
	v_mfma_f32_16x16x32_bf16 v[98:101], v[142:145], v[190:193], v[98:101]
	v_mfma_f32_16x16x32_bf16 v[126:129], v[136:139], v[170:173], v[126:129]
	v_mfma_f32_16x16x32_bf16 v[122:125], v[156:159], v[170:173], v[122:125]
	v_mfma_f32_16x16x32_bf16 v[118:121], v[136:139], v[178:181], v[118:121]
	v_mfma_f32_16x16x32_bf16 v[114:117], v[156:159], v[178:181], v[114:117]
	v_mfma_f32_16x16x32_bf16 v[110:113], v[132:135], v[182:185], v[110:113]
	v_mfma_f32_16x16x32_bf16 v[106:109], v[142:145], v[182:185], v[106:109]
	v_mfma_f32_16x16x32_bf16 v[102:105], v[136:139], v[194:197], v[102:105]
	v_mfma_f32_16x16x32_bf16 v[98:101], v[156:159], v[194:197], v[98:101]
	v_mfma_f32_16x16x32_bf16 v[166:169], v[136:139], v[186:189], v[110:113]
	v_mfma_f32_16x16x32_bf16 v[198:201], v[156:159], v[186:189], v[106:109]
	s_setprio 1
	s_barrier
	s_nop 1
	ds_read_b128 v[106:109], v165
	ds_read_b128 v[110:113], v165 offset:1024
	ds_read_b128 v[202:205], v165 offset:2048
	ds_read_b128 v[206:209], v165 offset:3072
	s_barrier
	s_waitcnt lgkmcnt(0)
	s_setprio 0
	s_waitcnt lgkmcnt(0)
	v_mfma_f32_16x16x32_bf16 v[86:89], v[106:109], v[174:177], v[86:89]
	v_mfma_f32_16x16x32_bf16 v[82:85], v[202:205], v[174:177], v[82:85]
	v_mfma_f32_16x16x32_bf16 v[70:73], v[106:109], v[190:193], v[70:73]
	v_mfma_f32_16x16x32_bf16 v[66:69], v[202:205], v[190:193], v[66:69]
	v_mfma_f32_16x16x32_bf16 v[94:97], v[106:109], v[160:163], v[94:97]
	v_mfma_f32_16x16x32_bf16 v[90:93], v[202:205], v[160:163], v[90:93]
	v_mfma_f32_16x16x32_bf16 v[86:89], v[110:113], v[178:181], v[86:89]
	v_mfma_f32_16x16x32_bf16 v[82:85], v[206:209], v[178:181], v[82:85]
	v_mfma_f32_16x16x32_bf16 v[78:81], v[106:109], v[182:185], v[78:81]
	v_mfma_f32_16x16x32_bf16 v[74:77], v[202:205], v[182:185], v[74:77]
	v_mfma_f32_16x16x32_bf16 v[70:73], v[110:113], v[194:197], v[70:73]
	v_mfma_f32_16x16x32_bf16 v[66:69], v[206:209], v[194:197], v[66:69]
	v_mfma_f32_16x16x32_bf16 v[210:213], v[110:113], v[170:173], v[94:97]
	v_mfma_f32_16x16x32_bf16 v[160:163], v[206:209], v[170:173], v[90:93]
	v_mfma_f32_16x16x32_bf16 v[170:173], v[110:113], v[186:189], v[78:81]
	v_mfma_f32_16x16x32_bf16 v[174:177], v[206:209], v[186:189], v[74:77]
	s_setprio 1
	s_barrier
; #define LDA(dst, b, h) _Pragma("unroll") for (int m = 0; m < 4; ++m) _Pragma("unroll") for (int k = 0; k < 2; ++k) \
;     dst[m][k] = *(const bf16x8*)(lds + SA_(b, h) + lds_byte(wr * 64 + m * 16 + fr, k * 32 + fq * 8));
; #define LDB(dst, b, h) _Pragma("unroll") for (int n = 0; n < 2; ++n) _Pragma("unroll") for (int k = 0; k < 2; ++k) \
;     dst[n][k] = *(const bf16x8*)(lds + SB_(b, h) + lds_byte(wc * 32 + n * 16 + fr, k * 32 + fq * 8));
; #define MMA(ai, bj, At_, Bt_) { __builtin_amdgcn_s_setprio(1); \
;     _Pragma("unroll") for (int m = 0; m < 4; ++m) _Pragma("unroll") for (int n = 0; n < 2; ++n) _Pragma("unroll") for (int k = 0; k < 2; ++k) \
;       acc[ai][bj][m][n] = MFMA16(Bt_[n][k], At_[m][k], acc[ai][bj][m][n]); \
;     __builtin_amdgcn_s_setprio(0); }
; #define WAIT_V(n) asm volatile("s_waitcnt vmcnt(" #n ")" ::: "memory");
; #define WAIT_L(n) asm volatile("s_waitcnt lgkmcnt(" #n ")" ::: "memory");
; #define BAR __builtin_amdgcn_s_barrier();
; DI void gemm256(const u16* __restrict__ A, int lda, const u16* __restrict__ B0, const u16* __restrict__ B1, int ldb, int nt, acc_t& acc, char* lds) {
;     ...
;     LDA(At, 0, 1) WAIT_V(4) BAR WAIT_L(0) MMA(1, 0, At, Bq0) MMA(1, 1, At, Bq1) BAR }
;   { LDB(Bq0, 1, 0) LDA(At, 1, 0) WAIT_V(2) BAR WAIT_L(0) MMA(0, 0, At, Bq0) BAR
	s_nop 0
	ds_read_b128 v[74:77], v148 offset:16384
	ds_read_b128 v[78:81], v148 offset:17408
	ds_read_b128 v[90:93], v147 offset:16384
	ds_read_b128 v[94:97], v147 offset:17408
	ds_read_b128 v[178:181], v146 offset:16384
	ds_read_b128 v[182:185], v146 offset:17408
	ds_read_b128 v[186:189], v141 offset:16384
	ds_read_b128 v[190:193], v141 offset:17408
	s_waitcnt vmcnt(4)
	s_barrier
	s_waitcnt lgkmcnt(0)
	s_setprio 0
	s_waitcnt lgkmcnt(0)
	v_mfma_f32_16x16x32_bf16 v[60:63], v[132:135], v[74:77], v[60:63]
	v_mfma_f32_16x16x32_bf16 v[56:59], v[142:145], v[74:77], v[56:59]
	v_mfma_f32_16x16x32_bf16 v[52:55], v[132:135], v[90:93], v[52:55]
	v_mfma_f32_16x16x32_bf16 v[48:51], v[142:145], v[90:93], v[48:51]
	v_mfma_f32_16x16x32_bf16 v[36:39], v[132:135], v[186:189], v[36:39]
	v_mfma_f32_16x16x32_bf16 v[32:35], v[142:145], v[186:189], v[32:35]
	v_mfma_f32_16x16x32_bf16 v[60:63], v[136:139], v[78:81], v[60:63]
	v_mfma_f32_16x16x32_bf16 v[56:59], v[156:159], v[78:81], v[56:59]
	v_mfma_f32_16x16x32_bf16 v[52:55], v[136:139], v[94:97], v[52:55]
	v_mfma_f32_16x16x32_bf16 v[48:51], v[156:159], v[94:97], v[48:51]
	v_mfma_f32_16x16x32_bf16 v[44:47], v[132:135], v[178:181], v[44:47]
	v_mfma_f32_16x16x32_bf16 v[40:43], v[142:145], v[178:181], v[40:43]
	v_mfma_f32_16x16x32_bf16 v[36:39], v[136:139], v[190:193], v[36:39]
	v_mfma_f32_16x16x32_bf16 v[32:35], v[156:159], v[190:193], v[32:35]
	v_mfma_f32_16x16x32_bf16 v[194:197], v[136:139], v[182:185], v[44:47]
	v_mfma_f32_16x16x32_bf16 v[216:219], v[156:159], v[182:185], v[40:43]
	s_setprio 1
	s_setprio 0
	v_mfma_f32_16x16x32_bf16 v[20:23], v[106:109], v[90:93], v[20:23]
	v_mfma_f32_16x16x32_bf16 v[16:19], v[202:205], v[90:93], v[16:19]
	v_mfma_f32_16x16x32_bf16 v[4:7], v[106:109], v[186:189], v[4:7]
	v_mfma_f32_16x16x32_bf16 v[0:3], v[202:205], v[186:189], v[0:3]
	v_mfma_f32_16x16x32_bf16 v[28:31], v[106:109], v[74:77], v[28:31]
	v_mfma_f32_16x16x32_bf16 v[24:27], v[202:205], v[74:77], v[24:27]
	v_mfma_f32_16x16x32_bf16 v[20:23], v[110:113], v[94:97], v[20:23]
	v_mfma_f32_16x16x32_bf16 v[16:19], v[206:209], v[94:97], v[16:19]
	v_mfma_f32_16x16x32_bf16 v[12:15], v[106:109], v[178:181], v[12:15]
	v_mfma_f32_16x16x32_bf16 v[8:11], v[202:205], v[178:181], v[8:11]
	v_mfma_f32_16x16x32_bf16 v[4:7], v[110:113], v[190:193], v[4:7]
	v_mfma_f32_16x16x32_bf16 v[0:3], v[206:209], v[190:193], v[0:3]
	v_mfma_f32_16x16x32_bf16 v[130:133], v[110:113], v[78:81], v[28:31]
	v_mfma_f32_16x16x32_bf16 v[134:137], v[206:209], v[78:81], v[24:27]
	v_mfma_f32_16x16x32_bf16 v[142:145], v[110:113], v[182:185], v[12:15]
	v_mfma_f32_16x16x32_bf16 v[156:159], v[206:209], v[182:185], v[8:11]
	s_setprio 1
	s_barrier
	s_nop 0
	ds_read_b128 v[8:11], v155
	ds_read_b128 v[12:15], v155 offset:1024
	ds_read_b128 v[178:181], v155 offset:2048
	ds_read_b128 v[152:155], v155 offset:3072
	ds_read_b128 v[24:27], v148 offset:32768
	ds_read_b128 v[28:31], v148 offset:33792
	ds_read_b128 v[40:43], v147 offset:32768
	ds_read_b128 v[44:47], v147 offset:33792
	ds_read_b128 v[182:185], v146 offset:32768
	ds_read_b128 v[186:189], v146 offset:33792
	ds_read_b128 v[190:193], v141 offset:32768
	ds_read_b128 v[202:205], v141 offset:33792
	s_waitcnt vmcnt(2)
	s_barrier
	s_waitcnt lgkmcnt(0)
	s_setprio 0
	s_waitcnt lgkmcnt(0)
	v_mfma_f32_16x16x32_bf16 v[74:77], v[8:11], v[24:27], v[126:129]
	v_mfma_f32_16x16x32_bf16 v[126:129], v[12:15], v[28:31], v[74:77]
	v_mfma_f32_16x16x32_bf16 v[74:77], v[178:181], v[24:27], v[122:125]
	v_mfma_f32_16x16x32_bf16 v[122:125], v[152:155], v[28:31], v[74:77]
	v_mfma_f32_16x16x32_bf16 v[74:77], v[8:11], v[40:43], v[118:121]
	v_mfma_f32_16x16x32_bf16 v[110:113], v[12:15], v[44:47], v[74:77]
	v_mfma_f32_16x16x32_bf16 v[74:77], v[178:181], v[40:43], v[114:117]
	v_mfma_f32_16x16x32_bf16 v[106:109], v[152:155], v[44:47], v[74:77]
	v_mfma_f32_16x16x32_bf16 v[74:77], v[8:11], v[182:185], v[166:169]
	v_mfma_f32_16x16x32_bf16 v[94:97], v[12:15], v[186:189], v[74:77]
	v_mfma_f32_16x16x32_bf16 v[74:77], v[178:181], v[182:185], v[198:201]
	v_mfma_f32_16x16x32_bf16 v[90:93], v[152:155], v[186:189], v[74:77]
	v_mfma_f32_16x16x32_bf16 v[74:77], v[8:11], v[190:193], v[102:105]
	v_mfma_f32_16x16x32_bf16 v[78:81], v[12:15], v[202:205], v[74:77]
	v_mfma_f32_16x16x32_bf16 v[74:77], v[178:181], v[190:193], v[98:101]
	v_mfma_f32_16x16x32_bf16 v[74:77], v[152:155], v[202:205], v[74:77]
	s_setprio 1
	s_barrier
; #define LDA(dst, b, h) _Pragma("unroll") for (int m = 0; m < 4; ++m) _Pragma("unroll") for (int k = 0; k < 2; ++k) \
;     dst[m][k] = *(const bf16x8*)(lds + SA_(b, h) + lds_byte(wr * 64 + m * 16 + fr, k * 32 + fq * 8));
; #define LDB(dst, b, h) _Pragma("unroll") for (int n = 0; n < 2; ++n) _Pragma("unroll") for (int k = 0; k < 2; ++k) \
;     dst[n][k] = *(const bf16x8*)(lds + SB_(b, h) + lds_byte(wc * 32 + n * 16 + fr, k * 32 + fq * 8));
; #define MMA(ai, bj, At_, Bt_) { __builtin_amdgcn_s_setprio(1); \
;     _Pragma("unroll") for (int m = 0; m < 4; ++m) _Pragma("unroll") for (int n = 0; n < 2; ++n) _Pragma("unroll") for (int k = 0; k < 2; ++k) \
;       acc[ai][bj][m][n] = MFMA16(Bt_[n][k], At_[m][k], acc[ai][bj][m][n]); \
;     __builtin_amdgcn_s_setprio(0); }
; #define WAIT_V(n) asm volatile("s_waitcnt vmcnt(" #n ")" ::: "memory");
; #define WAIT_L(n) asm volatile("s_waitcnt lgkmcnt(" #n ")" ::: "memory");
; #define BAR __builtin_amdgcn_s_barrier();
; DI void gemm256(const u16* __restrict__ A, int lda, const u16* __restrict__ B0, const u16* __restrict__ B1, int ldb, int nt, acc_t& acc, char* lds) {
;     ...
;     LDB(Bq1, 1, 1) WAIT_V(0) BAR WAIT_L(0) MMA(0, 1, At, Bq1) BAR
;     LDA(At, 1, 1) BAR WAIT_L(0) MMA(1, 0, At, Bq0) MMA(1, 1, At, Bq1) BAR }
;   if (wr == 0) BAR
;   __syncthreads();
	ds_read_b128 v[164:167], v151
	ds_read_b128 v[198:201], v151 offset:1024
	ds_read_b128 v[206:209], v151 offset:2048
	ds_read_b128 v[226:229], v151 offset:3072
	s_waitcnt vmcnt(0)
	s_barrier
	s_waitcnt lgkmcnt(0)
	s_setprio 0
	s_waitcnt lgkmcnt(0)
	v_mfma_f32_16x16x32_bf16 v[98:101], v[164:167], v[24:27], v[210:213]
	v_mfma_f32_16x16x32_bf16 v[24:27], v[206:209], v[24:27], v[160:163]
	v_mfma_f32_16x16x32_bf16 v[114:117], v[226:229], v[28:31], v[24:27]
	v_mfma_f32_16x16x32_bf16 v[24:27], v[164:167], v[40:43], v[86:89]
	v_mfma_f32_16x16x32_bf16 v[102:105], v[198:201], v[44:47], v[24:27]
	v_mfma_f32_16x16x32_bf16 v[24:27], v[206:209], v[40:43], v[82:85]
	v_mfma_f32_16x16x32_bf16 v[118:121], v[198:201], v[28:31], v[98:101]
	v_mfma_f32_16x16x32_bf16 v[98:101], v[226:229], v[44:47], v[24:27]
	v_mfma_f32_16x16x32_bf16 v[24:27], v[164:167], v[182:185], v[170:173]
	v_mfma_f32_16x16x32_bf16 v[86:89], v[198:201], v[186:189], v[24:27]
	v_mfma_f32_16x16x32_bf16 v[24:27], v[206:209], v[182:185], v[174:177]
	v_mfma_f32_16x16x32_bf16 v[82:85], v[226:229], v[186:189], v[24:27]
	v_mfma_f32_16x16x32_bf16 v[24:27], v[164:167], v[190:193], v[70:73]
	v_mfma_f32_16x16x32_bf16 v[70:73], v[198:201], v[202:205], v[24:27]
	v_mfma_f32_16x16x32_bf16 v[24:27], v[206:209], v[190:193], v[66:69]
	v_mfma_f32_16x16x32_bf16 v[66:69], v[226:229], v[202:205], v[24:27]
	s_setprio 1
	s_barrier
	ds_read_b128 v[160:163], v148 offset:49152
	ds_read_b128 v[148:151], v148 offset:50176
	ds_read_b128 v[168:171], v147 offset:49152
	ds_read_b128 v[172:175], v147 offset:50176
	ds_read_b128 v[182:185], v146 offset:49152
	ds_read_b128 v[186:189], v146 offset:50176
	ds_read_b128 v[190:193], v141 offset:49152
	ds_read_b128 v[202:205], v141 offset:50176
	s_barrier
	s_waitcnt lgkmcnt(0)
	s_setprio 0
	s_waitcnt lgkmcnt(0)
	v_mfma_f32_16x16x32_bf16 v[24:27], v[8:11], v[160:163], v[60:63]
	v_mfma_f32_16x16x32_bf16 v[60:63], v[12:15], v[148:151], v[24:27]
	v_mfma_f32_16x16x32_bf16 v[24:27], v[178:181], v[160:163], v[56:59]
	v_mfma_f32_16x16x32_bf16 v[56:59], v[152:155], v[148:151], v[24:27]
	v_mfma_f32_16x16x32_bf16 v[24:27], v[8:11], v[168:171], v[52:55]
	v_mfma_f32_16x16x32_bf16 v[44:47], v[12:15], v[172:175], v[24:27]
	v_mfma_f32_16x16x32_bf16 v[24:27], v[178:181], v[168:171], v[48:51]
	v_mfma_f32_16x16x32_bf16 v[40:43], v[152:155], v[172:175], v[24:27]
	v_mfma_f32_16x16x32_bf16 v[24:27], v[8:11], v[182:185], v[194:197]
	v_mfma_f32_16x16x32_bf16 v[8:11], v[8:11], v[190:193], v[36:39]
	v_mfma_f32_16x16x32_bf16 v[28:31], v[12:15], v[186:189], v[24:27]
	v_mfma_f32_16x16x32_bf16 v[24:27], v[178:181], v[182:185], v[216:219]
	v_mfma_f32_16x16x32_bf16 v[12:15], v[12:15], v[202:205], v[8:11]
	v_mfma_f32_16x16x32_bf16 v[8:11], v[178:181], v[190:193], v[32:35]
	v_mfma_f32_16x16x32_bf16 v[24:27], v[152:155], v[186:189], v[24:27]
	v_mfma_f32_16x16x32_bf16 v[8:11], v[152:155], v[202:205], v[8:11]
	s_setprio 1
	s_setprio 0
	v_mfma_f32_16x16x32_bf16 v[32:35], v[164:167], v[160:163], v[130:133]
	v_mfma_f32_16x16x32_bf16 v[52:55], v[198:201], v[148:151], v[32:35]
	v_mfma_f32_16x16x32_bf16 v[32:35], v[206:209], v[160:163], v[134:137]
	v_mfma_f32_16x16x32_bf16 v[16:19], v[206:209], v[168:171], v[16:19]
	v_mfma_f32_16x16x32_bf16 v[48:51], v[226:229], v[148:151], v[32:35]
	v_mfma_f32_16x16x32_bf16 v[20:23], v[164:167], v[168:171], v[20:23]
	v_mfma_f32_16x16x32_bf16 v[32:35], v[226:229], v[172:175], v[16:19]
	v_mfma_f32_16x16x32_bf16 v[16:19], v[164:167], v[182:185], v[142:145]
	v_mfma_f32_16x16x32_bf16 v[36:39], v[198:201], v[172:175], v[20:23]
	v_mfma_f32_16x16x32_bf16 v[20:23], v[198:201], v[186:189], v[16:19]
	v_mfma_f32_16x16x32_bf16 v[16:19], v[206:209], v[182:185], v[156:159]
	v_mfma_f32_16x16x32_bf16 v[4:7], v[164:167], v[190:193], v[4:7]
	v_mfma_f32_16x16x32_bf16 v[0:3], v[206:209], v[190:193], v[0:3]
	v_mfma_f32_16x16x32_bf16 v[16:19], v[226:229], v[186:189], v[16:19]
	v_mfma_f32_16x16x32_bf16 v[4:7], v[198:201], v[202:205], v[4:7]
	v_mfma_f32_16x16x32_bf16 v[0:3], v[226:229], v[202:205], v[0:3]
	s_setprio 1
	s_movk_i32 s2, 0x100
	v_cmp_gt_u32_e32 vcc, s2, v140
	s_barrier
	s_and_saveexec_b64 s[8:9], vcc
	s_cbranch_execz .LBB0_969
	s_barrier
	s_branch .LBB0_969

; #define STAGE_A(b, h, kt) { const u16* ap_ = A + (size_t)((h) * ahalf + (unsigned)(kt) * 64u); glds16(ap_ + ao0, l0 + SA_(b, h)); glds16(ap_ + ao1, l0 + SA_(b, h) + 8192); }
; #define STAGE_B(b, h, kt) { const u16* bp_ = ((h) ? B1 : B0) + (unsigned)(kt) * 64u; glds16(bp_ + bo0, l0 + SB_(b, h)); glds16(bp_ + bo1, l0 + SB_(b, h) + 8192); }
; #define LDA(dst, b, h) _Pragma("unroll") for (int m = 0; m < 4; ++m) _Pragma("unroll") for (int k = 0; k < 2; ++k) \
;     dst[m][k] = *(const bf16x8*)(lds + SA_(b, h) + lds_byte(wr * 64 + m * 16 + fr, k * 32 + fq * 8));
; #define LDB(dst, b, h) _Pragma("unroll") for (int n = 0; n < 2; ++n) _Pragma("unroll") for (int k = 0; k < 2; ++k) \
;     dst[n][k] = *(const bf16x8*)(lds + SB_(b, h) + lds_byte(wc * 32 + n * 16 + fr, k * 32 + fq * 8));
; #define MMA(ai, bj, At_, Bt_) { __builtin_amdgcn_s_setprio(1); \
;     _Pragma("unroll") for (int m = 0; m < 4; ++m) _Pragma("unroll") for (int n = 0; n < 2; ++n) _Pragma("unroll") for (int k = 0; k < 2; ++k) \
;       acc[ai][bj][m][n] = MFMA16(Bt_[n][k], At_[m][k], acc[ai][bj][m][n]); \
;     __builtin_amdgcn_s_setprio(0); }
; #define WAIT_L(n) asm volatile("s_waitcnt lgkmcnt(" #n ")" ::: "memory");
; #define BAR __builtin_amdgcn_s_barrier();
; #define SCHED __builtin_amdgcn_sched_barrier(0);
; DI void gemm256(const u16* __restrict__ A, int lda, const u16* __restrict__ B0, const u16* __restrict__ B1, int ldb, int nt, acc_t& acc, char* lds) {
;     ...
;     LDB(Bq0, 0, 0) SCHED LDA(At, 0, 0) STAGE_A(1, 1, t + 1)
;     WAIT_L(8) BAR WAIT_L(0) MMA(0, 0, At, Bq0) BAR SCHED
;     LDB(Bq1, 0, 1) STAGE_B(0, 0, t + 2)
;     BAR WAIT_L(0) MMA(0, 1, At, Bq1) BAR
;     LDA(At, 0, 1) STAGE_A(0, 0, t + 2)
;     BAR WAIT_L(0) MMA(1, 0, At, Bq0) BAR SCHED
.LBB0_1053:
	ds_read_b128 v[142:145], v166
	ds_read_b128 v[170:173], v166 offset:1024
	ds_read_b128 v[174:177], v166 offset:2048
	ds_read_b128 v[178:181], v166 offset:3072
	v_add_u32_e32 v167, 0xc000, v149
	v_lshl_add_u64 v[222:223], s[36:37], 0, v[136:137]
	v_readfirstlane_b32 s7, v167
	v_lshl_add_u64 v[168:169], v[222:223], 0, s[38:39]
	s_mov_b32 m0, s7
	ds_read_b128 v[182:185], v148
	ds_read_b128 v[186:189], v148 offset:1024
	ds_read_b128 v[190:193], v147
	ds_read_b128 v[194:197], v147 offset:1024
	ds_read_b128 v[198:201], v146
	ds_read_b128 v[202:205], v146 offset:1024
	ds_read_b128 v[206:209], v141
	ds_read_b128 v[210:213], v141 offset:1024
	global_load_lds_dwordx4 v[168:169], off
	v_add_u32_e32 v168, 0xe000, v149
	v_lshl_add_u64 v[224:225], s[36:37], 0, v[138:139]
	v_readfirstlane_b32 s7, v168
	v_lshl_add_u64 v[216:217], v[224:225], 0, s[38:39]
	s_mov_b32 m0, s7
	s_nop 0
	global_load_lds_dwordx4 v[216:217], off
	s_waitcnt lgkmcnt(8)
	s_barrier
	s_waitcnt lgkmcnt(0)
	s_setprio 0
	s_waitcnt lgkmcnt(0)
	v_mfma_f32_16x16x32_bf16 v[126:129], v[142:145], v[182:185], v[126:129]
	v_mfma_f32_16x16x32_bf16 v[122:125], v[174:177], v[182:185], v[122:125]
	v_mfma_f32_16x16x32_bf16 v[118:121], v[142:145], v[190:193], v[118:121]
	v_mfma_f32_16x16x32_bf16 v[114:117], v[174:177], v[190:193], v[114:117]
	v_mfma_f32_16x16x32_bf16 v[110:113], v[142:145], v[198:201], v[110:113]
	v_mfma_f32_16x16x32_bf16 v[106:109], v[174:177], v[198:201], v[106:109]
	v_mfma_f32_16x16x32_bf16 v[102:105], v[142:145], v[206:209], v[102:105]
	v_mfma_f32_16x16x32_bf16 v[98:101], v[174:177], v[206:209], v[98:101]
	v_mfma_f32_16x16x32_bf16 v[126:129], v[170:173], v[186:189], v[126:129]
	v_mfma_f32_16x16x32_bf16 v[122:125], v[178:181], v[186:189], v[122:125]
	v_mfma_f32_16x16x32_bf16 v[118:121], v[170:173], v[194:197], v[118:121]
	v_mfma_f32_16x16x32_bf16 v[114:117], v[178:181], v[194:197], v[114:117]
	v_mfma_f32_16x16x32_bf16 v[110:113], v[170:173], v[202:205], v[110:113]
	v_mfma_f32_16x16x32_bf16 v[106:109], v[178:181], v[202:205], v[106:109]
	v_mfma_f32_16x16x32_bf16 v[102:105], v[170:173], v[210:213], v[102:105]
	v_mfma_f32_16x16x32_bf16 v[98:101], v[178:181], v[210:213], v[98:101]
	s_setprio 1
	s_barrier
	v_lshl_add_u64 v[238:239], s[36:37], 0, v[132:133]
	v_readfirstlane_b32 s7, v150
	v_lshl_add_u64 v[240:241], v[238:239], 0, s[40:41]
	s_mov_b32 m0, s7
	ds_read_b128 v[216:219], v165
	ds_read_b128 v[226:229], v165 offset:1024
	ds_read_b128 v[230:233], v165 offset:2048
	ds_read_b128 v[234:237], v165 offset:3072
	global_load_lds_dwordx4 v[240:241], off
	v_lshl_add_u64 v[240:241], s[36:37], 0, v[134:135]
	v_readfirstlane_b32 s7, v152
	v_lshl_add_u64 v[242:243], v[240:241], 0, s[40:41]
	s_mov_b32 m0, s7
	s_nop 0
	global_load_lds_dwordx4 v[242:243], off
	s_barrier
	s_waitcnt lgkmcnt(0)
	s_setprio 0
	s_waitcnt lgkmcnt(0)
	v_mfma_f32_16x16x32_bf16 v[94:97], v[216:219], v[182:185], v[94:97]
	v_mfma_f32_16x16x32_bf16 v[90:93], v[230:233], v[182:185], v[90:93]
	v_mfma_f32_16x16x32_bf16 v[86:89], v[216:219], v[190:193], v[86:89]
	v_mfma_f32_16x16x32_bf16 v[82:85], v[230:233], v[190:193], v[82:85]
	v_mfma_f32_16x16x32_bf16 v[78:81], v[216:219], v[198:201], v[78:81]
	v_mfma_f32_16x16x32_bf16 v[74:77], v[230:233], v[198:201], v[74:77]
	v_mfma_f32_16x16x32_bf16 v[70:73], v[216:219], v[206:209], v[70:73]
	v_mfma_f32_16x16x32_bf16 v[66:69], v[230:233], v[206:209], v[66:69]
	v_mfma_f32_16x16x32_bf16 v[94:97], v[226:229], v[186:189], v[94:97]
	v_mfma_f32_16x16x32_bf16 v[90:93], v[234:237], v[186:189], v[90:93]
	v_mfma_f32_16x16x32_bf16 v[86:89], v[226:229], v[194:197], v[86:89]
	v_mfma_f32_16x16x32_bf16 v[82:85], v[234:237], v[194:197], v[82:85]
	v_mfma_f32_16x16x32_bf16 v[78:81], v[226:229], v[202:205], v[78:81]
	v_mfma_f32_16x16x32_bf16 v[74:77], v[234:237], v[202:205], v[74:77]
	v_mfma_f32_16x16x32_bf16 v[70:73], v[226:229], v[210:213], v[70:73]
	v_mfma_f32_16x16x32_bf16 v[66:69], v[234:237], v[210:213], v[66:69]
	s_setprio 1
	v_readfirstlane_b32 s7, v149
	v_lshl_add_u64 v[242:243], v[222:223], 0, s[70:71]
	s_mov_b32 m0, s7
	v_readfirstlane_b32 s7, v153
	s_barrier
	ds_read_b128 v[182:185], v148 offset:16384
	ds_read_b128 v[186:189], v148 offset:17408
	ds_read_b128 v[190:193], v147 offset:16384
	ds_read_b128 v[194:197], v147 offset:17408
	ds_read_b128 v[198:201], v146 offset:16384
	ds_read_b128 v[202:205], v146 offset:17408
	ds_read_b128 v[206:209], v141 offset:16384
	ds_read_b128 v[210:213], v141 offset:17408
	global_load_lds_dwordx4 v[242:243], off
	v_lshl_add_u64 v[242:243], v[224:225], 0, s[70:71]
	s_mov_b32 m0, s7
	s_nop 0
	global_load_lds_dwordx4 v[242:243], off
	s_barrier
	s_waitcnt lgkmcnt(0)
	s_setprio 0
	s_waitcnt lgkmcnt(0)
	v_mfma_f32_16x16x32_bf16 v[60:63], v[142:145], v[182:185], v[60:63]
	v_mfma_f32_16x16x32_bf16 v[56:59], v[174:177], v[182:185], v[56:59]
	v_mfma_f32_16x16x32_bf16 v[52:55], v[142:145], v[190:193], v[52:55]
	v_mfma_f32_16x16x32_bf16 v[48:51], v[174:177], v[190:193], v[48:51]
	v_mfma_f32_16x16x32_bf16 v[44:47], v[142:145], v[198:201], v[44:47]
	v_mfma_f32_16x16x32_bf16 v[40:43], v[174:177], v[198:201], v[40:43]
	v_mfma_f32_16x16x32_bf16 v[36:39], v[142:145], v[206:209], v[36:39]
	v_mfma_f32_16x16x32_bf16 v[32:35], v[174:177], v[206:209], v[32:35]
	v_mfma_f32_16x16x32_bf16 v[60:63], v[170:173], v[186:189], v[60:63]
	v_mfma_f32_16x16x32_bf16 v[56:59], v[178:181], v[186:189], v[56:59]
	v_mfma_f32_16x16x32_bf16 v[52:55], v[170:173], v[194:197], v[52:55]
	v_mfma_f32_16x16x32_bf16 v[48:51], v[178:181], v[194:197], v[48:51]
	v_mfma_f32_16x16x32_bf16 v[44:47], v[170:173], v[202:205], v[44:47]
	v_mfma_f32_16x16x32_bf16 v[40:43], v[178:181], v[202:205], v[40:43]
	v_mfma_f32_16x16x32_bf16 v[36:39], v[170:173], v[210:213], v[36:39]
	v_mfma_f32_16x16x32_bf16 v[32:35], v[178:181], v[210:213], v[32:35]
	s_setprio 1
	s_barrier
; #define STAGE_A(b, h, kt) { const u16* ap_ = A + (size_t)((h) * ahalf + (unsigned)(kt) * 64u); glds16(ap_ + ao0, l0 + SA_(b, h)); glds16(ap_ + ao1, l0 + SA_(b, h) + 8192); }
; #define STAGE_B(b, h, kt) { const u16* bp_ = ((h) ? B1 : B0) + (unsigned)(kt) * 64u; glds16(bp_ + bo0, l0 + SB_(b, h)); glds16(bp_ + bo1, l0 + SB_(b, h) + 8192); }
; #define LDA(dst, b, h) _Pragma("unroll") for (int m = 0; m < 4; ++m) _Pragma("unroll") for (int k = 0; k < 2; ++k) \
;     dst[m][k] = *(const bf16x8*)(lds + SA_(b, h) + lds_byte(wr * 64 + m * 16 + fr, k * 32 + fq * 8));
; #define LDB(dst, b, h) _Pragma("unroll") for (int n = 0; n < 2; ++n) _Pragma("unroll") for (int k = 0; k < 2; ++k) \
;     dst[n][k] = *(const bf16x8*)(lds + SB_(b, h) + lds_byte(wc * 32 + n * 16 + fr, k * 32 + fq * 8));
; #define MMA(ai, bj, At_, Bt_) { __builtin_amdgcn_s_setprio(1); \
;     _Pragma("unroll") for (int m = 0; m < 4; ++m) _Pragma("unroll") for (int n = 0; n < 2; ++n) _Pragma("unroll") for (int k = 0; k < 2; ++k) \
;       acc[ai][bj][m][n] = MFMA16(Bt_[n][k], At_[m][k], acc[ai][bj][m][n]); \
;     __builtin_amdgcn_s_setprio(0); }
; #define WAIT_V(n) asm volatile("s_waitcnt vmcnt(" #n ")" ::: "memory");
; #define WAIT_L(n) asm volatile("s_waitcnt lgkmcnt(" #n ")" ::: "memory");
; #define BAR __builtin_amdgcn_s_barrier();
; #define SCHED __builtin_amdgcn_sched_barrier(0);
; DI void gemm256(const u16* __restrict__ A, int lda, const u16* __restrict__ B0, const u16* __restrict__ B1, int ldb, int nt, acc_t& acc, char* lds) {
;     ...
;     STAGE_B(0, 1, t + 2)
;     WAIT_V(6) BAR MMA(1, 1, At, Bq1) BAR
;     LDB(Bq0, 1, 0) SCHED LDA(At, 1, 0) STAGE_A(0, 1, t + 2)
;     WAIT_L(8) BAR WAIT_L(0) MMA(0, 0, At, Bq0) BAR SCHED
;     LDB(Bq1, 1, 1) STAGE_B(1, 0, t + 3)
;     BAR WAIT_L(0) MMA(0, 1, At, Bq1) BAR
;     LDA(At, 1, 1) STAGE_A(1, 0, t + 3)
	v_readfirstlane_b32 s7, v154
	v_lshl_add_u64 v[142:143], v[238:239], 0, s[42:43]
	s_mov_b32 m0, s7
	v_readfirstlane_b32 s7, v155
	global_load_lds_dwordx4 v[142:143], off
	v_lshl_add_u64 v[142:143], v[240:241], 0, s[42:43]
	s_mov_b32 m0, s7
	s_nop 0
	global_load_lds_dwordx4 v[142:143], off
	s_waitcnt vmcnt(6)
	s_barrier
	s_setprio 0
	v_mfma_f32_16x16x32_bf16 v[28:31], v[216:219], v[182:185], v[28:31]
	v_mfma_f32_16x16x32_bf16 v[24:27], v[230:233], v[182:185], v[24:27]
	v_mfma_f32_16x16x32_bf16 v[20:23], v[216:219], v[190:193], v[20:23]
	v_mfma_f32_16x16x32_bf16 v[16:19], v[230:233], v[190:193], v[16:19]
	v_mfma_f32_16x16x32_bf16 v[12:15], v[216:219], v[198:201], v[12:15]
	v_mfma_f32_16x16x32_bf16 v[8:11], v[230:233], v[198:201], v[8:11]
	v_mfma_f32_16x16x32_bf16 v[4:7], v[216:219], v[206:209], v[4:7]
	v_mfma_f32_16x16x32_bf16 v[0:3], v[230:233], v[206:209], v[0:3]
	v_mfma_f32_16x16x32_bf16 v[28:31], v[226:229], v[186:189], v[28:31]
	v_mfma_f32_16x16x32_bf16 v[24:27], v[234:237], v[186:189], v[24:27]
	v_mfma_f32_16x16x32_bf16 v[20:23], v[226:229], v[194:197], v[20:23]
	v_mfma_f32_16x16x32_bf16 v[16:19], v[234:237], v[194:197], v[16:19]
	v_mfma_f32_16x16x32_bf16 v[12:15], v[226:229], v[202:205], v[12:15]
	v_mfma_f32_16x16x32_bf16 v[8:11], v[234:237], v[202:205], v[8:11]
	v_mfma_f32_16x16x32_bf16 v[4:7], v[226:229], v[210:213], v[4:7]
	v_mfma_f32_16x16x32_bf16 v[0:3], v[234:237], v[210:213], v[0:3]
	s_setprio 1
	s_barrier
	ds_read_b128 v[142:145], v156
	ds_read_b128 v[170:173], v156 offset:1024
	ds_read_b128 v[174:177], v156 offset:2048
	ds_read_b128 v[178:181], v156 offset:3072
	v_readfirstlane_b32 s7, v157
	v_lshl_add_u64 v[216:217], v[222:223], 0, s[44:45]
	s_mov_b32 m0, s7
	v_readfirstlane_b32 s7, v158
	ds_read_b128 v[182:185], v148 offset:32768
	ds_read_b128 v[186:189], v148 offset:33792
	ds_read_b128 v[190:193], v147 offset:32768
	ds_read_b128 v[194:197], v147 offset:33792
	ds_read_b128 v[198:201], v146 offset:32768
	ds_read_b128 v[202:205], v146 offset:33792
	ds_read_b128 v[206:209], v141 offset:32768
	ds_read_b128 v[210:213], v141 offset:33792
	global_load_lds_dwordx4 v[216:217], off
	v_lshl_add_u64 v[216:217], v[224:225], 0, s[44:45]
	s_mov_b32 m0, s7
	s_nop 0
	global_load_lds_dwordx4 v[216:217], off
	s_waitcnt lgkmcnt(8)
	s_barrier
	s_waitcnt lgkmcnt(0)
	s_setprio 0
	s_waitcnt lgkmcnt(0)
	v_mfma_f32_16x16x32_bf16 v[126:129], v[142:145], v[182:185], v[126:129]
	v_mfma_f32_16x16x32_bf16 v[122:125], v[174:177], v[182:185], v[122:125]
	v_mfma_f32_16x16x32_bf16 v[118:121], v[142:145], v[190:193], v[118:121]
	v_mfma_f32_16x16x32_bf16 v[114:117], v[174:177], v[190:193], v[114:117]
	v_mfma_f32_16x16x32_bf16 v[110:113], v[142:145], v[198:201], v[110:113]
	v_mfma_f32_16x16x32_bf16 v[106:109], v[174:177], v[198:201], v[106:109]
	v_mfma_f32_16x16x32_bf16 v[102:105], v[142:145], v[206:209], v[102:105]
	v_mfma_f32_16x16x32_bf16 v[98:101], v[174:177], v[206:209], v[98:101]
	v_mfma_f32_16x16x32_bf16 v[126:129], v[170:173], v[186:189], v[126:129]
	v_mfma_f32_16x16x32_bf16 v[122:125], v[178:181], v[186:189], v[122:125]
	v_mfma_f32_16x16x32_bf16 v[118:121], v[170:173], v[194:197], v[118:121]
	v_mfma_f32_16x16x32_bf16 v[114:117], v[178:181], v[194:197], v[114:117]
	v_mfma_f32_16x16x32_bf16 v[110:113], v[170:173], v[202:205], v[110:113]
	v_mfma_f32_16x16x32_bf16 v[106:109], v[178:181], v[202:205], v[106:109]
	v_mfma_f32_16x16x32_bf16 v[102:105], v[170:173], v[210:213], v[102:105]
	v_mfma_f32_16x16x32_bf16 v[98:101], v[178:181], v[210:213], v[98:101]
	s_setprio 1
	s_barrier
	v_readfirstlane_b32 s7, v159
	v_lshl_add_u64 v[242:243], v[238:239], 0, s[46:47]
	s_mov_b32 m0, s7
	v_readfirstlane_b32 s7, v160
	ds_read_b128 v[216:219], v151
	ds_read_b128 v[226:229], v151 offset:1024
	ds_read_b128 v[230:233], v151 offset:2048
	ds_read_b128 v[234:237], v151 offset:3072
	global_load_lds_dwordx4 v[242:243], off
	v_lshl_add_u64 v[242:243], v[240:241], 0, s[46:47]
	s_mov_b32 m0, s7
	s_nop 0
	global_load_lds_dwordx4 v[242:243], off
	s_barrier
	s_waitcnt lgkmcnt(0)
	s_setprio 0
	s_waitcnt lgkmcnt(0)
	v_mfma_f32_16x16x32_bf16 v[94:97], v[216:219], v[182:185], v[94:97]
	v_mfma_f32_16x16x32_bf16 v[90:93], v[230:233], v[182:185], v[90:93]
	v_mfma_f32_16x16x32_bf16 v[86:89], v[216:219], v[190:193], v[86:89]
	v_mfma_f32_16x16x32_bf16 v[82:85], v[230:233], v[190:193], v[82:85]
	v_mfma_f32_16x16x32_bf16 v[78:81], v[216:219], v[198:201], v[78:81]
	v_mfma_f32_16x16x32_bf16 v[74:77], v[230:233], v[198:201], v[74:77]
	v_mfma_f32_16x16x32_bf16 v[70:73], v[216:219], v[206:209], v[70:73]
	v_mfma_f32_16x16x32_bf16 v[66:69], v[230:233], v[206:209], v[66:69]
	v_mfma_f32_16x16x32_bf16 v[94:97], v[226:229], v[186:189], v[94:97]
	v_mfma_f32_16x16x32_bf16 v[90:93], v[234:237], v[186:189], v[90:93]
	v_mfma_f32_16x16x32_bf16 v[86:89], v[226:229], v[194:197], v[86:89]
	v_mfma_f32_16x16x32_bf16 v[82:85], v[234:237], v[194:197], v[82:85]
	v_mfma_f32_16x16x32_bf16 v[78:81], v[226:229], v[202:205], v[78:81]
	v_mfma_f32_16x16x32_bf16 v[74:77], v[234:237], v[202:205], v[74:77]
	v_mfma_f32_16x16x32_bf16 v[70:73], v[226:229], v[210:213], v[70:73]
	v_mfma_f32_16x16x32_bf16 v[66:69], v[234:237], v[210:213], v[66:69]
	s_setprio 1
	v_readfirstlane_b32 s7, v161
	v_lshl_add_u64 v[222:223], v[222:223], 0, s[72:73]
	s_mov_b32 m0, s7
	v_readfirstlane_b32 s7, v162
	s_barrier
	ds_read_b128 v[182:185], v148 offset:49152
	ds_read_b128 v[186:189], v148 offset:50176
	ds_read_b128 v[190:193], v147 offset:49152
	ds_read_b128 v[194:197], v147 offset:50176
	ds_read_b128 v[198:201], v146 offset:49152
	ds_read_b128 v[202:205], v146 offset:50176
	ds_read_b128 v[206:209], v141 offset:49152
	ds_read_b128 v[210:213], v141 offset:50176
	global_load_lds_dwordx4 v[222:223], off
	v_lshl_add_u64 v[222:223], v[224:225], 0, s[72:73]
	s_mov_b32 m0, s7
	s_nop 0
	global_load_lds_dwordx4 v[222:223], off
	s_barrier
; #define STAGE_A(b, h, kt) { const u16* ap_ = A + (size_t)((h) * ahalf + (unsigned)(kt) * 64u); glds16(ap_ + ao0, l0 + SA_(b, h)); glds16(ap_ + ao1, l0 + SA_(b, h) + 8192); }
; #define STAGE_B(b, h, kt) { const u16* bp_ = ((h) ? B1 : B0) + (unsigned)(kt) * 64u; glds16(bp_ + bo0, l0 + SB_(b, h)); glds16(bp_ + bo1, l0 + SB_(b, h) + 8192); }
; #define LDA(dst, b, h) _Pragma("unroll") for (int m = 0; m < 4; ++m) _Pragma("unroll") for (int k = 0; k < 2; ++k) \
;     dst[m][k] = *(const bf16x8*)(lds + SA_(b, h) + lds_byte(wr * 64 + m * 16 + fr, k * 32 + fq * 8));
; #define LDB(dst, b, h) _Pragma("unroll") for (int n = 0; n < 2; ++n) _Pragma("unroll") for (int k = 0; k < 2; ++k) \
;     dst[n][k] = *(const bf16x8*)(lds + SB_(b, h) + lds_byte(wc * 32 + n * 16 + fr, k * 32 + fq * 8));
; #define MMA(ai, bj, At_, Bt_) { __builtin_amdgcn_s_setprio(1); \
;     _Pragma("unroll") for (int m = 0; m < 4; ++m) _Pragma("unroll") for (int n = 0; n < 2; ++n) _Pragma("unroll") for (int k = 0; k < 2; ++k) \
;       acc[ai][bj][m][n] = MFMA16(Bt_[n][k], At_[m][k], acc[ai][bj][m][n]); \
;     __builtin_amdgcn_s_setprio(0); }
; #define WAIT_V(n) asm volatile("s_waitcnt vmcnt(" #n ")" ::: "memory");
; #define WAIT_L(n) asm volatile("s_waitcnt lgkmcnt(" #n ")" ::: "memory");
; #define BAR __builtin_amdgcn_s_barrier();
; #define SCHED __builtin_amdgcn_sched_barrier(0);
; DI void gemm256(const u16* __restrict__ A, int lda, const u16* __restrict__ B0, const u16* __restrict__ B1, int ldb, int nt, acc_t& acc, char* lds) {
;     ...
;     BAR WAIT_L(0) MMA(1, 0, At, Bq0) BAR SCHED
;     STAGE_B(1, 1, t + 3)
;     WAIT_V(6) BAR MMA(1, 1, At, Bq1) BAR
;   }
;   { LDB(Bq0, 0, 0) LDA(At, 0, 0) STAGE_A(1, 1, nt - 1)
;     BAR WAIT_L(0) MMA(0, 0, At, Bq0) BAR
;     LDB(Bq1, 0, 1) BAR WAIT_L(0) MMA(0, 1, At, Bq1) BAR
	s_waitcnt lgkmcnt(0)
	s_setprio 0
	s_waitcnt lgkmcnt(0)
	v_mfma_f32_16x16x32_bf16 v[60:63], v[142:145], v[182:185], v[60:63]
	v_mfma_f32_16x16x32_bf16 v[56:59], v[174:177], v[182:185], v[56:59]
	v_mfma_f32_16x16x32_bf16 v[52:55], v[142:145], v[190:193], v[52:55]
	v_mfma_f32_16x16x32_bf16 v[48:51], v[174:177], v[190:193], v[48:51]
	v_mfma_f32_16x16x32_bf16 v[44:47], v[142:145], v[198:201], v[44:47]
	v_mfma_f32_16x16x32_bf16 v[40:43], v[174:177], v[198:201], v[40:43]
	v_mfma_f32_16x16x32_bf16 v[36:39], v[142:145], v[206:209], v[36:39]
	v_mfma_f32_16x16x32_bf16 v[32:35], v[174:177], v[206:209], v[32:35]
	v_mfma_f32_16x16x32_bf16 v[60:63], v[170:173], v[186:189], v[60:63]
	v_mfma_f32_16x16x32_bf16 v[56:59], v[178:181], v[186:189], v[56:59]
	v_mfma_f32_16x16x32_bf16 v[52:55], v[170:173], v[194:197], v[52:55]
	v_mfma_f32_16x16x32_bf16 v[48:51], v[178:181], v[194:197], v[48:51]
	v_mfma_f32_16x16x32_bf16 v[44:47], v[170:173], v[202:205], v[44:47]
	v_mfma_f32_16x16x32_bf16 v[40:43], v[178:181], v[202:205], v[40:43]
	v_mfma_f32_16x16x32_bf16 v[36:39], v[170:173], v[210:213], v[36:39]
	v_mfma_f32_16x16x32_bf16 v[32:35], v[178:181], v[210:213], v[32:35]
	s_setprio 1
	s_barrier
	v_readfirstlane_b32 s7, v163
	v_lshl_add_u64 v[142:143], v[238:239], 0, s[48:49]
	s_mov_b32 m0, s7
	v_readfirstlane_b32 s7, v164
	global_load_lds_dwordx4 v[142:143], off
	v_lshl_add_u64 v[142:143], v[240:241], 0, s[48:49]
	s_mov_b32 m0, s7
	s_nop 0
	global_load_lds_dwordx4 v[142:143], off
	s_waitcnt vmcnt(6)
	s_barrier
	s_setprio 0
	v_mfma_f32_16x16x32_bf16 v[28:31], v[216:219], v[182:185], v[28:31]
	v_mfma_f32_16x16x32_bf16 v[24:27], v[230:233], v[182:185], v[24:27]
	v_mfma_f32_16x16x32_bf16 v[20:23], v[216:219], v[190:193], v[20:23]
	v_mfma_f32_16x16x32_bf16 v[16:19], v[230:233], v[190:193], v[16:19]
	v_mfma_f32_16x16x32_bf16 v[12:15], v[216:219], v[198:201], v[12:15]
	v_mfma_f32_16x16x32_bf16 v[8:11], v[230:233], v[198:201], v[8:11]
	v_mfma_f32_16x16x32_bf16 v[4:7], v[216:219], v[206:209], v[4:7]
	v_mfma_f32_16x16x32_bf16 v[0:3], v[230:233], v[206:209], v[0:3]
	v_mfma_f32_16x16x32_bf16 v[28:31], v[226:229], v[186:189], v[28:31]
	v_mfma_f32_16x16x32_bf16 v[24:27], v[234:237], v[186:189], v[24:27]
	v_mfma_f32_16x16x32_bf16 v[20:23], v[226:229], v[194:197], v[20:23]
	v_mfma_f32_16x16x32_bf16 v[16:19], v[234:237], v[194:197], v[16:19]
	v_mfma_f32_16x16x32_bf16 v[12:15], v[226:229], v[202:205], v[12:15]
	v_mfma_f32_16x16x32_bf16 v[8:11], v[234:237], v[202:205], v[8:11]
	v_mfma_f32_16x16x32_bf16 v[4:7], v[226:229], v[210:213], v[4:7]
	v_mfma_f32_16x16x32_bf16 v[0:3], v[234:237], v[210:213], v[0:3]
	s_setprio 1
	s_add_i32 s3, s3, 2
	s_add_u32 s36, s36, 0x100
	s_addc_u32 s37, s37, 0
	s_cmp_lt_u32 s3, 12
	s_barrier
	s_cbranch_scc1 .LBB0_1053
	s_add_u32 s28, s28, 0x40780
	s_addc_u32 s29, s29, 0
	v_readfirstlane_b32 s3, v167
	v_lshl_add_u64 v[162:163], v[64:65], 1, s[28:29]
	s_mov_b32 m0, s3
	v_readfirstlane_b32 s3, v168
	ds_read_b128 v[132:135], v166
	ds_read_b128 v[136:139], v166 offset:1024
	ds_read_b128 v[142:145], v166 offset:2048
	ds_read_b128 v[152:155], v166 offset:3072
	ds_read_b128 v[158:161], v148
	ds_read_b128 v[170:173], v148 offset:1024
	ds_read_b128 v[174:177], v147
	ds_read_b128 v[178:181], v147 offset:1024
	ds_read_b128 v[182:185], v146
	ds_read_b128 v[186:189], v146 offset:1024
	ds_read_b128 v[190:193], v141
	ds_read_b128 v[194:197], v141 offset:1024
	global_load_lds_dwordx4 v[162:163], off
	v_lshl_add_u64 v[130:131], v[130:131], 1, s[28:29]
	s_mov_b32 m0, s3
	s_nop 0
	global_load_lds_dwordx4 v[130:131], off
	s_barrier
	s_waitcnt lgkmcnt(0)
	s_setprio 0
	s_waitcnt lgkmcnt(0)
	v_mfma_f32_16x16x32_bf16 v[126:129], v[132:135], v[158:161], v[126:129]
	v_mfma_f32_16x16x32_bf16 v[118:121], v[132:135], v[174:177], v[118:121]
	v_mfma_f32_16x16x32_bf16 v[114:117], v[142:145], v[174:177], v[114:117]
	v_mfma_f32_16x16x32_bf16 v[102:105], v[132:135], v[190:193], v[102:105]
	v_mfma_f32_16x16x32_bf16 v[98:101], v[142:145], v[190:193], v[98:101]
	v_mfma_f32_16x16x32_bf16 v[126:129], v[136:139], v[170:173], v[126:129]
	v_mfma_f32_16x16x32_bf16 v[122:125], v[142:145], v[158:161], v[122:125]
	v_mfma_f32_16x16x32_bf16 v[118:121], v[136:139], v[178:181], v[118:121]
	v_mfma_f32_16x16x32_bf16 v[114:117], v[152:155], v[178:181], v[114:117]
	v_mfma_f32_16x16x32_bf16 v[110:113], v[132:135], v[182:185], v[110:113]
	v_mfma_f32_16x16x32_bf16 v[106:109], v[142:145], v[182:185], v[106:109]
	v_mfma_f32_16x16x32_bf16 v[102:105], v[136:139], v[194:197], v[102:105]
	v_mfma_f32_16x16x32_bf16 v[98:101], v[152:155], v[194:197], v[98:101]
	v_mfma_f32_16x16x32_bf16 v[122:125], v[152:155], v[170:173], v[122:125]
	v_mfma_f32_16x16x32_bf16 v[166:169], v[136:139], v[186:189], v[110:113]
	v_mfma_f32_16x16x32_bf16 v[198:201], v[152:155], v[186:189], v[106:109]
	s_setprio 1
	s_barrier
	s_nop 0
	ds_read_b128 v[106:109], v165
	ds_read_b128 v[110:113], v165 offset:1024
	ds_read_b128 v[202:205], v165 offset:2048
	ds_read_b128 v[162:165], v165 offset:3072
	s_barrier
	s_waitcnt lgkmcnt(0)
	s_setprio 0
	s_waitcnt lgkmcnt(0)
	v_mfma_f32_16x16x32_bf16 v[86:89], v[106:109], v[174:177], v[86:89]
	v_mfma_f32_16x16x32_bf16 v[82:85], v[202:205], v[174:177], v[82:85]
	v_mfma_f32_16x16x32_bf16 v[70:73], v[106:109], v[190:193], v[70:73]
	v_mfma_f32_16x16x32_bf16 v[66:69], v[202:205], v[190:193], v[66:69]
	v_mfma_f32_16x16x32_bf16 v[94:97], v[106:109], v[158:161], v[94:97]
	v_mfma_f32_16x16x32_bf16 v[90:93], v[202:205], v[158:161], v[90:93]
	v_mfma_f32_16x16x32_bf16 v[86:89], v[110:113], v[178:181], v[86:89]
	v_mfma_f32_16x16x32_bf16 v[82:85], v[162:165], v[178:181], v[82:85]
	v_mfma_f32_16x16x32_bf16 v[78:81], v[106:109], v[182:185], v[78:81]
	v_mfma_f32_16x16x32_bf16 v[74:77], v[202:205], v[182:185], v[74:77]
	v_mfma_f32_16x16x32_bf16 v[70:73], v[110:113], v[194:197], v[70:73]
	v_mfma_f32_16x16x32_bf16 v[66:69], v[162:165], v[194:197], v[66:69]
	v_mfma_f32_16x16x32_bf16 v[206:209], v[110:113], v[170:173], v[94:97]
	v_mfma_f32_16x16x32_bf16 v[158:161], v[162:165], v[170:173], v[90:93]
	v_mfma_f32_16x16x32_bf16 v[170:173], v[110:113], v[186:189], v[78:81]
	v_mfma_f32_16x16x32_bf16 v[174:177], v[162:165], v[186:189], v[74:77]
	s_setprio 1
	s_barrier
; #define LDA(dst, b, h) _Pragma("unroll") for (int m = 0; m < 4; ++m) _Pragma("unroll") for (int k = 0; k < 2; ++k) \
;     dst[m][k] = *(const bf16x8*)(lds + SA_(b, h) + lds_byte(wr * 64 + m * 16 + fr, k * 32 + fq * 8));
; #define LDB(dst, b, h) _Pragma("unroll") for (int n = 0; n < 2; ++n) _Pragma("unroll") for (int k = 0; k < 2; ++k) \
;     dst[n][k] = *(const bf16x8*)(lds + SB_(b, h) + lds_byte(wc * 32 + n * 16 + fr, k * 32 + fq * 8));
; #define MMA(ai, bj, At_, Bt_) { __builtin_amdgcn_s_setprio(1); \
;     _Pragma("unroll") for (int m = 0; m < 4; ++m) _Pragma("unroll") for (int n = 0; n < 2; ++n) _Pragma("unroll") for (int k = 0; k < 2; ++k) \
;       acc[ai][bj][m][n] = MFMA16(Bt_[n][k], At_[m][k], acc[ai][bj][m][n]); \
;     __builtin_amdgcn_s_setprio(0); }
; #define WAIT_V(n) asm volatile("s_waitcnt vmcnt(" #n ")" ::: "memory");
; #define WAIT_L(n) asm volatile("s_waitcnt lgkmcnt(" #n ")" ::: "memory");
; #define BAR __builtin_amdgcn_s_barrier();
; DI void gemm256(const u16* __restrict__ A, int lda, const u16* __restrict__ B0, const u16* __restrict__ B1, int ldb, int nt, acc_t& acc, char* lds) {
;     ...
;     LDA(At, 0, 1) WAIT_V(4) BAR WAIT_L(0) MMA(1, 0, At, Bq0) MMA(1, 1, At, Bq1) BAR }
;   { LDB(Bq0, 1, 0) LDA(At, 1, 0) WAIT_V(2) BAR WAIT_L(0) MMA(0, 0, At, Bq0) BAR
	s_nop 0
	ds_read_b128 v[74:77], v148 offset:16384
	ds_read_b128 v[78:81], v148 offset:17408
	ds_read_b128 v[90:93], v147 offset:16384
	ds_read_b128 v[94:97], v147 offset:17408
	ds_read_b128 v[178:181], v146 offset:16384
	ds_read_b128 v[182:185], v146 offset:17408
	ds_read_b128 v[186:189], v141 offset:16384
	ds_read_b128 v[190:193], v141 offset:17408
	s_waitcnt vmcnt(4)
	s_barrier
	s_waitcnt lgkmcnt(0)
	s_setprio 0
	s_waitcnt lgkmcnt(0)
	v_mfma_f32_16x16x32_bf16 v[60:63], v[132:135], v[74:77], v[60:63]
	v_mfma_f32_16x16x32_bf16 v[56:59], v[142:145], v[74:77], v[56:59]
	v_mfma_f32_16x16x32_bf16 v[52:55], v[132:135], v[90:93], v[52:55]
	v_mfma_f32_16x16x32_bf16 v[48:51], v[142:145], v[90:93], v[48:51]
	v_mfma_f32_16x16x32_bf16 v[36:39], v[132:135], v[186:189], v[36:39]
	v_mfma_f32_16x16x32_bf16 v[32:35], v[142:145], v[186:189], v[32:35]
	v_mfma_f32_16x16x32_bf16 v[60:63], v[136:139], v[78:81], v[60:63]
	v_mfma_f32_16x16x32_bf16 v[56:59], v[152:155], v[78:81], v[56:59]
	v_mfma_f32_16x16x32_bf16 v[52:55], v[136:139], v[94:97], v[52:55]
	v_mfma_f32_16x16x32_bf16 v[48:51], v[152:155], v[94:97], v[48:51]
	v_mfma_f32_16x16x32_bf16 v[44:47], v[132:135], v[178:181], v[44:47]
	v_mfma_f32_16x16x32_bf16 v[40:43], v[142:145], v[178:181], v[40:43]
	v_mfma_f32_16x16x32_bf16 v[36:39], v[136:139], v[190:193], v[36:39]
	v_mfma_f32_16x16x32_bf16 v[32:35], v[152:155], v[190:193], v[32:35]
	v_mfma_f32_16x16x32_bf16 v[194:197], v[136:139], v[182:185], v[44:47]
	v_mfma_f32_16x16x32_bf16 v[210:213], v[152:155], v[182:185], v[40:43]
	s_setprio 1
	s_setprio 0
	v_mfma_f32_16x16x32_bf16 v[20:23], v[106:109], v[90:93], v[20:23]
	v_mfma_f32_16x16x32_bf16 v[16:19], v[202:205], v[90:93], v[16:19]
	v_mfma_f32_16x16x32_bf16 v[4:7], v[106:109], v[186:189], v[4:7]
	v_mfma_f32_16x16x32_bf16 v[0:3], v[202:205], v[186:189], v[0:3]
	v_mfma_f32_16x16x32_bf16 v[28:31], v[106:109], v[74:77], v[28:31]
	v_mfma_f32_16x16x32_bf16 v[24:27], v[202:205], v[74:77], v[24:27]
	v_mfma_f32_16x16x32_bf16 v[20:23], v[110:113], v[94:97], v[20:23]
	v_mfma_f32_16x16x32_bf16 v[16:19], v[162:165], v[94:97], v[16:19]
	v_mfma_f32_16x16x32_bf16 v[12:15], v[106:109], v[178:181], v[12:15]
	v_mfma_f32_16x16x32_bf16 v[8:11], v[202:205], v[178:181], v[8:11]
	v_mfma_f32_16x16x32_bf16 v[4:7], v[110:113], v[190:193], v[4:7]
	v_mfma_f32_16x16x32_bf16 v[0:3], v[162:165], v[190:193], v[0:3]
	v_mfma_f32_16x16x32_bf16 v[134:137], v[110:113], v[78:81], v[28:31]
	v_mfma_f32_16x16x32_bf16 v[142:145], v[162:165], v[78:81], v[24:27]
	v_mfma_f32_16x16x32_bf16 v[152:155], v[110:113], v[182:185], v[12:15]
	v_mfma_f32_16x16x32_bf16 v[178:181], v[162:165], v[182:185], v[8:11]
	s_setprio 1
	s_barrier
	s_nop 0
	ds_read_b128 v[8:11], v156
	ds_read_b128 v[12:15], v156 offset:1024
	ds_read_b128 v[162:165], v156 offset:2048
	ds_read_b128 v[182:185], v156 offset:3072
	ds_read_b128 v[24:27], v148 offset:32768
	ds_read_b128 v[28:31], v148 offset:33792
	ds_read_b128 v[40:43], v147 offset:32768
	ds_read_b128 v[44:47], v147 offset:33792
	ds_read_b128 v[186:189], v146 offset:32768
	ds_read_b128 v[190:193], v146 offset:33792
	ds_read_b128 v[202:205], v141 offset:32768
	ds_read_b128 v[216:219], v141 offset:33792
	s_waitcnt vmcnt(2)
	s_barrier
	s_waitcnt lgkmcnt(0)
	s_setprio 0
	s_waitcnt lgkmcnt(0)
	v_mfma_f32_16x16x32_bf16 v[74:77], v[8:11], v[24:27], v[126:129]
	v_mfma_f32_16x16x32_bf16 v[126:129], v[12:15], v[28:31], v[74:77]
	v_mfma_f32_16x16x32_bf16 v[74:77], v[162:165], v[24:27], v[122:125]
	v_mfma_f32_16x16x32_bf16 v[130:133], v[182:185], v[28:31], v[74:77]
	v_mfma_f32_16x16x32_bf16 v[74:77], v[8:11], v[40:43], v[118:121]
	v_mfma_f32_16x16x32_bf16 v[110:113], v[12:15], v[44:47], v[74:77]
	v_mfma_f32_16x16x32_bf16 v[74:77], v[162:165], v[40:43], v[114:117]
	v_mfma_f32_16x16x32_bf16 v[106:109], v[182:185], v[44:47], v[74:77]
	v_mfma_f32_16x16x32_bf16 v[74:77], v[8:11], v[186:189], v[166:169]
	v_mfma_f32_16x16x32_bf16 v[94:97], v[12:15], v[190:193], v[74:77]
	v_mfma_f32_16x16x32_bf16 v[74:77], v[162:165], v[186:189], v[198:201]
	v_mfma_f32_16x16x32_bf16 v[90:93], v[182:185], v[190:193], v[74:77]
	v_mfma_f32_16x16x32_bf16 v[74:77], v[8:11], v[202:205], v[102:105]
	v_mfma_f32_16x16x32_bf16 v[78:81], v[12:15], v[216:219], v[74:77]
	v_mfma_f32_16x16x32_bf16 v[74:77], v[162:165], v[202:205], v[98:101]
	v_mfma_f32_16x16x32_bf16 v[74:77], v[182:185], v[216:219], v[74:77]
	s_setprio 1
	s_barrier
; #define LDA(dst, b, h) _Pragma("unroll") for (int m = 0; m < 4; ++m) _Pragma("unroll") for (int k = 0; k < 2; ++k) \
;     dst[m][k] = *(const bf16x8*)(lds + SA_(b, h) + lds_byte(wr * 64 + m * 16 + fr, k * 32 + fq * 8));
; #define LDB(dst, b, h) _Pragma("unroll") for (int n = 0; n < 2; ++n) _Pragma("unroll") for (int k = 0; k < 2; ++k) \
;     dst[n][k] = *(const bf16x8*)(lds + SB_(b, h) + lds_byte(wc * 32 + n * 16 + fr, k * 32 + fq * 8));
; #define MMA(ai, bj, At_, Bt_) { __builtin_amdgcn_s_setprio(1); \
;     _Pragma("unroll") for (int m = 0; m < 4; ++m) _Pragma("unroll") for (int n = 0; n < 2; ++n) _Pragma("unroll") for (int k = 0; k < 2; ++k) \
;       acc[ai][bj][m][n] = MFMA16(Bt_[n][k], At_[m][k], acc[ai][bj][m][n]); \
;     __builtin_amdgcn_s_setprio(0); }
; #define WAIT_V(n) asm volatile("s_waitcnt vmcnt(" #n ")" ::: "memory");
; #define WAIT_L(n) asm volatile("s_waitcnt lgkmcnt(" #n ")" ::: "memory");
; #define BAR __builtin_amdgcn_s_barrier();
; DI void gemm256(const u16* __restrict__ A, int lda, const u16* __restrict__ B0, const u16* __restrict__ B1, int ldb, int nt, acc_t& acc, char* lds) {
;     ...
;     LDB(Bq1, 1, 1) WAIT_V(0) BAR WAIT_L(0) MMA(0, 1, At, Bq1) BAR
;     LDA(At, 1, 1) BAR WAIT_L(0) MMA(1, 0, At, Bq0) MMA(1, 1, At, Bq1) BAR }
;   if (wr == 0) BAR
;   __syncthreads();
	ds_read_b128 v[122:125], v151
	ds_read_b128 v[166:169], v151 offset:1024
	ds_read_b128 v[198:201], v151 offset:2048
	ds_read_b128 v[226:229], v151 offset:3072
	s_waitcnt vmcnt(0)
	s_barrier
	s_waitcnt lgkmcnt(0)
	s_setprio 0
	s_waitcnt lgkmcnt(0)
	v_mfma_f32_16x16x32_bf16 v[98:101], v[122:125], v[24:27], v[206:209]
	v_mfma_f32_16x16x32_bf16 v[24:27], v[198:201], v[24:27], v[158:161]
	v_mfma_f32_16x16x32_bf16 v[114:117], v[226:229], v[28:31], v[24:27]
	v_mfma_f32_16x16x32_bf16 v[24:27], v[122:125], v[40:43], v[86:89]
	v_mfma_f32_16x16x32_bf16 v[102:105], v[166:169], v[44:47], v[24:27]
	v_mfma_f32_16x16x32_bf16 v[24:27], v[198:201], v[40:43], v[82:85]
	v_mfma_f32_16x16x32_bf16 v[118:121], v[166:169], v[28:31], v[98:101]
	v_mfma_f32_16x16x32_bf16 v[98:101], v[226:229], v[44:47], v[24:27]
	v_mfma_f32_16x16x32_bf16 v[24:27], v[122:125], v[186:189], v[170:173]
	v_mfma_f32_16x16x32_bf16 v[86:89], v[166:169], v[190:193], v[24:27]
	v_mfma_f32_16x16x32_bf16 v[24:27], v[198:201], v[186:189], v[174:177]
	v_mfma_f32_16x16x32_bf16 v[82:85], v[226:229], v[190:193], v[24:27]
	v_mfma_f32_16x16x32_bf16 v[24:27], v[122:125], v[202:205], v[70:73]
	v_mfma_f32_16x16x32_bf16 v[70:73], v[166:169], v[216:219], v[24:27]
	v_mfma_f32_16x16x32_bf16 v[24:27], v[198:201], v[202:205], v[66:69]
	v_mfma_f32_16x16x32_bf16 v[66:69], v[226:229], v[216:219], v[24:27]
	s_setprio 1
	s_barrier
	ds_read_b128 v[156:159], v148 offset:49152
	ds_read_b128 v[148:151], v148 offset:50176
	ds_read_b128 v[170:173], v147 offset:49152
	ds_read_b128 v[174:177], v147 offset:50176
	ds_read_b128 v[186:189], v146 offset:49152
	ds_read_b128 v[190:193], v146 offset:50176
	ds_read_b128 v[202:205], v141 offset:49152
	ds_read_b128 v[206:209], v141 offset:50176
	s_barrier
	s_waitcnt lgkmcnt(0)
	s_setprio 0
	s_waitcnt lgkmcnt(0)
	v_mfma_f32_16x16x32_bf16 v[24:27], v[8:11], v[156:159], v[60:63]
	v_mfma_f32_16x16x32_bf16 v[60:63], v[12:15], v[148:151], v[24:27]
	v_mfma_f32_16x16x32_bf16 v[24:27], v[162:165], v[156:159], v[56:59]
	v_mfma_f32_16x16x32_bf16 v[56:59], v[182:185], v[148:151], v[24:27]
	v_mfma_f32_16x16x32_bf16 v[24:27], v[8:11], v[170:173], v[52:55]
	v_mfma_f32_16x16x32_bf16 v[44:47], v[12:15], v[174:177], v[24:27]
	v_mfma_f32_16x16x32_bf16 v[24:27], v[162:165], v[170:173], v[48:51]
	v_mfma_f32_16x16x32_bf16 v[40:43], v[182:185], v[174:177], v[24:27]
	v_mfma_f32_16x16x32_bf16 v[24:27], v[8:11], v[186:189], v[194:197]
	v_mfma_f32_16x16x32_bf16 v[8:11], v[8:11], v[202:205], v[36:39]
	v_mfma_f32_16x16x32_bf16 v[28:31], v[12:15], v[190:193], v[24:27]
	v_mfma_f32_16x16x32_bf16 v[24:27], v[162:165], v[186:189], v[210:213]
	v_mfma_f32_16x16x32_bf16 v[12:15], v[12:15], v[206:209], v[8:11]
	v_mfma_f32_16x16x32_bf16 v[8:11], v[162:165], v[202:205], v[32:35]
	v_mfma_f32_16x16x32_bf16 v[24:27], v[182:185], v[190:193], v[24:27]
	v_mfma_f32_16x16x32_bf16 v[8:11], v[182:185], v[206:209], v[8:11]
	s_setprio 1
	s_setprio 0
	v_mfma_f32_16x16x32_bf16 v[32:35], v[122:125], v[156:159], v[134:137]
	v_mfma_f32_16x16x32_bf16 v[52:55], v[166:169], v[148:151], v[32:35]
	v_mfma_f32_16x16x32_bf16 v[32:35], v[198:201], v[156:159], v[142:145]
	v_mfma_f32_16x16x32_bf16 v[16:19], v[198:201], v[170:173], v[16:19]
	v_mfma_f32_16x16x32_bf16 v[48:51], v[226:229], v[148:151], v[32:35]
	v_mfma_f32_16x16x32_bf16 v[20:23], v[122:125], v[170:173], v[20:23]
	v_mfma_f32_16x16x32_bf16 v[32:35], v[226:229], v[174:177], v[16:19]
	v_mfma_f32_16x16x32_bf16 v[16:19], v[122:125], v[186:189], v[152:155]
	v_mfma_f32_16x16x32_bf16 v[36:39], v[166:169], v[174:177], v[20:23]
	v_mfma_f32_16x16x32_bf16 v[20:23], v[166:169], v[190:193], v[16:19]
	v_mfma_f32_16x16x32_bf16 v[16:19], v[198:201], v[186:189], v[178:181]
	v_mfma_f32_16x16x32_bf16 v[4:7], v[122:125], v[202:205], v[4:7]
	v_mfma_f32_16x16x32_bf16 v[0:3], v[198:201], v[202:205], v[0:3]
	v_mfma_f32_16x16x32_bf16 v[16:19], v[226:229], v[190:193], v[16:19]
	v_mfma_f32_16x16x32_bf16 v[4:7], v[166:169], v[206:209], v[4:7]
	v_mfma_f32_16x16x32_bf16 v[0:3], v[226:229], v[206:209], v[0:3]
	s_setprio 1
	s_movk_i32 s3, 0x100
	v_cmp_gt_u32_e32 vcc, s3, v140
	s_barrier
	s_and_saveexec_b64 s[28:29], vcc
	s_cbranch_execz .LBB0_1049
	s_barrier
	s_branch .LBB0_1049

; #define STAGE_A(b, h, kt) { const u16* ap_ = A + (size_t)((h) * ahalf + (unsigned)(kt) * 64u); glds16(ap_ + ao0, l0 + SA_(b, h)); glds16(ap_ + ao1, l0 + SA_(b, h) + 8192); }
; #define STAGE_B(b, h, kt) { const u16* bp_ = ((h) ? B1 : B0) + (unsigned)(kt) * 64u; glds16(bp_ + bo0, l0 + SB_(b, h)); glds16(bp_ + bo1, l0 + SB_(b, h) + 8192); }
; #define LDA(dst, b, h) _Pragma("unroll") for (int m = 0; m < 4; ++m) _Pragma("unroll") for (int k = 0; k < 2; ++k) \
;     dst[m][k] = *(const bf16x8*)(lds + SA_(b, h) + lds_byte(wr * 64 + m * 16 + fr, k * 32 + fq * 8));
; #define LDB(dst, b, h) _Pragma("unroll") for (int n = 0; n < 2; ++n) _Pragma("unroll") for (int k = 0; k < 2; ++k) \
;     dst[n][k] = *(const bf16x8*)(lds + SB_(b, h) + lds_byte(wc * 32 + n * 16 + fr, k * 32 + fq * 8));
; #define MMA(ai, bj, At_, Bt_) { __builtin_amdgcn_s_setprio(1); \
;     _Pragma("unroll") for (int m = 0; m < 4; ++m) _Pragma("unroll") for (int n = 0; n < 2; ++n) _Pragma("unroll") for (int k = 0; k < 2; ++k) \
;       acc[ai][bj][m][n] = MFMA16(Bt_[n][k], At_[m][k], acc[ai][bj][m][n]); \
;     __builtin_amdgcn_s_setprio(0); }
; #define WAIT_L(n) asm volatile("s_waitcnt lgkmcnt(" #n ")" ::: "memory");
; #define BAR __builtin_amdgcn_s_barrier();
; #define SCHED __builtin_amdgcn_sched_barrier(0);
; DI void gemm256(const u16* __restrict__ A, int lda, const u16* __restrict__ B0, const u16* __restrict__ B1, int ldb, int nt, acc_t& acc, char* lds) {
;     ...
;     LDB(Bq0, 0, 0) SCHED LDA(At, 0, 0) STAGE_A(1, 1, t + 1)
;     WAIT_L(8) BAR WAIT_L(0) MMA(0, 0, At, Bq0) BAR SCHED
;     LDB(Bq1, 0, 1) STAGE_B(0, 0, t + 2)
;     BAR WAIT_L(0) MMA(0, 1, At, Bq1) BAR
;     LDA(At, 0, 1) STAGE_A(0, 0, t + 2)
;     BAR WAIT_L(0) MMA(1, 0, At, Bq0) BAR SCHED
.LBB0_1172:
	ds_read_b128 v[142:145], v166
	ds_read_b128 v[170:173], v166 offset:1024
	ds_read_b128 v[174:177], v166 offset:2048
	ds_read_b128 v[178:181], v166 offset:3072
	v_add_u32_e32 v167, 0xc000, v149
	v_lshl_add_u64 v[222:223], s[36:37], 0, v[136:137]
	v_readfirstlane_b32 s9, v167
	v_lshl_add_u64 v[168:169], v[222:223], 0, s[76:77]
	s_mov_b32 m0, s9
	ds_read_b128 v[182:185], v148
	ds_read_b128 v[186:189], v148 offset:1024
	ds_read_b128 v[190:193], v147
	ds_read_b128 v[194:197], v147 offset:1024
	ds_read_b128 v[198:201], v146
	ds_read_b128 v[202:205], v146 offset:1024
	ds_read_b128 v[206:209], v141
	ds_read_b128 v[210:213], v141 offset:1024
	global_load_lds_dwordx4 v[168:169], off
	v_add_u32_e32 v168, 0xe000, v149
	v_lshl_add_u64 v[224:225], s[36:37], 0, v[138:139]
	v_readfirstlane_b32 s9, v168
	v_lshl_add_u64 v[216:217], v[224:225], 0, s[76:77]
	s_mov_b32 m0, s9
	s_nop 0
	global_load_lds_dwordx4 v[216:217], off
	s_waitcnt lgkmcnt(8)
	s_barrier
	s_waitcnt lgkmcnt(0)
	s_setprio 0
	s_waitcnt lgkmcnt(0)
	v_mfma_f32_16x16x32_bf16 v[126:129], v[142:145], v[182:185], v[126:129]
	v_mfma_f32_16x16x32_bf16 v[122:125], v[174:177], v[182:185], v[122:125]
	v_mfma_f32_16x16x32_bf16 v[118:121], v[142:145], v[190:193], v[118:121]
	v_mfma_f32_16x16x32_bf16 v[114:117], v[174:177], v[190:193], v[114:117]
	v_mfma_f32_16x16x32_bf16 v[110:113], v[142:145], v[198:201], v[110:113]
	v_mfma_f32_16x16x32_bf16 v[106:109], v[174:177], v[198:201], v[106:109]
	v_mfma_f32_16x16x32_bf16 v[102:105], v[142:145], v[206:209], v[102:105]
	v_mfma_f32_16x16x32_bf16 v[98:101], v[174:177], v[206:209], v[98:101]
	v_mfma_f32_16x16x32_bf16 v[126:129], v[170:173], v[186:189], v[126:129]
	v_mfma_f32_16x16x32_bf16 v[122:125], v[178:181], v[186:189], v[122:125]
	v_mfma_f32_16x16x32_bf16 v[118:121], v[170:173], v[194:197], v[118:121]
	v_mfma_f32_16x16x32_bf16 v[114:117], v[178:181], v[194:197], v[114:117]
	v_mfma_f32_16x16x32_bf16 v[110:113], v[170:173], v[202:205], v[110:113]
	v_mfma_f32_16x16x32_bf16 v[106:109], v[178:181], v[202:205], v[106:109]
	v_mfma_f32_16x16x32_bf16 v[102:105], v[170:173], v[210:213], v[102:105]
	v_mfma_f32_16x16x32_bf16 v[98:101], v[178:181], v[210:213], v[98:101]
	s_setprio 1
	s_barrier
	v_lshl_add_u64 v[238:239], s[36:37], 0, v[132:133]
	v_readfirstlane_b32 s9, v150
	v_lshl_add_u64 v[240:241], v[238:239], 0, s[42:43]
	s_mov_b32 m0, s9
	ds_read_b128 v[216:219], v165
	ds_read_b128 v[226:229], v165 offset:1024
	ds_read_b128 v[230:233], v165 offset:2048
	ds_read_b128 v[234:237], v165 offset:3072
	global_load_lds_dwordx4 v[240:241], off
	v_lshl_add_u64 v[240:241], s[36:37], 0, v[134:135]
	v_readfirstlane_b32 s9, v152
	v_lshl_add_u64 v[242:243], v[240:241], 0, s[42:43]
	s_mov_b32 m0, s9
	s_nop 0
	global_load_lds_dwordx4 v[242:243], off
	s_barrier
	s_waitcnt lgkmcnt(0)
	s_setprio 0
	s_waitcnt lgkmcnt(0)
	v_mfma_f32_16x16x32_bf16 v[94:97], v[216:219], v[182:185], v[94:97]
	v_mfma_f32_16x16x32_bf16 v[90:93], v[230:233], v[182:185], v[90:93]
	v_mfma_f32_16x16x32_bf16 v[86:89], v[216:219], v[190:193], v[86:89]
	v_mfma_f32_16x16x32_bf16 v[82:85], v[230:233], v[190:193], v[82:85]
	v_mfma_f32_16x16x32_bf16 v[78:81], v[216:219], v[198:201], v[78:81]
	v_mfma_f32_16x16x32_bf16 v[74:77], v[230:233], v[198:201], v[74:77]
	v_mfma_f32_16x16x32_bf16 v[70:73], v[216:219], v[206:209], v[70:73]
	v_mfma_f32_16x16x32_bf16 v[66:69], v[230:233], v[206:209], v[66:69]
	v_mfma_f32_16x16x32_bf16 v[94:97], v[226:229], v[186:189], v[94:97]
	v_mfma_f32_16x16x32_bf16 v[90:93], v[234:237], v[186:189], v[90:93]
	v_mfma_f32_16x16x32_bf16 v[86:89], v[226:229], v[194:197], v[86:89]
	v_mfma_f32_16x16x32_bf16 v[82:85], v[234:237], v[194:197], v[82:85]
	v_mfma_f32_16x16x32_bf16 v[78:81], v[226:229], v[202:205], v[78:81]
	v_mfma_f32_16x16x32_bf16 v[74:77], v[234:237], v[202:205], v[74:77]
	v_mfma_f32_16x16x32_bf16 v[70:73], v[226:229], v[210:213], v[70:73]
	v_mfma_f32_16x16x32_bf16 v[66:69], v[234:237], v[210:213], v[66:69]
	s_setprio 1
	v_readfirstlane_b32 s9, v149
	v_lshl_add_u64 v[242:243], v[222:223], 0, s[80:81]
	s_mov_b32 m0, s9
	v_readfirstlane_b32 s9, v153
	s_barrier
	ds_read_b128 v[182:185], v148 offset:16384
	ds_read_b128 v[186:189], v148 offset:17408
	ds_read_b128 v[190:193], v147 offset:16384
	ds_read_b128 v[194:197], v147 offset:17408
	ds_read_b128 v[198:201], v146 offset:16384
	ds_read_b128 v[202:205], v146 offset:17408
	ds_read_b128 v[206:209], v141 offset:16384
	ds_read_b128 v[210:213], v141 offset:17408
	global_load_lds_dwordx4 v[242:243], off
	v_lshl_add_u64 v[242:243], v[224:225], 0, s[80:81]
	s_mov_b32 m0, s9
	s_nop 0
	global_load_lds_dwordx4 v[242:243], off
	s_barrier
	s_waitcnt lgkmcnt(0)
	s_setprio 0
	s_waitcnt lgkmcnt(0)
	v_mfma_f32_16x16x32_bf16 v[60:63], v[142:145], v[182:185], v[60:63]
	v_mfma_f32_16x16x32_bf16 v[56:59], v[174:177], v[182:185], v[56:59]
	v_mfma_f32_16x16x32_bf16 v[52:55], v[142:145], v[190:193], v[52:55]
	v_mfma_f32_16x16x32_bf16 v[48:51], v[174:177], v[190:193], v[48:51]
	v_mfma_f32_16x16x32_bf16 v[44:47], v[142:145], v[198:201], v[44:47]
	v_mfma_f32_16x16x32_bf16 v[40:43], v[174:177], v[198:201], v[40:43]
	v_mfma_f32_16x16x32_bf16 v[36:39], v[142:145], v[206:209], v[36:39]
	v_mfma_f32_16x16x32_bf16 v[32:35], v[174:177], v[206:209], v[32:35]
	v_mfma_f32_16x16x32_bf16 v[60:63], v[170:173], v[186:189], v[60:63]
	v_mfma_f32_16x16x32_bf16 v[56:59], v[178:181], v[186:189], v[56:59]
	v_mfma_f32_16x16x32_bf16 v[52:55], v[170:173], v[194:197], v[52:55]
	v_mfma_f32_16x16x32_bf16 v[48:51], v[178:181], v[194:197], v[48:51]
	v_mfma_f32_16x16x32_bf16 v[44:47], v[170:173], v[202:205], v[44:47]
	v_mfma_f32_16x16x32_bf16 v[40:43], v[178:181], v[202:205], v[40:43]
	v_mfma_f32_16x16x32_bf16 v[36:39], v[170:173], v[210:213], v[36:39]
	v_mfma_f32_16x16x32_bf16 v[32:35], v[178:181], v[210:213], v[32:35]
	s_setprio 1
	s_barrier
; #define STAGE_A(b, h, kt) { const u16* ap_ = A + (size_t)((h) * ahalf + (unsigned)(kt) * 64u); glds16(ap_ + ao0, l0 + SA_(b, h)); glds16(ap_ + ao1, l0 + SA_(b, h) + 8192); }
; #define STAGE_B(b, h, kt) { const u16* bp_ = ((h) ? B1 : B0) + (unsigned)(kt) * 64u; glds16(bp_ + bo0, l0 + SB_(b, h)); glds16(bp_ + bo1, l0 + SB_(b, h) + 8192); }
; #define LDA(dst, b, h) _Pragma("unroll") for (int m = 0; m < 4; ++m) _Pragma("unroll") for (int k = 0; k < 2; ++k) \
;     dst[m][k] = *(const bf16x8*)(lds + SA_(b, h) + lds_byte(wr * 64 + m * 16 + fr, k * 32 + fq * 8));
; #define LDB(dst, b, h) _Pragma("unroll") for (int n = 0; n < 2; ++n) _Pragma("unroll") for (int k = 0; k < 2; ++k) \
;     dst[n][k] = *(const bf16x8*)(lds + SB_(b, h) + lds_byte(wc * 32 + n * 16 + fr, k * 32 + fq * 8));
; #define MMA(ai, bj, At_, Bt_) { __builtin_amdgcn_s_setprio(1); \
;     _Pragma("unroll") for (int m = 0; m < 4; ++m) _Pragma("unroll") for (int n = 0; n < 2; ++n) _Pragma("unroll") for (int k = 0; k < 2; ++k) \
;       acc[ai][bj][m][n] = MFMA16(Bt_[n][k], At_[m][k], acc[ai][bj][m][n]); \
;     __builtin_amdgcn_s_setprio(0); }
; #define WAIT_V(n) asm volatile("s_waitcnt vmcnt(" #n ")" ::: "memory");
; #define WAIT_L(n) asm volatile("s_waitcnt lgkmcnt(" #n ")" ::: "memory");
; #define BAR __builtin_amdgcn_s_barrier();
; #define SCHED __builtin_amdgcn_sched_barrier(0);
; DI void gemm256(const u16* __restrict__ A, int lda, const u16* __restrict__ B0, const u16* __restrict__ B1, int ldb, int nt, acc_t& acc, char* lds) {
;     ...
;     STAGE_B(0, 1, t + 2)
;     WAIT_V(6) BAR MMA(1, 1, At, Bq1) BAR
;     LDB(Bq0, 1, 0) SCHED LDA(At, 1, 0) STAGE_A(0, 1, t + 2)
;     WAIT_L(8) BAR WAIT_L(0) MMA(0, 0, At, Bq0) BAR SCHED
;     LDB(Bq1, 1, 1) STAGE_B(1, 0, t + 3)
;     BAR WAIT_L(0) MMA(0, 1, At, Bq1) BAR
;     LDA(At, 1, 1) STAGE_A(1, 0, t + 3)
	v_readfirstlane_b32 s9, v154
	v_lshl_add_u64 v[142:143], v[238:239], 0, s[44:45]
	s_mov_b32 m0, s9
	v_readfirstlane_b32 s9, v155
	global_load_lds_dwordx4 v[142:143], off
	v_lshl_add_u64 v[142:143], v[240:241], 0, s[44:45]
	s_mov_b32 m0, s9
	s_nop 0
	global_load_lds_dwordx4 v[142:143], off
	s_waitcnt vmcnt(6)
	s_barrier
	s_setprio 0
	v_mfma_f32_16x16x32_bf16 v[28:31], v[216:219], v[182:185], v[28:31]
	v_mfma_f32_16x16x32_bf16 v[24:27], v[230:233], v[182:185], v[24:27]
	v_mfma_f32_16x16x32_bf16 v[20:23], v[216:219], v[190:193], v[20:23]
	v_mfma_f32_16x16x32_bf16 v[16:19], v[230:233], v[190:193], v[16:19]
	v_mfma_f32_16x16x32_bf16 v[12:15], v[216:219], v[198:201], v[12:15]
	v_mfma_f32_16x16x32_bf16 v[8:11], v[230:233], v[198:201], v[8:11]
	v_mfma_f32_16x16x32_bf16 v[4:7], v[216:219], v[206:209], v[4:7]
	v_mfma_f32_16x16x32_bf16 v[0:3], v[230:233], v[206:209], v[0:3]
	v_mfma_f32_16x16x32_bf16 v[28:31], v[226:229], v[186:189], v[28:31]
	v_mfma_f32_16x16x32_bf16 v[24:27], v[234:237], v[186:189], v[24:27]
	v_mfma_f32_16x16x32_bf16 v[20:23], v[226:229], v[194:197], v[20:23]
	v_mfma_f32_16x16x32_bf16 v[16:19], v[234:237], v[194:197], v[16:19]
	v_mfma_f32_16x16x32_bf16 v[12:15], v[226:229], v[202:205], v[12:15]
	v_mfma_f32_16x16x32_bf16 v[8:11], v[234:237], v[202:205], v[8:11]
	v_mfma_f32_16x16x32_bf16 v[4:7], v[226:229], v[210:213], v[4:7]
	v_mfma_f32_16x16x32_bf16 v[0:3], v[234:237], v[210:213], v[0:3]
	s_setprio 1
	s_barrier
	ds_read_b128 v[142:145], v156
	ds_read_b128 v[170:173], v156 offset:1024
	ds_read_b128 v[174:177], v156 offset:2048
	ds_read_b128 v[178:181], v156 offset:3072
	v_readfirstlane_b32 s9, v157
	v_lshl_add_u64 v[216:217], v[222:223], 0, s[4:5]
	s_mov_b32 m0, s9
	v_readfirstlane_b32 s9, v158
	ds_read_b128 v[182:185], v148 offset:32768
	ds_read_b128 v[186:189], v148 offset:33792
	ds_read_b128 v[190:193], v147 offset:32768
	ds_read_b128 v[194:197], v147 offset:33792
	ds_read_b128 v[198:201], v146 offset:32768
	ds_read_b128 v[202:205], v146 offset:33792
	ds_read_b128 v[206:209], v141 offset:32768
	ds_read_b128 v[210:213], v141 offset:33792
	global_load_lds_dwordx4 v[216:217], off
	v_lshl_add_u64 v[216:217], v[224:225], 0, s[4:5]
	s_mov_b32 m0, s9
	s_nop 0
	global_load_lds_dwordx4 v[216:217], off
	s_waitcnt lgkmcnt(8)
	s_barrier
	s_waitcnt lgkmcnt(0)
	s_setprio 0
	s_waitcnt lgkmcnt(0)
	v_mfma_f32_16x16x32_bf16 v[126:129], v[142:145], v[182:185], v[126:129]
	v_mfma_f32_16x16x32_bf16 v[122:125], v[174:177], v[182:185], v[122:125]
	v_mfma_f32_16x16x32_bf16 v[118:121], v[142:145], v[190:193], v[118:121]
	v_mfma_f32_16x16x32_bf16 v[114:117], v[174:177], v[190:193], v[114:117]
	v_mfma_f32_16x16x32_bf16 v[110:113], v[142:145], v[198:201], v[110:113]
	v_mfma_f32_16x16x32_bf16 v[106:109], v[174:177], v[198:201], v[106:109]
	v_mfma_f32_16x16x32_bf16 v[102:105], v[142:145], v[206:209], v[102:105]
	v_mfma_f32_16x16x32_bf16 v[98:101], v[174:177], v[206:209], v[98:101]
	v_mfma_f32_16x16x32_bf16 v[126:129], v[170:173], v[186:189], v[126:129]
	v_mfma_f32_16x16x32_bf16 v[122:125], v[178:181], v[186:189], v[122:125]
	v_mfma_f32_16x16x32_bf16 v[118:121], v[170:173], v[194:197], v[118:121]
	v_mfma_f32_16x16x32_bf16 v[114:117], v[178:181], v[194:197], v[114:117]
	v_mfma_f32_16x16x32_bf16 v[110:113], v[170:173], v[202:205], v[110:113]
	v_mfma_f32_16x16x32_bf16 v[106:109], v[178:181], v[202:205], v[106:109]
	v_mfma_f32_16x16x32_bf16 v[102:105], v[170:173], v[210:213], v[102:105]
	v_mfma_f32_16x16x32_bf16 v[98:101], v[178:181], v[210:213], v[98:101]
	s_setprio 1
	s_barrier
	v_readfirstlane_b32 s9, v159
	v_lshl_add_u64 v[242:243], v[238:239], 0, s[46:47]
	s_mov_b32 m0, s9
	v_readfirstlane_b32 s9, v160
	ds_read_b128 v[216:219], v151
	ds_read_b128 v[226:229], v151 offset:1024
	ds_read_b128 v[230:233], v151 offset:2048
	ds_read_b128 v[234:237], v151 offset:3072
	global_load_lds_dwordx4 v[242:243], off
	v_lshl_add_u64 v[242:243], v[240:241], 0, s[46:47]
	s_mov_b32 m0, s9
	s_nop 0
	global_load_lds_dwordx4 v[242:243], off
	s_barrier
	s_waitcnt lgkmcnt(0)
	s_setprio 0
	s_waitcnt lgkmcnt(0)
	v_mfma_f32_16x16x32_bf16 v[94:97], v[216:219], v[182:185], v[94:97]
	v_mfma_f32_16x16x32_bf16 v[90:93], v[230:233], v[182:185], v[90:93]
	v_mfma_f32_16x16x32_bf16 v[86:89], v[216:219], v[190:193], v[86:89]
	v_mfma_f32_16x16x32_bf16 v[82:85], v[230:233], v[190:193], v[82:85]
	v_mfma_f32_16x16x32_bf16 v[78:81], v[216:219], v[198:201], v[78:81]
	v_mfma_f32_16x16x32_bf16 v[74:77], v[230:233], v[198:201], v[74:77]
	v_mfma_f32_16x16x32_bf16 v[70:73], v[216:219], v[206:209], v[70:73]
	v_mfma_f32_16x16x32_bf16 v[66:69], v[230:233], v[206:209], v[66:69]
	v_mfma_f32_16x16x32_bf16 v[94:97], v[226:229], v[186:189], v[94:97]
	v_mfma_f32_16x16x32_bf16 v[90:93], v[234:237], v[186:189], v[90:93]
	v_mfma_f32_16x16x32_bf16 v[86:89], v[226:229], v[194:197], v[86:89]
	v_mfma_f32_16x16x32_bf16 v[82:85], v[234:237], v[194:197], v[82:85]
	v_mfma_f32_16x16x32_bf16 v[78:81], v[226:229], v[202:205], v[78:81]
	v_mfma_f32_16x16x32_bf16 v[74:77], v[234:237], v[202:205], v[74:77]
	v_mfma_f32_16x16x32_bf16 v[70:73], v[226:229], v[210:213], v[70:73]
	v_mfma_f32_16x16x32_bf16 v[66:69], v[234:237], v[210:213], v[66:69]
	s_setprio 1
	v_readfirstlane_b32 s9, v161
	v_lshl_add_u64 v[222:223], v[222:223], 0, s[30:31]
	s_mov_b32 m0, s9
	v_readfirstlane_b32 s9, v162
	s_barrier
	ds_read_b128 v[182:185], v148 offset:49152
	ds_read_b128 v[186:189], v148 offset:50176
	ds_read_b128 v[190:193], v147 offset:49152
	ds_read_b128 v[194:197], v147 offset:50176
	ds_read_b128 v[198:201], v146 offset:49152
	ds_read_b128 v[202:205], v146 offset:50176
	ds_read_b128 v[206:209], v141 offset:49152
	ds_read_b128 v[210:213], v141 offset:50176
	global_load_lds_dwordx4 v[222:223], off
	v_lshl_add_u64 v[222:223], v[224:225], 0, s[30:31]
	s_mov_b32 m0, s9
	s_nop 0
	global_load_lds_dwordx4 v[222:223], off
	s_barrier
; #define STAGE_A(b, h, kt) { const u16* ap_ = A + (size_t)((h) * ahalf + (unsigned)(kt) * 64u); glds16(ap_ + ao0, l0 + SA_(b, h)); glds16(ap_ + ao1, l0 + SA_(b, h) + 8192); }
; #define STAGE_B(b, h, kt) { const u16* bp_ = ((h) ? B1 : B0) + (unsigned)(kt) * 64u; glds16(bp_ + bo0, l0 + SB_(b, h)); glds16(bp_ + bo1, l0 + SB_(b, h) + 8192); }
; #define LDA(dst, b, h) _Pragma("unroll") for (int m = 0; m < 4; ++m) _Pragma("unroll") for (int k = 0; k < 2; ++k) \
;     dst[m][k] = *(const bf16x8*)(lds + SA_(b, h) + lds_byte(wr * 64 + m * 16 + fr, k * 32 + fq * 8));
; #define LDB(dst, b, h) _Pragma("unroll") for (int n = 0; n < 2; ++n) _Pragma("unroll") for (int k = 0; k < 2; ++k) \
;     dst[n][k] = *(const bf16x8*)(lds + SB_(b, h) + lds_byte(wc * 32 + n * 16 + fr, k * 32 + fq * 8));
; #define MMA(ai, bj, At_, Bt_) { __builtin_amdgcn_s_setprio(1); \
;     _Pragma("unroll") for (int m = 0; m < 4; ++m) _Pragma("unroll") for (int n = 0; n < 2; ++n) _Pragma("unroll") for (int k = 0; k < 2; ++k) \
;       acc[ai][bj][m][n] = MFMA16(Bt_[n][k], At_[m][k], acc[ai][bj][m][n]); \
;     __builtin_amdgcn_s_setprio(0); }
; #define WAIT_V(n) asm volatile("s_waitcnt vmcnt(" #n ")" ::: "memory");
; #define WAIT_L(n) asm volatile("s_waitcnt lgkmcnt(" #n ")" ::: "memory");
; #define BAR __builtin_amdgcn_s_barrier();
; #define SCHED __builtin_amdgcn_sched_barrier(0);
; DI void gemm256(const u16* __restrict__ A, int lda, const u16* __restrict__ B0, const u16* __restrict__ B1, int ldb, int nt, acc_t& acc, char* lds) {
;     ...
;     BAR WAIT_L(0) MMA(1, 0, At, Bq0) BAR SCHED
;     STAGE_B(1, 1, t + 3)
;     WAIT_V(6) BAR MMA(1, 1, At, Bq1) BAR
;   }
;   { LDB(Bq0, 0, 0) LDA(At, 0, 0) STAGE_A(1, 1, nt - 1)
;     BAR WAIT_L(0) MMA(0, 0, At, Bq0) BAR
;     LDB(Bq1, 0, 1) BAR WAIT_L(0) MMA(0, 1, At, Bq1) BAR
	s_waitcnt lgkmcnt(0)
	s_setprio 0
	s_waitcnt lgkmcnt(0)
	v_mfma_f32_16x16x32_bf16 v[60:63], v[142:145], v[182:185], v[60:63]
	v_mfma_f32_16x16x32_bf16 v[56:59], v[174:177], v[182:185], v[56:59]
	v_mfma_f32_16x16x32_bf16 v[52:55], v[142:145], v[190:193], v[52:55]
	v_mfma_f32_16x16x32_bf16 v[48:51], v[174:177], v[190:193], v[48:51]
	v_mfma_f32_16x16x32_bf16 v[44:47], v[142:145], v[198:201], v[44:47]
	v_mfma_f32_16x16x32_bf16 v[40:43], v[174:177], v[198:201], v[40:43]
	v_mfma_f32_16x16x32_bf16 v[36:39], v[142:145], v[206:209], v[36:39]
	v_mfma_f32_16x16x32_bf16 v[32:35], v[174:177], v[206:209], v[32:35]
	v_mfma_f32_16x16x32_bf16 v[60:63], v[170:173], v[186:189], v[60:63]
	v_mfma_f32_16x16x32_bf16 v[56:59], v[178:181], v[186:189], v[56:59]
	v_mfma_f32_16x16x32_bf16 v[52:55], v[170:173], v[194:197], v[52:55]
	v_mfma_f32_16x16x32_bf16 v[48:51], v[178:181], v[194:197], v[48:51]
	v_mfma_f32_16x16x32_bf16 v[44:47], v[170:173], v[202:205], v[44:47]
	v_mfma_f32_16x16x32_bf16 v[40:43], v[178:181], v[202:205], v[40:43]
	v_mfma_f32_16x16x32_bf16 v[36:39], v[170:173], v[210:213], v[36:39]
	v_mfma_f32_16x16x32_bf16 v[32:35], v[178:181], v[210:213], v[32:35]
	s_setprio 1
	s_barrier
	v_readfirstlane_b32 s9, v163
	v_lshl_add_u64 v[142:143], v[238:239], 0, s[48:49]
	s_mov_b32 m0, s9
	v_readfirstlane_b32 s9, v164
	global_load_lds_dwordx4 v[142:143], off
	v_lshl_add_u64 v[142:143], v[240:241], 0, s[48:49]
	s_mov_b32 m0, s9
	s_nop 0
	global_load_lds_dwordx4 v[142:143], off
	s_waitcnt vmcnt(6)
	s_barrier
	s_setprio 0
	v_mfma_f32_16x16x32_bf16 v[28:31], v[216:219], v[182:185], v[28:31]
	v_mfma_f32_16x16x32_bf16 v[24:27], v[230:233], v[182:185], v[24:27]
	v_mfma_f32_16x16x32_bf16 v[20:23], v[216:219], v[190:193], v[20:23]
	v_mfma_f32_16x16x32_bf16 v[16:19], v[230:233], v[190:193], v[16:19]
	v_mfma_f32_16x16x32_bf16 v[12:15], v[216:219], v[198:201], v[12:15]
	v_mfma_f32_16x16x32_bf16 v[8:11], v[230:233], v[198:201], v[8:11]
	v_mfma_f32_16x16x32_bf16 v[4:7], v[216:219], v[206:209], v[4:7]
	v_mfma_f32_16x16x32_bf16 v[0:3], v[230:233], v[206:209], v[0:3]
	v_mfma_f32_16x16x32_bf16 v[28:31], v[226:229], v[186:189], v[28:31]
	v_mfma_f32_16x16x32_bf16 v[24:27], v[234:237], v[186:189], v[24:27]
	v_mfma_f32_16x16x32_bf16 v[20:23], v[226:229], v[194:197], v[20:23]
	v_mfma_f32_16x16x32_bf16 v[16:19], v[234:237], v[194:197], v[16:19]
	v_mfma_f32_16x16x32_bf16 v[12:15], v[226:229], v[202:205], v[12:15]
	v_mfma_f32_16x16x32_bf16 v[8:11], v[234:237], v[202:205], v[8:11]
	v_mfma_f32_16x16x32_bf16 v[4:7], v[226:229], v[210:213], v[4:7]
	v_mfma_f32_16x16x32_bf16 v[0:3], v[234:237], v[210:213], v[0:3]
	s_setprio 1
	s_add_i32 s7, s7, 2
	s_add_u32 s36, s36, 0x100
	s_addc_u32 s37, s37, 0
	s_cmp_lt_u32 s7, 12
	s_barrier
	s_cbranch_scc1 .LBB0_1172
	s_add_u32 s28, s28, 0x40780
	s_addc_u32 s29, s29, 0
	v_readfirstlane_b32 s7, v167
	v_lshl_add_u64 v[162:163], v[64:65], 1, s[28:29]
	s_mov_b32 m0, s7
	v_readfirstlane_b32 s7, v168
	ds_read_b128 v[132:135], v166
	ds_read_b128 v[136:139], v166 offset:1024
	ds_read_b128 v[142:145], v166 offset:2048
	ds_read_b128 v[152:155], v166 offset:3072
	ds_read_b128 v[158:161], v148
	ds_read_b128 v[170:173], v148 offset:1024
	ds_read_b128 v[174:177], v147
	ds_read_b128 v[178:181], v147 offset:1024
	ds_read_b128 v[182:185], v146
	ds_read_b128 v[186:189], v146 offset:1024
	ds_read_b128 v[190:193], v141
	ds_read_b128 v[194:197], v141 offset:1024
	global_load_lds_dwordx4 v[162:163], off
	v_lshl_add_u64 v[130:131], v[130:131], 1, s[28:29]
	s_mov_b32 m0, s7
	s_nop 0
	global_load_lds_dwordx4 v[130:131], off
	s_barrier
	s_waitcnt lgkmcnt(0)
	s_setprio 0
	s_waitcnt lgkmcnt(0)
	v_mfma_f32_16x16x32_bf16 v[126:129], v[132:135], v[158:161], v[126:129]
	v_mfma_f32_16x16x32_bf16 v[122:125], v[142:145], v[158:161], v[122:125]
	v_mfma_f32_16x16x32_bf16 v[110:113], v[132:135], v[182:185], v[110:113]
	v_mfma_f32_16x16x32_bf16 v[106:109], v[142:145], v[182:185], v[106:109]
	v_mfma_f32_16x16x32_bf16 v[102:105], v[132:135], v[190:193], v[102:105]
	v_mfma_f32_16x16x32_bf16 v[98:101], v[142:145], v[190:193], v[98:101]
	v_mfma_f32_16x16x32_bf16 v[126:129], v[136:139], v[170:173], v[126:129]
	v_mfma_f32_16x16x32_bf16 v[122:125], v[152:155], v[170:173], v[122:125]
	v_mfma_f32_16x16x32_bf16 v[118:121], v[132:135], v[174:177], v[118:121]
	v_mfma_f32_16x16x32_bf16 v[114:117], v[142:145], v[174:177], v[114:117]
	v_mfma_f32_16x16x32_bf16 v[110:113], v[136:139], v[186:189], v[110:113]
	v_mfma_f32_16x16x32_bf16 v[106:109], v[152:155], v[186:189], v[106:109]
	v_mfma_f32_16x16x32_bf16 v[102:105], v[136:139], v[194:197], v[102:105]
	v_mfma_f32_16x16x32_bf16 v[98:101], v[152:155], v[194:197], v[98:101]
	v_mfma_f32_16x16x32_bf16 v[166:169], v[136:139], v[178:181], v[118:121]
	v_mfma_f32_16x16x32_bf16 v[198:201], v[152:155], v[178:181], v[114:117]
	s_setprio 1
	s_barrier
	s_nop 0
	ds_read_b128 v[114:117], v165
	ds_read_b128 v[118:121], v165 offset:1024
	ds_read_b128 v[202:205], v165 offset:2048
	ds_read_b128 v[162:165], v165 offset:3072
	s_barrier
	s_waitcnt lgkmcnt(0)
	s_setprio 0
	s_waitcnt lgkmcnt(0)
	v_mfma_f32_16x16x32_bf16 v[94:97], v[114:117], v[158:161], v[94:97]
	v_mfma_f32_16x16x32_bf16 v[90:93], v[202:205], v[158:161], v[90:93]
	v_mfma_f32_16x16x32_bf16 v[78:81], v[114:117], v[182:185], v[78:81]
	v_mfma_f32_16x16x32_bf16 v[74:77], v[202:205], v[182:185], v[74:77]
	v_mfma_f32_16x16x32_bf16 v[70:73], v[114:117], v[190:193], v[70:73]
	v_mfma_f32_16x16x32_bf16 v[66:69], v[202:205], v[190:193], v[66:69]
	v_mfma_f32_16x16x32_bf16 v[94:97], v[118:121], v[170:173], v[94:97]
	v_mfma_f32_16x16x32_bf16 v[90:93], v[162:165], v[170:173], v[90:93]
	v_mfma_f32_16x16x32_bf16 v[86:89], v[114:117], v[174:177], v[86:89]
	v_mfma_f32_16x16x32_bf16 v[82:85], v[202:205], v[174:177], v[82:85]
	v_mfma_f32_16x16x32_bf16 v[78:81], v[118:121], v[186:189], v[78:81]
	v_mfma_f32_16x16x32_bf16 v[74:77], v[162:165], v[186:189], v[74:77]
	v_mfma_f32_16x16x32_bf16 v[70:73], v[118:121], v[194:197], v[70:73]
	v_mfma_f32_16x16x32_bf16 v[66:69], v[162:165], v[194:197], v[66:69]
	v_mfma_f32_16x16x32_bf16 v[158:161], v[118:121], v[178:181], v[86:89]
	v_mfma_f32_16x16x32_bf16 v[170:173], v[162:165], v[178:181], v[82:85]
	s_setprio 1
	s_barrier
; #define LDA(dst, b, h) _Pragma("unroll") for (int m = 0; m < 4; ++m) _Pragma("unroll") for (int k = 0; k < 2; ++k) \
;     dst[m][k] = *(const bf16x8*)(lds + SA_(b, h) + lds_byte(wr * 64 + m * 16 + fr, k * 32 + fq * 8));
; #define LDB(dst, b, h) _Pragma("unroll") for (int n = 0; n < 2; ++n) _Pragma("unroll") for (int k = 0; k < 2; ++k) \
;     dst[n][k] = *(const bf16x8*)(lds + SB_(b, h) + lds_byte(wc * 32 + n * 16 + fr, k * 32 + fq * 8));
; #define MMA(ai, bj, At_, Bt_) { __builtin_amdgcn_s_setprio(1); \
;     _Pragma("unroll") for (int m = 0; m < 4; ++m) _Pragma("unroll") for (int n = 0; n < 2; ++n) _Pragma("unroll") for (int k = 0; k < 2; ++k) \
;       acc[ai][bj][m][n] = MFMA16(Bt_[n][k], At_[m][k], acc[ai][bj][m][n]); \
;     __builtin_amdgcn_s_setprio(0); }
; #define WAIT_V(n) asm volatile("s_waitcnt vmcnt(" #n ")" ::: "memory");
; #define WAIT_L(n) asm volatile("s_waitcnt lgkmcnt(" #n ")" ::: "memory");
; #define BAR __builtin_amdgcn_s_barrier();
; DI void gemm256(const u16* __restrict__ A, int lda, const u16* __restrict__ B0, const u16* __restrict__ B1, int ldb, int nt, acc_t& acc, char* lds) {
;     ...
;     LDA(At, 0, 1) WAIT_V(4) BAR WAIT_L(0) MMA(1, 0, At, Bq0) MMA(1, 1, At, Bq1) BAR }
;   { LDB(Bq0, 1, 0) LDA(At, 1, 0) WAIT_V(2) BAR WAIT_L(0) MMA(0, 0, At, Bq0) BAR
	s_nop 0
	ds_read_b128 v[82:85], v148 offset:16384
	ds_read_b128 v[86:89], v148 offset:17408
	ds_read_b128 v[174:177], v147 offset:16384
	ds_read_b128 v[178:181], v147 offset:17408
	ds_read_b128 v[182:185], v146 offset:16384
	ds_read_b128 v[186:189], v146 offset:17408
	ds_read_b128 v[190:193], v141 offset:16384
	ds_read_b128 v[194:197], v141 offset:17408
	s_waitcnt vmcnt(4)
	s_barrier
	s_waitcnt lgkmcnt(0)
	s_setprio 0
	s_waitcnt lgkmcnt(0)
	v_mfma_f32_16x16x32_bf16 v[36:39], v[132:135], v[190:193], v[36:39]
	v_mfma_f32_16x16x32_bf16 v[32:35], v[142:145], v[190:193], v[32:35]
	v_mfma_f32_16x16x32_bf16 v[60:63], v[132:135], v[82:85], v[60:63]
	v_mfma_f32_16x16x32_bf16 v[56:59], v[142:145], v[82:85], v[56:59]
	v_mfma_f32_16x16x32_bf16 v[52:55], v[132:135], v[174:177], v[52:55]
	v_mfma_f32_16x16x32_bf16 v[48:51], v[142:145], v[174:177], v[48:51]
	v_mfma_f32_16x16x32_bf16 v[44:47], v[132:135], v[182:185], v[44:47]
	v_mfma_f32_16x16x32_bf16 v[40:43], v[142:145], v[182:185], v[40:43]
	v_mfma_f32_16x16x32_bf16 v[36:39], v[136:139], v[194:197], v[36:39]
	v_mfma_f32_16x16x32_bf16 v[32:35], v[152:155], v[194:197], v[32:35]
	v_mfma_f32_16x16x32_bf16 v[206:209], v[136:139], v[86:89], v[60:63]
	v_mfma_f32_16x16x32_bf16 v[210:213], v[152:155], v[86:89], v[56:59]
	v_mfma_f32_16x16x32_bf16 v[216:219], v[136:139], v[178:181], v[52:55]
	v_mfma_f32_16x16x32_bf16 v[226:229], v[152:155], v[178:181], v[48:51]
	v_mfma_f32_16x16x32_bf16 v[230:233], v[136:139], v[186:189], v[44:47]
	v_mfma_f32_16x16x32_bf16 v[234:237], v[152:155], v[186:189], v[40:43]
	s_setprio 1
	s_setprio 0
	v_mfma_f32_16x16x32_bf16 v[12:15], v[114:117], v[182:185], v[12:15]
	v_mfma_f32_16x16x32_bf16 v[8:11], v[202:205], v[182:185], v[8:11]
	v_mfma_f32_16x16x32_bf16 v[28:31], v[114:117], v[82:85], v[28:31]
	v_mfma_f32_16x16x32_bf16 v[24:27], v[202:205], v[82:85], v[24:27]
	v_mfma_f32_16x16x32_bf16 v[20:23], v[114:117], v[174:177], v[20:23]
	v_mfma_f32_16x16x32_bf16 v[16:19], v[202:205], v[174:177], v[16:19]
	v_mfma_f32_16x16x32_bf16 v[12:15], v[118:121], v[186:189], v[12:15]
	v_mfma_f32_16x16x32_bf16 v[8:11], v[162:165], v[186:189], v[8:11]
	v_mfma_f32_16x16x32_bf16 v[4:7], v[114:117], v[190:193], v[4:7]
	v_mfma_f32_16x16x32_bf16 v[0:3], v[202:205], v[190:193], v[0:3]
	v_mfma_f32_16x16x32_bf16 v[130:133], v[118:121], v[86:89], v[28:31]
	v_mfma_f32_16x16x32_bf16 v[134:137], v[162:165], v[86:89], v[24:27]
	v_mfma_f32_16x16x32_bf16 v[142:145], v[118:121], v[178:181], v[20:23]
	v_mfma_f32_16x16x32_bf16 v[152:155], v[162:165], v[178:181], v[16:19]
	v_mfma_f32_16x16x32_bf16 v[174:177], v[118:121], v[194:197], v[4:7]
	v_mfma_f32_16x16x32_bf16 v[162:165], v[162:165], v[194:197], v[0:3]
	s_setprio 1
	s_barrier
	s_nop 0
	ds_read_b128 v[0:3], v156
	ds_read_b128 v[4:7], v156 offset:1024
	ds_read_b128 v[178:181], v156 offset:2048
	ds_read_b128 v[182:185], v156 offset:3072
	ds_read_b128 v[16:19], v148 offset:32768
	ds_read_b128 v[20:23], v148 offset:33792
	ds_read_b128 v[40:43], v147 offset:32768
	ds_read_b128 v[44:47], v147 offset:33792
	ds_read_b128 v[56:59], v146 offset:32768
	ds_read_b128 v[60:63], v146 offset:33792
	ds_read_b128 v[186:189], v141 offset:32768
	ds_read_b128 v[190:193], v141 offset:33792
	s_waitcnt vmcnt(2)
	s_barrier
	s_waitcnt lgkmcnt(0)
	s_setprio 0
	s_waitcnt lgkmcnt(0)
	v_mfma_f32_16x16x32_bf16 v[24:27], v[0:3], v[16:19], v[126:129]
	v_mfma_f32_16x16x32_bf16 v[114:117], v[4:7], v[20:23], v[24:27]
	v_mfma_f32_16x16x32_bf16 v[24:27], v[178:181], v[16:19], v[122:125]
	v_mfma_f32_16x16x32_bf16 v[118:121], v[182:185], v[20:23], v[24:27]
	v_mfma_f32_16x16x32_bf16 v[24:27], v[0:3], v[40:43], v[166:169]
	v_mfma_f32_16x16x32_bf16 v[82:85], v[4:7], v[44:47], v[24:27]
	v_mfma_f32_16x16x32_bf16 v[24:27], v[178:181], v[40:43], v[198:201]
	v_mfma_f32_16x16x32_bf16 v[86:89], v[182:185], v[44:47], v[24:27]
	v_mfma_f32_16x16x32_bf16 v[24:27], v[0:3], v[56:59], v[110:113]
	v_mfma_f32_16x16x32_bf16 v[48:51], v[4:7], v[60:63], v[24:27]
	v_mfma_f32_16x16x32_bf16 v[24:27], v[178:181], v[56:59], v[106:109]
	v_mfma_f32_16x16x32_bf16 v[52:55], v[182:185], v[60:63], v[24:27]
	v_mfma_f32_16x16x32_bf16 v[24:27], v[0:3], v[186:189], v[102:105]
	v_mfma_f32_16x16x32_bf16 v[28:31], v[178:181], v[186:189], v[98:101]
	v_mfma_f32_16x16x32_bf16 v[24:27], v[4:7], v[190:193], v[24:27]
	v_mfma_f32_16x16x32_bf16 v[28:31], v[182:185], v[190:193], v[28:31]
	s_setprio 1
	s_barrier
; #define LDA(dst, b, h) _Pragma("unroll") for (int m = 0; m < 4; ++m) _Pragma("unroll") for (int k = 0; k < 2; ++k) \
;     dst[m][k] = *(const bf16x8*)(lds + SA_(b, h) + lds_byte(wr * 64 + m * 16 + fr, k * 32 + fq * 8));
; #define LDB(dst, b, h) _Pragma("unroll") for (int n = 0; n < 2; ++n) _Pragma("unroll") for (int k = 0; k < 2; ++k) \
;     dst[n][k] = *(const bf16x8*)(lds + SB_(b, h) + lds_byte(wc * 32 + n * 16 + fr, k * 32 + fq * 8));
; #define MMA(ai, bj, At_, Bt_) { __builtin_amdgcn_s_setprio(1); \
;     _Pragma("unroll") for (int m = 0; m < 4; ++m) _Pragma("unroll") for (int n = 0; n < 2; ++n) _Pragma("unroll") for (int k = 0; k < 2; ++k) \
;       acc[ai][bj][m][n] = MFMA16(Bt_[n][k], At_[m][k], acc[ai][bj][m][n]); \
;     __builtin_amdgcn_s_setprio(0); }
; #define WAIT_V(n) asm volatile("s_waitcnt vmcnt(" #n ")" ::: "memory");
; #define WAIT_L(n) asm volatile("s_waitcnt lgkmcnt(" #n ")" ::: "memory");
; #define BAR __builtin_amdgcn_s_barrier();
; DI void gemm256(const u16* __restrict__ A, int lda, const u16* __restrict__ B0, const u16* __restrict__ B1, int ldb, int nt, acc_t& acc, char* lds) {
;     ...
;     LDB(Bq1, 1, 1) WAIT_V(0) BAR WAIT_L(0) MMA(0, 1, At, Bq1) BAR
;     LDA(At, 1, 1) BAR WAIT_L(0) MMA(1, 0, At, Bq0) MMA(1, 1, At, Bq1) BAR }
;   if (wr == 0) BAR
;   __syncthreads();
	ds_read_b128 v[166:169], v151
	ds_read_b128 v[194:197], v151 offset:1024
	ds_read_b128 v[198:201], v151 offset:2048
	ds_read_b128 v[202:205], v151 offset:3072
	s_waitcnt vmcnt(0)
	s_barrier
	s_waitcnt lgkmcnt(0)
	s_setprio 0
	s_waitcnt lgkmcnt(0)
	v_mfma_f32_16x16x32_bf16 v[94:97], v[166:169], v[16:19], v[94:97]
	v_mfma_f32_16x16x32_bf16 v[16:19], v[198:201], v[16:19], v[90:93]
	v_mfma_f32_16x16x32_bf16 v[126:129], v[202:205], v[20:23], v[16:19]
	v_mfma_f32_16x16x32_bf16 v[16:19], v[166:169], v[40:43], v[158:161]
	v_mfma_f32_16x16x32_bf16 v[106:109], v[194:197], v[44:47], v[16:19]
	v_mfma_f32_16x16x32_bf16 v[16:19], v[198:201], v[40:43], v[170:173]
	v_mfma_f32_16x16x32_bf16 v[110:113], v[202:205], v[44:47], v[16:19]
	v_mfma_f32_16x16x32_bf16 v[16:19], v[166:169], v[56:59], v[78:81]
	v_mfma_f32_16x16x32_bf16 v[90:93], v[194:197], v[60:63], v[16:19]
	v_mfma_f32_16x16x32_bf16 v[16:19], v[198:201], v[56:59], v[74:77]
	v_mfma_f32_16x16x32_bf16 v[122:125], v[194:197], v[20:23], v[94:97]
	v_mfma_f32_16x16x32_bf16 v[94:97], v[202:205], v[60:63], v[16:19]
	v_mfma_f32_16x16x32_bf16 v[16:19], v[166:169], v[186:189], v[70:73]
	v_mfma_f32_16x16x32_bf16 v[56:59], v[194:197], v[190:193], v[16:19]
	v_mfma_f32_16x16x32_bf16 v[16:19], v[198:201], v[186:189], v[66:69]
	v_mfma_f32_16x16x32_bf16 v[60:63], v[202:205], v[190:193], v[16:19]
	s_setprio 1
	s_barrier
	ds_read_b128 v[66:69], v148 offset:49152
	ds_read_b128 v[70:73], v148 offset:50176
	ds_read_b128 v[148:151], v147 offset:49152
	ds_read_b128 v[156:159], v147 offset:50176
	ds_read_b128 v[170:173], v146 offset:49152
	ds_read_b128 v[186:189], v146 offset:50176
	ds_read_b128 v[190:193], v141 offset:49152
	ds_read_b128 v[238:241], v141 offset:50176
	s_barrier
	s_waitcnt lgkmcnt(0)
	s_setprio 0
	s_waitcnt lgkmcnt(0)
	v_mfma_f32_16x16x32_bf16 v[16:19], v[0:3], v[66:69], v[206:209]
	v_mfma_f32_16x16x32_bf16 v[74:77], v[4:7], v[70:73], v[16:19]
	v_mfma_f32_16x16x32_bf16 v[16:19], v[178:181], v[66:69], v[210:213]
	v_mfma_f32_16x16x32_bf16 v[78:81], v[182:185], v[70:73], v[16:19]
	v_mfma_f32_16x16x32_bf16 v[16:19], v[0:3], v[148:151], v[216:219]
	v_mfma_f32_16x16x32_bf16 v[40:43], v[4:7], v[156:159], v[16:19]
	v_mfma_f32_16x16x32_bf16 v[16:19], v[178:181], v[148:151], v[226:229]
	v_mfma_f32_16x16x32_bf16 v[44:47], v[182:185], v[156:159], v[16:19]
	v_mfma_f32_16x16x32_bf16 v[16:19], v[0:3], v[170:173], v[230:233]
	v_mfma_f32_16x16x32_bf16 v[0:3], v[0:3], v[190:193], v[36:39]
	v_mfma_f32_16x16x32_bf16 v[16:19], v[4:7], v[186:189], v[16:19]
	v_mfma_f32_16x16x32_bf16 v[20:23], v[178:181], v[170:173], v[234:237]
	v_mfma_f32_16x16x32_bf16 v[0:3], v[4:7], v[238:241], v[0:3]
	v_mfma_f32_16x16x32_bf16 v[4:7], v[178:181], v[190:193], v[32:35]
	v_mfma_f32_16x16x32_bf16 v[20:23], v[182:185], v[186:189], v[20:23]
	v_mfma_f32_16x16x32_bf16 v[4:7], v[182:185], v[238:241], v[4:7]
	s_setprio 1
	s_setprio 0
	v_mfma_f32_16x16x32_bf16 v[32:35], v[166:169], v[66:69], v[130:133]
	v_mfma_f32_16x16x32_bf16 v[98:101], v[194:197], v[70:73], v[32:35]
	v_mfma_f32_16x16x32_bf16 v[32:35], v[198:201], v[66:69], v[134:137]
	v_mfma_f32_16x16x32_bf16 v[102:105], v[202:205], v[70:73], v[32:35]
	v_mfma_f32_16x16x32_bf16 v[32:35], v[166:169], v[148:151], v[142:145]
	v_mfma_f32_16x16x32_bf16 v[66:69], v[194:197], v[156:159], v[32:35]
	v_mfma_f32_16x16x32_bf16 v[32:35], v[198:201], v[148:151], v[152:155]
	v_mfma_f32_16x16x32_bf16 v[12:15], v[166:169], v[170:173], v[12:15]
	v_mfma_f32_16x16x32_bf16 v[8:11], v[198:201], v[170:173], v[8:11]
	v_mfma_f32_16x16x32_bf16 v[70:73], v[202:205], v[156:159], v[32:35]
	v_mfma_f32_16x16x32_bf16 v[32:35], v[194:197], v[186:189], v[12:15]
	v_mfma_f32_16x16x32_bf16 v[36:39], v[202:205], v[186:189], v[8:11]
	v_mfma_f32_16x16x32_bf16 v[8:11], v[166:169], v[190:193], v[174:177]
	v_mfma_f32_16x16x32_bf16 v[12:15], v[198:201], v[190:193], v[162:165]
	v_mfma_f32_16x16x32_bf16 v[8:11], v[194:197], v[238:241], v[8:11]
	v_mfma_f32_16x16x32_bf16 v[12:15], v[202:205], v[238:241], v[12:15]
	s_setprio 1
	s_movk_i32 s7, 0x100
	v_cmp_gt_u32_e32 vcc, s7, v140
	s_barrier
	s_and_saveexec_b64 s[28:29], vcc
	s_cbranch_execz .LBB0_1175
	s_barrier

; #define STAGE_A(b, h, kt) { const u16* ap_ = A + (size_t)((h) * ahalf + (unsigned)(kt) * 64u); glds16(ap_ + ao0, l0 + SA_(b, h)); glds16(ap_ + ao1, l0 + SA_(b, h) + 8192); }
; #define STAGE_B(b, h, kt) { const u16* bp_ = ((h) ? B1 : B0) + (unsigned)(kt) * 64u; glds16(bp_ + bo0, l0 + SB_(b, h)); glds16(bp_ + bo1, l0 + SB_(b, h) + 8192); }
; #define LDA(dst, b, h) _Pragma("unroll") for (int m = 0; m < 4; ++m) _Pragma("unroll") for (int k = 0; k < 2; ++k) \
;     dst[m][k] = *(const bf16x8*)(lds + SA_(b, h) + lds_byte(wr * 64 + m * 16 + fr, k * 32 + fq * 8));
; #define LDB(dst, b, h) _Pragma("unroll") for (int n = 0; n < 2; ++n) _Pragma("unroll") for (int k = 0; k < 2; ++k) \
;     dst[n][k] = *(const bf16x8*)(lds + SB_(b, h) + lds_byte(wc * 32 + n * 16 + fr, k * 32 + fq * 8));
; #define MMA(ai, bj, At_, Bt_) { __builtin_amdgcn_s_setprio(1); \
;     _Pragma("unroll") for (int m = 0; m < 4; ++m) _Pragma("unroll") for (int n = 0; n < 2; ++n) _Pragma("unroll") for (int k = 0; k < 2; ++k) \
;       acc[ai][bj][m][n] = MFMA16(Bt_[n][k], At_[m][k], acc[ai][bj][m][n]); \
;     __builtin_amdgcn_s_setprio(0); }
; #define WAIT_V(n) asm volatile("s_waitcnt vmcnt(" #n ")" ::: "memory");
; #define WAIT_L(n) asm volatile("s_waitcnt lgkmcnt(" #n ")" ::: "memory");
; #define BAR __builtin_amdgcn_s_barrier();
; #define SCHED __builtin_amdgcn_sched_barrier(0);
; DI void gemm256(const u16* __restrict__ A, int lda, const u16* __restrict__ B0, const u16* __restrict__ B1, int ldb, int nt, acc_t& acc, char* lds) {
;     ...
;   WAIT_V(0)
;   STAGE_B(0, 0, 0) STAGE_A(0, 0, 0) STAGE_B(0, 1, 0) STAGE_A(0, 1, 0)
;   if (wr == 1) BAR
;   WAIT_V(4) BAR
;   STAGE_B(1, 0, 1) STAGE_A(1, 0, 1) STAGE_B(1, 1, 1)
;   WAIT_V(6) BAR
;   for (int t = 0; t < nt - 2; t += 2) {
;     LDB(Bq0, 0, 0) SCHED LDA(At, 0, 0) STAGE_A(1, 1, t + 1)
;     WAIT_L(8) BAR WAIT_L(0) MMA(0, 0, At, Bq0) BAR SCHED
;     LDB(Bq1, 0, 1) STAGE_B(0, 0, t + 2)
;     BAR WAIT_L(0) MMA(0, 1, At, Bq1) BAR
;     LDA(At, 0, 1) STAGE_A(0, 0, t + 2)
;     BAR WAIT_L(0) MMA(1, 0, At, Bq0) BAR SCHED
.LBB0_1255:
	s_or_b64 exec, exec, s[28:29]
	v_add_u32_e32 v29, 0x18000, v20
	s_mov_b64 s[48:49], 0x80
	v_readfirstlane_b32 s47, v29
	v_add_u32_e32 v29, 0x1a000, v20
	v_lshl_add_u64 v[26:27], v[12:13], 0, s[48:49]
	s_mov_b32 m0, s47
	v_readfirstlane_b32 s46, v29
	v_add_u32_e32 v29, 0x8000, v20
	s_waitcnt vmcnt(4)
	s_barrier
	global_load_lds_dwordx4 v[26:27], off
	v_lshl_add_u64 v[26:27], v[14:15], 0, s[48:49]
	s_mov_b32 m0, s46
	v_readfirstlane_b32 s44, v29
	v_add_u32_e32 v29, 0xa000, v20
	global_load_lds_dwordx4 v[26:27], off
	v_lshl_add_u64 v[26:27], v[8:9], 0, s[48:49]
	s_mov_b32 m0, s44
	v_readfirstlane_b32 s29, v29
	v_add_u32_e32 v29, 0x1c000, v20
	global_load_lds_dwordx4 v[26:27], off
	v_lshl_add_u64 v[26:27], v[10:11], 0, s[48:49]
	s_mov_b32 m0, s29
	v_readfirstlane_b32 s28, v29
	v_add_u32_e32 v29, 0x1e000, v20
	global_load_lds_dwordx4 v[26:27], off
	v_lshl_add_u64 v[26:27], v[4:5], 0, s[48:49]
	s_mov_b32 m0, s28
	v_readfirstlane_b32 s2, v29
	global_load_lds_dwordx4 v[26:27], off
	v_lshl_add_u64 v[26:27], v[6:7], 0, s[48:49]
	s_mov_b32 m0, s2
	v_and_b32_e32 v17, 15, v130
	global_load_lds_dwordx4 v[26:27], off
	v_lshlrev_b32_e32 v26, 2, v130
	v_and_b32_e32 v28, 48, v130
	v_lshlrev_b32_e32 v17, 6, v17
	v_and_b32_e32 v26, 32, v26
	v_lshlrev_b32_e32 v29, 6, v130
	v_bitop3_b32 v27, v17, v26, v28 bitop3:0x36
	s_add_i32 s48, 0, 0x10000
	v_and_b32_e32 v30, 0x3000, v29
	v_and_b32_e32 v29, 0x3c0, v29
	s_add_i32 s49, 0, 0x14000
	s_add_i32 s52, 0, 0x18000
	s_add_i32 s53, 0, 0x1c000
	v_add3_u32 v131, s48, v27, v30
	v_lshlrev_b32_e32 v16, 13, v16
	v_bitop3_b32 v26, v29, v26, v28 bitop3:0x36
	s_waitcnt vmcnt(6)
	s_barrier
	v_add3_u32 v17, 0, v27, v16
	v_add3_u32 v16, 0, v26, v16
	v_add3_u32 v212, s49, v27, v30
	v_add3_u32 v213, s52, v27, v30
	v_add3_u32 v222, s53, v27, v30
	ds_read_b128 v[26:29], v131
	ds_read_b128 v[30:33], v131 offset:1024
	ds_read_b128 v[34:37], v131 offset:2048
	ds_read_b128 v[38:41], v131 offset:3072
	v_add_u32_e32 v78, 0xe000, v20
	v_add_u32_e32 v64, 0xc000, v20
	s_add_u32 s56, s22, 0x10080
	s_addc_u32 s57, s23, 0
	v_readfirstlane_b32 s54, v64
	v_lshl_add_u64 v[62:63], s[56:57], 0, v[0:1]
	s_mov_b32 m0, s54
	v_readfirstlane_b32 s45, v78
	ds_read_b128 v[42:45], v17
	ds_read_b128 v[46:49], v17 offset:1024
	ds_read_b128 v[50:53], v16 offset:2048
	ds_read_b128 v[54:57], v16 offset:3072
	ds_read_b128 v[58:61], v16 offset:4096
	ds_read_b128 v[66:69], v16 offset:5120
	ds_read_b128 v[70:73], v16 offset:6144
	ds_read_b128 v[74:77], v16 offset:7168
	global_load_lds_dwordx4 v[62:63], off
	v_lshl_add_u64 v[62:63], s[56:57], 0, v[2:3]
	s_mov_b32 m0, s45
	s_nop 0
	global_load_lds_dwordx4 v[62:63], off
	s_waitcnt lgkmcnt(8)
	s_barrier
	s_waitcnt lgkmcnt(0)
	s_setprio 0
	s_waitcnt lgkmcnt(0)
	v_mfma_f32_16x16x32_bf16 v[78:81], v[26:29], v[42:45], 0
	v_mfma_f32_16x16x32_bf16 v[82:85], v[34:37], v[42:45], 0
	v_mfma_f32_16x16x32_bf16 v[86:89], v[26:29], v[50:53], 0
	v_mfma_f32_16x16x32_bf16 v[90:93], v[34:37], v[50:53], 0
	v_mfma_f32_16x16x32_bf16 v[94:97], v[26:29], v[58:61], 0
	v_mfma_f32_16x16x32_bf16 v[98:101], v[34:37], v[58:61], 0
	v_mfma_f32_16x16x32_bf16 v[102:105], v[26:29], v[70:73], 0
	v_mfma_f32_16x16x32_bf16 v[106:109], v[34:37], v[70:73], 0
	v_mfma_f32_16x16x32_bf16 v[78:81], v[30:33], v[46:49], v[78:81]
	v_mfma_f32_16x16x32_bf16 v[82:85], v[38:41], v[46:49], v[82:85]
	v_mfma_f32_16x16x32_bf16 v[86:89], v[30:33], v[54:57], v[86:89]
	v_mfma_f32_16x16x32_bf16 v[90:93], v[38:41], v[54:57], v[90:93]
	v_mfma_f32_16x16x32_bf16 v[94:97], v[30:33], v[66:69], v[94:97]
	v_mfma_f32_16x16x32_bf16 v[98:101], v[38:41], v[66:69], v[98:101]
	v_mfma_f32_16x16x32_bf16 v[102:105], v[30:33], v[74:77], v[102:105]
	v_mfma_f32_16x16x32_bf16 v[106:109], v[38:41], v[74:77], v[106:109]
	s_setprio 1
	s_barrier
	s_mov_b64 s[56:57], 0x100
	v_readfirstlane_b32 s55, v24
	v_lshl_add_u64 v[62:63], v[12:13], 0, s[56:57]
	s_mov_b32 m0, s55
	v_readfirstlane_b32 s55, v25
	ds_read_b128 v[110:113], v212
	ds_read_b128 v[114:117], v212 offset:1024
	ds_read_b128 v[118:121], v212 offset:2048
	ds_read_b128 v[122:125], v212 offset:3072
	global_load_lds_dwordx4 v[62:63], off
	v_lshl_add_u64 v[62:63], v[14:15], 0, s[56:57]
	s_mov_b32 m0, s55
	s_nop 0
	global_load_lds_dwordx4 v[62:63], off
	s_barrier
	s_waitcnt lgkmcnt(0)
	s_setprio 0
	s_waitcnt lgkmcnt(0)
	v_mfma_f32_16x16x32_bf16 v[126:129], v[110:113], v[42:45], 0
	v_mfma_f32_16x16x32_bf16 v[42:45], v[118:121], v[42:45], 0
	v_mfma_f32_16x16x32_bf16 v[126:129], v[114:117], v[46:49], v[126:129]
	v_mfma_f32_16x16x32_bf16 v[42:45], v[122:125], v[46:49], v[42:45]
	v_mfma_f32_16x16x32_bf16 v[46:49], v[110:113], v[50:53], 0
	v_mfma_f32_16x16x32_bf16 v[50:53], v[118:121], v[50:53], 0
	v_mfma_f32_16x16x32_bf16 v[46:49], v[114:117], v[54:57], v[46:49]
	v_mfma_f32_16x16x32_bf16 v[50:53], v[122:125], v[54:57], v[50:53]
	v_mfma_f32_16x16x32_bf16 v[54:57], v[110:113], v[58:61], 0
	v_mfma_f32_16x16x32_bf16 v[58:61], v[118:121], v[58:61], 0
	v_mfma_f32_16x16x32_bf16 v[54:57], v[114:117], v[66:69], v[54:57]
	v_mfma_f32_16x16x32_bf16 v[58:61], v[122:125], v[66:69], v[58:61]
	v_mfma_f32_16x16x32_bf16 v[66:69], v[110:113], v[70:73], 0
	v_mfma_f32_16x16x32_bf16 v[70:73], v[118:121], v[70:73], 0
	v_mfma_f32_16x16x32_bf16 v[66:69], v[114:117], v[74:77], v[66:69]
	v_mfma_f32_16x16x32_bf16 v[70:73], v[122:125], v[74:77], v[70:73]
	s_setprio 1
	v_readfirstlane_b32 s55, v20
	v_lshl_add_u64 v[24:25], v[8:9], 0, s[56:57]
	s_mov_b32 m0, s55
	v_readfirstlane_b32 s55, v23
	s_barrier
; #define STAGE_A(b, h, kt) { const u16* ap_ = A + (size_t)((h) * ahalf + (unsigned)(kt) * 64u); glds16(ap_ + ao0, l0 + SA_(b, h)); glds16(ap_ + ao1, l0 + SA_(b, h) + 8192); }
; #define STAGE_B(b, h, kt) { const u16* bp_ = ((h) ? B1 : B0) + (unsigned)(kt) * 64u; glds16(bp_ + bo0, l0 + SB_(b, h)); glds16(bp_ + bo1, l0 + SB_(b, h) + 8192); }
; #define LDA(dst, b, h) _Pragma("unroll") for (int m = 0; m < 4; ++m) _Pragma("unroll") for (int k = 0; k < 2; ++k) \
;     dst[m][k] = *(const bf16x8*)(lds + SA_(b, h) + lds_byte(wr * 64 + m * 16 + fr, k * 32 + fq * 8));
; #define LDB(dst, b, h) _Pragma("unroll") for (int n = 0; n < 2; ++n) _Pragma("unroll") for (int k = 0; k < 2; ++k) \
;     dst[n][k] = *(const bf16x8*)(lds + SB_(b, h) + lds_byte(wc * 32 + n * 16 + fr, k * 32 + fq * 8));
; #define MMA(ai, bj, At_, Bt_) { __builtin_amdgcn_s_setprio(1); \
;     _Pragma("unroll") for (int m = 0; m < 4; ++m) _Pragma("unroll") for (int n = 0; n < 2; ++n) _Pragma("unroll") for (int k = 0; k < 2; ++k) \
;       acc[ai][bj][m][n] = MFMA16(Bt_[n][k], At_[m][k], acc[ai][bj][m][n]); \
;     __builtin_amdgcn_s_setprio(0); }
; #define WAIT_V(n) asm volatile("s_waitcnt vmcnt(" #n ")" ::: "memory");
; #define WAIT_L(n) asm volatile("s_waitcnt lgkmcnt(" #n ")" ::: "memory");
; #define BAR __builtin_amdgcn_s_barrier();
; #define SCHED __builtin_amdgcn_sched_barrier(0);
; DI void gemm256(const u16* __restrict__ A, int lda, const u16* __restrict__ B0, const u16* __restrict__ B1, int ldb, int nt, acc_t& acc, char* lds) {
;     ...
;     LDA(At, 0, 1) STAGE_A(0, 0, t + 2)
;     BAR WAIT_L(0) MMA(1, 0, At, Bq0) BAR SCHED
;     STAGE_B(0, 1, t + 2)
;     WAIT_V(6) BAR MMA(1, 1, At, Bq1) BAR
;     LDB(Bq0, 1, 0) SCHED LDA(At, 1, 0) STAGE_A(0, 1, t + 2)
;     WAIT_L(8) BAR WAIT_L(0) MMA(0, 0, At, Bq0) BAR SCHED
;     LDB(Bq1, 1, 1) STAGE_B(1, 0, t + 3)
	ds_read_b128 v[74:77], v17 offset:16384
	ds_read_b128 v[132:135], v17 offset:17408
	ds_read_b128 v[136:139], v16 offset:18432
	ds_read_b128 v[140:143], v16 offset:19456
	ds_read_b128 v[144:147], v16 offset:20480
	ds_read_b128 v[148:151], v16 offset:21504
	ds_read_b128 v[152:155], v16 offset:22528
	ds_read_b128 v[156:159], v16 offset:23552
	global_load_lds_dwordx4 v[24:25], off
	v_lshl_add_u64 v[24:25], v[10:11], 0, s[56:57]
	s_mov_b32 m0, s55
	s_nop 0
	global_load_lds_dwordx4 v[24:25], off
	s_barrier
	s_waitcnt lgkmcnt(0)
	s_setprio 0
	s_waitcnt lgkmcnt(0)
	v_mfma_f32_16x16x32_bf16 v[160:163], v[26:29], v[74:77], 0
	v_mfma_f32_16x16x32_bf16 v[168:171], v[26:29], v[136:139], 0
	v_mfma_f32_16x16x32_bf16 v[176:179], v[26:29], v[144:147], 0
	v_mfma_f32_16x16x32_bf16 v[24:27], v[26:29], v[152:155], 0
	v_mfma_f32_16x16x32_bf16 v[160:163], v[30:33], v[132:135], v[160:163]
	v_mfma_f32_16x16x32_bf16 v[168:171], v[30:33], v[140:143], v[168:171]
	v_mfma_f32_16x16x32_bf16 v[176:179], v[30:33], v[148:151], v[176:179]
	v_mfma_f32_16x16x32_bf16 v[24:27], v[30:33], v[156:159], v[24:27]
	v_mfma_f32_16x16x32_bf16 v[28:31], v[34:37], v[152:155], 0
	v_mfma_f32_16x16x32_bf16 v[164:167], v[34:37], v[74:77], 0
	v_mfma_f32_16x16x32_bf16 v[172:175], v[34:37], v[136:139], 0
	v_mfma_f32_16x16x32_bf16 v[180:183], v[34:37], v[144:147], 0
	v_mfma_f32_16x16x32_bf16 v[28:31], v[38:41], v[156:159], v[28:31]
	v_mfma_f32_16x16x32_bf16 v[164:167], v[38:41], v[132:135], v[164:167]
	v_mfma_f32_16x16x32_bf16 v[172:175], v[38:41], v[140:143], v[172:175]
	v_mfma_f32_16x16x32_bf16 v[180:183], v[38:41], v[148:151], v[180:183]
	s_setprio 1
	s_barrier
	v_readfirstlane_b32 s55, v21
	v_lshl_add_u64 v[32:33], v[4:5], 0, s[56:57]
	s_mov_b32 m0, s55
	v_readfirstlane_b32 s55, v22
	global_load_lds_dwordx4 v[32:33], off
	v_lshl_add_u64 v[20:21], v[6:7], 0, s[56:57]
	s_mov_b32 m0, s55
	s_nop 0
	global_load_lds_dwordx4 v[20:21], off
	s_waitcnt vmcnt(6)
	s_barrier
	s_setprio 0
	v_mfma_f32_16x16x32_bf16 v[20:23], v[110:113], v[74:77], 0
	v_mfma_f32_16x16x32_bf16 v[32:35], v[118:121], v[74:77], 0
	v_mfma_f32_16x16x32_bf16 v[20:23], v[114:117], v[132:135], v[20:23]
	v_mfma_f32_16x16x32_bf16 v[32:35], v[122:125], v[132:135], v[32:35]
	v_mfma_f32_16x16x32_bf16 v[36:39], v[110:113], v[136:139], 0
	v_mfma_f32_16x16x32_bf16 v[132:135], v[110:113], v[144:147], 0
	v_mfma_f32_16x16x32_bf16 v[110:113], v[110:113], v[152:155], 0
	v_mfma_f32_16x16x32_bf16 v[36:39], v[114:117], v[140:143], v[36:39]
	v_mfma_f32_16x16x32_bf16 v[74:77], v[118:121], v[136:139], 0
	v_mfma_f32_16x16x32_bf16 v[132:135], v[114:117], v[148:151], v[132:135]
	v_mfma_f32_16x16x32_bf16 v[110:113], v[114:117], v[156:159], v[110:113]
	v_mfma_f32_16x16x32_bf16 v[114:117], v[118:121], v[152:155], 0
	v_mfma_f32_16x16x32_bf16 v[74:77], v[122:125], v[140:143], v[74:77]
	v_mfma_f32_16x16x32_bf16 v[136:139], v[118:121], v[144:147], 0
	v_mfma_f32_16x16x32_bf16 v[114:117], v[122:125], v[156:159], v[114:117]
	v_mfma_f32_16x16x32_bf16 v[136:139], v[122:125], v[148:151], v[136:139]
	s_setprio 1
	s_barrier
	ds_read_b128 v[118:121], v213
	ds_read_b128 v[122:125], v213 offset:1024
	ds_read_b128 v[140:143], v213 offset:2048
	ds_read_b128 v[144:147], v213 offset:3072
	s_add_u32 s56, s22, 0x10100
	s_addc_u32 s57, s23, 0
	v_readfirstlane_b32 s55, v18
	v_lshl_add_u64 v[40:41], s[56:57], 0, v[0:1]
	s_mov_b32 m0, s55
	v_readfirstlane_b32 s55, v19
	ds_read_b128 v[148:151], v17 offset:32768
	ds_read_b128 v[152:155], v17 offset:33792
	ds_read_b128 v[156:159], v16 offset:34816
	ds_read_b128 v[184:187], v16 offset:35840
	ds_read_b128 v[188:191], v16 offset:36864
	ds_read_b128 v[192:195], v16 offset:37888
	ds_read_b128 v[196:199], v16 offset:38912
	ds_read_b128 v[200:203], v16 offset:39936
	global_load_lds_dwordx4 v[40:41], off
	v_lshl_add_u64 v[40:41], s[56:57], 0, v[2:3]
	s_mov_b32 m0, s55
	s_nop 0
	global_load_lds_dwordx4 v[40:41], off
	s_waitcnt lgkmcnt(8)
	s_barrier
	s_waitcnt lgkmcnt(0)
	s_setprio 0
	s_waitcnt lgkmcnt(0)
	v_mfma_f32_16x16x32_bf16 v[78:81], v[118:121], v[148:151], v[78:81]
	v_mfma_f32_16x16x32_bf16 v[82:85], v[140:143], v[148:151], v[82:85]
	v_mfma_f32_16x16x32_bf16 v[86:89], v[118:121], v[156:159], v[86:89]
	v_mfma_f32_16x16x32_bf16 v[90:93], v[140:143], v[156:159], v[90:93]
	v_mfma_f32_16x16x32_bf16 v[94:97], v[118:121], v[188:191], v[94:97]
	v_mfma_f32_16x16x32_bf16 v[98:101], v[140:143], v[188:191], v[98:101]
	v_mfma_f32_16x16x32_bf16 v[102:105], v[118:121], v[196:199], v[102:105]
	v_mfma_f32_16x16x32_bf16 v[106:109], v[140:143], v[196:199], v[106:109]
	v_mfma_f32_16x16x32_bf16 v[78:81], v[122:125], v[152:155], v[78:81]
	v_mfma_f32_16x16x32_bf16 v[82:85], v[144:147], v[152:155], v[82:85]
	v_mfma_f32_16x16x32_bf16 v[86:89], v[122:125], v[184:187], v[86:89]
	v_mfma_f32_16x16x32_bf16 v[90:93], v[144:147], v[184:187], v[90:93]
	v_mfma_f32_16x16x32_bf16 v[94:97], v[122:125], v[192:195], v[94:97]
	v_mfma_f32_16x16x32_bf16 v[98:101], v[144:147], v[192:195], v[98:101]
	v_mfma_f32_16x16x32_bf16 v[102:105], v[122:125], v[200:203], v[102:105]
	v_mfma_f32_16x16x32_bf16 v[106:109], v[144:147], v[200:203], v[106:109]
	s_setprio 1
	s_barrier
	s_mov_b32 m0, s47
	v_lshl_add_u64 v[12:13], v[12:13], 0, s[26:27]
	ds_read_b128 v[204:207], v222
	ds_read_b128 v[208:211], v222 offset:1024
	ds_read_b128 v[216:219], v222 offset:2048
	ds_read_b128 v[226:229], v222 offset:3072
	global_load_lds_dwordx4 v[12:13], off
	v_lshl_add_u64 v[12:13], v[14:15], 0, s[26:27]
	s_mov_b32 m0, s46
	s_nop 0
	global_load_lds_dwordx4 v[12:13], off
	s_barrier
; #define STAGE_A(b, h, kt) { const u16* ap_ = A + (size_t)((h) * ahalf + (unsigned)(kt) * 64u); glds16(ap_ + ao0, l0 + SA_(b, h)); glds16(ap_ + ao1, l0 + SA_(b, h) + 8192); }
; #define STAGE_B(b, h, kt) { const u16* bp_ = ((h) ? B1 : B0) + (unsigned)(kt) * 64u; glds16(bp_ + bo0, l0 + SB_(b, h)); glds16(bp_ + bo1, l0 + SB_(b, h) + 8192); }
; #define LDA(dst, b, h) _Pragma("unroll") for (int m = 0; m < 4; ++m) _Pragma("unroll") for (int k = 0; k < 2; ++k) \
;     dst[m][k] = *(const bf16x8*)(lds + SA_(b, h) + lds_byte(wr * 64 + m * 16 + fr, k * 32 + fq * 8));
; #define LDB(dst, b, h) _Pragma("unroll") for (int n = 0; n < 2; ++n) _Pragma("unroll") for (int k = 0; k < 2; ++k) \
;     dst[n][k] = *(const bf16x8*)(lds + SB_(b, h) + lds_byte(wc * 32 + n * 16 + fr, k * 32 + fq * 8));
; #define MMA(ai, bj, At_, Bt_) { __builtin_amdgcn_s_setprio(1); \
;     _Pragma("unroll") for (int m = 0; m < 4; ++m) _Pragma("unroll") for (int n = 0; n < 2; ++n) _Pragma("unroll") for (int k = 0; k < 2; ++k) \
;       acc[ai][bj][m][n] = MFMA16(Bt_[n][k], At_[m][k], acc[ai][bj][m][n]); \
;     __builtin_amdgcn_s_setprio(0); }
; #define WAIT_V(n) asm volatile("s_waitcnt vmcnt(" #n ")" ::: "memory");
; #define WAIT_L(n) asm volatile("s_waitcnt lgkmcnt(" #n ")" ::: "memory");
; #define BAR __builtin_amdgcn_s_barrier();
; #define SCHED __builtin_amdgcn_sched_barrier(0);
; DI void gemm256(const u16* __restrict__ A, int lda, const u16* __restrict__ B0, const u16* __restrict__ B1, int ldb, int nt, acc_t& acc, char* lds) {
;     ...
;     BAR WAIT_L(0) MMA(0, 1, At, Bq1) BAR
;     LDA(At, 1, 1) STAGE_A(1, 0, t + 3)
;     BAR WAIT_L(0) MMA(1, 0, At, Bq0) BAR SCHED
;     STAGE_B(1, 1, t + 3)
;     WAIT_V(6) BAR MMA(1, 1, At, Bq1) BAR
;   }
;   { LDB(Bq0, 0, 0) LDA(At, 0, 0) STAGE_A(1, 1, nt - 1)
	s_waitcnt lgkmcnt(0)
	s_setprio 0
	s_waitcnt lgkmcnt(0)
	v_mfma_f32_16x16x32_bf16 v[12:15], v[204:207], v[148:151], v[126:129]
	v_mfma_f32_16x16x32_bf16 v[40:43], v[216:219], v[148:151], v[42:45]
	v_mfma_f32_16x16x32_bf16 v[44:47], v[204:207], v[156:159], v[46:49]
	v_mfma_f32_16x16x32_bf16 v[48:51], v[216:219], v[156:159], v[50:53]
	v_mfma_f32_16x16x32_bf16 v[52:55], v[204:207], v[188:191], v[54:57]
	v_mfma_f32_16x16x32_bf16 v[56:59], v[216:219], v[188:191], v[58:61]
	v_mfma_f32_16x16x32_bf16 v[60:63], v[204:207], v[196:199], v[66:69]
	v_mfma_f32_16x16x32_bf16 v[66:69], v[216:219], v[196:199], v[70:73]
	v_mfma_f32_16x16x32_bf16 v[12:15], v[208:211], v[152:155], v[12:15]
	v_mfma_f32_16x16x32_bf16 v[40:43], v[226:229], v[152:155], v[40:43]
	v_mfma_f32_16x16x32_bf16 v[44:47], v[208:211], v[184:187], v[44:47]
	v_mfma_f32_16x16x32_bf16 v[48:51], v[226:229], v[184:187], v[48:51]
	v_mfma_f32_16x16x32_bf16 v[52:55], v[208:211], v[192:195], v[52:55]
	v_mfma_f32_16x16x32_bf16 v[56:59], v[226:229], v[192:195], v[56:59]
	v_mfma_f32_16x16x32_bf16 v[60:63], v[208:211], v[200:203], v[60:63]
	v_mfma_f32_16x16x32_bf16 v[66:69], v[226:229], v[200:203], v[66:69]
	s_setprio 1
	s_mov_b32 m0, s44
	v_lshl_add_u64 v[8:9], v[8:9], 0, s[26:27]
	s_barrier
	ds_read_b128 v[70:73], v17 offset:49152
	ds_read_b128 v[126:129], v17 offset:50176
	ds_read_b128 v[148:151], v16 offset:51200
	ds_read_b128 v[152:155], v16 offset:52224
	ds_read_b128 v[156:159], v16 offset:53248
	ds_read_b128 v[184:187], v16 offset:54272
	ds_read_b128 v[188:191], v16 offset:55296
	ds_read_b128 v[192:195], v16 offset:56320
	global_load_lds_dwordx4 v[8:9], off
	v_lshl_add_u64 v[8:9], v[10:11], 0, s[26:27]
	s_mov_b32 m0, s29
	s_nop 0
	global_load_lds_dwordx4 v[8:9], off
	s_barrier
	s_waitcnt lgkmcnt(0)
	s_setprio 0
	s_waitcnt lgkmcnt(0)
	v_mfma_f32_16x16x32_bf16 v[8:11], v[118:121], v[70:73], v[160:163]
	v_mfma_f32_16x16x32_bf16 v[24:27], v[118:121], v[188:191], v[24:27]
	v_mfma_f32_16x16x32_bf16 v[28:31], v[140:143], v[188:191], v[28:31]
	v_mfma_f32_16x16x32_bf16 v[8:11], v[122:125], v[126:129], v[8:11]
	v_mfma_f32_16x16x32_bf16 v[160:163], v[140:143], v[70:73], v[164:167]
	v_mfma_f32_16x16x32_bf16 v[164:167], v[118:121], v[148:151], v[168:171]
	v_mfma_f32_16x16x32_bf16 v[168:171], v[140:143], v[148:151], v[172:175]
	v_mfma_f32_16x16x32_bf16 v[172:175], v[118:121], v[156:159], v[176:179]
	v_mfma_f32_16x16x32_bf16 v[176:179], v[140:143], v[156:159], v[180:183]
	v_mfma_f32_16x16x32_bf16 v[24:27], v[122:125], v[192:195], v[24:27]
	v_mfma_f32_16x16x32_bf16 v[28:31], v[144:147], v[192:195], v[28:31]
	v_mfma_f32_16x16x32_bf16 v[160:163], v[144:147], v[126:129], v[160:163]
	v_mfma_f32_16x16x32_bf16 v[164:167], v[122:125], v[152:155], v[164:167]
	v_mfma_f32_16x16x32_bf16 v[168:171], v[144:147], v[152:155], v[168:171]
	v_mfma_f32_16x16x32_bf16 v[172:175], v[122:125], v[184:187], v[172:175]
	v_mfma_f32_16x16x32_bf16 v[176:179], v[144:147], v[184:187], v[176:179]
	s_setprio 1
	s_barrier
	s_mov_b32 m0, s28
	v_lshl_add_u64 v[4:5], v[4:5], 0, s[26:27]
	global_load_lds_dwordx4 v[4:5], off
	v_lshl_add_u64 v[4:5], v[6:7], 0, s[26:27]
	s_mov_b32 m0, s2
	s_nop 0
	global_load_lds_dwordx4 v[4:5], off
	s_waitcnt vmcnt(6)
	s_barrier
	s_setprio 0
	v_mfma_f32_16x16x32_bf16 v[4:7], v[204:207], v[70:73], v[20:23]
	v_mfma_f32_16x16x32_bf16 v[18:21], v[216:219], v[70:73], v[32:35]
	v_mfma_f32_16x16x32_bf16 v[32:35], v[204:207], v[148:151], v[36:39]
	v_mfma_f32_16x16x32_bf16 v[36:39], v[216:219], v[148:151], v[74:77]
	v_mfma_f32_16x16x32_bf16 v[70:73], v[204:207], v[156:159], v[132:135]
	v_mfma_f32_16x16x32_bf16 v[74:77], v[216:219], v[156:159], v[136:139]
	v_mfma_f32_16x16x32_bf16 v[110:113], v[204:207], v[188:191], v[110:113]
	v_mfma_f32_16x16x32_bf16 v[114:117], v[216:219], v[188:191], v[114:117]
	v_mfma_f32_16x16x32_bf16 v[4:7], v[208:211], v[126:129], v[4:7]
	v_mfma_f32_16x16x32_bf16 v[18:21], v[226:229], v[126:129], v[18:21]
	v_mfma_f32_16x16x32_bf16 v[32:35], v[208:211], v[152:155], v[32:35]
	v_mfma_f32_16x16x32_bf16 v[36:39], v[226:229], v[152:155], v[36:39]
	v_mfma_f32_16x16x32_bf16 v[70:73], v[208:211], v[184:187], v[70:73]
	v_mfma_f32_16x16x32_bf16 v[74:77], v[226:229], v[184:187], v[74:77]
	v_mfma_f32_16x16x32_bf16 v[110:113], v[208:211], v[192:195], v[110:113]
	v_mfma_f32_16x16x32_bf16 v[114:117], v[226:229], v[192:195], v[114:117]
	s_setprio 1
	s_add_u32 s22, s22, 0x10180
	s_addc_u32 s23, s23, 0
	s_mov_b32 m0, s54
	v_lshl_add_u64 v[0:1], s[22:23], 0, v[0:1]
	s_barrier
	ds_read_b128 v[118:121], v131
	ds_read_b128 v[122:125], v131 offset:1024
	ds_read_b128 v[126:129], v131 offset:2048
	ds_read_b128 v[132:135], v131 offset:3072
	ds_read_b128 v[136:139], v17
	ds_read_b128 v[140:143], v17 offset:1024
	ds_read_b128 v[144:147], v16 offset:2048
	ds_read_b128 v[148:151], v16 offset:3072
	ds_read_b128 v[152:155], v16 offset:4096
	ds_read_b128 v[156:159], v16 offset:5120
	ds_read_b128 v[180:183], v16 offset:6144
	ds_read_b128 v[184:187], v16 offset:7168
	global_load_lds_dwordx4 v[0:1], off
	v_lshl_add_u64 v[0:1], s[22:23], 0, v[2:3]
	s_mov_b32 m0, s45
	s_nop 0
	global_load_lds_dwordx4 v[0:1], off
	s_barrier
; #define LDA(dst, b, h) _Pragma("unroll") for (int m = 0; m < 4; ++m) _Pragma("unroll") for (int k = 0; k < 2; ++k) \
;     dst[m][k] = *(const bf16x8*)(lds + SA_(b, h) + lds_byte(wr * 64 + m * 16 + fr, k * 32 + fq * 8));
; #define LDB(dst, b, h) _Pragma("unroll") for (int n = 0; n < 2; ++n) _Pragma("unroll") for (int k = 0; k < 2; ++k) \
;     dst[n][k] = *(const bf16x8*)(lds + SB_(b, h) + lds_byte(wc * 32 + n * 16 + fr, k * 32 + fq * 8));
; #define MMA(ai, bj, At_, Bt_) { __builtin_amdgcn_s_setprio(1); \
;     _Pragma("unroll") for (int m = 0; m < 4; ++m) _Pragma("unroll") for (int n = 0; n < 2; ++n) _Pragma("unroll") for (int k = 0; k < 2; ++k) \
;       acc[ai][bj][m][n] = MFMA16(Bt_[n][k], At_[m][k], acc[ai][bj][m][n]); \
;     __builtin_amdgcn_s_setprio(0); }
; #define WAIT_V(n) asm volatile("s_waitcnt vmcnt(" #n ")" ::: "memory");
; #define WAIT_L(n) asm volatile("s_waitcnt lgkmcnt(" #n ")" ::: "memory");
; #define BAR __builtin_amdgcn_s_barrier();
; DI void gemm256(const u16* __restrict__ A, int lda, const u16* __restrict__ B0, const u16* __restrict__ B1, int ldb, int nt, acc_t& acc, char* lds) {
;     ...
;     BAR WAIT_L(0) MMA(0, 0, At, Bq0) BAR
;     LDB(Bq1, 0, 1) BAR WAIT_L(0) MMA(0, 1, At, Bq1) BAR
;     LDA(At, 0, 1) WAIT_V(4) BAR WAIT_L(0) MMA(1, 0, At, Bq0) MMA(1, 1, At, Bq1) BAR }
	s_waitcnt lgkmcnt(0)
	s_setprio 0
	s_waitcnt lgkmcnt(0)
	v_mfma_f32_16x16x32_bf16 v[0:3], v[118:121], v[136:139], v[78:81]
	v_mfma_f32_16x16x32_bf16 v[78:81], v[126:129], v[136:139], v[82:85]
	v_mfma_f32_16x16x32_bf16 v[82:85], v[118:121], v[144:147], v[86:89]
	v_mfma_f32_16x16x32_bf16 v[86:89], v[126:129], v[144:147], v[90:93]
	v_mfma_f32_16x16x32_bf16 v[90:93], v[118:121], v[152:155], v[94:97]
	v_mfma_f32_16x16x32_bf16 v[94:97], v[126:129], v[152:155], v[98:101]
	v_mfma_f32_16x16x32_bf16 v[98:101], v[118:121], v[180:183], v[102:105]
	v_mfma_f32_16x16x32_bf16 v[0:3], v[122:125], v[140:143], v[0:3]
	v_mfma_f32_16x16x32_bf16 v[78:81], v[132:135], v[140:143], v[78:81]
	v_mfma_f32_16x16x32_bf16 v[82:85], v[122:125], v[148:151], v[82:85]
	v_mfma_f32_16x16x32_bf16 v[86:89], v[132:135], v[148:151], v[86:89]
	v_mfma_f32_16x16x32_bf16 v[90:93], v[122:125], v[156:159], v[90:93]
	v_mfma_f32_16x16x32_bf16 v[94:97], v[132:135], v[156:159], v[94:97]
	v_mfma_f32_16x16x32_bf16 v[102:105], v[122:125], v[184:187], v[98:101]
	v_mfma_f32_16x16x32_bf16 v[98:101], v[126:129], v[180:183], v[106:109]
	v_mfma_f32_16x16x32_bf16 v[188:191], v[132:135], v[184:187], v[98:101]
	s_setprio 1
	s_barrier
	s_nop 4
	ds_read_b128 v[98:101], v212
	ds_read_b128 v[106:109], v212 offset:1024
	ds_read_b128 v[192:195], v212 offset:2048
	ds_read_b128 v[196:199], v212 offset:3072
	s_barrier
	s_waitcnt lgkmcnt(0)
	s_setprio 0
	s_waitcnt lgkmcnt(0)
	v_mfma_f32_16x16x32_bf16 v[48:51], v[192:195], v[144:147], v[48:51]
	v_mfma_f32_16x16x32_bf16 v[12:15], v[98:101], v[136:139], v[12:15]
	v_mfma_f32_16x16x32_bf16 v[40:43], v[192:195], v[136:139], v[40:43]
	v_mfma_f32_16x16x32_bf16 v[136:139], v[196:199], v[148:151], v[48:51]
	v_mfma_f32_16x16x32_bf16 v[48:51], v[98:101], v[152:155], v[52:55]
	v_mfma_f32_16x16x32_bf16 v[52:55], v[106:109], v[156:159], v[48:51]
	v_mfma_f32_16x16x32_bf16 v[48:51], v[192:195], v[152:155], v[56:59]
	v_mfma_f32_16x16x32_bf16 v[44:47], v[98:101], v[144:147], v[44:47]
	v_mfma_f32_16x16x32_bf16 v[56:59], v[196:199], v[156:159], v[48:51]
	v_mfma_f32_16x16x32_bf16 v[48:51], v[98:101], v[180:183], v[60:63]
	v_mfma_f32_16x16x32_bf16 v[12:15], v[106:109], v[140:143], v[12:15]
	v_mfma_f32_16x16x32_bf16 v[40:43], v[196:199], v[140:143], v[40:43]
	v_mfma_f32_16x16x32_bf16 v[44:47], v[106:109], v[148:151], v[44:47]
	v_mfma_f32_16x16x32_bf16 v[60:63], v[106:109], v[184:187], v[48:51]
	v_mfma_f32_16x16x32_bf16 v[48:51], v[192:195], v[180:183], v[66:69]
	v_mfma_f32_16x16x32_bf16 v[140:143], v[196:199], v[184:187], v[48:51]
	s_setprio 1
	s_barrier
	s_nop 4
	ds_read_b128 v[48:51], v17 offset:16384
	ds_read_b128 v[66:69], v17 offset:17408
	ds_read_b128 v[144:147], v16 offset:18432
	ds_read_b128 v[148:151], v16 offset:19456
	ds_read_b128 v[152:155], v16 offset:20480
	ds_read_b128 v[156:159], v16 offset:21504
	ds_read_b128 v[180:183], v16 offset:22528
	ds_read_b128 v[184:187], v16 offset:23552
	s_waitcnt vmcnt(4)
	s_barrier
	s_waitcnt lgkmcnt(0)
	s_setprio 0
	s_waitcnt lgkmcnt(0)
	v_mfma_f32_16x16x32_bf16 v[8:11], v[118:121], v[48:51], v[8:11]
	v_mfma_f32_16x16x32_bf16 v[22:25], v[118:121], v[180:183], v[24:27]
	v_mfma_f32_16x16x32_bf16 v[8:11], v[122:125], v[66:69], v[8:11]
	v_mfma_f32_16x16x32_bf16 v[160:163], v[126:129], v[48:51], v[160:163]
	v_mfma_f32_16x16x32_bf16 v[164:167], v[118:121], v[144:147], v[164:167]
	v_mfma_f32_16x16x32_bf16 v[168:171], v[126:129], v[144:147], v[168:171]
	v_mfma_f32_16x16x32_bf16 v[172:175], v[118:121], v[152:155], v[172:175]
	v_mfma_f32_16x16x32_bf16 v[176:179], v[126:129], v[152:155], v[176:179]
	v_mfma_f32_16x16x32_bf16 v[24:27], v[122:125], v[184:187], v[22:25]
	v_mfma_f32_16x16x32_bf16 v[28:31], v[126:129], v[180:183], v[28:31]
	v_mfma_f32_16x16x32_bf16 v[160:163], v[132:135], v[66:69], v[160:163]
	v_mfma_f32_16x16x32_bf16 v[164:167], v[122:125], v[148:151], v[164:167]
	v_mfma_f32_16x16x32_bf16 v[168:171], v[132:135], v[148:151], v[168:171]
	v_mfma_f32_16x16x32_bf16 v[172:175], v[122:125], v[156:159], v[172:175]
	v_mfma_f32_16x16x32_bf16 v[176:179], v[132:135], v[156:159], v[176:179]
	v_mfma_f32_16x16x32_bf16 v[132:135], v[132:135], v[184:187], v[28:31]
	s_setprio 1
	s_setprio 0
	v_mfma_f32_16x16x32_bf16 v[4:7], v[98:101], v[48:51], v[4:7]
	v_mfma_f32_16x16x32_bf16 v[200:203], v[106:109], v[66:69], v[4:7]
	v_mfma_f32_16x16x32_bf16 v[4:7], v[192:195], v[48:51], v[18:21]
	v_mfma_f32_16x16x32_bf16 v[204:207], v[196:199], v[66:69], v[4:7]
	v_mfma_f32_16x16x32_bf16 v[4:7], v[98:101], v[144:147], v[32:35]
	v_mfma_f32_16x16x32_bf16 v[32:35], v[106:109], v[148:151], v[4:7]
	v_mfma_f32_16x16x32_bf16 v[4:7], v[192:195], v[144:147], v[36:39]
	v_mfma_f32_16x16x32_bf16 v[144:147], v[196:199], v[148:151], v[4:7]
	v_mfma_f32_16x16x32_bf16 v[4:7], v[98:101], v[152:155], v[70:73]
	v_mfma_f32_16x16x32_bf16 v[148:151], v[106:109], v[156:159], v[4:7]
	v_mfma_f32_16x16x32_bf16 v[4:7], v[192:195], v[152:155], v[74:77]
	v_mfma_f32_16x16x32_bf16 v[152:155], v[196:199], v[156:159], v[4:7]
	v_mfma_f32_16x16x32_bf16 v[4:7], v[98:101], v[180:183], v[110:113]
	v_mfma_f32_16x16x32_bf16 v[156:159], v[106:109], v[184:187], v[4:7]
	v_mfma_f32_16x16x32_bf16 v[4:7], v[192:195], v[180:183], v[114:117]
	v_mfma_f32_16x16x32_bf16 v[180:183], v[196:199], v[184:187], v[4:7]
	s_setprio 1
	s_barrier
; #define LDA(dst, b, h) _Pragma("unroll") for (int m = 0; m < 4; ++m) _Pragma("unroll") for (int k = 0; k < 2; ++k) \
;     dst[m][k] = *(const bf16x8*)(lds + SA_(b, h) + lds_byte(wr * 64 + m * 16 + fr, k * 32 + fq * 8));
; #define LDB(dst, b, h) _Pragma("unroll") for (int n = 0; n < 2; ++n) _Pragma("unroll") for (int k = 0; k < 2; ++k) \
;     dst[n][k] = *(const bf16x8*)(lds + SB_(b, h) + lds_byte(wc * 32 + n * 16 + fr, k * 32 + fq * 8));
; #define MMA(ai, bj, At_, Bt_) { __builtin_amdgcn_s_setprio(1); \
;     _Pragma("unroll") for (int m = 0; m < 4; ++m) _Pragma("unroll") for (int n = 0; n < 2; ++n) _Pragma("unroll") for (int k = 0; k < 2; ++k) \
;       acc[ai][bj][m][n] = MFMA16(Bt_[n][k], At_[m][k], acc[ai][bj][m][n]); \
;     __builtin_amdgcn_s_setprio(0); }
; #define WAIT_V(n) asm volatile("s_waitcnt vmcnt(" #n ")" ::: "memory");
; #define WAIT_L(n) asm volatile("s_waitcnt lgkmcnt(" #n ")" ::: "memory");
; #define BAR __builtin_amdgcn_s_barrier();
; DI void gemm256(const u16* __restrict__ A, int lda, const u16* __restrict__ B0, const u16* __restrict__ B1, int ldb, int nt, acc_t& acc, char* lds) {
;     ...
;   { LDB(Bq0, 1, 0) LDA(At, 1, 0) WAIT_V(2) BAR WAIT_L(0) MMA(0, 0, At, Bq0) BAR
;     LDB(Bq1, 1, 1) WAIT_V(0) BAR WAIT_L(0) MMA(0, 1, At, Bq1) BAR
;     LDA(At, 1, 1) BAR WAIT_L(0) MMA(1, 0, At, Bq0) MMA(1, 1, At, Bq1) BAR }
;   if (wr == 0) BAR
;   __syncthreads();
	s_nop 4
	ds_read_b128 v[4:7], v213
	ds_read_b128 v[70:73], v213 offset:1024
	ds_read_b128 v[184:187], v213 offset:2048
	ds_read_b128 v[192:195], v213 offset:3072
	ds_read_b128 v[18:21], v17 offset:32768
	ds_read_b128 v[28:31], v17 offset:33792
	ds_read_b128 v[36:39], v16 offset:34816
	ds_read_b128 v[74:77], v16 offset:35840
	ds_read_b128 v[196:199], v16 offset:36864
	ds_read_b128 v[208:211], v16 offset:37888
	ds_read_b128 v[216:219], v16 offset:38912
	ds_read_b128 v[226:229], v16 offset:39936
	s_waitcnt vmcnt(2)
	s_barrier
	s_waitcnt lgkmcnt(0)
	s_setprio 0
	s_waitcnt lgkmcnt(0)
	v_mfma_f32_16x16x32_bf16 v[0:3], v[4:7], v[18:21], v[0:3]
	v_mfma_f32_16x16x32_bf16 v[122:125], v[70:73], v[28:31], v[0:3]
	v_mfma_f32_16x16x32_bf16 v[0:3], v[184:187], v[18:21], v[78:81]
	v_mfma_f32_16x16x32_bf16 v[114:117], v[192:195], v[28:31], v[0:3]
	v_mfma_f32_16x16x32_bf16 v[0:3], v[4:7], v[36:39], v[82:85]
	v_mfma_f32_16x16x32_bf16 v[106:109], v[70:73], v[74:77], v[0:3]
	v_mfma_f32_16x16x32_bf16 v[0:3], v[184:187], v[36:39], v[86:89]
	v_mfma_f32_16x16x32_bf16 v[98:101], v[192:195], v[74:77], v[0:3]
	v_mfma_f32_16x16x32_bf16 v[0:3], v[4:7], v[196:199], v[90:93]
	v_mfma_f32_16x16x32_bf16 v[90:93], v[70:73], v[208:211], v[0:3]
	v_mfma_f32_16x16x32_bf16 v[0:3], v[184:187], v[196:199], v[94:97]
	v_mfma_f32_16x16x32_bf16 v[82:85], v[192:195], v[208:211], v[0:3]
	v_mfma_f32_16x16x32_bf16 v[0:3], v[4:7], v[216:219], v[102:105]
	v_mfma_f32_16x16x32_bf16 v[66:69], v[70:73], v[226:229], v[0:3]
	v_mfma_f32_16x16x32_bf16 v[0:3], v[184:187], v[216:219], v[188:191]
	v_mfma_f32_16x16x32_bf16 v[48:51], v[192:195], v[226:229], v[0:3]
	s_setprio 1
	s_barrier
	s_nop 4
	ds_read_b128 v[0:3], v222
	ds_read_b128 v[188:191], v222 offset:1024
	ds_read_b128 v[230:233], v222 offset:2048
	ds_read_b128 v[234:237], v222 offset:3072
	s_waitcnt vmcnt(0)
	s_barrier
	s_waitcnt lgkmcnt(0)
	s_setprio 0
	s_waitcnt lgkmcnt(0)
	v_mfma_f32_16x16x32_bf16 v[12:15], v[0:3], v[18:21], v[12:15]
	v_mfma_f32_16x16x32_bf16 v[126:129], v[188:191], v[28:31], v[12:15]
	v_mfma_f32_16x16x32_bf16 v[12:15], v[230:233], v[18:21], v[40:43]
	v_mfma_f32_16x16x32_bf16 v[118:121], v[234:237], v[28:31], v[12:15]
	v_mfma_f32_16x16x32_bf16 v[12:15], v[0:3], v[36:39], v[44:47]
	v_mfma_f32_16x16x32_bf16 v[110:113], v[188:191], v[74:77], v[12:15]
	v_mfma_f32_16x16x32_bf16 v[12:15], v[230:233], v[36:39], v[136:139]
	v_mfma_f32_16x16x32_bf16 v[102:105], v[234:237], v[74:77], v[12:15]
	v_mfma_f32_16x16x32_bf16 v[12:15], v[0:3], v[196:199], v[52:55]
	v_mfma_f32_16x16x32_bf16 v[94:97], v[188:191], v[208:211], v[12:15]
	v_mfma_f32_16x16x32_bf16 v[12:15], v[230:233], v[196:199], v[56:59]
	v_mfma_f32_16x16x32_bf16 v[86:89], v[234:237], v[208:211], v[12:15]
	v_mfma_f32_16x16x32_bf16 v[12:15], v[0:3], v[216:219], v[60:63]
	v_mfma_f32_16x16x32_bf16 v[78:81], v[188:191], v[226:229], v[12:15]
	v_mfma_f32_16x16x32_bf16 v[12:15], v[230:233], v[216:219], v[140:143]
	v_mfma_f32_16x16x32_bf16 v[60:63], v[234:237], v[226:229], v[12:15]
	s_setprio 1
	s_barrier
	ds_read_b128 v[40:43], v17 offset:49152
	ds_read_b128 v[52:55], v17 offset:50176
	ds_read_b128 v[136:139], v16 offset:51200
	ds_read_b128 v[140:143], v16 offset:52224
	ds_read_b128 v[196:199], v16 offset:53248
	ds_read_b128 v[208:211], v16 offset:54272
	ds_read_b128 v[216:219], v16 offset:55296
	ds_read_b128 v[226:229], v16 offset:56320
	s_barrier
	s_waitcnt lgkmcnt(0)
	s_setprio 0
	s_waitcnt lgkmcnt(0)
	v_mfma_f32_16x16x32_bf16 v[8:11], v[4:7], v[40:43], v[8:11]
	v_mfma_f32_16x16x32_bf16 v[74:77], v[70:73], v[52:55], v[8:11]
	v_mfma_f32_16x16x32_bf16 v[8:11], v[184:187], v[40:43], v[160:163]
	v_mfma_f32_16x16x32_bf16 v[56:59], v[192:195], v[52:55], v[8:11]
	v_mfma_f32_16x16x32_bf16 v[8:11], v[4:7], v[136:139], v[164:167]
	v_mfma_f32_16x16x32_bf16 v[44:47], v[70:73], v[140:143], v[8:11]
	v_mfma_f32_16x16x32_bf16 v[8:11], v[184:187], v[136:139], v[168:171]
	v_mfma_f32_16x16x32_bf16 v[36:39], v[192:195], v[140:143], v[8:11]
	v_mfma_f32_16x16x32_bf16 v[8:11], v[4:7], v[196:199], v[172:175]
	v_mfma_f32_16x16x32_bf16 v[4:7], v[4:7], v[216:219], v[24:27]
	v_mfma_f32_16x16x32_bf16 v[28:31], v[70:73], v[208:211], v[8:11]
	v_mfma_f32_16x16x32_bf16 v[8:11], v[184:187], v[196:199], v[176:179]
	v_mfma_f32_16x16x32_bf16 v[12:15], v[70:73], v[226:229], v[4:7]
	v_mfma_f32_16x16x32_bf16 v[4:7], v[184:187], v[216:219], v[132:135]
	v_mfma_f32_16x16x32_bf16 v[20:23], v[192:195], v[208:211], v[8:11]
	v_mfma_f32_16x16x32_bf16 v[4:7], v[192:195], v[226:229], v[4:7]
	s_setprio 1
	s_setprio 0
	v_mfma_f32_16x16x32_bf16 v[8:11], v[0:3], v[40:43], v[200:203]
	v_mfma_f32_16x16x32_bf16 v[70:73], v[188:191], v[52:55], v[8:11]
	v_mfma_f32_16x16x32_bf16 v[8:11], v[230:233], v[40:43], v[204:207]
	v_mfma_f32_16x16x32_bf16 v[52:55], v[234:237], v[52:55], v[8:11]
	v_mfma_f32_16x16x32_bf16 v[8:11], v[0:3], v[136:139], v[32:35]
	v_mfma_f32_16x16x32_bf16 v[40:43], v[188:191], v[140:143], v[8:11]
	v_mfma_f32_16x16x32_bf16 v[8:11], v[230:233], v[136:139], v[144:147]
	v_mfma_f32_16x16x32_bf16 v[32:35], v[234:237], v[140:143], v[8:11]
	v_mfma_f32_16x16x32_bf16 v[8:11], v[0:3], v[196:199], v[148:151]
	v_mfma_f32_16x16x32_bf16 v[24:27], v[188:191], v[208:211], v[8:11]
	v_mfma_f32_16x16x32_bf16 v[8:11], v[230:233], v[196:199], v[152:155]
	v_mfma_f32_16x16x32_bf16 v[0:3], v[0:3], v[216:219], v[156:159]
	v_mfma_f32_16x16x32_bf16 v[16:19], v[234:237], v[208:211], v[8:11]
	v_mfma_f32_16x16x32_bf16 v[8:11], v[188:191], v[226:229], v[0:3]
	v_mfma_f32_16x16x32_bf16 v[0:3], v[230:233], v[216:219], v[180:183]
	v_mfma_f32_16x16x32_bf16 v[0:3], v[234:237], v[226:229], v[0:3]
	s_setprio 1
	s_movk_i32 s2, 0x100
	v_cmp_gt_u32_e32 vcc, s2, v130
	s_barrier
	s_and_saveexec_b64 s[22:23], vcc
	s_cbranch_execz .LBB0_1257
	s_barrier

; #define STAGE_A(b, h, kt) { const u16* ap_ = A + (size_t)((h) * ahalf + (unsigned)(kt) * 64u); glds16(ap_ + ao0, l0 + SA_(b, h)); glds16(ap_ + ao1, l0 + SA_(b, h) + 8192); }
; #define STAGE_B(b, h, kt) { const u16* bp_ = ((h) ? B1 : B0) + (unsigned)(kt) * 64u; glds16(bp_ + bo0, l0 + SB_(b, h)); glds16(bp_ + bo1, l0 + SB_(b, h) + 8192); }
; #define LDA(dst, b, h) _Pragma("unroll") for (int m = 0; m < 4; ++m) _Pragma("unroll") for (int k = 0; k < 2; ++k) \
;     dst[m][k] = *(const bf16x8*)(lds + SA_(b, h) + lds_byte(wr * 64 + m * 16 + fr, k * 32 + fq * 8));
; #define LDB(dst, b, h) _Pragma("unroll") for (int n = 0; n < 2; ++n) _Pragma("unroll") for (int k = 0; k < 2; ++k) \
;     dst[n][k] = *(const bf16x8*)(lds + SB_(b, h) + lds_byte(wc * 32 + n * 16 + fr, k * 32 + fq * 8));
; #define MMA(ai, bj, At_, Bt_) { __builtin_amdgcn_s_setprio(1); \
;     _Pragma("unroll") for (int m = 0; m < 4; ++m) _Pragma("unroll") for (int n = 0; n < 2; ++n) _Pragma("unroll") for (int k = 0; k < 2; ++k) \
;       acc[ai][bj][m][n] = MFMA16(Bt_[n][k], At_[m][k], acc[ai][bj][m][n]); \
;     __builtin_amdgcn_s_setprio(0); }
; #define WAIT_L(n) asm volatile("s_waitcnt lgkmcnt(" #n ")" ::: "memory");
; #define BAR __builtin_amdgcn_s_barrier();
; #define SCHED __builtin_amdgcn_sched_barrier(0);
; DI void gemm256(const u16* __restrict__ A, int lda, const u16* __restrict__ B0, const u16* __restrict__ B1, int ldb, int nt, acc_t& acc, char* lds) {
;     ...
;     LDB(Bq0, 0, 0) SCHED LDA(At, 0, 0) STAGE_A(1, 1, t + 1)
;     WAIT_L(8) BAR WAIT_L(0) MMA(0, 0, At, Bq0) BAR SCHED
;     LDB(Bq1, 0, 1) STAGE_B(0, 0, t + 2)
;     BAR WAIT_L(0) MMA(0, 1, At, Bq1) BAR
;     LDA(At, 0, 1) STAGE_A(0, 0, t + 2)
;     BAR WAIT_L(0) MMA(1, 0, At, Bq0) BAR SCHED
.LBB0_1260:
	ds_read_b128 v[142:145], v166
	ds_read_b128 v[170:173], v166 offset:1024
	ds_read_b128 v[174:177], v166 offset:2048
	ds_read_b128 v[178:181], v166 offset:3072
	v_add_u32_e32 v167, 0xc000, v140
	v_lshl_add_u64 v[222:223], s[28:29], 0, v[136:137]
	v_readfirstlane_b32 s7, v167
	v_lshl_add_u64 v[168:169], v[222:223], 0, s[76:77]
	s_mov_b32 m0, s7
	ds_read_b128 v[182:185], v150
	ds_read_b128 v[186:189], v150 offset:1024
	ds_read_b128 v[190:193], v149
	ds_read_b128 v[194:197], v149 offset:1024
	ds_read_b128 v[198:201], v148
	ds_read_b128 v[202:205], v148 offset:1024
	ds_read_b128 v[206:209], v147
	ds_read_b128 v[210:213], v147 offset:1024
	global_load_lds_dwordx4 v[168:169], off
	v_add_u32_e32 v168, 0xe000, v140
	v_lshl_add_u64 v[224:225], s[28:29], 0, v[138:139]
	v_readfirstlane_b32 s7, v168
	v_lshl_add_u64 v[216:217], v[224:225], 0, s[76:77]
	s_mov_b32 m0, s7
	s_nop 0
	global_load_lds_dwordx4 v[216:217], off
	s_waitcnt lgkmcnt(8)
	s_barrier
	s_waitcnt lgkmcnt(0)
	s_setprio 0
	s_waitcnt lgkmcnt(0)
	v_mfma_f32_16x16x32_bf16 v[126:129], v[142:145], v[182:185], v[126:129]
	v_mfma_f32_16x16x32_bf16 v[122:125], v[174:177], v[182:185], v[122:125]
	v_mfma_f32_16x16x32_bf16 v[118:121], v[142:145], v[190:193], v[118:121]
	v_mfma_f32_16x16x32_bf16 v[114:117], v[174:177], v[190:193], v[114:117]
	v_mfma_f32_16x16x32_bf16 v[110:113], v[142:145], v[198:201], v[110:113]
	v_mfma_f32_16x16x32_bf16 v[106:109], v[174:177], v[198:201], v[106:109]
	v_mfma_f32_16x16x32_bf16 v[102:105], v[142:145], v[206:209], v[102:105]
	v_mfma_f32_16x16x32_bf16 v[98:101], v[174:177], v[206:209], v[98:101]
	v_mfma_f32_16x16x32_bf16 v[126:129], v[170:173], v[186:189], v[126:129]
	v_mfma_f32_16x16x32_bf16 v[122:125], v[178:181], v[186:189], v[122:125]
	v_mfma_f32_16x16x32_bf16 v[118:121], v[170:173], v[194:197], v[118:121]
	v_mfma_f32_16x16x32_bf16 v[114:117], v[178:181], v[194:197], v[114:117]
	v_mfma_f32_16x16x32_bf16 v[110:113], v[170:173], v[202:205], v[110:113]
	v_mfma_f32_16x16x32_bf16 v[106:109], v[178:181], v[202:205], v[106:109]
	v_mfma_f32_16x16x32_bf16 v[102:105], v[170:173], v[210:213], v[102:105]
	v_mfma_f32_16x16x32_bf16 v[98:101], v[178:181], v[210:213], v[98:101]
	s_setprio 1
	s_barrier
	v_lshl_add_u64 v[238:239], s[28:29], 0, v[132:133]
	v_readfirstlane_b32 s7, v141
	v_lshl_add_u64 v[240:241], v[238:239], 0, s[44:45]
	s_mov_b32 m0, s7
	ds_read_b128 v[216:219], v165
	ds_read_b128 v[226:229], v165 offset:1024
	ds_read_b128 v[230:233], v165 offset:2048
	ds_read_b128 v[234:237], v165 offset:3072
	global_load_lds_dwordx4 v[240:241], off
	v_lshl_add_u64 v[240:241], s[28:29], 0, v[134:135]
	v_readfirstlane_b32 s7, v152
	v_lshl_add_u64 v[242:243], v[240:241], 0, s[44:45]
	s_mov_b32 m0, s7
	s_nop 0
	global_load_lds_dwordx4 v[242:243], off
	s_barrier
	s_waitcnt lgkmcnt(0)
	s_setprio 0
	s_waitcnt lgkmcnt(0)
	v_mfma_f32_16x16x32_bf16 v[94:97], v[216:219], v[182:185], v[94:97]
	v_mfma_f32_16x16x32_bf16 v[90:93], v[230:233], v[182:185], v[90:93]
	v_mfma_f32_16x16x32_bf16 v[86:89], v[216:219], v[190:193], v[86:89]
	v_mfma_f32_16x16x32_bf16 v[82:85], v[230:233], v[190:193], v[82:85]
	v_mfma_f32_16x16x32_bf16 v[78:81], v[216:219], v[198:201], v[78:81]
	v_mfma_f32_16x16x32_bf16 v[74:77], v[230:233], v[198:201], v[74:77]
	v_mfma_f32_16x16x32_bf16 v[70:73], v[216:219], v[206:209], v[70:73]
	v_mfma_f32_16x16x32_bf16 v[66:69], v[230:233], v[206:209], v[66:69]
	v_mfma_f32_16x16x32_bf16 v[94:97], v[226:229], v[186:189], v[94:97]
	v_mfma_f32_16x16x32_bf16 v[90:93], v[234:237], v[186:189], v[90:93]
	v_mfma_f32_16x16x32_bf16 v[86:89], v[226:229], v[194:197], v[86:89]
	v_mfma_f32_16x16x32_bf16 v[82:85], v[234:237], v[194:197], v[82:85]
	v_mfma_f32_16x16x32_bf16 v[78:81], v[226:229], v[202:205], v[78:81]
	v_mfma_f32_16x16x32_bf16 v[74:77], v[234:237], v[202:205], v[74:77]
	v_mfma_f32_16x16x32_bf16 v[70:73], v[226:229], v[210:213], v[70:73]
	v_mfma_f32_16x16x32_bf16 v[66:69], v[234:237], v[210:213], v[66:69]
	s_setprio 1
	v_readfirstlane_b32 s7, v140
	v_lshl_add_u64 v[242:243], v[222:223], 0, s[80:81]
	s_mov_b32 m0, s7
	v_readfirstlane_b32 s7, v153
	s_barrier
	ds_read_b128 v[182:185], v150 offset:16384
	ds_read_b128 v[186:189], v150 offset:17408
	ds_read_b128 v[190:193], v149 offset:16384
	ds_read_b128 v[194:197], v149 offset:17408
	ds_read_b128 v[198:201], v148 offset:16384
	ds_read_b128 v[202:205], v148 offset:17408
	ds_read_b128 v[206:209], v147 offset:16384
	ds_read_b128 v[210:213], v147 offset:17408
	global_load_lds_dwordx4 v[242:243], off
	v_lshl_add_u64 v[242:243], v[224:225], 0, s[80:81]
	s_mov_b32 m0, s7
	s_nop 0
	global_load_lds_dwordx4 v[242:243], off
	s_barrier
	s_waitcnt lgkmcnt(0)
	s_setprio 0
	s_waitcnt lgkmcnt(0)
	v_mfma_f32_16x16x32_bf16 v[60:63], v[142:145], v[182:185], v[60:63]
	v_mfma_f32_16x16x32_bf16 v[56:59], v[174:177], v[182:185], v[56:59]
	v_mfma_f32_16x16x32_bf16 v[52:55], v[142:145], v[190:193], v[52:55]
	v_mfma_f32_16x16x32_bf16 v[48:51], v[174:177], v[190:193], v[48:51]
	v_mfma_f32_16x16x32_bf16 v[44:47], v[142:145], v[198:201], v[44:47]
	v_mfma_f32_16x16x32_bf16 v[40:43], v[174:177], v[198:201], v[40:43]
	v_mfma_f32_16x16x32_bf16 v[36:39], v[142:145], v[206:209], v[36:39]
	v_mfma_f32_16x16x32_bf16 v[32:35], v[174:177], v[206:209], v[32:35]
	v_mfma_f32_16x16x32_bf16 v[60:63], v[170:173], v[186:189], v[60:63]
	v_mfma_f32_16x16x32_bf16 v[56:59], v[178:181], v[186:189], v[56:59]
	v_mfma_f32_16x16x32_bf16 v[52:55], v[170:173], v[194:197], v[52:55]
	v_mfma_f32_16x16x32_bf16 v[48:51], v[178:181], v[194:197], v[48:51]
	v_mfma_f32_16x16x32_bf16 v[44:47], v[170:173], v[202:205], v[44:47]
	v_mfma_f32_16x16x32_bf16 v[40:43], v[178:181], v[202:205], v[40:43]
	v_mfma_f32_16x16x32_bf16 v[36:39], v[170:173], v[210:213], v[36:39]
	v_mfma_f32_16x16x32_bf16 v[32:35], v[178:181], v[210:213], v[32:35]
	s_setprio 1
	s_barrier
; #define STAGE_A(b, h, kt) { const u16* ap_ = A + (size_t)((h) * ahalf + (unsigned)(kt) * 64u); glds16(ap_ + ao0, l0 + SA_(b, h)); glds16(ap_ + ao1, l0 + SA_(b, h) + 8192); }
; #define STAGE_B(b, h, kt) { const u16* bp_ = ((h) ? B1 : B0) + (unsigned)(kt) * 64u; glds16(bp_ + bo0, l0 + SB_(b, h)); glds16(bp_ + bo1, l0 + SB_(b, h) + 8192); }
; #define LDA(dst, b, h) _Pragma("unroll") for (int m = 0; m < 4; ++m) _Pragma("unroll") for (int k = 0; k < 2; ++k) \
;     dst[m][k] = *(const bf16x8*)(lds + SA_(b, h) + lds_byte(wr * 64 + m * 16 + fr, k * 32 + fq * 8));
; #define LDB(dst, b, h) _Pragma("unroll") for (int n = 0; n < 2; ++n) _Pragma("unroll") for (int k = 0; k < 2; ++k) \
;     dst[n][k] = *(const bf16x8*)(lds + SB_(b, h) + lds_byte(wc * 32 + n * 16 + fr, k * 32 + fq * 8));
; #define MMA(ai, bj, At_, Bt_) { __builtin_amdgcn_s_setprio(1); \
;     _Pragma("unroll") for (int m = 0; m < 4; ++m) _Pragma("unroll") for (int n = 0; n < 2; ++n) _Pragma("unroll") for (int k = 0; k < 2; ++k) \
;       acc[ai][bj][m][n] = MFMA16(Bt_[n][k], At_[m][k], acc[ai][bj][m][n]); \
;     __builtin_amdgcn_s_setprio(0); }
; #define WAIT_V(n) asm volatile("s_waitcnt vmcnt(" #n ")" ::: "memory");
; #define WAIT_L(n) asm volatile("s_waitcnt lgkmcnt(" #n ")" ::: "memory");
; #define BAR __builtin_amdgcn_s_barrier();
; #define SCHED __builtin_amdgcn_sched_barrier(0);
; DI void gemm256(const u16* __restrict__ A, int lda, const u16* __restrict__ B0, const u16* __restrict__ B1, int ldb, int nt, acc_t& acc, char* lds) {
;     ...
;     STAGE_B(0, 1, t + 2)
;     WAIT_V(6) BAR MMA(1, 1, At, Bq1) BAR
;     LDB(Bq0, 1, 0) SCHED LDA(At, 1, 0) STAGE_A(0, 1, t + 2)
;     WAIT_L(8) BAR WAIT_L(0) MMA(0, 0, At, Bq0) BAR SCHED
;     LDB(Bq1, 1, 1) STAGE_B(1, 0, t + 3)
;     BAR WAIT_L(0) MMA(0, 1, At, Bq1) BAR
;     LDA(At, 1, 1) STAGE_A(1, 0, t + 3)
	v_readfirstlane_b32 s7, v154
	v_lshl_add_u64 v[142:143], v[238:239], 0, s[46:47]
	s_mov_b32 m0, s7
	v_readfirstlane_b32 s7, v155
	global_load_lds_dwordx4 v[142:143], off
	v_lshl_add_u64 v[142:143], v[240:241], 0, s[46:47]
	s_mov_b32 m0, s7
	s_nop 0
	global_load_lds_dwordx4 v[142:143], off
	s_waitcnt vmcnt(6)
	s_barrier
	s_setprio 0
	v_mfma_f32_16x16x32_bf16 v[28:31], v[216:219], v[182:185], v[28:31]
	v_mfma_f32_16x16x32_bf16 v[24:27], v[230:233], v[182:185], v[24:27]
	v_mfma_f32_16x16x32_bf16 v[20:23], v[216:219], v[190:193], v[20:23]
	v_mfma_f32_16x16x32_bf16 v[16:19], v[230:233], v[190:193], v[16:19]
	v_mfma_f32_16x16x32_bf16 v[12:15], v[216:219], v[198:201], v[12:15]
	v_mfma_f32_16x16x32_bf16 v[8:11], v[230:233], v[198:201], v[8:11]
	v_mfma_f32_16x16x32_bf16 v[4:7], v[216:219], v[206:209], v[4:7]
	v_mfma_f32_16x16x32_bf16 v[0:3], v[230:233], v[206:209], v[0:3]
	v_mfma_f32_16x16x32_bf16 v[28:31], v[226:229], v[186:189], v[28:31]
	v_mfma_f32_16x16x32_bf16 v[24:27], v[234:237], v[186:189], v[24:27]
	v_mfma_f32_16x16x32_bf16 v[20:23], v[226:229], v[194:197], v[20:23]
	v_mfma_f32_16x16x32_bf16 v[16:19], v[234:237], v[194:197], v[16:19]
	v_mfma_f32_16x16x32_bf16 v[12:15], v[226:229], v[202:205], v[12:15]
	v_mfma_f32_16x16x32_bf16 v[8:11], v[234:237], v[202:205], v[8:11]
	v_mfma_f32_16x16x32_bf16 v[4:7], v[226:229], v[210:213], v[4:7]
	v_mfma_f32_16x16x32_bf16 v[0:3], v[234:237], v[210:213], v[0:3]
	s_setprio 1
	s_barrier
	ds_read_b128 v[142:145], v156
	ds_read_b128 v[170:173], v156 offset:1024
	ds_read_b128 v[174:177], v156 offset:2048
	ds_read_b128 v[178:181], v156 offset:3072
	v_readfirstlane_b32 s7, v157
	v_lshl_add_u64 v[216:217], v[222:223], 0, s[4:5]
	s_mov_b32 m0, s7
	v_readfirstlane_b32 s7, v158
	ds_read_b128 v[182:185], v150 offset:32768
	ds_read_b128 v[186:189], v150 offset:33792
	ds_read_b128 v[190:193], v149 offset:32768
	ds_read_b128 v[194:197], v149 offset:33792
	ds_read_b128 v[198:201], v148 offset:32768
	ds_read_b128 v[202:205], v148 offset:33792
	ds_read_b128 v[206:209], v147 offset:32768
	ds_read_b128 v[210:213], v147 offset:33792
	global_load_lds_dwordx4 v[216:217], off
	v_lshl_add_u64 v[216:217], v[224:225], 0, s[4:5]
	s_mov_b32 m0, s7
	s_nop 0
	global_load_lds_dwordx4 v[216:217], off
	s_waitcnt lgkmcnt(8)
	s_barrier
	s_waitcnt lgkmcnt(0)
	s_setprio 0
	s_waitcnt lgkmcnt(0)
	v_mfma_f32_16x16x32_bf16 v[126:129], v[142:145], v[182:185], v[126:129]
	v_mfma_f32_16x16x32_bf16 v[122:125], v[174:177], v[182:185], v[122:125]
	v_mfma_f32_16x16x32_bf16 v[118:121], v[142:145], v[190:193], v[118:121]
	v_mfma_f32_16x16x32_bf16 v[114:117], v[174:177], v[190:193], v[114:117]
	v_mfma_f32_16x16x32_bf16 v[110:113], v[142:145], v[198:201], v[110:113]
	v_mfma_f32_16x16x32_bf16 v[106:109], v[174:177], v[198:201], v[106:109]
	v_mfma_f32_16x16x32_bf16 v[102:105], v[142:145], v[206:209], v[102:105]
	v_mfma_f32_16x16x32_bf16 v[98:101], v[174:177], v[206:209], v[98:101]
	v_mfma_f32_16x16x32_bf16 v[126:129], v[170:173], v[186:189], v[126:129]
	v_mfma_f32_16x16x32_bf16 v[122:125], v[178:181], v[186:189], v[122:125]
	v_mfma_f32_16x16x32_bf16 v[118:121], v[170:173], v[194:197], v[118:121]
	v_mfma_f32_16x16x32_bf16 v[114:117], v[178:181], v[194:197], v[114:117]
	v_mfma_f32_16x16x32_bf16 v[110:113], v[170:173], v[202:205], v[110:113]
	v_mfma_f32_16x16x32_bf16 v[106:109], v[178:181], v[202:205], v[106:109]
	v_mfma_f32_16x16x32_bf16 v[102:105], v[170:173], v[210:213], v[102:105]
	v_mfma_f32_16x16x32_bf16 v[98:101], v[178:181], v[210:213], v[98:101]
	s_setprio 1
	s_barrier
	v_readfirstlane_b32 s7, v159
	v_lshl_add_u64 v[242:243], v[238:239], 0, s[54:55]
	s_mov_b32 m0, s7
	v_readfirstlane_b32 s7, v160
	ds_read_b128 v[216:219], v151
	ds_read_b128 v[226:229], v151 offset:1024
	ds_read_b128 v[230:233], v151 offset:2048
	ds_read_b128 v[234:237], v151 offset:3072
	global_load_lds_dwordx4 v[242:243], off
	v_lshl_add_u64 v[242:243], v[240:241], 0, s[54:55]
	s_mov_b32 m0, s7
	s_nop 0
	global_load_lds_dwordx4 v[242:243], off
	s_barrier
	s_waitcnt lgkmcnt(0)
	s_setprio 0
	s_waitcnt lgkmcnt(0)
	v_mfma_f32_16x16x32_bf16 v[94:97], v[216:219], v[182:185], v[94:97]
	v_mfma_f32_16x16x32_bf16 v[90:93], v[230:233], v[182:185], v[90:93]
	v_mfma_f32_16x16x32_bf16 v[86:89], v[216:219], v[190:193], v[86:89]
	v_mfma_f32_16x16x32_bf16 v[82:85], v[230:233], v[190:193], v[82:85]
	v_mfma_f32_16x16x32_bf16 v[78:81], v[216:219], v[198:201], v[78:81]
	v_mfma_f32_16x16x32_bf16 v[74:77], v[230:233], v[198:201], v[74:77]
	v_mfma_f32_16x16x32_bf16 v[70:73], v[216:219], v[206:209], v[70:73]
	v_mfma_f32_16x16x32_bf16 v[66:69], v[230:233], v[206:209], v[66:69]
	v_mfma_f32_16x16x32_bf16 v[94:97], v[226:229], v[186:189], v[94:97]
	v_mfma_f32_16x16x32_bf16 v[90:93], v[234:237], v[186:189], v[90:93]
	v_mfma_f32_16x16x32_bf16 v[86:89], v[226:229], v[194:197], v[86:89]
	v_mfma_f32_16x16x32_bf16 v[82:85], v[234:237], v[194:197], v[82:85]
	v_mfma_f32_16x16x32_bf16 v[78:81], v[226:229], v[202:205], v[78:81]
	v_mfma_f32_16x16x32_bf16 v[74:77], v[234:237], v[202:205], v[74:77]
	v_mfma_f32_16x16x32_bf16 v[70:73], v[226:229], v[210:213], v[70:73]
	v_mfma_f32_16x16x32_bf16 v[66:69], v[234:237], v[210:213], v[66:69]
	s_setprio 1
	v_readfirstlane_b32 s7, v161
	v_lshl_add_u64 v[222:223], v[222:223], 0, s[30:31]
	s_mov_b32 m0, s7
	v_readfirstlane_b32 s7, v162
	s_barrier
	ds_read_b128 v[182:185], v150 offset:49152
	ds_read_b128 v[186:189], v150 offset:50176
	ds_read_b128 v[190:193], v149 offset:49152
	ds_read_b128 v[194:197], v149 offset:50176
	ds_read_b128 v[198:201], v148 offset:49152
	ds_read_b128 v[202:205], v148 offset:50176
	ds_read_b128 v[206:209], v147 offset:49152
	ds_read_b128 v[210:213], v147 offset:50176
	global_load_lds_dwordx4 v[222:223], off
	v_lshl_add_u64 v[222:223], v[224:225], 0, s[30:31]
	s_mov_b32 m0, s7
	s_nop 0
	global_load_lds_dwordx4 v[222:223], off
	s_barrier
; #define STAGE_A(b, h, kt) { const u16* ap_ = A + (size_t)((h) * ahalf + (unsigned)(kt) * 64u); glds16(ap_ + ao0, l0 + SA_(b, h)); glds16(ap_ + ao1, l0 + SA_(b, h) + 8192); }
; #define STAGE_B(b, h, kt) { const u16* bp_ = ((h) ? B1 : B0) + (unsigned)(kt) * 64u; glds16(bp_ + bo0, l0 + SB_(b, h)); glds16(bp_ + bo1, l0 + SB_(b, h) + 8192); }
; #define LDA(dst, b, h) _Pragma("unroll") for (int m = 0; m < 4; ++m) _Pragma("unroll") for (int k = 0; k < 2; ++k) \
;     dst[m][k] = *(const bf16x8*)(lds + SA_(b, h) + lds_byte(wr * 64 + m * 16 + fr, k * 32 + fq * 8));
; #define LDB(dst, b, h) _Pragma("unroll") for (int n = 0; n < 2; ++n) _Pragma("unroll") for (int k = 0; k < 2; ++k) \
;     dst[n][k] = *(const bf16x8*)(lds + SB_(b, h) + lds_byte(wc * 32 + n * 16 + fr, k * 32 + fq * 8));
; #define MMA(ai, bj, At_, Bt_) { __builtin_amdgcn_s_setprio(1); \
;     _Pragma("unroll") for (int m = 0; m < 4; ++m) _Pragma("unroll") for (int n = 0; n < 2; ++n) _Pragma("unroll") for (int k = 0; k < 2; ++k) \
;       acc[ai][bj][m][n] = MFMA16(Bt_[n][k], At_[m][k], acc[ai][bj][m][n]); \
;     __builtin_amdgcn_s_setprio(0); }
; #define WAIT_V(n) asm volatile("s_waitcnt vmcnt(" #n ")" ::: "memory");
; #define WAIT_L(n) asm volatile("s_waitcnt lgkmcnt(" #n ")" ::: "memory");
; #define BAR __builtin_amdgcn_s_barrier();
; #define SCHED __builtin_amdgcn_sched_barrier(0);
; DI void gemm256(const u16* __restrict__ A, int lda, const u16* __restrict__ B0, const u16* __restrict__ B1, int ldb, int nt, acc_t& acc, char* lds) {
;     ...
;     BAR WAIT_L(0) MMA(1, 0, At, Bq0) BAR SCHED
;     STAGE_B(1, 1, t + 3)
;     WAIT_V(6) BAR MMA(1, 1, At, Bq1) BAR
;   }
;   { LDB(Bq0, 0, 0) LDA(At, 0, 0) STAGE_A(1, 1, nt - 1)
;     BAR WAIT_L(0) MMA(0, 0, At, Bq0) BAR
;     LDB(Bq1, 0, 1) BAR WAIT_L(0) MMA(0, 1, At, Bq1) BAR
	s_waitcnt lgkmcnt(0)
	s_setprio 0
	s_waitcnt lgkmcnt(0)
	v_mfma_f32_16x16x32_bf16 v[60:63], v[142:145], v[182:185], v[60:63]
	v_mfma_f32_16x16x32_bf16 v[56:59], v[174:177], v[182:185], v[56:59]
	v_mfma_f32_16x16x32_bf16 v[52:55], v[142:145], v[190:193], v[52:55]
	v_mfma_f32_16x16x32_bf16 v[48:51], v[174:177], v[190:193], v[48:51]
	v_mfma_f32_16x16x32_bf16 v[44:47], v[142:145], v[198:201], v[44:47]
	v_mfma_f32_16x16x32_bf16 v[40:43], v[174:177], v[198:201], v[40:43]
	v_mfma_f32_16x16x32_bf16 v[36:39], v[142:145], v[206:209], v[36:39]
	v_mfma_f32_16x16x32_bf16 v[32:35], v[174:177], v[206:209], v[32:35]
	v_mfma_f32_16x16x32_bf16 v[60:63], v[170:173], v[186:189], v[60:63]
	v_mfma_f32_16x16x32_bf16 v[56:59], v[178:181], v[186:189], v[56:59]
	v_mfma_f32_16x16x32_bf16 v[52:55], v[170:173], v[194:197], v[52:55]
	v_mfma_f32_16x16x32_bf16 v[48:51], v[178:181], v[194:197], v[48:51]
	v_mfma_f32_16x16x32_bf16 v[44:47], v[170:173], v[202:205], v[44:47]
	v_mfma_f32_16x16x32_bf16 v[40:43], v[178:181], v[202:205], v[40:43]
	v_mfma_f32_16x16x32_bf16 v[36:39], v[170:173], v[210:213], v[36:39]
	v_mfma_f32_16x16x32_bf16 v[32:35], v[178:181], v[210:213], v[32:35]
	s_setprio 1
	s_barrier
	v_readfirstlane_b32 s7, v163
	v_lshl_add_u64 v[142:143], v[238:239], 0, s[56:57]
	s_mov_b32 m0, s7
	v_readfirstlane_b32 s7, v164
	global_load_lds_dwordx4 v[142:143], off
	v_lshl_add_u64 v[142:143], v[240:241], 0, s[56:57]
	s_mov_b32 m0, s7
	s_nop 0
	global_load_lds_dwordx4 v[142:143], off
	s_waitcnt vmcnt(6)
	s_barrier
	s_setprio 0
	v_mfma_f32_16x16x32_bf16 v[28:31], v[216:219], v[182:185], v[28:31]
	v_mfma_f32_16x16x32_bf16 v[24:27], v[230:233], v[182:185], v[24:27]
	v_mfma_f32_16x16x32_bf16 v[20:23], v[216:219], v[190:193], v[20:23]
	v_mfma_f32_16x16x32_bf16 v[16:19], v[230:233], v[190:193], v[16:19]
	v_mfma_f32_16x16x32_bf16 v[12:15], v[216:219], v[198:201], v[12:15]
	v_mfma_f32_16x16x32_bf16 v[8:11], v[230:233], v[198:201], v[8:11]
	v_mfma_f32_16x16x32_bf16 v[4:7], v[216:219], v[206:209], v[4:7]
	v_mfma_f32_16x16x32_bf16 v[0:3], v[230:233], v[206:209], v[0:3]
	v_mfma_f32_16x16x32_bf16 v[28:31], v[226:229], v[186:189], v[28:31]
	v_mfma_f32_16x16x32_bf16 v[24:27], v[234:237], v[186:189], v[24:27]
	v_mfma_f32_16x16x32_bf16 v[20:23], v[226:229], v[194:197], v[20:23]
	v_mfma_f32_16x16x32_bf16 v[16:19], v[234:237], v[194:197], v[16:19]
	v_mfma_f32_16x16x32_bf16 v[12:15], v[226:229], v[202:205], v[12:15]
	v_mfma_f32_16x16x32_bf16 v[8:11], v[234:237], v[202:205], v[8:11]
	v_mfma_f32_16x16x32_bf16 v[4:7], v[226:229], v[210:213], v[4:7]
	v_mfma_f32_16x16x32_bf16 v[0:3], v[234:237], v[210:213], v[0:3]
	s_setprio 1
	s_add_i32 s3, s3, 2
	s_add_u32 s28, s28, 0x100
	s_addc_u32 s29, s29, 0
	s_cmp_lt_u32 s3, 12
	s_barrier
	s_cbranch_scc1 .LBB0_1260
	s_add_u32 s22, s22, 0x40780
	s_addc_u32 s23, s23, 0
	v_readfirstlane_b32 s3, v167
	v_lshl_add_u64 v[144:145], v[64:65], 1, s[22:23]
	s_mov_b32 m0, s3
	v_readfirstlane_b32 s3, v168
	ds_read_b128 v[132:135], v166
	ds_read_b128 v[136:139], v166 offset:1024
	ds_read_b128 v[140:143], v166 offset:2048
	ds_read_b128 v[152:155], v166 offset:3072
	ds_read_b128 v[158:161], v150
	ds_read_b128 v[170:173], v150 offset:1024
	ds_read_b128 v[174:177], v149
	ds_read_b128 v[178:181], v149 offset:1024
	ds_read_b128 v[182:185], v148
	ds_read_b128 v[186:189], v148 offset:1024
	ds_read_b128 v[190:193], v147
	ds_read_b128 v[194:197], v147 offset:1024
	global_load_lds_dwordx4 v[144:145], off
	v_lshl_add_u64 v[130:131], v[130:131], 1, s[22:23]
	s_mov_b32 m0, s3
	s_nop 0
	global_load_lds_dwordx4 v[130:131], off
	s_barrier
	s_waitcnt lgkmcnt(0)
	s_setprio 0
	s_waitcnt lgkmcnt(0)
	v_mfma_f32_16x16x32_bf16 v[126:129], v[132:135], v[158:161], v[126:129]
	v_mfma_f32_16x16x32_bf16 v[122:125], v[140:143], v[158:161], v[122:125]
	v_mfma_f32_16x16x32_bf16 v[118:121], v[132:135], v[174:177], v[118:121]
	v_mfma_f32_16x16x32_bf16 v[114:117], v[140:143], v[174:177], v[114:117]
	v_mfma_f32_16x16x32_bf16 v[110:113], v[132:135], v[182:185], v[110:113]
	v_mfma_f32_16x16x32_bf16 v[106:109], v[140:143], v[182:185], v[106:109]
	v_mfma_f32_16x16x32_bf16 v[102:105], v[132:135], v[190:193], v[102:105]
	v_mfma_f32_16x16x32_bf16 v[126:129], v[136:139], v[170:173], v[126:129]
	v_mfma_f32_16x16x32_bf16 v[122:125], v[152:155], v[170:173], v[122:125]
	v_mfma_f32_16x16x32_bf16 v[118:121], v[136:139], v[178:181], v[118:121]
	v_mfma_f32_16x16x32_bf16 v[114:117], v[152:155], v[178:181], v[114:117]
	v_mfma_f32_16x16x32_bf16 v[110:113], v[136:139], v[186:189], v[110:113]
	v_mfma_f32_16x16x32_bf16 v[106:109], v[152:155], v[186:189], v[106:109]
	v_mfma_f32_16x16x32_bf16 v[102:105], v[136:139], v[194:197], v[102:105]
	v_mfma_f32_16x16x32_bf16 v[98:101], v[140:143], v[190:193], v[98:101]
	v_mfma_f32_16x16x32_bf16 v[98:101], v[152:155], v[194:197], v[98:101]
	s_setprio 1
	s_barrier
	ds_read_b128 v[166:169], v165
	ds_read_b128 v[198:201], v165 offset:1024
	ds_read_b128 v[202:205], v165 offset:2048
	ds_read_b128 v[162:165], v165 offset:3072
	s_barrier
	s_waitcnt lgkmcnt(0)
	s_setprio 0
	s_waitcnt lgkmcnt(0)
	v_mfma_f32_16x16x32_bf16 v[94:97], v[166:169], v[158:161], v[94:97]
	v_mfma_f32_16x16x32_bf16 v[90:93], v[202:205], v[158:161], v[90:93]
	v_mfma_f32_16x16x32_bf16 v[86:89], v[166:169], v[174:177], v[86:89]
	v_mfma_f32_16x16x32_bf16 v[82:85], v[202:205], v[174:177], v[82:85]
	v_mfma_f32_16x16x32_bf16 v[78:81], v[166:169], v[182:185], v[78:81]
	v_mfma_f32_16x16x32_bf16 v[74:77], v[202:205], v[182:185], v[74:77]
	v_mfma_f32_16x16x32_bf16 v[70:73], v[166:169], v[190:193], v[70:73]
	v_mfma_f32_16x16x32_bf16 v[66:69], v[202:205], v[190:193], v[66:69]
	v_mfma_f32_16x16x32_bf16 v[94:97], v[198:201], v[170:173], v[94:97]
	v_mfma_f32_16x16x32_bf16 v[90:93], v[162:165], v[170:173], v[90:93]
	v_mfma_f32_16x16x32_bf16 v[86:89], v[198:201], v[178:181], v[86:89]
	v_mfma_f32_16x16x32_bf16 v[82:85], v[162:165], v[178:181], v[82:85]
	v_mfma_f32_16x16x32_bf16 v[78:81], v[198:201], v[186:189], v[78:81]
	v_mfma_f32_16x16x32_bf16 v[74:77], v[162:165], v[186:189], v[74:77]
	v_mfma_f32_16x16x32_bf16 v[70:73], v[198:201], v[194:197], v[70:73]
	v_mfma_f32_16x16x32_bf16 v[66:69], v[162:165], v[194:197], v[66:69]
	s_setprio 1
	s_barrier
; #define LDA(dst, b, h) _Pragma("unroll") for (int m = 0; m < 4; ++m) _Pragma("unroll") for (int k = 0; k < 2; ++k) \
;     dst[m][k] = *(const bf16x8*)(lds + SA_(b, h) + lds_byte(wr * 64 + m * 16 + fr, k * 32 + fq * 8));
; #define LDB(dst, b, h) _Pragma("unroll") for (int n = 0; n < 2; ++n) _Pragma("unroll") for (int k = 0; k < 2; ++k) \
;     dst[n][k] = *(const bf16x8*)(lds + SB_(b, h) + lds_byte(wc * 32 + n * 16 + fr, k * 32 + fq * 8));
; #define MMA(ai, bj, At_, Bt_) { __builtin_amdgcn_s_setprio(1); \
;     _Pragma("unroll") for (int m = 0; m < 4; ++m) _Pragma("unroll") for (int n = 0; n < 2; ++n) _Pragma("unroll") for (int k = 0; k < 2; ++k) \
;       acc[ai][bj][m][n] = MFMA16(Bt_[n][k], At_[m][k], acc[ai][bj][m][n]); \
;     __builtin_amdgcn_s_setprio(0); }
; #define WAIT_V(n) asm volatile("s_waitcnt vmcnt(" #n ")" ::: "memory");
; #define WAIT_L(n) asm volatile("s_waitcnt lgkmcnt(" #n ")" ::: "memory");
; #define BAR __builtin_amdgcn_s_barrier();
; DI void gemm256(const u16* __restrict__ A, int lda, const u16* __restrict__ B0, const u16* __restrict__ B1, int ldb, int nt, acc_t& acc, char* lds) {
;     ...
;     LDA(At, 0, 1) WAIT_V(4) BAR WAIT_L(0) MMA(1, 0, At, Bq0) MMA(1, 1, At, Bq1) BAR }
;   { LDB(Bq0, 1, 0) LDA(At, 1, 0) WAIT_V(2) BAR WAIT_L(0) MMA(0, 0, At, Bq0) BAR
	ds_read_b128 v[158:161], v150 offset:16384
	ds_read_b128 v[170:173], v150 offset:17408
	ds_read_b128 v[174:177], v149 offset:16384
	ds_read_b128 v[178:181], v149 offset:17408
	ds_read_b128 v[182:185], v148 offset:16384
	ds_read_b128 v[186:189], v148 offset:17408
	ds_read_b128 v[190:193], v147 offset:16384
	ds_read_b128 v[194:197], v147 offset:17408
	s_waitcnt vmcnt(4)
	s_barrier
	s_waitcnt lgkmcnt(0)
	s_setprio 0
	s_waitcnt lgkmcnt(0)
	v_mfma_f32_16x16x32_bf16 v[36:39], v[132:135], v[190:193], v[36:39]
	v_mfma_f32_16x16x32_bf16 v[32:35], v[140:143], v[190:193], v[32:35]
	v_mfma_f32_16x16x32_bf16 v[60:63], v[132:135], v[158:161], v[60:63]
	v_mfma_f32_16x16x32_bf16 v[56:59], v[140:143], v[158:161], v[56:59]
	v_mfma_f32_16x16x32_bf16 v[52:55], v[132:135], v[174:177], v[52:55]
	v_mfma_f32_16x16x32_bf16 v[48:51], v[140:143], v[174:177], v[48:51]
	v_mfma_f32_16x16x32_bf16 v[44:47], v[132:135], v[182:185], v[44:47]
	v_mfma_f32_16x16x32_bf16 v[40:43], v[140:143], v[182:185], v[40:43]
	v_mfma_f32_16x16x32_bf16 v[130:133], v[136:139], v[194:197], v[36:39]
	v_mfma_f32_16x16x32_bf16 v[142:145], v[152:155], v[194:197], v[32:35]
	v_mfma_f32_16x16x32_bf16 v[206:209], v[136:139], v[170:173], v[60:63]
	v_mfma_f32_16x16x32_bf16 v[210:213], v[152:155], v[170:173], v[56:59]
	v_mfma_f32_16x16x32_bf16 v[216:219], v[136:139], v[178:181], v[52:55]
	v_mfma_f32_16x16x32_bf16 v[226:229], v[152:155], v[178:181], v[48:51]
	v_mfma_f32_16x16x32_bf16 v[230:233], v[136:139], v[186:189], v[44:47]
	v_mfma_f32_16x16x32_bf16 v[234:237], v[152:155], v[186:189], v[40:43]
	s_setprio 1
	s_setprio 0
	v_mfma_f32_16x16x32_bf16 v[28:31], v[166:169], v[158:161], v[28:31]
	v_mfma_f32_16x16x32_bf16 v[24:27], v[202:205], v[158:161], v[24:27]
	v_mfma_f32_16x16x32_bf16 v[20:23], v[166:169], v[174:177], v[20:23]
	v_mfma_f32_16x16x32_bf16 v[16:19], v[202:205], v[174:177], v[16:19]
	v_mfma_f32_16x16x32_bf16 v[12:15], v[166:169], v[182:185], v[12:15]
	v_mfma_f32_16x16x32_bf16 v[8:11], v[202:205], v[182:185], v[8:11]
	v_mfma_f32_16x16x32_bf16 v[4:7], v[166:169], v[190:193], v[4:7]
	v_mfma_f32_16x16x32_bf16 v[0:3], v[202:205], v[190:193], v[0:3]
	v_mfma_f32_16x16x32_bf16 v[152:155], v[198:201], v[170:173], v[28:31]
	v_mfma_f32_16x16x32_bf16 v[158:161], v[162:165], v[170:173], v[24:27]
	v_mfma_f32_16x16x32_bf16 v[170:173], v[198:201], v[178:181], v[20:23]
	v_mfma_f32_16x16x32_bf16 v[174:177], v[162:165], v[178:181], v[16:19]
	v_mfma_f32_16x16x32_bf16 v[178:181], v[198:201], v[186:189], v[12:15]
	v_mfma_f32_16x16x32_bf16 v[182:185], v[162:165], v[186:189], v[8:11]
	v_mfma_f32_16x16x32_bf16 v[166:169], v[198:201], v[194:197], v[4:7]
	v_mfma_f32_16x16x32_bf16 v[162:165], v[162:165], v[194:197], v[0:3]
	s_setprio 1
	s_barrier
	ds_read_b128 v[186:189], v156
	ds_read_b128 v[190:193], v156 offset:1024
	ds_read_b128 v[194:197], v156 offset:2048
	ds_read_b128 v[198:201], v156 offset:3072
	ds_read_b128 v[10:13], v150 offset:32768
	ds_read_b128 v[22:25], v150 offset:33792
	ds_read_b128 v[26:29], v149 offset:32768
	ds_read_b128 v[38:41], v149 offset:33792
	ds_read_b128 v[42:45], v148 offset:32768
	ds_read_b128 v[54:57], v148 offset:33792
	ds_read_b128 v[58:61], v147 offset:32768
	ds_read_b128 v[134:137], v147 offset:33792
	s_waitcnt vmcnt(2)
	s_barrier
	s_waitcnt lgkmcnt(0)
	s_setprio 0
	s_waitcnt lgkmcnt(0)
	v_mfma_f32_16x16x32_bf16 v[6:9], v[186:189], v[26:29], v[118:121]
	v_mfma_f32_16x16x32_bf16 v[14:17], v[190:193], v[38:41], v[6:9]
	v_mfma_f32_16x16x32_bf16 v[6:9], v[194:197], v[26:29], v[114:117]
	v_mfma_f32_16x16x32_bf16 v[18:21], v[198:201], v[38:41], v[6:9]
	v_mfma_f32_16x16x32_bf16 v[6:9], v[186:189], v[42:45], v[110:113]
	v_mfma_f32_16x16x32_bf16 v[30:33], v[190:193], v[54:57], v[6:9]
	v_mfma_f32_16x16x32_bf16 v[6:9], v[194:197], v[42:45], v[106:109]
	v_mfma_f32_16x16x32_bf16 v[0:3], v[186:189], v[10:13], v[126:129]
	v_mfma_f32_16x16x32_bf16 v[34:37], v[198:201], v[54:57], v[6:9]
	v_mfma_f32_16x16x32_bf16 v[6:9], v[186:189], v[58:61], v[102:105]
	v_mfma_f32_16x16x32_bf16 v[138:141], v[190:193], v[22:25], v[0:3]
	v_mfma_f32_16x16x32_bf16 v[0:3], v[194:197], v[10:13], v[122:125]
	v_mfma_f32_16x16x32_bf16 v[46:49], v[190:193], v[134:137], v[6:9]
	v_mfma_f32_16x16x32_bf16 v[6:9], v[194:197], v[58:61], v[98:101]
	v_mfma_f32_16x16x32_bf16 v[2:5], v[198:201], v[22:25], v[0:3]
	v_mfma_f32_16x16x32_bf16 v[50:53], v[198:201], v[134:137], v[6:9]
	s_setprio 1
	s_barrier
; #define LDA(dst, b, h) _Pragma("unroll") for (int m = 0; m < 4; ++m) _Pragma("unroll") for (int k = 0; k < 2; ++k) \
;     dst[m][k] = *(const bf16x8*)(lds + SA_(b, h) + lds_byte(wr * 64 + m * 16 + fr, k * 32 + fq * 8));
; #define LDB(dst, b, h) _Pragma("unroll") for (int n = 0; n < 2; ++n) _Pragma("unroll") for (int k = 0; k < 2; ++k) \
;     dst[n][k] = *(const bf16x8*)(lds + SB_(b, h) + lds_byte(wc * 32 + n * 16 + fr, k * 32 + fq * 8));
; #define MMA(ai, bj, At_, Bt_) { __builtin_amdgcn_s_setprio(1); \
;     _Pragma("unroll") for (int m = 0; m < 4; ++m) _Pragma("unroll") for (int n = 0; n < 2; ++n) _Pragma("unroll") for (int k = 0; k < 2; ++k) \
;       acc[ai][bj][m][n] = MFMA16(Bt_[n][k], At_[m][k], acc[ai][bj][m][n]); \
;     __builtin_amdgcn_s_setprio(0); }
; #define WAIT_V(n) asm volatile("s_waitcnt vmcnt(" #n ")" ::: "memory");
; #define WAIT_L(n) asm volatile("s_waitcnt lgkmcnt(" #n ")" ::: "memory");
; #define BAR __builtin_amdgcn_s_barrier();
; DI void gemm256(const u16* __restrict__ A, int lda, const u16* __restrict__ B0, const u16* __restrict__ B1, int ldb, int nt, acc_t& acc, char* lds) {
;     ...
;     LDB(Bq1, 1, 1) WAIT_V(0) BAR WAIT_L(0) MMA(0, 1, At, Bq1) BAR
;     LDA(At, 1, 1) BAR WAIT_L(0) MMA(1, 0, At, Bq0) MMA(1, 1, At, Bq1) BAR }
;   if (wr == 0) BAR
;   __syncthreads();
	ds_read_b128 v[202:205], v151
	ds_read_b128 v[238:241], v151 offset:1024
	ds_read_b128 v[242:245], v151 offset:2048
	ds_read_b128 v[246:249], v151 offset:3072
	s_waitcnt vmcnt(0)
	s_barrier
	s_waitcnt lgkmcnt(0)
	s_setprio 0
	s_waitcnt lgkmcnt(0)
	v_mfma_f32_16x16x32_bf16 v[6:9], v[202:205], v[10:13], v[94:97]
	v_mfma_f32_16x16x32_bf16 v[10:13], v[242:245], v[10:13], v[90:93]
	v_mfma_f32_16x16x32_bf16 v[6:9], v[238:241], v[22:25], v[6:9]
	v_mfma_f32_16x16x32_bf16 v[10:13], v[246:249], v[22:25], v[10:13]
	v_mfma_f32_16x16x32_bf16 v[22:25], v[202:205], v[26:29], v[86:89]
	v_mfma_f32_16x16x32_bf16 v[26:29], v[242:245], v[26:29], v[82:85]
	v_mfma_f32_16x16x32_bf16 v[22:25], v[238:241], v[38:41], v[22:25]
	v_mfma_f32_16x16x32_bf16 v[26:29], v[246:249], v[38:41], v[26:29]
	v_mfma_f32_16x16x32_bf16 v[38:41], v[202:205], v[42:45], v[78:81]
	v_mfma_f32_16x16x32_bf16 v[42:45], v[242:245], v[42:45], v[74:77]
	v_mfma_f32_16x16x32_bf16 v[38:41], v[238:241], v[54:57], v[38:41]
	v_mfma_f32_16x16x32_bf16 v[42:45], v[246:249], v[54:57], v[42:45]
	v_mfma_f32_16x16x32_bf16 v[54:57], v[202:205], v[58:61], v[70:73]
	v_mfma_f32_16x16x32_bf16 v[58:61], v[242:245], v[58:61], v[66:69]
	v_mfma_f32_16x16x32_bf16 v[54:57], v[238:241], v[134:137], v[54:57]
	v_mfma_f32_16x16x32_bf16 v[58:61], v[246:249], v[134:137], v[58:61]
	s_setprio 1
	s_barrier
	ds_read_b128 v[76:79], v150 offset:49152
	ds_read_b128 v[80:83], v150 offset:50176
	ds_read_b128 v[88:91], v149 offset:49152
	ds_read_b128 v[110:113], v149 offset:50176
	ds_read_b128 v[114:117], v148 offset:49152
	ds_read_b128 v[148:151], v148 offset:50176
	ds_read_b128 v[222:225], v147 offset:49152
	ds_read_b128 v[98:101], v147 offset:50176
	s_barrier
	s_waitcnt lgkmcnt(0)
	s_setprio 0
	s_waitcnt lgkmcnt(0)
	v_mfma_f32_16x16x32_bf16 v[72:75], v[186:189], v[88:91], v[216:219]
	v_mfma_f32_16x16x32_bf16 v[84:87], v[190:193], v[110:113], v[72:75]
	v_mfma_f32_16x16x32_bf16 v[72:75], v[194:197], v[88:91], v[226:229]
	v_mfma_f32_16x16x32_bf16 v[94:97], v[198:201], v[110:113], v[72:75]
	v_mfma_f32_16x16x32_bf16 v[72:75], v[186:189], v[114:117], v[230:233]
	v_mfma_f32_16x16x32_bf16 v[118:121], v[190:193], v[148:151], v[72:75]
	v_mfma_f32_16x16x32_bf16 v[72:75], v[194:197], v[114:117], v[234:237]
	v_mfma_f32_16x16x32_bf16 v[66:69], v[186:189], v[76:79], v[206:209]
	v_mfma_f32_16x16x32_bf16 v[126:129], v[198:201], v[148:151], v[72:75]
	v_mfma_f32_16x16x32_bf16 v[72:75], v[186:189], v[222:225], v[130:133]
	v_mfma_f32_16x16x32_bf16 v[134:137], v[190:193], v[80:83], v[66:69]
	v_mfma_f32_16x16x32_bf16 v[66:69], v[194:197], v[76:79], v[210:213]
	v_mfma_f32_16x16x32_bf16 v[106:109], v[190:193], v[98:101], v[72:75]
	v_mfma_f32_16x16x32_bf16 v[72:75], v[194:197], v[222:225], v[142:145]
	v_mfma_f32_16x16x32_bf16 v[68:71], v[198:201], v[80:83], v[66:69]
	v_mfma_f32_16x16x32_bf16 v[142:145], v[198:201], v[98:101], v[72:75]
	s_setprio 1
	s_setprio 0
	v_mfma_f32_16x16x32_bf16 v[72:75], v[202:205], v[76:79], v[152:155]
	v_mfma_f32_16x16x32_bf16 v[76:79], v[242:245], v[76:79], v[158:161]
	v_mfma_f32_16x16x32_bf16 v[130:133], v[246:249], v[80:83], v[76:79]
	v_mfma_f32_16x16x32_bf16 v[76:79], v[202:205], v[88:91], v[170:173]
	v_mfma_f32_16x16x32_bf16 v[102:105], v[238:241], v[110:113], v[76:79]
	v_mfma_f32_16x16x32_bf16 v[76:79], v[242:245], v[88:91], v[174:177]
	v_mfma_f32_16x16x32_bf16 v[110:113], v[246:249], v[110:113], v[76:79]
	v_mfma_f32_16x16x32_bf16 v[76:79], v[202:205], v[114:117], v[178:181]
	v_mfma_f32_16x16x32_bf16 v[122:125], v[238:241], v[148:151], v[76:79]
	v_mfma_f32_16x16x32_bf16 v[76:79], v[242:245], v[114:117], v[182:185]
	v_mfma_f32_16x16x32_bf16 v[114:117], v[246:249], v[148:151], v[76:79]
	v_mfma_f32_16x16x32_bf16 v[76:79], v[202:205], v[222:225], v[166:169]
	v_mfma_f32_16x16x32_bf16 v[90:93], v[238:241], v[98:101], v[76:79]
	v_mfma_f32_16x16x32_bf16 v[76:79], v[242:245], v[222:225], v[162:165]
	v_mfma_f32_16x16x32_bf16 v[72:75], v[238:241], v[80:83], v[72:75]
	v_mfma_f32_16x16x32_bf16 v[78:81], v[246:249], v[98:101], v[76:79]
	s_setprio 1
	s_movk_i32 s3, 0x100
	v_cmp_gt_u32_e32 vcc, s3, v146
	s_barrier
	s_and_saveexec_b64 s[22:23], vcc
	s_cbranch_execz .LBB0_1263
	s_barrier

; #define STAGE_A(b, h, kt) { const u16* ap_ = A + (size_t)((h) * ahalf + (unsigned)(kt) * 64u); glds16(ap_ + ao0, l0 + SA_(b, h)); glds16(ap_ + ao1, l0 + SA_(b, h) + 8192); }
; #define STAGE_B(b, h, kt) { const u16* bp_ = ((h) ? B1 : B0) + (unsigned)(kt) * 64u; glds16(bp_ + bo0, l0 + SB_(b, h)); glds16(bp_ + bo1, l0 + SB_(b, h) + 8192); }
; #define LDA(dst, b, h) _Pragma("unroll") for (int m = 0; m < 4; ++m) _Pragma("unroll") for (int k = 0; k < 2; ++k) \
;     dst[m][k] = *(const bf16x8*)(lds + SA_(b, h) + lds_byte(wr * 64 + m * 16 + fr, k * 32 + fq * 8));
; #define LDB(dst, b, h) _Pragma("unroll") for (int n = 0; n < 2; ++n) _Pragma("unroll") for (int k = 0; k < 2; ++k) \
;     dst[n][k] = *(const bf16x8*)(lds + SB_(b, h) + lds_byte(wc * 32 + n * 16 + fr, k * 32 + fq * 8));
; #define MMA(ai, bj, At_, Bt_) { __builtin_amdgcn_s_setprio(1); \
;     _Pragma("unroll") for (int m = 0; m < 4; ++m) _Pragma("unroll") for (int n = 0; n < 2; ++n) _Pragma("unroll") for (int k = 0; k < 2; ++k) \
;       acc[ai][bj][m][n] = MFMA16(Bt_[n][k], At_[m][k], acc[ai][bj][m][n]); \
;     __builtin_amdgcn_s_setprio(0); }
; #define WAIT_V(n) asm volatile("s_waitcnt vmcnt(" #n ")" ::: "memory");
; #define WAIT_L(n) asm volatile("s_waitcnt lgkmcnt(" #n ")" ::: "memory");
; #define BAR __builtin_amdgcn_s_barrier();
; #define SCHED __builtin_amdgcn_sched_barrier(0);
; DI void gemm256(const u16* __restrict__ A, int lda, const u16* __restrict__ B0, const u16* __restrict__ B1, int ldb, int nt, acc_t& acc, char* lds) {
;     ...
;   for (int t = 0; t < nt - 2; t += 2) {
;     LDB(Bq0, 0, 0) SCHED LDA(At, 0, 0) STAGE_A(1, 1, t + 1)
;     WAIT_L(8) BAR WAIT_L(0) MMA(0, 0, At, Bq0) BAR SCHED
;     LDB(Bq1, 0, 1) STAGE_B(0, 0, t + 2)
;     BAR WAIT_L(0) MMA(0, 1, At, Bq1) BAR
;     LDA(At, 0, 1) STAGE_A(0, 0, t + 2)
;     BAR WAIT_L(0) MMA(1, 0, At, Bq0) BAR SCHED
;     STAGE_B(0, 1, t + 2)
;     WAIT_V(6) BAR MMA(1, 1, At, Bq1) BAR
.LBB0_1266:
	ds_read_b128 v[142:145], v157
	ds_read_b128 v[160:163], v157 offset:1024
	ds_read_b128 v[164:167], v157 offset:2048
	ds_read_b128 v[168:171], v157 offset:3072
	v_add_u32_e32 v158, 0xc000, v226
	v_lshl_add_u64 v[212:213], s[8:9], 0, v[134:135]
	v_readfirstlane_b32 s3, v158
	v_add_u32_e32 v159, 0xe000, v226
	v_lshl_add_u64 v[204:205], v[212:213], 0, s[28:29]
	s_mov_b32 m0, s3
	v_lshl_add_u64 v[222:223], s[8:9], 0, v[136:137]
	v_readfirstlane_b32 s3, v159
	ds_read_b128 v[172:175], v151
	ds_read_b128 v[176:179], v151 offset:1024
	ds_read_b128 v[180:183], v150
	ds_read_b128 v[184:187], v150 offset:1024
	ds_read_b128 v[188:191], v149
	ds_read_b128 v[192:195], v149 offset:1024
	ds_read_b128 v[196:199], v148
	ds_read_b128 v[200:203], v148 offset:1024
	global_load_lds_dwordx4 v[204:205], off
	v_lshl_add_u64 v[204:205], v[222:223], 0, s[28:29]
	s_mov_b32 m0, s3
	s_nop 0
	global_load_lds_dwordx4 v[204:205], off
	s_waitcnt lgkmcnt(8)
	s_barrier
	s_waitcnt lgkmcnt(0)
	s_setprio 0
	s_waitcnt lgkmcnt(0)
	v_mfma_f32_16x16x32_bf16 v[0:3], v[142:145], v[172:175], v[0:3]
	v_mfma_f32_16x16x32_bf16 v[4:7], v[164:167], v[172:175], v[4:7]
	v_mfma_f32_16x16x32_bf16 v[16:19], v[142:145], v[180:183], v[16:19]
	v_mfma_f32_16x16x32_bf16 v[20:23], v[164:167], v[180:183], v[20:23]
	v_mfma_f32_16x16x32_bf16 v[32:35], v[142:145], v[188:191], v[32:35]
	v_mfma_f32_16x16x32_bf16 v[36:39], v[164:167], v[188:191], v[36:39]
	v_mfma_f32_16x16x32_bf16 v[48:51], v[142:145], v[196:199], v[48:51]
	v_mfma_f32_16x16x32_bf16 v[52:55], v[164:167], v[196:199], v[52:55]
	v_mfma_f32_16x16x32_bf16 v[0:3], v[160:163], v[176:179], v[0:3]
	v_mfma_f32_16x16x32_bf16 v[4:7], v[168:171], v[176:179], v[4:7]
	v_mfma_f32_16x16x32_bf16 v[16:19], v[160:163], v[184:187], v[16:19]
	v_mfma_f32_16x16x32_bf16 v[20:23], v[168:171], v[184:187], v[20:23]
	v_mfma_f32_16x16x32_bf16 v[32:35], v[160:163], v[192:195], v[32:35]
	v_mfma_f32_16x16x32_bf16 v[36:39], v[168:171], v[192:195], v[36:39]
	v_mfma_f32_16x16x32_bf16 v[48:51], v[160:163], v[200:203], v[48:51]
	v_mfma_f32_16x16x32_bf16 v[52:55], v[168:171], v[200:203], v[52:55]
	s_setprio 1
	s_barrier
	v_lshl_add_u64 v[238:239], s[8:9], 0, v[130:131]
	v_readfirstlane_b32 s3, v227
	v_lshl_add_u64 v[240:241], v[238:239], 0, s[44:45]
	s_mov_b32 m0, s3
	ds_read_b128 v[204:207], v156
	ds_read_b128 v[208:211], v156 offset:1024
	ds_read_b128 v[216:219], v156 offset:2048
	ds_read_b128 v[234:237], v156 offset:3072
	global_load_lds_dwordx4 v[240:241], off
	v_lshl_add_u64 v[240:241], s[8:9], 0, v[132:133]
	v_readfirstlane_b32 s3, v228
	v_lshl_add_u64 v[242:243], v[240:241], 0, s[44:45]
	s_mov_b32 m0, s3
	s_nop 0
	global_load_lds_dwordx4 v[242:243], off
	s_barrier
	s_waitcnt lgkmcnt(0)
	s_setprio 0
	s_waitcnt lgkmcnt(0)
	v_mfma_f32_16x16x32_bf16 v[8:11], v[204:207], v[172:175], v[8:11]
	v_mfma_f32_16x16x32_bf16 v[12:15], v[216:219], v[172:175], v[12:15]
	v_mfma_f32_16x16x32_bf16 v[24:27], v[204:207], v[180:183], v[24:27]
	v_mfma_f32_16x16x32_bf16 v[28:31], v[216:219], v[180:183], v[28:31]
	v_mfma_f32_16x16x32_bf16 v[40:43], v[204:207], v[188:191], v[40:43]
	v_mfma_f32_16x16x32_bf16 v[44:47], v[216:219], v[188:191], v[44:47]
	v_mfma_f32_16x16x32_bf16 v[56:59], v[204:207], v[196:199], v[56:59]
	v_mfma_f32_16x16x32_bf16 v[60:63], v[216:219], v[196:199], v[60:63]
	v_mfma_f32_16x16x32_bf16 v[8:11], v[208:211], v[176:179], v[8:11]
	v_mfma_f32_16x16x32_bf16 v[12:15], v[234:237], v[176:179], v[12:15]
	v_mfma_f32_16x16x32_bf16 v[24:27], v[208:211], v[184:187], v[24:27]
	v_mfma_f32_16x16x32_bf16 v[28:31], v[234:237], v[184:187], v[28:31]
	v_mfma_f32_16x16x32_bf16 v[40:43], v[208:211], v[192:195], v[40:43]
	v_mfma_f32_16x16x32_bf16 v[44:47], v[234:237], v[192:195], v[44:47]
	v_mfma_f32_16x16x32_bf16 v[56:59], v[208:211], v[200:203], v[56:59]
	v_mfma_f32_16x16x32_bf16 v[60:63], v[234:237], v[200:203], v[60:63]
	s_setprio 1
	v_readfirstlane_b32 s3, v226
	v_lshl_add_u64 v[242:243], v[212:213], 0, s[70:71]
	s_mov_b32 m0, s3
	v_readfirstlane_b32 s3, v229
	s_barrier
	ds_read_b128 v[172:175], v151 offset:16384
	ds_read_b128 v[176:179], v151 offset:17408
	ds_read_b128 v[180:183], v150 offset:16384
	ds_read_b128 v[184:187], v150 offset:17408
	ds_read_b128 v[188:191], v149 offset:16384
	ds_read_b128 v[192:195], v149 offset:17408
	ds_read_b128 v[196:199], v148 offset:16384
	ds_read_b128 v[200:203], v148 offset:17408
	global_load_lds_dwordx4 v[242:243], off
	v_lshl_add_u64 v[242:243], v[222:223], 0, s[70:71]
	s_mov_b32 m0, s3
	s_nop 0
	global_load_lds_dwordx4 v[242:243], off
	s_barrier
	s_waitcnt lgkmcnt(0)
	s_setprio 0
	s_waitcnt lgkmcnt(0)
	v_mfma_f32_16x16x32_bf16 v[66:69], v[142:145], v[172:175], v[66:69]
	v_mfma_f32_16x16x32_bf16 v[70:73], v[164:167], v[172:175], v[70:73]
	v_mfma_f32_16x16x32_bf16 v[86:89], v[142:145], v[180:183], v[86:89]
	v_mfma_f32_16x16x32_bf16 v[94:97], v[164:167], v[180:183], v[94:97]
	v_mfma_f32_16x16x32_bf16 v[118:121], v[142:145], v[188:191], v[118:121]
	v_mfma_f32_16x16x32_bf16 v[126:129], v[164:167], v[188:191], v[126:129]
	v_mfma_f32_16x16x32_bf16 v[106:109], v[142:145], v[196:199], v[106:109]
	v_mfma_f32_16x16x32_bf16 v[98:101], v[164:167], v[196:199], v[98:101]
	v_mfma_f32_16x16x32_bf16 v[66:69], v[160:163], v[176:179], v[66:69]
	v_mfma_f32_16x16x32_bf16 v[70:73], v[168:171], v[176:179], v[70:73]
	v_mfma_f32_16x16x32_bf16 v[86:89], v[160:163], v[184:187], v[86:89]
	v_mfma_f32_16x16x32_bf16 v[94:97], v[168:171], v[184:187], v[94:97]
	v_mfma_f32_16x16x32_bf16 v[118:121], v[160:163], v[192:195], v[118:121]
	v_mfma_f32_16x16x32_bf16 v[126:129], v[168:171], v[192:195], v[126:129]
	v_mfma_f32_16x16x32_bf16 v[106:109], v[160:163], v[200:203], v[106:109]
	v_mfma_f32_16x16x32_bf16 v[98:101], v[168:171], v[200:203], v[98:101]
	s_setprio 1
	s_barrier
; #define STAGE_A(b, h, kt) { const u16* ap_ = A + (size_t)((h) * ahalf + (unsigned)(kt) * 64u); glds16(ap_ + ao0, l0 + SA_(b, h)); glds16(ap_ + ao1, l0 + SA_(b, h) + 8192); }
; #define STAGE_B(b, h, kt) { const u16* bp_ = ((h) ? B1 : B0) + (unsigned)(kt) * 64u; glds16(bp_ + bo0, l0 + SB_(b, h)); glds16(bp_ + bo1, l0 + SB_(b, h) + 8192); }
; #define LDA(dst, b, h) _Pragma("unroll") for (int m = 0; m < 4; ++m) _Pragma("unroll") for (int k = 0; k < 2; ++k) \
;     dst[m][k] = *(const bf16x8*)(lds + SA_(b, h) + lds_byte(wr * 64 + m * 16 + fr, k * 32 + fq * 8));
; #define LDB(dst, b, h) _Pragma("unroll") for (int n = 0; n < 2; ++n) _Pragma("unroll") for (int k = 0; k < 2; ++k) \
;     dst[n][k] = *(const bf16x8*)(lds + SB_(b, h) + lds_byte(wc * 32 + n * 16 + fr, k * 32 + fq * 8));
; #define MMA(ai, bj, At_, Bt_) { __builtin_amdgcn_s_setprio(1); \
;     _Pragma("unroll") for (int m = 0; m < 4; ++m) _Pragma("unroll") for (int n = 0; n < 2; ++n) _Pragma("unroll") for (int k = 0; k < 2; ++k) \
;       acc[ai][bj][m][n] = MFMA16(Bt_[n][k], At_[m][k], acc[ai][bj][m][n]); \
;     __builtin_amdgcn_s_setprio(0); }
; #define WAIT_V(n) asm volatile("s_waitcnt vmcnt(" #n ")" ::: "memory");
; #define WAIT_L(n) asm volatile("s_waitcnt lgkmcnt(" #n ")" ::: "memory");
; #define BAR __builtin_amdgcn_s_barrier();
; #define SCHED __builtin_amdgcn_sched_barrier(0);
; DI void gemm256(const u16* __restrict__ A, int lda, const u16* __restrict__ B0, const u16* __restrict__ B1, int ldb, int nt, acc_t& acc, char* lds) {
;     ...
;     WAIT_V(6) BAR MMA(1, 1, At, Bq1) BAR
;     LDB(Bq0, 1, 0) SCHED LDA(At, 1, 0) STAGE_A(0, 1, t + 2)
;     WAIT_L(8) BAR WAIT_L(0) MMA(0, 0, At, Bq0) BAR SCHED
;     LDB(Bq1, 1, 1) STAGE_B(1, 0, t + 3)
;     BAR WAIT_L(0) MMA(0, 1, At, Bq1) BAR
;     LDA(At, 1, 1) STAGE_A(1, 0, t + 3)
	v_readfirstlane_b32 s3, v230
	v_lshl_add_u64 v[142:143], v[238:239], 0, s[46:47]
	s_mov_b32 m0, s3
	v_readfirstlane_b32 s3, v231
	global_load_lds_dwordx4 v[142:143], off
	v_lshl_add_u64 v[142:143], v[240:241], 0, s[46:47]
	s_mov_b32 m0, s3
	s_nop 0
	global_load_lds_dwordx4 v[142:143], off
	s_waitcnt vmcnt(6)
	s_barrier
	s_setprio 0
	v_mfma_f32_16x16x32_bf16 v[74:77], v[204:207], v[172:175], v[74:77]
	v_mfma_f32_16x16x32_bf16 v[82:85], v[216:219], v[172:175], v[82:85]
	v_mfma_f32_16x16x32_bf16 v[102:105], v[204:207], v[180:183], v[102:105]
	v_mfma_f32_16x16x32_bf16 v[110:113], v[216:219], v[180:183], v[110:113]
	v_mfma_f32_16x16x32_bf16 v[122:125], v[204:207], v[188:191], v[122:125]
	v_mfma_f32_16x16x32_bf16 v[114:117], v[216:219], v[188:191], v[114:117]
	v_mfma_f32_16x16x32_bf16 v[90:93], v[204:207], v[196:199], v[90:93]
	v_mfma_f32_16x16x32_bf16 v[78:81], v[216:219], v[196:199], v[78:81]
	v_mfma_f32_16x16x32_bf16 v[74:77], v[208:211], v[176:179], v[74:77]
	v_mfma_f32_16x16x32_bf16 v[82:85], v[234:237], v[176:179], v[82:85]
	v_mfma_f32_16x16x32_bf16 v[102:105], v[208:211], v[184:187], v[102:105]
	v_mfma_f32_16x16x32_bf16 v[110:113], v[234:237], v[184:187], v[110:113]
	v_mfma_f32_16x16x32_bf16 v[122:125], v[208:211], v[192:195], v[122:125]
	v_mfma_f32_16x16x32_bf16 v[114:117], v[234:237], v[192:195], v[114:117]
	v_mfma_f32_16x16x32_bf16 v[90:93], v[208:211], v[200:203], v[90:93]
	v_mfma_f32_16x16x32_bf16 v[78:81], v[234:237], v[200:203], v[78:81]
	s_setprio 1
	s_barrier
	ds_read_b128 v[142:145], v155
	ds_read_b128 v[160:163], v155 offset:1024
	ds_read_b128 v[164:167], v155 offset:2048
	ds_read_b128 v[168:171], v155 offset:3072
	v_readfirstlane_b32 s3, v232
	v_lshl_add_u64 v[204:205], v[212:213], 0, s[48:49]
	s_mov_b32 m0, s3
	v_readfirstlane_b32 s3, v233
	ds_read_b128 v[172:175], v151 offset:32768
	ds_read_b128 v[176:179], v151 offset:33792
	ds_read_b128 v[180:183], v150 offset:32768
	ds_read_b128 v[184:187], v150 offset:33792
	ds_read_b128 v[188:191], v149 offset:32768
	ds_read_b128 v[192:195], v149 offset:33792
	ds_read_b128 v[196:199], v148 offset:32768
	ds_read_b128 v[200:203], v148 offset:33792
	global_load_lds_dwordx4 v[204:205], off
	v_lshl_add_u64 v[204:205], v[222:223], 0, s[48:49]
	s_mov_b32 m0, s3
	s_nop 0
	global_load_lds_dwordx4 v[204:205], off
	s_waitcnt lgkmcnt(8)
	s_barrier
	s_waitcnt lgkmcnt(0)
	s_setprio 0
	s_waitcnt lgkmcnt(0)
	v_mfma_f32_16x16x32_bf16 v[0:3], v[142:145], v[172:175], v[0:3]
	v_mfma_f32_16x16x32_bf16 v[4:7], v[164:167], v[172:175], v[4:7]
	v_mfma_f32_16x16x32_bf16 v[16:19], v[142:145], v[180:183], v[16:19]
	v_mfma_f32_16x16x32_bf16 v[20:23], v[164:167], v[180:183], v[20:23]
	v_mfma_f32_16x16x32_bf16 v[32:35], v[142:145], v[188:191], v[32:35]
	v_mfma_f32_16x16x32_bf16 v[36:39], v[164:167], v[188:191], v[36:39]
	v_mfma_f32_16x16x32_bf16 v[48:51], v[142:145], v[196:199], v[48:51]
	v_mfma_f32_16x16x32_bf16 v[52:55], v[164:167], v[196:199], v[52:55]
	v_mfma_f32_16x16x32_bf16 v[0:3], v[160:163], v[176:179], v[0:3]
	v_mfma_f32_16x16x32_bf16 v[4:7], v[168:171], v[176:179], v[4:7]
	v_mfma_f32_16x16x32_bf16 v[16:19], v[160:163], v[184:187], v[16:19]
	v_mfma_f32_16x16x32_bf16 v[20:23], v[168:171], v[184:187], v[20:23]
	v_mfma_f32_16x16x32_bf16 v[32:35], v[160:163], v[192:195], v[32:35]
	v_mfma_f32_16x16x32_bf16 v[36:39], v[168:171], v[192:195], v[36:39]
	v_mfma_f32_16x16x32_bf16 v[48:51], v[160:163], v[200:203], v[48:51]
	v_mfma_f32_16x16x32_bf16 v[52:55], v[168:171], v[200:203], v[52:55]
	s_setprio 1
	s_barrier
	v_readfirstlane_b32 s3, v138
	v_lshl_add_u64 v[242:243], v[238:239], 0, s[52:53]
	s_mov_b32 m0, s3
	v_readfirstlane_b32 s3, v139
	ds_read_b128 v[204:207], v154
	ds_read_b128 v[208:211], v154 offset:1024
	ds_read_b128 v[216:219], v154 offset:2048
	ds_read_b128 v[234:237], v154 offset:3072
	global_load_lds_dwordx4 v[242:243], off
	v_lshl_add_u64 v[242:243], v[240:241], 0, s[52:53]
	s_mov_b32 m0, s3
	s_nop 0
	global_load_lds_dwordx4 v[242:243], off
	s_barrier
	s_waitcnt lgkmcnt(0)
	s_setprio 0
	s_waitcnt lgkmcnt(0)
	v_mfma_f32_16x16x32_bf16 v[8:11], v[204:207], v[172:175], v[8:11]
	v_mfma_f32_16x16x32_bf16 v[12:15], v[216:219], v[172:175], v[12:15]
	v_mfma_f32_16x16x32_bf16 v[24:27], v[204:207], v[180:183], v[24:27]
	v_mfma_f32_16x16x32_bf16 v[28:31], v[216:219], v[180:183], v[28:31]
	v_mfma_f32_16x16x32_bf16 v[40:43], v[204:207], v[188:191], v[40:43]
	v_mfma_f32_16x16x32_bf16 v[44:47], v[216:219], v[188:191], v[44:47]
	v_mfma_f32_16x16x32_bf16 v[56:59], v[204:207], v[196:199], v[56:59]
	v_mfma_f32_16x16x32_bf16 v[60:63], v[216:219], v[196:199], v[60:63]
	v_mfma_f32_16x16x32_bf16 v[8:11], v[208:211], v[176:179], v[8:11]
	v_mfma_f32_16x16x32_bf16 v[12:15], v[234:237], v[176:179], v[12:15]
	v_mfma_f32_16x16x32_bf16 v[24:27], v[208:211], v[184:187], v[24:27]
	v_mfma_f32_16x16x32_bf16 v[28:31], v[234:237], v[184:187], v[28:31]
	v_mfma_f32_16x16x32_bf16 v[40:43], v[208:211], v[192:195], v[40:43]
	v_mfma_f32_16x16x32_bf16 v[44:47], v[234:237], v[192:195], v[44:47]
	v_mfma_f32_16x16x32_bf16 v[56:59], v[208:211], v[200:203], v[56:59]
	v_mfma_f32_16x16x32_bf16 v[60:63], v[234:237], v[200:203], v[60:63]
	s_setprio 1
	v_readfirstlane_b32 s3, v140
	v_lshl_add_u64 v[212:213], v[212:213], 0, s[72:73]
	s_mov_b32 m0, s3
	v_readfirstlane_b32 s3, v141
	s_barrier
	ds_read_b128 v[172:175], v151 offset:49152
	ds_read_b128 v[176:179], v151 offset:50176
	ds_read_b128 v[180:183], v150 offset:49152
	ds_read_b128 v[184:187], v150 offset:50176
	ds_read_b128 v[188:191], v149 offset:49152
	ds_read_b128 v[192:195], v149 offset:50176
	ds_read_b128 v[196:199], v148 offset:49152
	ds_read_b128 v[200:203], v148 offset:50176
	global_load_lds_dwordx4 v[212:213], off
	v_lshl_add_u64 v[212:213], v[222:223], 0, s[72:73]
	s_mov_b32 m0, s3
	s_nop 0
	global_load_lds_dwordx4 v[212:213], off
	s_barrier
; #define STAGE_A(b, h, kt) { const u16* ap_ = A + (size_t)((h) * ahalf + (unsigned)(kt) * 64u); glds16(ap_ + ao0, l0 + SA_(b, h)); glds16(ap_ + ao1, l0 + SA_(b, h) + 8192); }
; #define STAGE_B(b, h, kt) { const u16* bp_ = ((h) ? B1 : B0) + (unsigned)(kt) * 64u; glds16(bp_ + bo0, l0 + SB_(b, h)); glds16(bp_ + bo1, l0 + SB_(b, h) + 8192); }
; #define LDA(dst, b, h) _Pragma("unroll") for (int m = 0; m < 4; ++m) _Pragma("unroll") for (int k = 0; k < 2; ++k) \
;     dst[m][k] = *(const bf16x8*)(lds + SA_(b, h) + lds_byte(wr * 64 + m * 16 + fr, k * 32 + fq * 8));
; #define LDB(dst, b, h) _Pragma("unroll") for (int n = 0; n < 2; ++n) _Pragma("unroll") for (int k = 0; k < 2; ++k) \
;     dst[n][k] = *(const bf16x8*)(lds + SB_(b, h) + lds_byte(wc * 32 + n * 16 + fr, k * 32 + fq * 8));
; #define MMA(ai, bj, At_, Bt_) { __builtin_amdgcn_s_setprio(1); \
;     _Pragma("unroll") for (int m = 0; m < 4; ++m) _Pragma("unroll") for (int n = 0; n < 2; ++n) _Pragma("unroll") for (int k = 0; k < 2; ++k) \
;       acc[ai][bj][m][n] = MFMA16(Bt_[n][k], At_[m][k], acc[ai][bj][m][n]); \
;     __builtin_amdgcn_s_setprio(0); }
; #define WAIT_V(n) asm volatile("s_waitcnt vmcnt(" #n ")" ::: "memory");
; #define WAIT_L(n) asm volatile("s_waitcnt lgkmcnt(" #n ")" ::: "memory");
; #define BAR __builtin_amdgcn_s_barrier();
; #define SCHED __builtin_amdgcn_sched_barrier(0);
; DI void gemm256(const u16* __restrict__ A, int lda, const u16* __restrict__ B0, const u16* __restrict__ B1, int ldb, int nt, acc_t& acc, char* lds) {
;     ...
;     BAR WAIT_L(0) MMA(1, 0, At, Bq0) BAR SCHED
;     STAGE_B(1, 1, t + 3)
;     WAIT_V(6) BAR MMA(1, 1, At, Bq1) BAR
;   }
;   { LDB(Bq0, 0, 0) LDA(At, 0, 0) STAGE_A(1, 1, nt - 1)
;     BAR WAIT_L(0) MMA(0, 0, At, Bq0) BAR
;     LDB(Bq1, 0, 1) BAR WAIT_L(0) MMA(0, 1, At, Bq1) BAR
	s_waitcnt lgkmcnt(0)
	s_setprio 0
	s_waitcnt lgkmcnt(0)
	v_mfma_f32_16x16x32_bf16 v[66:69], v[142:145], v[172:175], v[66:69]
	v_mfma_f32_16x16x32_bf16 v[70:73], v[164:167], v[172:175], v[70:73]
	v_mfma_f32_16x16x32_bf16 v[86:89], v[142:145], v[180:183], v[86:89]
	v_mfma_f32_16x16x32_bf16 v[94:97], v[164:167], v[180:183], v[94:97]
	v_mfma_f32_16x16x32_bf16 v[118:121], v[142:145], v[188:191], v[118:121]
	v_mfma_f32_16x16x32_bf16 v[126:129], v[164:167], v[188:191], v[126:129]
	v_mfma_f32_16x16x32_bf16 v[106:109], v[142:145], v[196:199], v[106:109]
	v_mfma_f32_16x16x32_bf16 v[98:101], v[164:167], v[196:199], v[98:101]
	v_mfma_f32_16x16x32_bf16 v[66:69], v[160:163], v[176:179], v[66:69]
	v_mfma_f32_16x16x32_bf16 v[70:73], v[168:171], v[176:179], v[70:73]
	v_mfma_f32_16x16x32_bf16 v[86:89], v[160:163], v[184:187], v[86:89]
	v_mfma_f32_16x16x32_bf16 v[94:97], v[168:171], v[184:187], v[94:97]
	v_mfma_f32_16x16x32_bf16 v[118:121], v[160:163], v[192:195], v[118:121]
	v_mfma_f32_16x16x32_bf16 v[126:129], v[168:171], v[192:195], v[126:129]
	v_mfma_f32_16x16x32_bf16 v[106:109], v[160:163], v[200:203], v[106:109]
	v_mfma_f32_16x16x32_bf16 v[98:101], v[168:171], v[200:203], v[98:101]
	s_setprio 1
	s_barrier
	v_readfirstlane_b32 s3, v152
	v_lshl_add_u64 v[142:143], v[238:239], 0, s[54:55]
	s_mov_b32 m0, s3
	v_readfirstlane_b32 s3, v153
	global_load_lds_dwordx4 v[142:143], off
	v_lshl_add_u64 v[142:143], v[240:241], 0, s[54:55]
	s_mov_b32 m0, s3
	s_nop 0
	global_load_lds_dwordx4 v[142:143], off
	s_waitcnt vmcnt(6)
	s_barrier
	s_setprio 0
	v_mfma_f32_16x16x32_bf16 v[74:77], v[204:207], v[172:175], v[74:77]
	v_mfma_f32_16x16x32_bf16 v[82:85], v[216:219], v[172:175], v[82:85]
	v_mfma_f32_16x16x32_bf16 v[102:105], v[204:207], v[180:183], v[102:105]
	v_mfma_f32_16x16x32_bf16 v[110:113], v[216:219], v[180:183], v[110:113]
	v_mfma_f32_16x16x32_bf16 v[122:125], v[204:207], v[188:191], v[122:125]
	v_mfma_f32_16x16x32_bf16 v[114:117], v[216:219], v[188:191], v[114:117]
	v_mfma_f32_16x16x32_bf16 v[90:93], v[204:207], v[196:199], v[90:93]
	v_mfma_f32_16x16x32_bf16 v[78:81], v[216:219], v[196:199], v[78:81]
	v_mfma_f32_16x16x32_bf16 v[74:77], v[208:211], v[176:179], v[74:77]
	v_mfma_f32_16x16x32_bf16 v[82:85], v[234:237], v[176:179], v[82:85]
	v_mfma_f32_16x16x32_bf16 v[102:105], v[208:211], v[184:187], v[102:105]
	v_mfma_f32_16x16x32_bf16 v[110:113], v[234:237], v[184:187], v[110:113]
	v_mfma_f32_16x16x32_bf16 v[122:125], v[208:211], v[192:195], v[122:125]
	v_mfma_f32_16x16x32_bf16 v[114:117], v[234:237], v[192:195], v[114:117]
	v_mfma_f32_16x16x32_bf16 v[90:93], v[208:211], v[200:203], v[90:93]
	v_mfma_f32_16x16x32_bf16 v[78:81], v[234:237], v[200:203], v[78:81]
	s_setprio 1
	s_add_i32 s2, s2, 2
	s_add_u32 s8, s8, 0x100
	s_addc_u32 s9, s9, 0
	s_cmp_lt_u32 s2, 40
	s_barrier
	s_cbranch_scc1 .LBB0_1266
	s_add_u32 s2, s22, 0xb1580
	s_addc_u32 s3, s23, 0
	v_readfirstlane_b32 s7, v158
	v_lshl_add_u64 v[152:153], v[64:65], 1, s[2:3]
	s_mov_b32 m0, s7
	v_lshl_add_u64 v[146:147], v[146:147], 1, s[2:3]
	v_readfirstlane_b32 s2, v159
	ds_read_b128 v[130:133], v157
	ds_read_b128 v[134:137], v157 offset:1024
	ds_read_b128 v[138:141], v157 offset:2048
	ds_read_b128 v[142:145], v157 offset:3072
	ds_read_b128 v[160:163], v151
	ds_read_b128 v[164:167], v151 offset:1024
	ds_read_b128 v[168:171], v150
	ds_read_b128 v[172:175], v150 offset:1024
	ds_read_b128 v[176:179], v149
	ds_read_b128 v[180:183], v149 offset:1024
	ds_read_b128 v[184:187], v148
	ds_read_b128 v[188:191], v148 offset:1024
	global_load_lds_dwordx4 v[152:153], off
	s_mov_b32 m0, s2
	s_nop 0
	global_load_lds_dwordx4 v[146:147], off
	s_barrier
	s_waitcnt lgkmcnt(0)
	s_setprio 0
	s_waitcnt lgkmcnt(0)
	v_mfma_f32_16x16x32_bf16 v[0:3], v[130:133], v[160:163], v[0:3]
	v_mfma_f32_16x16x32_bf16 v[4:7], v[138:141], v[160:163], v[4:7]
	v_mfma_f32_16x16x32_bf16 v[16:19], v[130:133], v[168:171], v[16:19]
	v_mfma_f32_16x16x32_bf16 v[20:23], v[138:141], v[168:171], v[20:23]
	v_mfma_f32_16x16x32_bf16 v[32:35], v[130:133], v[176:179], v[32:35]
	v_mfma_f32_16x16x32_bf16 v[36:39], v[138:141], v[176:179], v[36:39]
	v_mfma_f32_16x16x32_bf16 v[48:51], v[130:133], v[184:187], v[48:51]
	v_mfma_f32_16x16x32_bf16 v[52:55], v[138:141], v[184:187], v[52:55]
	v_mfma_f32_16x16x32_bf16 v[0:3], v[134:137], v[164:167], v[0:3]
	v_mfma_f32_16x16x32_bf16 v[4:7], v[142:145], v[164:167], v[4:7]
	v_mfma_f32_16x16x32_bf16 v[16:19], v[134:137], v[172:175], v[16:19]
	v_mfma_f32_16x16x32_bf16 v[20:23], v[142:145], v[172:175], v[20:23]
	v_mfma_f32_16x16x32_bf16 v[32:35], v[134:137], v[180:183], v[32:35]
	v_mfma_f32_16x16x32_bf16 v[36:39], v[142:145], v[180:183], v[36:39]
	v_mfma_f32_16x16x32_bf16 v[48:51], v[134:137], v[188:191], v[48:51]
	v_mfma_f32_16x16x32_bf16 v[52:55], v[142:145], v[188:191], v[52:55]
	s_setprio 1
	s_barrier
	ds_read_b128 v[192:195], v156
	ds_read_b128 v[196:199], v156 offset:1024
	ds_read_b128 v[200:203], v156 offset:2048
	ds_read_b128 v[156:159], v156 offset:3072
	s_barrier
	s_waitcnt lgkmcnt(0)
	s_setprio 0
	s_waitcnt lgkmcnt(0)
	v_mfma_f32_16x16x32_bf16 v[8:11], v[192:195], v[160:163], v[8:11]
	v_mfma_f32_16x16x32_bf16 v[12:15], v[200:203], v[160:163], v[12:15]
	v_mfma_f32_16x16x32_bf16 v[24:27], v[192:195], v[168:171], v[24:27]
	v_mfma_f32_16x16x32_bf16 v[28:31], v[200:203], v[168:171], v[28:31]
	v_mfma_f32_16x16x32_bf16 v[40:43], v[192:195], v[176:179], v[40:43]
	v_mfma_f32_16x16x32_bf16 v[44:47], v[200:203], v[176:179], v[44:47]
	v_mfma_f32_16x16x32_bf16 v[56:59], v[192:195], v[184:187], v[56:59]
	v_mfma_f32_16x16x32_bf16 v[60:63], v[200:203], v[184:187], v[60:63]
	v_mfma_f32_16x16x32_bf16 v[8:11], v[196:199], v[164:167], v[8:11]
	v_mfma_f32_16x16x32_bf16 v[12:15], v[156:159], v[164:167], v[12:15]
	v_mfma_f32_16x16x32_bf16 v[24:27], v[196:199], v[172:175], v[24:27]
	v_mfma_f32_16x16x32_bf16 v[28:31], v[156:159], v[172:175], v[28:31]
	v_mfma_f32_16x16x32_bf16 v[40:43], v[196:199], v[180:183], v[40:43]
	v_mfma_f32_16x16x32_bf16 v[44:47], v[156:159], v[180:183], v[44:47]
	v_mfma_f32_16x16x32_bf16 v[56:59], v[196:199], v[188:191], v[56:59]
	v_mfma_f32_16x16x32_bf16 v[60:63], v[156:159], v[188:191], v[60:63]
	s_setprio 1
	s_barrier
; #define LDA(dst, b, h) _Pragma("unroll") for (int m = 0; m < 4; ++m) _Pragma("unroll") for (int k = 0; k < 2; ++k) \
;     dst[m][k] = *(const bf16x8*)(lds + SA_(b, h) + lds_byte(wr * 64 + m * 16 + fr, k * 32 + fq * 8));
; #define LDB(dst, b, h) _Pragma("unroll") for (int n = 0; n < 2; ++n) _Pragma("unroll") for (int k = 0; k < 2; ++k) \
;     dst[n][k] = *(const bf16x8*)(lds + SB_(b, h) + lds_byte(wc * 32 + n * 16 + fr, k * 32 + fq * 8));
; #define MMA(ai, bj, At_, Bt_) { __builtin_amdgcn_s_setprio(1); \
;     _Pragma("unroll") for (int m = 0; m < 4; ++m) _Pragma("unroll") for (int n = 0; n < 2; ++n) _Pragma("unroll") for (int k = 0; k < 2; ++k) \
;       acc[ai][bj][m][n] = MFMA16(Bt_[n][k], At_[m][k], acc[ai][bj][m][n]); \
;     __builtin_amdgcn_s_setprio(0); }
; #define WAIT_V(n) asm volatile("s_waitcnt vmcnt(" #n ")" ::: "memory");
; #define WAIT_L(n) asm volatile("s_waitcnt lgkmcnt(" #n ")" ::: "memory");
; #define BAR __builtin_amdgcn_s_barrier();
; DI void gemm256(const u16* __restrict__ A, int lda, const u16* __restrict__ B0, const u16* __restrict__ B1, int ldb, int nt, acc_t& acc, char* lds) {
;     ...
;     LDA(At, 0, 1) WAIT_V(4) BAR WAIT_L(0) MMA(1, 0, At, Bq0) MMA(1, 1, At, Bq1) BAR }
;   { LDB(Bq0, 1, 0) LDA(At, 1, 0) WAIT_V(2) BAR WAIT_L(0) MMA(0, 0, At, Bq0) BAR
	ds_read_b128 v[160:163], v151 offset:16384
	ds_read_b128 v[164:167], v151 offset:17408
	ds_read_b128 v[168:171], v150 offset:16384
	ds_read_b128 v[172:175], v150 offset:17408
	ds_read_b128 v[176:179], v149 offset:16384
	ds_read_b128 v[180:183], v149 offset:17408
	ds_read_b128 v[184:187], v148 offset:16384
	ds_read_b128 v[188:191], v148 offset:17408
	s_waitcnt vmcnt(4)
	s_barrier
	s_waitcnt lgkmcnt(0)
	s_setprio 0
	s_waitcnt lgkmcnt(0)
	v_mfma_f32_16x16x32_bf16 v[66:69], v[130:133], v[160:163], v[66:69]
	v_mfma_f32_16x16x32_bf16 v[204:207], v[134:137], v[164:167], v[66:69]
	v_mfma_f32_16x16x32_bf16 v[66:69], v[138:141], v[160:163], v[70:73]
	v_mfma_f32_16x16x32_bf16 v[208:211], v[142:145], v[164:167], v[66:69]
	v_mfma_f32_16x16x32_bf16 v[66:69], v[130:133], v[168:171], v[86:89]
	v_mfma_f32_16x16x32_bf16 v[216:219], v[134:137], v[172:175], v[66:69]
	v_mfma_f32_16x16x32_bf16 v[66:69], v[138:141], v[168:171], v[94:97]
	v_mfma_f32_16x16x32_bf16 v[226:229], v[142:145], v[172:175], v[66:69]
	v_mfma_f32_16x16x32_bf16 v[66:69], v[130:133], v[176:179], v[118:121]
	v_mfma_f32_16x16x32_bf16 v[230:233], v[134:137], v[180:183], v[66:69]
	v_mfma_f32_16x16x32_bf16 v[66:69], v[138:141], v[176:179], v[126:129]
	v_mfma_f32_16x16x32_bf16 v[234:237], v[142:145], v[180:183], v[66:69]
	v_mfma_f32_16x16x32_bf16 v[66:69], v[130:133], v[184:187], v[106:109]
	v_mfma_f32_16x16x32_bf16 v[134:137], v[134:137], v[188:191], v[66:69]
	v_mfma_f32_16x16x32_bf16 v[66:69], v[138:141], v[184:187], v[98:101]
	v_mfma_f32_16x16x32_bf16 v[138:141], v[142:145], v[188:191], v[66:69]
	s_setprio 1
	s_setprio 0
	v_mfma_f32_16x16x32_bf16 v[66:69], v[192:195], v[160:163], v[74:77]
	v_mfma_f32_16x16x32_bf16 v[142:145], v[196:199], v[164:167], v[66:69]
	v_mfma_f32_16x16x32_bf16 v[66:69], v[200:203], v[160:163], v[82:85]
	v_mfma_f32_16x16x32_bf16 v[160:163], v[156:159], v[164:167], v[66:69]
	v_mfma_f32_16x16x32_bf16 v[66:69], v[192:195], v[168:171], v[102:105]
	v_mfma_f32_16x16x32_bf16 v[164:167], v[196:199], v[172:175], v[66:69]
	v_mfma_f32_16x16x32_bf16 v[66:69], v[200:203], v[168:171], v[110:113]
	v_mfma_f32_16x16x32_bf16 v[168:171], v[156:159], v[172:175], v[66:69]
	v_mfma_f32_16x16x32_bf16 v[66:69], v[192:195], v[176:179], v[122:125]
	v_mfma_f32_16x16x32_bf16 v[122:125], v[196:199], v[180:183], v[66:69]
	v_mfma_f32_16x16x32_bf16 v[66:69], v[200:203], v[176:179], v[114:117]
	v_mfma_f32_16x16x32_bf16 v[172:175], v[156:159], v[180:183], v[66:69]
	v_mfma_f32_16x16x32_bf16 v[66:69], v[192:195], v[184:187], v[90:93]
	v_mfma_f32_16x16x32_bf16 v[176:179], v[196:199], v[188:191], v[66:69]
	v_mfma_f32_16x16x32_bf16 v[66:69], v[200:203], v[184:187], v[78:81]
	v_mfma_f32_16x16x32_bf16 v[156:159], v[156:159], v[188:191], v[66:69]
	s_setprio 1
	s_barrier
	ds_read_b128 v[180:183], v155
	ds_read_b128 v[184:187], v155 offset:1024
	ds_read_b128 v[188:191], v155 offset:2048
	ds_read_b128 v[192:195], v155 offset:3072
	s_nop 0
	ds_read_b128 v[66:69], v151 offset:32768
	ds_read_b128 v[70:73], v151 offset:33792
	ds_read_b128 v[82:85], v150 offset:32768
	ds_read_b128 v[86:89], v150 offset:33792
	ds_read_b128 v[196:199], v149 offset:32768
	ds_read_b128 v[200:203], v149 offset:33792
	ds_read_b128 v[238:241], v148 offset:32768
	ds_read_b128 v[242:245], v148 offset:33792
	s_waitcnt vmcnt(2)
	s_barrier
	s_waitcnt lgkmcnt(0)
	s_setprio 0
	s_waitcnt lgkmcnt(0)
	v_mfma_f32_16x16x32_bf16 v[0:3], v[180:183], v[66:69], v[0:3]
	v_mfma_f32_16x16x32_bf16 v[126:129], v[184:187], v[70:73], v[0:3]
	v_mfma_f32_16x16x32_bf16 v[0:3], v[188:191], v[66:69], v[4:7]
	v_mfma_f32_16x16x32_bf16 v[130:133], v[192:195], v[70:73], v[0:3]
	v_mfma_f32_16x16x32_bf16 v[0:3], v[180:183], v[82:85], v[16:19]
	v_mfma_f32_16x16x32_bf16 v[110:113], v[184:187], v[86:89], v[0:3]
	v_mfma_f32_16x16x32_bf16 v[0:3], v[188:191], v[82:85], v[20:23]
	v_mfma_f32_16x16x32_bf16 v[106:109], v[192:195], v[86:89], v[0:3]
	v_mfma_f32_16x16x32_bf16 v[0:3], v[180:183], v[196:199], v[32:35]
	v_mfma_f32_16x16x32_bf16 v[94:97], v[184:187], v[200:203], v[0:3]
	v_mfma_f32_16x16x32_bf16 v[0:3], v[188:191], v[196:199], v[36:39]
	v_mfma_f32_16x16x32_bf16 v[90:93], v[192:195], v[200:203], v[0:3]
	v_mfma_f32_16x16x32_bf16 v[0:3], v[180:183], v[238:241], v[48:51]
	v_mfma_f32_16x16x32_bf16 v[78:81], v[184:187], v[242:245], v[0:3]
	v_mfma_f32_16x16x32_bf16 v[0:3], v[188:191], v[238:241], v[52:55]
	v_mfma_f32_16x16x32_bf16 v[74:77], v[192:195], v[242:245], v[0:3]
	s_setprio 1
	s_barrier
; #define LDA(dst, b, h) _Pragma("unroll") for (int m = 0; m < 4; ++m) _Pragma("unroll") for (int k = 0; k < 2; ++k) \
;     dst[m][k] = *(const bf16x8*)(lds + SA_(b, h) + lds_byte(wr * 64 + m * 16 + fr, k * 32 + fq * 8));
; #define LDB(dst, b, h) _Pragma("unroll") for (int n = 0; n < 2; ++n) _Pragma("unroll") for (int k = 0; k < 2; ++k) \
;     dst[n][k] = *(const bf16x8*)(lds + SB_(b, h) + lds_byte(wc * 32 + n * 16 + fr, k * 32 + fq * 8));
; #define MMA(ai, bj, At_, Bt_) { __builtin_amdgcn_s_setprio(1); \
;     _Pragma("unroll") for (int m = 0; m < 4; ++m) _Pragma("unroll") for (int n = 0; n < 2; ++n) _Pragma("unroll") for (int k = 0; k < 2; ++k) \
;       acc[ai][bj][m][n] = MFMA16(Bt_[n][k], At_[m][k], acc[ai][bj][m][n]); \
;     __builtin_amdgcn_s_setprio(0); }
; #define WAIT_V(n) asm volatile("s_waitcnt vmcnt(" #n ")" ::: "memory");
; #define WAIT_L(n) asm volatile("s_waitcnt lgkmcnt(" #n ")" ::: "memory");
; #define BAR __builtin_amdgcn_s_barrier();
; DI void gemm256(const u16* __restrict__ A, int lda, const u16* __restrict__ B0, const u16* __restrict__ B1, int ldb, int nt, acc_t& acc, char* lds) {
;     ...
;   { LDB(Bq0, 1, 0) LDA(At, 1, 0) WAIT_V(2) BAR WAIT_L(0) MMA(0, 0, At, Bq0) BAR
;     LDB(Bq1, 1, 1) WAIT_V(0) BAR WAIT_L(0) MMA(0, 1, At, Bq1) BAR
;     LDA(At, 1, 1) BAR WAIT_L(0) MMA(1, 0, At, Bq0) MMA(1, 1, At, Bq1) BAR }
;   if (wr == 0) BAR
;   __syncthreads();
	s_nop 4
	ds_read_b128 v[0:3], v154
	ds_read_b128 v[4:7], v154 offset:1024
	ds_read_b128 v[246:249], v154 offset:2048
	ds_read_b128 v[152:155], v154 offset:3072
	s_waitcnt vmcnt(0)
	s_barrier
	s_waitcnt lgkmcnt(0)
	s_setprio 0
	s_waitcnt lgkmcnt(0)
	v_mfma_f32_16x16x32_bf16 v[8:11], v[0:3], v[66:69], v[8:11]
	v_mfma_f32_16x16x32_bf16 v[118:121], v[4:7], v[70:73], v[8:11]
	v_mfma_f32_16x16x32_bf16 v[8:11], v[246:249], v[66:69], v[12:15]
	v_mfma_f32_16x16x32_bf16 v[114:117], v[152:155], v[70:73], v[8:11]
	v_mfma_f32_16x16x32_bf16 v[8:11], v[0:3], v[82:85], v[24:27]
	v_mfma_f32_16x16x32_bf16 v[102:105], v[4:7], v[86:89], v[8:11]
	v_mfma_f32_16x16x32_bf16 v[8:11], v[246:249], v[82:85], v[28:31]
	v_mfma_f32_16x16x32_bf16 v[98:101], v[152:155], v[86:89], v[8:11]
	v_mfma_f32_16x16x32_bf16 v[8:11], v[0:3], v[196:199], v[40:43]
	v_mfma_f32_16x16x32_bf16 v[86:89], v[4:7], v[200:203], v[8:11]
	v_mfma_f32_16x16x32_bf16 v[8:11], v[246:249], v[196:199], v[44:47]
	v_mfma_f32_16x16x32_bf16 v[82:85], v[152:155], v[200:203], v[8:11]
	v_mfma_f32_16x16x32_bf16 v[8:11], v[0:3], v[238:241], v[56:59]
	v_mfma_f32_16x16x32_bf16 v[70:73], v[4:7], v[242:245], v[8:11]
	v_mfma_f32_16x16x32_bf16 v[8:11], v[246:249], v[238:241], v[60:63]
	v_mfma_f32_16x16x32_bf16 v[66:69], v[152:155], v[242:245], v[8:11]
	s_setprio 1
	s_barrier
	ds_read_b128 v[16:19], v151 offset:49152
	ds_read_b128 v[20:23], v151 offset:50176
	ds_read_b128 v[32:35], v150 offset:49152
	ds_read_b128 v[196:199], v150 offset:50176
	ds_read_b128 v[200:203], v149 offset:49152
	ds_read_b128 v[238:241], v149 offset:50176
	ds_read_b128 v[242:245], v148 offset:49152
	ds_read_b128 v[146:149], v148 offset:50176
	s_barrier
	s_waitcnt lgkmcnt(0)
	s_setprio 0
	s_waitcnt lgkmcnt(0)
	v_mfma_f32_16x16x32_bf16 v[8:11], v[180:183], v[16:19], v[204:207]
	v_mfma_f32_16x16x32_bf16 v[60:63], v[184:187], v[20:23], v[8:11]
	v_mfma_f32_16x16x32_bf16 v[8:11], v[188:191], v[16:19], v[208:211]
	v_mfma_f32_16x16x32_bf16 v[56:59], v[192:195], v[20:23], v[8:11]
	v_mfma_f32_16x16x32_bf16 v[8:11], v[180:183], v[32:35], v[216:219]
	v_mfma_f32_16x16x32_bf16 v[44:47], v[184:187], v[196:199], v[8:11]
	v_mfma_f32_16x16x32_bf16 v[8:11], v[188:191], v[32:35], v[226:229]
	v_mfma_f32_16x16x32_bf16 v[40:43], v[192:195], v[196:199], v[8:11]
	v_mfma_f32_16x16x32_bf16 v[8:11], v[180:183], v[200:203], v[230:233]
	v_mfma_f32_16x16x32_bf16 v[28:31], v[184:187], v[238:241], v[8:11]
	v_mfma_f32_16x16x32_bf16 v[8:11], v[188:191], v[200:203], v[234:237]
	v_mfma_f32_16x16x32_bf16 v[24:27], v[192:195], v[238:241], v[8:11]
	v_mfma_f32_16x16x32_bf16 v[8:11], v[180:183], v[242:245], v[134:137]
	v_mfma_f32_16x16x32_bf16 v[12:15], v[184:187], v[146:149], v[8:11]
	v_mfma_f32_16x16x32_bf16 v[8:11], v[188:191], v[242:245], v[138:141]
	v_mfma_f32_16x16x32_bf16 v[8:11], v[192:195], v[146:149], v[8:11]
	s_setprio 1
	s_setprio 0
	v_mfma_f32_16x16x32_bf16 v[36:39], v[0:3], v[16:19], v[142:145]
	v_mfma_f32_16x16x32_bf16 v[16:19], v[246:249], v[16:19], v[160:163]
	v_mfma_f32_16x16x32_bf16 v[48:51], v[152:155], v[20:23], v[16:19]
	v_mfma_f32_16x16x32_bf16 v[16:19], v[0:3], v[32:35], v[164:167]
	v_mfma_f32_16x16x32_bf16 v[52:55], v[4:7], v[20:23], v[36:39]
	v_mfma_f32_16x16x32_bf16 v[36:39], v[4:7], v[196:199], v[16:19]
	v_mfma_f32_16x16x32_bf16 v[16:19], v[246:249], v[32:35], v[168:171]
	v_mfma_f32_16x16x32_bf16 v[32:35], v[152:155], v[196:199], v[16:19]
	v_mfma_f32_16x16x32_bf16 v[16:19], v[0:3], v[200:203], v[122:125]
	v_mfma_f32_16x16x32_bf16 v[0:3], v[0:3], v[242:245], v[176:179]
	v_mfma_f32_16x16x32_bf16 v[20:23], v[4:7], v[238:241], v[16:19]
	v_mfma_f32_16x16x32_bf16 v[16:19], v[246:249], v[200:203], v[172:175]
	v_mfma_f32_16x16x32_bf16 v[4:7], v[4:7], v[146:149], v[0:3]
	v_mfma_f32_16x16x32_bf16 v[0:3], v[246:249], v[242:245], v[156:159]
	v_mfma_f32_16x16x32_bf16 v[16:19], v[152:155], v[238:241], v[16:19]
	v_mfma_f32_16x16x32_bf16 v[0:3], v[152:155], v[146:149], v[0:3]
	s_setprio 1
	s_movk_i32 s2, 0x100
	v_cmp_gt_u32_e32 vcc, s2, v225
	s_barrier
	s_and_saveexec_b64 s[8:9], vcc
	s_cbranch_execz .LBB0_1240
	s_barrier
	s_branch .LBB0_1240
